# accumulator zeroing via a peeled first K-iteration (SrcC=0) instead of a per-iteration scalar test and out-of-line segment copies
# baseline (speedup 1.0000x reference)
.LBB0_119:
	s_ashr_i32 s81, s80, 31
	s_lshl_b64 s[52:53], s[80:81], 19
	s_add_u32 s82, s12, s52
	s_addc_u32 s83, s13, s53
	s_and_b64 s[52:53], s[6:7], exec
	s_cselect_b32 s52, s83, s89
	s_cselect_b32 s53, s82, s88
	s_ashr_i32 s79, s78, 31
	s_lshl_b64 s[56:57], s[78:79], 19
	s_add_u32 s84, s14, s56
	s_addc_u32 s85, s15, s57
	s_and_b64 s[56:57], s[6:7], exec
	s_cselect_b32 s56, s85, s91
	s_cselect_b32 s57, s84, s90
	s_add_u32 s88, s88, 0x40080
	s_addc_u32 s89, s89, 0
	s_add_u32 s58, s90, 0x100
	v_mov_b32_e32 v0, 0
	s_addc_u32 s59, s91, 0
	s_mov_b32 s66, -2
	s_waitcnt lgkmcnt(0)
	ds_read_b128 v[128:131], v178
	ds_read_b128 v[132:135], v178 offset:1024
	ds_read_b128 v[154:157], v178 offset:2048
	ds_read_b128 v[158:161], v178 offset:3072
	ds_read_b128 v[162:165], v179
	ds_read_b128 v[166:169], v179 offset:1024
	ds_read_b128 v[182:185], v179 offset:2048
	ds_read_b128 v[186:189], v179 offset:3072
	s_add_u32 s67, s88, 0xfffc0080
	s_addc_u32 s68, s89, -1
	s_cmp_eq_u32 s66, 12
	s_cselect_b32 s93, s52, s68
	s_cselect_b32 s92, s53, s67
	s_cselect_b32 s91, s56, s59
	s_cselect_b32 s90, s57, s58
	v_lshl_add_u64 v[170:171], s[88:89], 0, v[144:145]
	s_add_i32 m0, s17, 0xc000
	ds_read_b128 v[190:193], v180
	ds_read_b128 v[194:197], v180 offset:1024
	ds_read_b128 v[198:201], v180 offset:2048
	ds_read_b128 v[202:205], v180 offset:3072
	ds_read_b128 v[206:209], v180 offset:4096
	ds_read_b128 v[210:213], v180 offset:5120
	ds_read_b128 v[214:217], v180 offset:6144
	ds_read_b128 v[218:221], v180 offset:7168
	global_load_lds_dwordx4 v[170:171], off
	s_add_i32 m0, s17, 0xe000
	v_lshl_add_u64 v[170:171], s[88:89], 0, v[148:149]
	global_load_lds_dwordx4 v[170:171], off
	s_waitcnt vmcnt(8) lgkmcnt(0)
	s_barrier
	s_setprio 1
	v_mfma_f32_16x16x32_bf16 v[124:127], v[128:131], v[190:193], 0
	v_mfma_f32_16x16x32_bf16 v[124:127], v[132:135], v[194:197], v[124:127]
	v_mfma_f32_16x16x32_bf16 v[116:119], v[154:157], v[190:193], 0
	v_mfma_f32_16x16x32_bf16 v[116:119], v[158:161], v[194:197], v[116:119]
	v_mfma_f32_16x16x32_bf16 v[108:111], v[128:131], v[198:201], 0
	v_mfma_f32_16x16x32_bf16 v[108:111], v[132:135], v[202:205], v[108:111]
	v_mfma_f32_16x16x32_bf16 v[100:103], v[154:157], v[198:201], 0
	v_mfma_f32_16x16x32_bf16 v[100:103], v[158:161], v[202:205], v[100:103]
	v_mfma_f32_16x16x32_bf16 v[92:95], v[128:131], v[206:209], 0
	v_mfma_f32_16x16x32_bf16 v[92:95], v[132:135], v[210:213], v[92:95]
	v_mfma_f32_16x16x32_bf16 v[84:87], v[154:157], v[206:209], 0
	v_mfma_f32_16x16x32_bf16 v[84:87], v[158:161], v[210:213], v[84:87]
	v_mfma_f32_16x16x32_bf16 v[76:79], v[128:131], v[214:217], 0
	v_mfma_f32_16x16x32_bf16 v[76:79], v[132:135], v[218:221], v[76:79]
	v_mfma_f32_16x16x32_bf16 v[68:71], v[154:157], v[214:217], 0
	v_mfma_f32_16x16x32_bf16 v[68:71], v[158:161], v[218:221], v[68:71]
	v_mfma_f32_16x16x32_bf16 v[120:123], v[162:165], v[190:193], 0
	v_mfma_f32_16x16x32_bf16 v[120:123], v[166:169], v[194:197], v[120:123]
	v_mfma_f32_16x16x32_bf16 v[112:115], v[182:185], v[190:193], 0
	v_mfma_f32_16x16x32_bf16 v[112:115], v[186:189], v[194:197], v[112:115]
	v_mfma_f32_16x16x32_bf16 v[104:107], v[162:165], v[198:201], 0
	v_mfma_f32_16x16x32_bf16 v[104:107], v[166:169], v[202:205], v[104:107]
	v_mfma_f32_16x16x32_bf16 v[96:99], v[182:185], v[198:201], 0
	v_mfma_f32_16x16x32_bf16 v[96:99], v[186:189], v[202:205], v[96:99]
	v_mfma_f32_16x16x32_bf16 v[88:91], v[162:165], v[206:209], 0
	v_mfma_f32_16x16x32_bf16 v[88:91], v[166:169], v[210:213], v[88:91]
	v_mfma_f32_16x16x32_bf16 v[80:83], v[182:185], v[206:209], 0
	v_mfma_f32_16x16x32_bf16 v[80:83], v[186:189], v[210:213], v[80:83]
	v_mfma_f32_16x16x32_bf16 v[72:75], v[162:165], v[214:217], 0
	v_mfma_f32_16x16x32_bf16 v[72:75], v[166:169], v[218:221], v[72:75]
	s_setprio 3
	s_barrier
	v_mfma_f32_16x16x32_bf16 v[64:67], v[182:185], v[214:217], 0
	v_mfma_f32_16x16x32_bf16 v[64:67], v[186:189], v[218:221], v[64:67]
	s_setprio 0
	s_add_i32 s67, s25, s16
	v_lshl_add_u64 v[170:171], s[90:91], 0, v[140:141]
	s_mov_b32 m0, s67
	ds_read_b128 v[190:193], v180 offset:16384
	ds_read_b128 v[194:197], v180 offset:17408
	ds_read_b128 v[198:201], v180 offset:18432
	ds_read_b128 v[202:205], v180 offset:19456
	ds_read_b128 v[206:209], v180 offset:20480
	ds_read_b128 v[210:213], v180 offset:21504
	ds_read_b128 v[214:217], v180 offset:22528
	ds_read_b128 v[218:221], v180 offset:23552
	global_load_lds_dwordx4 v[170:171], off
	s_add_i32 m0, s67, 0x2000
	s_add_u32 s68, s90, 0x40000
	v_lshl_add_u64 v[222:223], s[90:91], 0, v[136:137]
	s_addc_u32 s69, s91, 0
	s_add_i32 s67, s26, s16
	global_load_lds_dwordx4 v[222:223], off
	v_lshl_add_u64 v[224:225], s[68:69], 0, v[140:141]
	s_mov_b32 m0, s67
	global_load_lds_dwordx4 v[224:225], off
	s_add_i32 m0, s67, 0x2000
	v_lshl_add_u64 v[224:225], s[68:69], 0, v[136:137]
	global_load_lds_dwordx4 v[224:225], off
	s_mov_b32 m0, s17
	v_lshl_add_u64 v[224:225], s[92:93], 0, v[142:143]
	global_load_lds_dwordx4 v[224:225], off
	s_mov_b32 m0, s18
	v_lshl_add_u64 v[226:227], s[92:93], 0, v[138:139]
	global_load_lds_dwordx4 v[226:227], off
	s_waitcnt vmcnt(8) lgkmcnt(0)
	s_barrier
	s_setprio 1
	v_mfma_f32_16x16x32_bf16 v[60:63], v[128:131], v[190:193], 0
	v_mfma_f32_16x16x32_bf16 v[60:63], v[132:135], v[194:197], v[60:63]
	v_mfma_f32_16x16x32_bf16 v[52:55], v[154:157], v[190:193], 0
	v_mfma_f32_16x16x32_bf16 v[52:55], v[158:161], v[194:197], v[52:55]
	v_mfma_f32_16x16x32_bf16 v[44:47], v[128:131], v[198:201], 0
	v_mfma_f32_16x16x32_bf16 v[44:47], v[132:135], v[202:205], v[44:47]
	v_mfma_f32_16x16x32_bf16 v[36:39], v[154:157], v[198:201], 0
	v_mfma_f32_16x16x32_bf16 v[36:39], v[158:161], v[202:205], v[36:39]
	v_mfma_f32_16x16x32_bf16 v[28:31], v[128:131], v[206:209], 0
	v_mfma_f32_16x16x32_bf16 v[28:31], v[132:135], v[210:213], v[28:31]
	v_mfma_f32_16x16x32_bf16 v[20:23], v[154:157], v[206:209], 0
	v_mfma_f32_16x16x32_bf16 v[20:23], v[158:161], v[210:213], v[20:23]
	v_mfma_f32_16x16x32_bf16 v[12:15], v[128:131], v[214:217], 0
	v_mfma_f32_16x16x32_bf16 v[12:15], v[132:135], v[218:221], v[12:15]
	v_mfma_f32_16x16x32_bf16 v[4:7], v[154:157], v[214:217], 0
	v_mfma_f32_16x16x32_bf16 v[4:7], v[158:161], v[218:221], v[4:7]
	v_mfma_f32_16x16x32_bf16 v[56:59], v[162:165], v[190:193], 0
	v_mfma_f32_16x16x32_bf16 v[56:59], v[166:169], v[194:197], v[56:59]
	v_mfma_f32_16x16x32_bf16 v[48:51], v[182:185], v[190:193], 0
	v_mfma_f32_16x16x32_bf16 v[48:51], v[186:189], v[194:197], v[48:51]
	v_mfma_f32_16x16x32_bf16 v[40:43], v[162:165], v[198:201], 0
	v_mfma_f32_16x16x32_bf16 v[40:43], v[166:169], v[202:205], v[40:43]
	v_mfma_f32_16x16x32_bf16 v[32:35], v[182:185], v[198:201], 0
	v_mfma_f32_16x16x32_bf16 v[32:35], v[186:189], v[202:205], v[32:35]
	v_mfma_f32_16x16x32_bf16 v[24:27], v[162:165], v[206:209], 0
	v_mfma_f32_16x16x32_bf16 v[24:27], v[166:169], v[210:213], v[24:27]
	v_mfma_f32_16x16x32_bf16 v[16:19], v[182:185], v[206:209], 0
	v_mfma_f32_16x16x32_bf16 v[16:19], v[186:189], v[210:213], v[16:19]
	v_mfma_f32_16x16x32_bf16 v[8:11], v[162:165], v[214:217], 0
	v_mfma_f32_16x16x32_bf16 v[8:11], v[166:169], v[218:221], v[8:11]
	s_setprio 3
	s_barrier
	v_mfma_f32_16x16x32_bf16 v[0:3], v[182:185], v[214:217], 0
	v_mfma_f32_16x16x32_bf16 v[0:3], v[186:189], v[218:221], v[0:3]
	s_setprio 0
	s_add_i32 s67, 0, 0x18000
	s_add_i32 s73, 0, 0x1c000
	v_add_u32_e32 v158, s67, v175
	v_add_u32_e32 v186, s73, v175
	ds_read_b128 v[128:131], v158
	ds_read_b128 v[132:135], v158 offset:1024
	ds_read_b128 v[154:157], v158 offset:2048
	ds_read_b128 v[158:161], v158 offset:3072
	ds_read_b128 v[162:165], v186
	ds_read_b128 v[166:169], v186 offset:1024
	ds_read_b128 v[182:185], v186 offset:2048
	ds_read_b128 v[186:189], v186 offset:3072
	s_add_u32 s68, s92, 0x40000
	s_addc_u32 s69, s93, 0
	s_mov_b32 m0, s19
	v_lshl_add_u64 v[228:229], s[68:69], 0, v[142:143]
	ds_read_b128 v[190:193], v180 offset:32768
	ds_read_b128 v[194:197], v180 offset:33792
	ds_read_b128 v[198:201], v180 offset:34816
	ds_read_b128 v[202:205], v180 offset:35840
	ds_read_b128 v[206:209], v180 offset:36864
	ds_read_b128 v[210:213], v180 offset:37888
	ds_read_b128 v[214:217], v180 offset:38912
	ds_read_b128 v[218:221], v180 offset:39936
	global_load_lds_dwordx4 v[228:229], off
	s_mov_b32 m0, s20
	v_lshl_add_u64 v[228:229], s[68:69], 0, v[138:139]
	global_load_lds_dwordx4 v[228:229], off
	s_waitcnt vmcnt(8) lgkmcnt(0)
	s_barrier
	s_setprio 1
	v_mfma_f32_16x16x32_bf16 v[124:127], v[128:131], v[190:193], v[124:127]
	v_mfma_f32_16x16x32_bf16 v[124:127], v[132:135], v[194:197], v[124:127]
	v_mfma_f32_16x16x32_bf16 v[116:119], v[154:157], v[190:193], v[116:119]
	v_mfma_f32_16x16x32_bf16 v[116:119], v[158:161], v[194:197], v[116:119]
	v_mfma_f32_16x16x32_bf16 v[108:111], v[128:131], v[198:201], v[108:111]
	v_mfma_f32_16x16x32_bf16 v[108:111], v[132:135], v[202:205], v[108:111]
	v_mfma_f32_16x16x32_bf16 v[100:103], v[154:157], v[198:201], v[100:103]
	v_mfma_f32_16x16x32_bf16 v[100:103], v[158:161], v[202:205], v[100:103]
	v_mfma_f32_16x16x32_bf16 v[92:95], v[128:131], v[206:209], v[92:95]
	v_mfma_f32_16x16x32_bf16 v[92:95], v[132:135], v[210:213], v[92:95]
	v_mfma_f32_16x16x32_bf16 v[84:87], v[154:157], v[206:209], v[84:87]
	v_mfma_f32_16x16x32_bf16 v[84:87], v[158:161], v[210:213], v[84:87]
	v_mfma_f32_16x16x32_bf16 v[76:79], v[128:131], v[214:217], v[76:79]
	v_mfma_f32_16x16x32_bf16 v[76:79], v[132:135], v[218:221], v[76:79]
	v_mfma_f32_16x16x32_bf16 v[68:71], v[154:157], v[214:217], v[68:71]
	v_mfma_f32_16x16x32_bf16 v[68:71], v[158:161], v[218:221], v[68:71]
	v_mfma_f32_16x16x32_bf16 v[120:123], v[162:165], v[190:193], v[120:123]
	v_mfma_f32_16x16x32_bf16 v[120:123], v[166:169], v[194:197], v[120:123]
	v_mfma_f32_16x16x32_bf16 v[112:115], v[182:185], v[190:193], v[112:115]
	v_mfma_f32_16x16x32_bf16 v[112:115], v[186:189], v[194:197], v[112:115]
	v_mfma_f32_16x16x32_bf16 v[104:107], v[162:165], v[198:201], v[104:107]
	v_mfma_f32_16x16x32_bf16 v[104:107], v[166:169], v[202:205], v[104:107]
	v_mfma_f32_16x16x32_bf16 v[96:99], v[182:185], v[198:201], v[96:99]
	v_mfma_f32_16x16x32_bf16 v[96:99], v[186:189], v[202:205], v[96:99]
	v_mfma_f32_16x16x32_bf16 v[88:91], v[162:165], v[206:209], v[88:91]
	v_mfma_f32_16x16x32_bf16 v[88:91], v[166:169], v[210:213], v[88:91]
	v_mfma_f32_16x16x32_bf16 v[80:83], v[182:185], v[206:209], v[80:83]
	v_mfma_f32_16x16x32_bf16 v[80:83], v[186:189], v[210:213], v[80:83]
	v_mfma_f32_16x16x32_bf16 v[72:75], v[162:165], v[214:217], v[72:75]
	v_mfma_f32_16x16x32_bf16 v[72:75], v[166:169], v[218:221], v[72:75]
	s_setprio 3
	s_barrier
	v_mfma_f32_16x16x32_bf16 v[64:67], v[182:185], v[214:217], v[64:67]
	v_mfma_f32_16x16x32_bf16 v[64:67], v[186:189], v[218:221], v[64:67]
	s_setprio 0
	s_add_i32 s67, s67, s16
	v_lshl_add_u64 v[170:171], v[170:171], 0, s[74:75]
	s_mov_b32 m0, s67
	ds_read_b128 v[190:193], v180 offset:49152
	ds_read_b128 v[194:197], v180 offset:50176
	ds_read_b128 v[198:201], v180 offset:51200
	ds_read_b128 v[202:205], v180 offset:52224
	ds_read_b128 v[206:209], v180 offset:53248
	ds_read_b128 v[210:213], v180 offset:54272
	ds_read_b128 v[214:217], v180 offset:55296
	ds_read_b128 v[218:221], v180 offset:56320
	global_load_lds_dwordx4 v[170:171], off
	s_add_i32 m0, s67, 0x2000
	s_add_u32 s68, s90, 0x40080
	v_lshl_add_u64 v[170:171], v[222:223], 0, s[74:75]
	s_addc_u32 s69, s91, 0
	s_add_i32 s67, s73, s16
	global_load_lds_dwordx4 v[170:171], off
	s_mov_b32 m0, s67
	v_lshl_add_u64 v[170:171], s[68:69], 0, v[140:141]
	global_load_lds_dwordx4 v[170:171], off
	s_add_i32 m0, s67, 0x2000
	v_lshl_add_u64 v[170:171], s[68:69], 0, v[136:137]
	global_load_lds_dwordx4 v[170:171], off
	s_mov_b32 m0, s23
	v_lshl_add_u64 v[170:171], v[224:225], 0, s[74:75]
	global_load_lds_dwordx4 v[170:171], off
	s_mov_b32 m0, s24
	v_lshl_add_u64 v[170:171], v[226:227], 0, s[74:75]
	global_load_lds_dwordx4 v[170:171], off
	s_waitcnt vmcnt(8) lgkmcnt(0)
	s_barrier
	s_setprio 1
	v_mfma_f32_16x16x32_bf16 v[60:63], v[128:131], v[190:193], v[60:63]
	v_mfma_f32_16x16x32_bf16 v[60:63], v[132:135], v[194:197], v[60:63]
	v_mfma_f32_16x16x32_bf16 v[52:55], v[154:157], v[190:193], v[52:55]
	v_mfma_f32_16x16x32_bf16 v[52:55], v[158:161], v[194:197], v[52:55]
	v_mfma_f32_16x16x32_bf16 v[44:47], v[128:131], v[198:201], v[44:47]
	v_mfma_f32_16x16x32_bf16 v[44:47], v[132:135], v[202:205], v[44:47]
	v_mfma_f32_16x16x32_bf16 v[36:39], v[154:157], v[198:201], v[36:39]
	v_mfma_f32_16x16x32_bf16 v[36:39], v[158:161], v[202:205], v[36:39]
	v_mfma_f32_16x16x32_bf16 v[28:31], v[128:131], v[206:209], v[28:31]
	v_mfma_f32_16x16x32_bf16 v[28:31], v[132:135], v[210:213], v[28:31]
	v_mfma_f32_16x16x32_bf16 v[20:23], v[154:157], v[206:209], v[20:23]
	v_mfma_f32_16x16x32_bf16 v[20:23], v[158:161], v[210:213], v[20:23]
	v_mfma_f32_16x16x32_bf16 v[12:15], v[128:131], v[214:217], v[12:15]
	v_mfma_f32_16x16x32_bf16 v[12:15], v[132:135], v[218:221], v[12:15]
	v_mfma_f32_16x16x32_bf16 v[4:7], v[154:157], v[214:217], v[4:7]
	v_mfma_f32_16x16x32_bf16 v[4:7], v[158:161], v[218:221], v[4:7]
	v_mfma_f32_16x16x32_bf16 v[56:59], v[162:165], v[190:193], v[56:59]
	v_mfma_f32_16x16x32_bf16 v[56:59], v[166:169], v[194:197], v[56:59]
	v_mfma_f32_16x16x32_bf16 v[48:51], v[182:185], v[190:193], v[48:51]
	v_mfma_f32_16x16x32_bf16 v[48:51], v[186:189], v[194:197], v[48:51]
	v_mfma_f32_16x16x32_bf16 v[40:43], v[162:165], v[198:201], v[40:43]
	v_mfma_f32_16x16x32_bf16 v[40:43], v[166:169], v[202:205], v[40:43]
	v_mfma_f32_16x16x32_bf16 v[32:35], v[182:185], v[198:201], v[32:35]
	v_mfma_f32_16x16x32_bf16 v[32:35], v[186:189], v[202:205], v[32:35]
	v_mfma_f32_16x16x32_bf16 v[24:27], v[162:165], v[206:209], v[24:27]
	v_mfma_f32_16x16x32_bf16 v[24:27], v[166:169], v[210:213], v[24:27]
	v_mfma_f32_16x16x32_bf16 v[16:19], v[182:185], v[206:209], v[16:19]
	v_mfma_f32_16x16x32_bf16 v[16:19], v[186:189], v[210:213], v[16:19]
	v_mfma_f32_16x16x32_bf16 v[8:11], v[162:165], v[214:217], v[8:11]
	v_mfma_f32_16x16x32_bf16 v[8:11], v[166:169], v[218:221], v[8:11]
	s_setprio 3
	s_barrier
	v_mfma_f32_16x16x32_bf16 v[0:3], v[182:185], v[214:217], v[0:3]
	v_mfma_f32_16x16x32_bf16 v[0:3], v[186:189], v[218:221], v[0:3]
	s_setprio 0
	s_add_i32 s66, s66, 2
	s_add_u32 s88, s88, 0x100
	s_addc_u32 s89, s89, 0
	s_add_u32 s58, s58, 0x100
	s_addc_u32 s59, s59, 0
	s_cmp_gt_u32 s66, 13
.LBB0_120:
	ds_read_b128 v[128:131], v178
	ds_read_b128 v[132:135], v178 offset:1024
	ds_read_b128 v[154:157], v178 offset:2048
	ds_read_b128 v[158:161], v178 offset:3072
	ds_read_b128 v[162:165], v179
	ds_read_b128 v[166:169], v179 offset:1024
	ds_read_b128 v[182:185], v179 offset:2048
	ds_read_b128 v[186:189], v179 offset:3072
	s_add_u32 s67, s88, 0xfffc0080
	s_addc_u32 s68, s89, -1
	s_cmp_eq_u32 s66, 12
	s_cselect_b32 s93, s52, s68
	s_cselect_b32 s92, s53, s67
	s_cselect_b32 s91, s56, s59
	s_cselect_b32 s90, s57, s58
	v_lshl_add_u64 v[170:171], s[88:89], 0, v[144:145]
	s_add_i32 m0, s17, 0xc000
	ds_read_b128 v[190:193], v180
	ds_read_b128 v[194:197], v180 offset:1024
	ds_read_b128 v[198:201], v180 offset:2048
	ds_read_b128 v[202:205], v180 offset:3072
	ds_read_b128 v[206:209], v180 offset:4096
	ds_read_b128 v[210:213], v180 offset:5120
	ds_read_b128 v[214:217], v180 offset:6144
	ds_read_b128 v[218:221], v180 offset:7168
	global_load_lds_dwordx4 v[170:171], off
	s_add_i32 m0, s17, 0xe000
	v_lshl_add_u64 v[170:171], s[88:89], 0, v[148:149]
	global_load_lds_dwordx4 v[170:171], off
	s_waitcnt vmcnt(8) lgkmcnt(0)
	s_barrier
	s_setprio 1
	v_mfma_f32_16x16x32_bf16 v[124:127], v[128:131], v[190:193], v[124:127]
	v_mfma_f32_16x16x32_bf16 v[124:127], v[132:135], v[194:197], v[124:127]
	v_mfma_f32_16x16x32_bf16 v[116:119], v[154:157], v[190:193], v[116:119]
	v_mfma_f32_16x16x32_bf16 v[116:119], v[158:161], v[194:197], v[116:119]
	v_mfma_f32_16x16x32_bf16 v[108:111], v[128:131], v[198:201], v[108:111]
	v_mfma_f32_16x16x32_bf16 v[108:111], v[132:135], v[202:205], v[108:111]
	v_mfma_f32_16x16x32_bf16 v[100:103], v[154:157], v[198:201], v[100:103]
	v_mfma_f32_16x16x32_bf16 v[100:103], v[158:161], v[202:205], v[100:103]
	v_mfma_f32_16x16x32_bf16 v[92:95], v[128:131], v[206:209], v[92:95]
	v_mfma_f32_16x16x32_bf16 v[92:95], v[132:135], v[210:213], v[92:95]
	v_mfma_f32_16x16x32_bf16 v[84:87], v[154:157], v[206:209], v[84:87]
	v_mfma_f32_16x16x32_bf16 v[84:87], v[158:161], v[210:213], v[84:87]
	v_mfma_f32_16x16x32_bf16 v[76:79], v[128:131], v[214:217], v[76:79]
	v_mfma_f32_16x16x32_bf16 v[76:79], v[132:135], v[218:221], v[76:79]
	v_mfma_f32_16x16x32_bf16 v[68:71], v[154:157], v[214:217], v[68:71]
	v_mfma_f32_16x16x32_bf16 v[68:71], v[158:161], v[218:221], v[68:71]
	v_mfma_f32_16x16x32_bf16 v[120:123], v[162:165], v[190:193], v[120:123]
	v_mfma_f32_16x16x32_bf16 v[120:123], v[166:169], v[194:197], v[120:123]
	v_mfma_f32_16x16x32_bf16 v[112:115], v[182:185], v[190:193], v[112:115]
	v_mfma_f32_16x16x32_bf16 v[112:115], v[186:189], v[194:197], v[112:115]
	v_mfma_f32_16x16x32_bf16 v[104:107], v[162:165], v[198:201], v[104:107]
	v_mfma_f32_16x16x32_bf16 v[104:107], v[166:169], v[202:205], v[104:107]
	v_mfma_f32_16x16x32_bf16 v[96:99], v[182:185], v[198:201], v[96:99]
	v_mfma_f32_16x16x32_bf16 v[96:99], v[186:189], v[202:205], v[96:99]
	v_mfma_f32_16x16x32_bf16 v[88:91], v[162:165], v[206:209], v[88:91]
	v_mfma_f32_16x16x32_bf16 v[88:91], v[166:169], v[210:213], v[88:91]
	v_mfma_f32_16x16x32_bf16 v[80:83], v[182:185], v[206:209], v[80:83]
	v_mfma_f32_16x16x32_bf16 v[80:83], v[186:189], v[210:213], v[80:83]
	v_mfma_f32_16x16x32_bf16 v[72:75], v[162:165], v[214:217], v[72:75]
	v_mfma_f32_16x16x32_bf16 v[72:75], v[166:169], v[218:221], v[72:75]
	s_setprio 3
	s_barrier
	v_mfma_f32_16x16x32_bf16 v[64:67], v[182:185], v[214:217], v[64:67]
	v_mfma_f32_16x16x32_bf16 v[64:67], v[186:189], v[218:221], v[64:67]
	s_setprio 0
	s_add_i32 s67, s25, s16
	v_lshl_add_u64 v[170:171], s[90:91], 0, v[140:141]
	s_mov_b32 m0, s67
	ds_read_b128 v[190:193], v180 offset:16384
	ds_read_b128 v[194:197], v180 offset:17408
	ds_read_b128 v[198:201], v180 offset:18432
	ds_read_b128 v[202:205], v180 offset:19456
	ds_read_b128 v[206:209], v180 offset:20480
	ds_read_b128 v[210:213], v180 offset:21504
	ds_read_b128 v[214:217], v180 offset:22528
	ds_read_b128 v[218:221], v180 offset:23552
	global_load_lds_dwordx4 v[170:171], off
	s_add_i32 m0, s67, 0x2000
	s_add_u32 s68, s90, 0x40000
	v_lshl_add_u64 v[222:223], s[90:91], 0, v[136:137]
	s_addc_u32 s69, s91, 0
	s_add_i32 s67, s26, s16
	global_load_lds_dwordx4 v[222:223], off
	v_lshl_add_u64 v[224:225], s[68:69], 0, v[140:141]
	s_mov_b32 m0, s67
	global_load_lds_dwordx4 v[224:225], off
	s_add_i32 m0, s67, 0x2000
	v_lshl_add_u64 v[224:225], s[68:69], 0, v[136:137]
	global_load_lds_dwordx4 v[224:225], off
	s_mov_b32 m0, s17
	v_lshl_add_u64 v[224:225], s[92:93], 0, v[142:143]
	global_load_lds_dwordx4 v[224:225], off
	s_mov_b32 m0, s18
	v_lshl_add_u64 v[226:227], s[92:93], 0, v[138:139]
	global_load_lds_dwordx4 v[226:227], off
	s_waitcnt vmcnt(8) lgkmcnt(0)
	s_barrier
	s_setprio 1
	v_mfma_f32_16x16x32_bf16 v[60:63], v[128:131], v[190:193], v[60:63]
	v_mfma_f32_16x16x32_bf16 v[60:63], v[132:135], v[194:197], v[60:63]
	v_mfma_f32_16x16x32_bf16 v[52:55], v[154:157], v[190:193], v[52:55]
	v_mfma_f32_16x16x32_bf16 v[52:55], v[158:161], v[194:197], v[52:55]
	v_mfma_f32_16x16x32_bf16 v[44:47], v[128:131], v[198:201], v[44:47]
	v_mfma_f32_16x16x32_bf16 v[44:47], v[132:135], v[202:205], v[44:47]
	v_mfma_f32_16x16x32_bf16 v[36:39], v[154:157], v[198:201], v[36:39]
	v_mfma_f32_16x16x32_bf16 v[36:39], v[158:161], v[202:205], v[36:39]
	v_mfma_f32_16x16x32_bf16 v[28:31], v[128:131], v[206:209], v[28:31]
	v_mfma_f32_16x16x32_bf16 v[28:31], v[132:135], v[210:213], v[28:31]
	v_mfma_f32_16x16x32_bf16 v[20:23], v[154:157], v[206:209], v[20:23]
	v_mfma_f32_16x16x32_bf16 v[20:23], v[158:161], v[210:213], v[20:23]
	v_mfma_f32_16x16x32_bf16 v[12:15], v[128:131], v[214:217], v[12:15]
	v_mfma_f32_16x16x32_bf16 v[12:15], v[132:135], v[218:221], v[12:15]
	v_mfma_f32_16x16x32_bf16 v[4:7], v[154:157], v[214:217], v[4:7]
	v_mfma_f32_16x16x32_bf16 v[4:7], v[158:161], v[218:221], v[4:7]
	v_mfma_f32_16x16x32_bf16 v[56:59], v[162:165], v[190:193], v[56:59]
	v_mfma_f32_16x16x32_bf16 v[56:59], v[166:169], v[194:197], v[56:59]
	v_mfma_f32_16x16x32_bf16 v[48:51], v[182:185], v[190:193], v[48:51]
	v_mfma_f32_16x16x32_bf16 v[48:51], v[186:189], v[194:197], v[48:51]
	v_mfma_f32_16x16x32_bf16 v[40:43], v[162:165], v[198:201], v[40:43]
	v_mfma_f32_16x16x32_bf16 v[40:43], v[166:169], v[202:205], v[40:43]
	v_mfma_f32_16x16x32_bf16 v[32:35], v[182:185], v[198:201], v[32:35]
	v_mfma_f32_16x16x32_bf16 v[32:35], v[186:189], v[202:205], v[32:35]
	v_mfma_f32_16x16x32_bf16 v[24:27], v[162:165], v[206:209], v[24:27]
	v_mfma_f32_16x16x32_bf16 v[24:27], v[166:169], v[210:213], v[24:27]
	v_mfma_f32_16x16x32_bf16 v[16:19], v[182:185], v[206:209], v[16:19]
	v_mfma_f32_16x16x32_bf16 v[16:19], v[186:189], v[210:213], v[16:19]
	v_mfma_f32_16x16x32_bf16 v[8:11], v[162:165], v[214:217], v[8:11]
	v_mfma_f32_16x16x32_bf16 v[8:11], v[166:169], v[218:221], v[8:11]
	s_setprio 3
	s_barrier
	v_mfma_f32_16x16x32_bf16 v[0:3], v[182:185], v[214:217], v[0:3]
	v_mfma_f32_16x16x32_bf16 v[0:3], v[186:189], v[218:221], v[0:3]
	s_setprio 0
	s_add_i32 s67, 0, 0x18000
	s_add_i32 s73, 0, 0x1c000
	v_add_u32_e32 v158, s67, v175
	v_add_u32_e32 v186, s73, v175
	ds_read_b128 v[128:131], v158
	ds_read_b128 v[132:135], v158 offset:1024
	ds_read_b128 v[154:157], v158 offset:2048
	ds_read_b128 v[158:161], v158 offset:3072
	ds_read_b128 v[162:165], v186
	ds_read_b128 v[166:169], v186 offset:1024
	ds_read_b128 v[182:185], v186 offset:2048
	ds_read_b128 v[186:189], v186 offset:3072
	s_add_u32 s68, s92, 0x40000
	s_addc_u32 s69, s93, 0
	s_mov_b32 m0, s19
	v_lshl_add_u64 v[228:229], s[68:69], 0, v[142:143]
	ds_read_b128 v[190:193], v180 offset:32768
	ds_read_b128 v[194:197], v180 offset:33792
	ds_read_b128 v[198:201], v180 offset:34816
	ds_read_b128 v[202:205], v180 offset:35840
	ds_read_b128 v[206:209], v180 offset:36864
	ds_read_b128 v[210:213], v180 offset:37888
	ds_read_b128 v[214:217], v180 offset:38912
	ds_read_b128 v[218:221], v180 offset:39936
	global_load_lds_dwordx4 v[228:229], off
	s_mov_b32 m0, s20
	v_lshl_add_u64 v[228:229], s[68:69], 0, v[138:139]
	global_load_lds_dwordx4 v[228:229], off
	s_waitcnt vmcnt(8) lgkmcnt(0)
	s_barrier
	s_setprio 1
	v_mfma_f32_16x16x32_bf16 v[124:127], v[128:131], v[190:193], v[124:127]
	v_mfma_f32_16x16x32_bf16 v[124:127], v[132:135], v[194:197], v[124:127]
	v_mfma_f32_16x16x32_bf16 v[116:119], v[154:157], v[190:193], v[116:119]
	v_mfma_f32_16x16x32_bf16 v[116:119], v[158:161], v[194:197], v[116:119]
	v_mfma_f32_16x16x32_bf16 v[108:111], v[128:131], v[198:201], v[108:111]
	v_mfma_f32_16x16x32_bf16 v[108:111], v[132:135], v[202:205], v[108:111]
	v_mfma_f32_16x16x32_bf16 v[100:103], v[154:157], v[198:201], v[100:103]
	v_mfma_f32_16x16x32_bf16 v[100:103], v[158:161], v[202:205], v[100:103]
	v_mfma_f32_16x16x32_bf16 v[92:95], v[128:131], v[206:209], v[92:95]
	v_mfma_f32_16x16x32_bf16 v[92:95], v[132:135], v[210:213], v[92:95]
	v_mfma_f32_16x16x32_bf16 v[84:87], v[154:157], v[206:209], v[84:87]
	v_mfma_f32_16x16x32_bf16 v[84:87], v[158:161], v[210:213], v[84:87]
	v_mfma_f32_16x16x32_bf16 v[76:79], v[128:131], v[214:217], v[76:79]
	v_mfma_f32_16x16x32_bf16 v[76:79], v[132:135], v[218:221], v[76:79]
	v_mfma_f32_16x16x32_bf16 v[68:71], v[154:157], v[214:217], v[68:71]
	v_mfma_f32_16x16x32_bf16 v[68:71], v[158:161], v[218:221], v[68:71]
	v_mfma_f32_16x16x32_bf16 v[120:123], v[162:165], v[190:193], v[120:123]
	v_mfma_f32_16x16x32_bf16 v[120:123], v[166:169], v[194:197], v[120:123]
	v_mfma_f32_16x16x32_bf16 v[112:115], v[182:185], v[190:193], v[112:115]
	v_mfma_f32_16x16x32_bf16 v[112:115], v[186:189], v[194:197], v[112:115]
	v_mfma_f32_16x16x32_bf16 v[104:107], v[162:165], v[198:201], v[104:107]
	v_mfma_f32_16x16x32_bf16 v[104:107], v[166:169], v[202:205], v[104:107]
	v_mfma_f32_16x16x32_bf16 v[96:99], v[182:185], v[198:201], v[96:99]
	v_mfma_f32_16x16x32_bf16 v[96:99], v[186:189], v[202:205], v[96:99]
	v_mfma_f32_16x16x32_bf16 v[88:91], v[162:165], v[206:209], v[88:91]
	v_mfma_f32_16x16x32_bf16 v[88:91], v[166:169], v[210:213], v[88:91]
	v_mfma_f32_16x16x32_bf16 v[80:83], v[182:185], v[206:209], v[80:83]
	v_mfma_f32_16x16x32_bf16 v[80:83], v[186:189], v[210:213], v[80:83]
	v_mfma_f32_16x16x32_bf16 v[72:75], v[162:165], v[214:217], v[72:75]
	v_mfma_f32_16x16x32_bf16 v[72:75], v[166:169], v[218:221], v[72:75]
	s_setprio 3
	s_barrier
	v_mfma_f32_16x16x32_bf16 v[64:67], v[182:185], v[214:217], v[64:67]
	v_mfma_f32_16x16x32_bf16 v[64:67], v[186:189], v[218:221], v[64:67]
	s_setprio 0
	s_add_i32 s67, s67, s16
	v_lshl_add_u64 v[170:171], v[170:171], 0, s[74:75]
	s_mov_b32 m0, s67
	ds_read_b128 v[190:193], v180 offset:49152
	ds_read_b128 v[194:197], v180 offset:50176
	ds_read_b128 v[198:201], v180 offset:51200
	ds_read_b128 v[202:205], v180 offset:52224
	ds_read_b128 v[206:209], v180 offset:53248
	ds_read_b128 v[210:213], v180 offset:54272
	ds_read_b128 v[214:217], v180 offset:55296
	ds_read_b128 v[218:221], v180 offset:56320
	global_load_lds_dwordx4 v[170:171], off
	s_add_i32 m0, s67, 0x2000
	s_add_u32 s68, s90, 0x40080
	v_lshl_add_u64 v[170:171], v[222:223], 0, s[74:75]
	s_addc_u32 s69, s91, 0
	s_add_i32 s67, s73, s16
	global_load_lds_dwordx4 v[170:171], off
	s_mov_b32 m0, s67
	v_lshl_add_u64 v[170:171], s[68:69], 0, v[140:141]
	global_load_lds_dwordx4 v[170:171], off
	s_add_i32 m0, s67, 0x2000
	v_lshl_add_u64 v[170:171], s[68:69], 0, v[136:137]
	global_load_lds_dwordx4 v[170:171], off
	s_mov_b32 m0, s23
	v_lshl_add_u64 v[170:171], v[224:225], 0, s[74:75]
	global_load_lds_dwordx4 v[170:171], off
	s_mov_b32 m0, s24
	v_lshl_add_u64 v[170:171], v[226:227], 0, s[74:75]
	global_load_lds_dwordx4 v[170:171], off
	s_waitcnt vmcnt(8) lgkmcnt(0)
	s_barrier
	s_setprio 1
	v_mfma_f32_16x16x32_bf16 v[60:63], v[128:131], v[190:193], v[60:63]
	v_mfma_f32_16x16x32_bf16 v[60:63], v[132:135], v[194:197], v[60:63]
	v_mfma_f32_16x16x32_bf16 v[52:55], v[154:157], v[190:193], v[52:55]
	v_mfma_f32_16x16x32_bf16 v[52:55], v[158:161], v[194:197], v[52:55]
	v_mfma_f32_16x16x32_bf16 v[44:47], v[128:131], v[198:201], v[44:47]
	v_mfma_f32_16x16x32_bf16 v[44:47], v[132:135], v[202:205], v[44:47]
	v_mfma_f32_16x16x32_bf16 v[36:39], v[154:157], v[198:201], v[36:39]
	v_mfma_f32_16x16x32_bf16 v[36:39], v[158:161], v[202:205], v[36:39]
	v_mfma_f32_16x16x32_bf16 v[28:31], v[128:131], v[206:209], v[28:31]
	v_mfma_f32_16x16x32_bf16 v[28:31], v[132:135], v[210:213], v[28:31]
	v_mfma_f32_16x16x32_bf16 v[20:23], v[154:157], v[206:209], v[20:23]
	v_mfma_f32_16x16x32_bf16 v[20:23], v[158:161], v[210:213], v[20:23]
	v_mfma_f32_16x16x32_bf16 v[12:15], v[128:131], v[214:217], v[12:15]
	v_mfma_f32_16x16x32_bf16 v[12:15], v[132:135], v[218:221], v[12:15]
	v_mfma_f32_16x16x32_bf16 v[4:7], v[154:157], v[214:217], v[4:7]
	v_mfma_f32_16x16x32_bf16 v[4:7], v[158:161], v[218:221], v[4:7]
	v_mfma_f32_16x16x32_bf16 v[56:59], v[162:165], v[190:193], v[56:59]
	v_mfma_f32_16x16x32_bf16 v[56:59], v[166:169], v[194:197], v[56:59]
	v_mfma_f32_16x16x32_bf16 v[48:51], v[182:185], v[190:193], v[48:51]
	v_mfma_f32_16x16x32_bf16 v[48:51], v[186:189], v[194:197], v[48:51]
	v_mfma_f32_16x16x32_bf16 v[40:43], v[162:165], v[198:201], v[40:43]
	v_mfma_f32_16x16x32_bf16 v[40:43], v[166:169], v[202:205], v[40:43]
	v_mfma_f32_16x16x32_bf16 v[32:35], v[182:185], v[198:201], v[32:35]
	v_mfma_f32_16x16x32_bf16 v[32:35], v[186:189], v[202:205], v[32:35]
	v_mfma_f32_16x16x32_bf16 v[24:27], v[162:165], v[206:209], v[24:27]
	v_mfma_f32_16x16x32_bf16 v[24:27], v[166:169], v[210:213], v[24:27]
	v_mfma_f32_16x16x32_bf16 v[16:19], v[182:185], v[206:209], v[16:19]
	v_mfma_f32_16x16x32_bf16 v[16:19], v[186:189], v[210:213], v[16:19]
	v_mfma_f32_16x16x32_bf16 v[8:11], v[162:165], v[214:217], v[8:11]
	v_mfma_f32_16x16x32_bf16 v[8:11], v[166:169], v[218:221], v[8:11]
	s_setprio 3
	s_barrier
	v_mfma_f32_16x16x32_bf16 v[0:3], v[182:185], v[214:217], v[0:3]
	v_mfma_f32_16x16x32_bf16 v[0:3], v[186:189], v[218:221], v[0:3]
	s_setprio 0
	s_add_i32 s66, s66, 2
	s_add_u32 s88, s88, 0x100
	s_addc_u32 s89, s89, 0
	s_add_u32 s58, s58, 0x100
	s_addc_u32 s59, s59, 0
	s_cmp_gt_u32 s66, 13
	s_cbranch_scc0 .LBB0_120
	s_and_b64 vcc, exec, s[76:77]
	s_cbranch_vccz .LBB0_123
	s_barrier

.LBB0_271:
	s_add_u32 s86, s86, 0xb0080
	s_addc_u32 s87, s87, 0
	s_add_u32 s56, s88, 0x100
	v_mov_b32_e32 v0, 0
	s_addc_u32 s57, s89, 0
	s_mov_b32 s58, -2
	ds_read_b128 v[120:123], v245
	ds_read_b128 v[124:127], v245 offset:1024
	ds_read_b128 v[128:131], v245 offset:2048
	ds_read_b128 v[132:135], v245 offset:3072
	ds_read_b128 v[144:147], v246
	ds_read_b128 v[148:151], v246 offset:1024
	ds_read_b128 v[152:155], v246 offset:2048
	ds_read_b128 v[156:159], v246 offset:3072
	s_add_u32 s59, s86, 0xfff50080
	s_addc_u32 s66, s87, -1
	s_cmp_eq_u32 s58, 40
	s_cselect_b32 s91, s11, s66
	s_cselect_b32 s90, s10, s59
	s_cselect_b32 s89, s85, s57
	s_cselect_b32 s88, s84, s56
	v_lshl_add_u64 v[204:205], s[86:87], 0, v[200:201]
	s_add_i32 m0, s16, 0xc000
	ds_read_b128 v[160:163], v247
	ds_read_b128 v[164:167], v247 offset:1024
	ds_read_b128 v[168:171], v247 offset:2048
	ds_read_b128 v[172:175], v247 offset:3072
	ds_read_b128 v[176:179], v247 offset:4096
	ds_read_b128 v[180:183], v247 offset:5120
	ds_read_b128 v[184:187], v247 offset:6144
	ds_read_b128 v[188:191], v247 offset:7168
	global_load_lds_dwordx4 v[204:205], off
	s_add_i32 m0, s16, 0xe000
	v_lshl_add_u64 v[204:205], s[86:87], 0, v[202:203]
	global_load_lds_dwordx4 v[204:205], off
	s_waitcnt vmcnt(8) lgkmcnt(0)
	s_barrier
	s_setprio 1
	v_mfma_f32_16x16x32_bf16 v[140:143], v[120:123], v[160:163], 0
	v_mfma_f32_16x16x32_bf16 v[140:143], v[124:127], v[164:167], v[140:143]
	v_mfma_f32_16x16x32_bf16 v[136:139], v[128:131], v[160:163], 0
	v_mfma_f32_16x16x32_bf16 v[136:139], v[132:135], v[164:167], v[136:139]
	v_mfma_f32_16x16x32_bf16 v[108:111], v[120:123], v[168:171], 0
	v_mfma_f32_16x16x32_bf16 v[108:111], v[124:127], v[172:175], v[108:111]
	v_mfma_f32_16x16x32_bf16 v[104:107], v[128:131], v[168:171], 0
	v_mfma_f32_16x16x32_bf16 v[104:107], v[132:135], v[172:175], v[104:107]
	v_mfma_f32_16x16x32_bf16 v[92:95], v[120:123], v[176:179], 0
	v_mfma_f32_16x16x32_bf16 v[92:95], v[124:127], v[180:183], v[92:95]
	v_mfma_f32_16x16x32_bf16 v[88:91], v[128:131], v[176:179], 0
	v_mfma_f32_16x16x32_bf16 v[88:91], v[132:135], v[180:183], v[88:91]
	v_mfma_f32_16x16x32_bf16 v[76:79], v[120:123], v[184:187], 0
	v_mfma_f32_16x16x32_bf16 v[76:79], v[124:127], v[188:191], v[76:79]
	v_mfma_f32_16x16x32_bf16 v[72:75], v[128:131], v[184:187], 0
	v_mfma_f32_16x16x32_bf16 v[72:75], v[132:135], v[188:191], v[72:75]
	v_mfma_f32_16x16x32_bf16 v[116:119], v[144:147], v[160:163], 0
	v_mfma_f32_16x16x32_bf16 v[116:119], v[148:151], v[164:167], v[116:119]
	v_mfma_f32_16x16x32_bf16 v[112:115], v[152:155], v[160:163], 0
	v_mfma_f32_16x16x32_bf16 v[112:115], v[156:159], v[164:167], v[112:115]
	v_mfma_f32_16x16x32_bf16 v[100:103], v[144:147], v[168:171], 0
	v_mfma_f32_16x16x32_bf16 v[100:103], v[148:151], v[172:175], v[100:103]
	v_mfma_f32_16x16x32_bf16 v[96:99], v[152:155], v[168:171], 0
	v_mfma_f32_16x16x32_bf16 v[96:99], v[156:159], v[172:175], v[96:99]
	v_mfma_f32_16x16x32_bf16 v[84:87], v[144:147], v[176:179], 0
	v_mfma_f32_16x16x32_bf16 v[84:87], v[148:151], v[180:183], v[84:87]
	v_mfma_f32_16x16x32_bf16 v[80:83], v[152:155], v[176:179], 0
	v_mfma_f32_16x16x32_bf16 v[80:83], v[156:159], v[180:183], v[80:83]
	v_mfma_f32_16x16x32_bf16 v[68:71], v[144:147], v[184:187], 0
	v_mfma_f32_16x16x32_bf16 v[68:71], v[148:151], v[188:191], v[68:71]
	s_setprio 3
	s_barrier
	v_mfma_f32_16x16x32_bf16 v[64:67], v[152:155], v[184:187], 0
	v_mfma_f32_16x16x32_bf16 v[64:67], v[156:159], v[188:191], v[64:67]
	s_setprio 0
	s_add_i32 s59, s26, s15
	v_lshl_add_u64 v[204:205], s[88:89], 0, v[194:195]
	s_mov_b32 m0, s59
	ds_read_b128 v[160:163], v247 offset:16384
	ds_read_b128 v[164:167], v247 offset:17408
	ds_read_b128 v[168:171], v247 offset:18432
	ds_read_b128 v[172:175], v247 offset:19456
	ds_read_b128 v[176:179], v247 offset:20480
	ds_read_b128 v[180:183], v247 offset:21504
	ds_read_b128 v[184:187], v247 offset:22528
	ds_read_b128 v[188:191], v247 offset:23552
	global_load_lds_dwordx4 v[204:205], off
	s_add_i32 m0, s59, 0x2000
	s_add_u32 s66, s88, 0xb0000
	v_lshl_add_u64 v[206:207], s[88:89], 0, v[198:199]
	s_addc_u32 s67, s89, 0
	s_add_i32 s59, s27, s15
	global_load_lds_dwordx4 v[206:207], off
	v_lshl_add_u64 v[208:209], s[66:67], 0, v[194:195]
	s_mov_b32 m0, s59
	global_load_lds_dwordx4 v[208:209], off
	s_add_i32 m0, s59, 0x2000
	v_lshl_add_u64 v[208:209], s[66:67], 0, v[198:199]
	global_load_lds_dwordx4 v[208:209], off
	s_mov_b32 m0, s16
	v_lshl_add_u64 v[208:209], s[90:91], 0, v[192:193]
	global_load_lds_dwordx4 v[208:209], off
	s_mov_b32 m0, s17
	v_lshl_add_u64 v[210:211], s[90:91], 0, v[196:197]
	global_load_lds_dwordx4 v[210:211], off
	s_waitcnt vmcnt(8) lgkmcnt(0)
	s_barrier
	s_setprio 1
	v_mfma_f32_16x16x32_bf16 v[60:63], v[120:123], v[160:163], 0
	v_mfma_f32_16x16x32_bf16 v[60:63], v[124:127], v[164:167], v[60:63]
	v_mfma_f32_16x16x32_bf16 v[56:59], v[128:131], v[160:163], 0
	v_mfma_f32_16x16x32_bf16 v[56:59], v[132:135], v[164:167], v[56:59]
	v_mfma_f32_16x16x32_bf16 v[44:47], v[120:123], v[168:171], 0
	v_mfma_f32_16x16x32_bf16 v[44:47], v[124:127], v[172:175], v[44:47]
	v_mfma_f32_16x16x32_bf16 v[40:43], v[128:131], v[168:171], 0
	v_mfma_f32_16x16x32_bf16 v[40:43], v[132:135], v[172:175], v[40:43]
	v_mfma_f32_16x16x32_bf16 v[28:31], v[120:123], v[176:179], 0
	v_mfma_f32_16x16x32_bf16 v[28:31], v[124:127], v[180:183], v[28:31]
	v_mfma_f32_16x16x32_bf16 v[24:27], v[128:131], v[176:179], 0
	v_mfma_f32_16x16x32_bf16 v[24:27], v[132:135], v[180:183], v[24:27]
	v_mfma_f32_16x16x32_bf16 v[12:15], v[120:123], v[184:187], 0
	v_mfma_f32_16x16x32_bf16 v[12:15], v[124:127], v[188:191], v[12:15]
	v_mfma_f32_16x16x32_bf16 v[8:11], v[128:131], v[184:187], 0
	v_mfma_f32_16x16x32_bf16 v[8:11], v[132:135], v[188:191], v[8:11]
	v_mfma_f32_16x16x32_bf16 v[52:55], v[144:147], v[160:163], 0
	v_mfma_f32_16x16x32_bf16 v[52:55], v[148:151], v[164:167], v[52:55]
	v_mfma_f32_16x16x32_bf16 v[48:51], v[152:155], v[160:163], 0
	v_mfma_f32_16x16x32_bf16 v[48:51], v[156:159], v[164:167], v[48:51]
	v_mfma_f32_16x16x32_bf16 v[36:39], v[144:147], v[168:171], 0
	v_mfma_f32_16x16x32_bf16 v[36:39], v[148:151], v[172:175], v[36:39]
	v_mfma_f32_16x16x32_bf16 v[32:35], v[152:155], v[168:171], 0
	v_mfma_f32_16x16x32_bf16 v[32:35], v[156:159], v[172:175], v[32:35]
	v_mfma_f32_16x16x32_bf16 v[20:23], v[144:147], v[176:179], 0
	v_mfma_f32_16x16x32_bf16 v[20:23], v[148:151], v[180:183], v[20:23]
	v_mfma_f32_16x16x32_bf16 v[16:19], v[152:155], v[176:179], 0
	v_mfma_f32_16x16x32_bf16 v[16:19], v[156:159], v[180:183], v[16:19]
	v_mfma_f32_16x16x32_bf16 v[4:7], v[144:147], v[184:187], 0
	v_mfma_f32_16x16x32_bf16 v[4:7], v[148:151], v[188:191], v[4:7]
	s_setprio 3
	s_barrier
	v_mfma_f32_16x16x32_bf16 v[0:3], v[152:155], v[184:187], 0
	v_mfma_f32_16x16x32_bf16 v[0:3], v[156:159], v[188:191], v[0:3]
	s_setprio 0
	s_add_i32 s59, 0, 0x18000
	s_add_i32 s68, 0, 0x1c000
	v_add_u32_e32 v132, s59, v243
	v_add_u32_e32 v156, s68, v243
	ds_read_b128 v[120:123], v132
	ds_read_b128 v[124:127], v132 offset:1024
	ds_read_b128 v[128:131], v132 offset:2048
	ds_read_b128 v[132:135], v132 offset:3072
	ds_read_b128 v[144:147], v156
	ds_read_b128 v[148:151], v156 offset:1024
	ds_read_b128 v[152:155], v156 offset:2048
	ds_read_b128 v[156:159], v156 offset:3072
	s_add_u32 s66, s90, 0xb0000
	s_addc_u32 s67, s91, 0
	s_mov_b32 m0, s18
	v_lshl_add_u64 v[212:213], s[66:67], 0, v[192:193]
	ds_read_b128 v[160:163], v247 offset:32768
	ds_read_b128 v[164:167], v247 offset:33792
	ds_read_b128 v[168:171], v247 offset:34816
	ds_read_b128 v[172:175], v247 offset:35840
	ds_read_b128 v[176:179], v247 offset:36864
	ds_read_b128 v[180:183], v247 offset:37888
	ds_read_b128 v[184:187], v247 offset:38912
	ds_read_b128 v[188:191], v247 offset:39936
	global_load_lds_dwordx4 v[212:213], off
	s_mov_b32 m0, s19
	v_lshl_add_u64 v[212:213], s[66:67], 0, v[196:197]
	global_load_lds_dwordx4 v[212:213], off
	s_waitcnt vmcnt(8) lgkmcnt(0)
	s_barrier
	s_setprio 1
	v_mfma_f32_16x16x32_bf16 v[140:143], v[120:123], v[160:163], v[140:143]
	v_mfma_f32_16x16x32_bf16 v[140:143], v[124:127], v[164:167], v[140:143]
	v_mfma_f32_16x16x32_bf16 v[136:139], v[128:131], v[160:163], v[136:139]
	v_mfma_f32_16x16x32_bf16 v[136:139], v[132:135], v[164:167], v[136:139]
	v_mfma_f32_16x16x32_bf16 v[108:111], v[120:123], v[168:171], v[108:111]
	v_mfma_f32_16x16x32_bf16 v[108:111], v[124:127], v[172:175], v[108:111]
	v_mfma_f32_16x16x32_bf16 v[104:107], v[128:131], v[168:171], v[104:107]
	v_mfma_f32_16x16x32_bf16 v[104:107], v[132:135], v[172:175], v[104:107]
	v_mfma_f32_16x16x32_bf16 v[92:95], v[120:123], v[176:179], v[92:95]
	v_mfma_f32_16x16x32_bf16 v[92:95], v[124:127], v[180:183], v[92:95]
	v_mfma_f32_16x16x32_bf16 v[88:91], v[128:131], v[176:179], v[88:91]
	v_mfma_f32_16x16x32_bf16 v[88:91], v[132:135], v[180:183], v[88:91]
	v_mfma_f32_16x16x32_bf16 v[76:79], v[120:123], v[184:187], v[76:79]
	v_mfma_f32_16x16x32_bf16 v[76:79], v[124:127], v[188:191], v[76:79]
	v_mfma_f32_16x16x32_bf16 v[72:75], v[128:131], v[184:187], v[72:75]
	v_mfma_f32_16x16x32_bf16 v[72:75], v[132:135], v[188:191], v[72:75]
	v_mfma_f32_16x16x32_bf16 v[116:119], v[144:147], v[160:163], v[116:119]
	v_mfma_f32_16x16x32_bf16 v[116:119], v[148:151], v[164:167], v[116:119]
	v_mfma_f32_16x16x32_bf16 v[112:115], v[152:155], v[160:163], v[112:115]
	v_mfma_f32_16x16x32_bf16 v[112:115], v[156:159], v[164:167], v[112:115]
	v_mfma_f32_16x16x32_bf16 v[100:103], v[144:147], v[168:171], v[100:103]
	v_mfma_f32_16x16x32_bf16 v[100:103], v[148:151], v[172:175], v[100:103]
	v_mfma_f32_16x16x32_bf16 v[96:99], v[152:155], v[168:171], v[96:99]
	v_mfma_f32_16x16x32_bf16 v[96:99], v[156:159], v[172:175], v[96:99]
	v_mfma_f32_16x16x32_bf16 v[84:87], v[144:147], v[176:179], v[84:87]
	v_mfma_f32_16x16x32_bf16 v[84:87], v[148:151], v[180:183], v[84:87]
	v_mfma_f32_16x16x32_bf16 v[80:83], v[152:155], v[176:179], v[80:83]
	v_mfma_f32_16x16x32_bf16 v[80:83], v[156:159], v[180:183], v[80:83]
	v_mfma_f32_16x16x32_bf16 v[68:71], v[144:147], v[184:187], v[68:71]
	v_mfma_f32_16x16x32_bf16 v[68:71], v[148:151], v[188:191], v[68:71]
	s_setprio 3
	s_barrier
	v_mfma_f32_16x16x32_bf16 v[64:67], v[152:155], v[184:187], v[64:67]
	v_mfma_f32_16x16x32_bf16 v[64:67], v[156:159], v[188:191], v[64:67]
	s_setprio 0
	s_add_i32 s59, s59, s15
	v_lshl_add_u64 v[204:205], v[204:205], 0, s[80:81]
	s_mov_b32 m0, s59
	ds_read_b128 v[160:163], v247 offset:49152
	ds_read_b128 v[164:167], v247 offset:50176
	ds_read_b128 v[168:171], v247 offset:51200
	ds_read_b128 v[172:175], v247 offset:52224
	ds_read_b128 v[176:179], v247 offset:53248
	ds_read_b128 v[180:183], v247 offset:54272
	ds_read_b128 v[184:187], v247 offset:55296
	ds_read_b128 v[188:191], v247 offset:56320
	global_load_lds_dwordx4 v[204:205], off
	s_add_i32 m0, s59, 0x2000
	s_add_u32 s66, s88, 0xb0080
	v_lshl_add_u64 v[204:205], v[206:207], 0, s[80:81]
	s_addc_u32 s67, s89, 0
	s_add_i32 s59, s68, s15
	global_load_lds_dwordx4 v[204:205], off
	s_mov_b32 m0, s59
	v_lshl_add_u64 v[204:205], s[66:67], 0, v[194:195]
	global_load_lds_dwordx4 v[204:205], off
	s_add_i32 m0, s59, 0x2000
	v_lshl_add_u64 v[204:205], s[66:67], 0, v[198:199]
	global_load_lds_dwordx4 v[204:205], off
	s_mov_b32 m0, s21
	v_lshl_add_u64 v[204:205], v[208:209], 0, s[80:81]
	global_load_lds_dwordx4 v[204:205], off
	s_mov_b32 m0, s22
	v_lshl_add_u64 v[204:205], v[210:211], 0, s[80:81]
	global_load_lds_dwordx4 v[204:205], off
	s_waitcnt vmcnt(8) lgkmcnt(0)
	s_barrier
	s_setprio 1
	v_mfma_f32_16x16x32_bf16 v[60:63], v[120:123], v[160:163], v[60:63]
	v_mfma_f32_16x16x32_bf16 v[60:63], v[124:127], v[164:167], v[60:63]
	v_mfma_f32_16x16x32_bf16 v[56:59], v[128:131], v[160:163], v[56:59]
	v_mfma_f32_16x16x32_bf16 v[56:59], v[132:135], v[164:167], v[56:59]
	v_mfma_f32_16x16x32_bf16 v[44:47], v[120:123], v[168:171], v[44:47]
	v_mfma_f32_16x16x32_bf16 v[44:47], v[124:127], v[172:175], v[44:47]
	v_mfma_f32_16x16x32_bf16 v[40:43], v[128:131], v[168:171], v[40:43]
	v_mfma_f32_16x16x32_bf16 v[40:43], v[132:135], v[172:175], v[40:43]
	v_mfma_f32_16x16x32_bf16 v[28:31], v[120:123], v[176:179], v[28:31]
	v_mfma_f32_16x16x32_bf16 v[28:31], v[124:127], v[180:183], v[28:31]
	v_mfma_f32_16x16x32_bf16 v[24:27], v[128:131], v[176:179], v[24:27]
	v_mfma_f32_16x16x32_bf16 v[24:27], v[132:135], v[180:183], v[24:27]
	v_mfma_f32_16x16x32_bf16 v[12:15], v[120:123], v[184:187], v[12:15]
	v_mfma_f32_16x16x32_bf16 v[12:15], v[124:127], v[188:191], v[12:15]
	v_mfma_f32_16x16x32_bf16 v[8:11], v[128:131], v[184:187], v[8:11]
	v_mfma_f32_16x16x32_bf16 v[8:11], v[132:135], v[188:191], v[8:11]
	v_mfma_f32_16x16x32_bf16 v[52:55], v[144:147], v[160:163], v[52:55]
	v_mfma_f32_16x16x32_bf16 v[52:55], v[148:151], v[164:167], v[52:55]
	v_mfma_f32_16x16x32_bf16 v[48:51], v[152:155], v[160:163], v[48:51]
	v_mfma_f32_16x16x32_bf16 v[48:51], v[156:159], v[164:167], v[48:51]
	v_mfma_f32_16x16x32_bf16 v[36:39], v[144:147], v[168:171], v[36:39]
	v_mfma_f32_16x16x32_bf16 v[36:39], v[148:151], v[172:175], v[36:39]
	v_mfma_f32_16x16x32_bf16 v[32:35], v[152:155], v[168:171], v[32:35]
	v_mfma_f32_16x16x32_bf16 v[32:35], v[156:159], v[172:175], v[32:35]
	v_mfma_f32_16x16x32_bf16 v[20:23], v[144:147], v[176:179], v[20:23]
	v_mfma_f32_16x16x32_bf16 v[20:23], v[148:151], v[180:183], v[20:23]
	v_mfma_f32_16x16x32_bf16 v[16:19], v[152:155], v[176:179], v[16:19]
	v_mfma_f32_16x16x32_bf16 v[16:19], v[156:159], v[180:183], v[16:19]
	v_mfma_f32_16x16x32_bf16 v[4:7], v[144:147], v[184:187], v[4:7]
	v_mfma_f32_16x16x32_bf16 v[4:7], v[148:151], v[188:191], v[4:7]
	s_setprio 3
	s_barrier
	v_mfma_f32_16x16x32_bf16 v[0:3], v[152:155], v[184:187], v[0:3]
	v_mfma_f32_16x16x32_bf16 v[0:3], v[156:159], v[188:191], v[0:3]
	s_setprio 0
	s_add_i32 s58, s58, 2
	s_add_u32 s86, s86, 0x100
	s_addc_u32 s87, s87, 0
	s_add_u32 s56, s56, 0x100
	s_addc_u32 s57, s57, 0
	s_cmp_gt_u32 s58, 41
.LBB0_272:
	ds_read_b128 v[120:123], v245
	ds_read_b128 v[124:127], v245 offset:1024
	ds_read_b128 v[128:131], v245 offset:2048
	ds_read_b128 v[132:135], v245 offset:3072
	ds_read_b128 v[144:147], v246
	ds_read_b128 v[148:151], v246 offset:1024
	ds_read_b128 v[152:155], v246 offset:2048
	ds_read_b128 v[156:159], v246 offset:3072
	s_add_u32 s59, s86, 0xfff50080
	s_addc_u32 s66, s87, -1
	s_cmp_eq_u32 s58, 40
	s_cselect_b32 s91, s11, s66
	s_cselect_b32 s90, s10, s59
	s_cselect_b32 s89, s85, s57
	s_cselect_b32 s88, s84, s56
	v_lshl_add_u64 v[204:205], s[86:87], 0, v[200:201]
	s_add_i32 m0, s16, 0xc000
	ds_read_b128 v[160:163], v247
	ds_read_b128 v[164:167], v247 offset:1024
	ds_read_b128 v[168:171], v247 offset:2048
	ds_read_b128 v[172:175], v247 offset:3072
	ds_read_b128 v[176:179], v247 offset:4096
	ds_read_b128 v[180:183], v247 offset:5120
	ds_read_b128 v[184:187], v247 offset:6144
	ds_read_b128 v[188:191], v247 offset:7168
	global_load_lds_dwordx4 v[204:205], off
	s_add_i32 m0, s16, 0xe000
	v_lshl_add_u64 v[204:205], s[86:87], 0, v[202:203]
	global_load_lds_dwordx4 v[204:205], off
	s_waitcnt vmcnt(8) lgkmcnt(0)
	s_barrier
	s_setprio 1
	v_mfma_f32_16x16x32_bf16 v[140:143], v[120:123], v[160:163], v[140:143]
	v_mfma_f32_16x16x32_bf16 v[140:143], v[124:127], v[164:167], v[140:143]
	v_mfma_f32_16x16x32_bf16 v[136:139], v[128:131], v[160:163], v[136:139]
	v_mfma_f32_16x16x32_bf16 v[136:139], v[132:135], v[164:167], v[136:139]
	v_mfma_f32_16x16x32_bf16 v[108:111], v[120:123], v[168:171], v[108:111]
	v_mfma_f32_16x16x32_bf16 v[108:111], v[124:127], v[172:175], v[108:111]
	v_mfma_f32_16x16x32_bf16 v[104:107], v[128:131], v[168:171], v[104:107]
	v_mfma_f32_16x16x32_bf16 v[104:107], v[132:135], v[172:175], v[104:107]
	v_mfma_f32_16x16x32_bf16 v[92:95], v[120:123], v[176:179], v[92:95]
	v_mfma_f32_16x16x32_bf16 v[92:95], v[124:127], v[180:183], v[92:95]
	v_mfma_f32_16x16x32_bf16 v[88:91], v[128:131], v[176:179], v[88:91]
	v_mfma_f32_16x16x32_bf16 v[88:91], v[132:135], v[180:183], v[88:91]
	v_mfma_f32_16x16x32_bf16 v[76:79], v[120:123], v[184:187], v[76:79]
	v_mfma_f32_16x16x32_bf16 v[76:79], v[124:127], v[188:191], v[76:79]
	v_mfma_f32_16x16x32_bf16 v[72:75], v[128:131], v[184:187], v[72:75]
	v_mfma_f32_16x16x32_bf16 v[72:75], v[132:135], v[188:191], v[72:75]
	v_mfma_f32_16x16x32_bf16 v[116:119], v[144:147], v[160:163], v[116:119]
	v_mfma_f32_16x16x32_bf16 v[116:119], v[148:151], v[164:167], v[116:119]
	v_mfma_f32_16x16x32_bf16 v[112:115], v[152:155], v[160:163], v[112:115]
	v_mfma_f32_16x16x32_bf16 v[112:115], v[156:159], v[164:167], v[112:115]
	v_mfma_f32_16x16x32_bf16 v[100:103], v[144:147], v[168:171], v[100:103]
	v_mfma_f32_16x16x32_bf16 v[100:103], v[148:151], v[172:175], v[100:103]
	v_mfma_f32_16x16x32_bf16 v[96:99], v[152:155], v[168:171], v[96:99]
	v_mfma_f32_16x16x32_bf16 v[96:99], v[156:159], v[172:175], v[96:99]
	v_mfma_f32_16x16x32_bf16 v[84:87], v[144:147], v[176:179], v[84:87]
	v_mfma_f32_16x16x32_bf16 v[84:87], v[148:151], v[180:183], v[84:87]
	v_mfma_f32_16x16x32_bf16 v[80:83], v[152:155], v[176:179], v[80:83]
	v_mfma_f32_16x16x32_bf16 v[80:83], v[156:159], v[180:183], v[80:83]
	v_mfma_f32_16x16x32_bf16 v[68:71], v[144:147], v[184:187], v[68:71]
	v_mfma_f32_16x16x32_bf16 v[68:71], v[148:151], v[188:191], v[68:71]
	s_setprio 3
	s_barrier
	v_mfma_f32_16x16x32_bf16 v[64:67], v[152:155], v[184:187], v[64:67]
	v_mfma_f32_16x16x32_bf16 v[64:67], v[156:159], v[188:191], v[64:67]
	s_setprio 0
	s_add_i32 s59, s26, s15
	v_lshl_add_u64 v[204:205], s[88:89], 0, v[194:195]
	s_mov_b32 m0, s59
	ds_read_b128 v[160:163], v247 offset:16384
	ds_read_b128 v[164:167], v247 offset:17408
	ds_read_b128 v[168:171], v247 offset:18432
	ds_read_b128 v[172:175], v247 offset:19456
	ds_read_b128 v[176:179], v247 offset:20480
	ds_read_b128 v[180:183], v247 offset:21504
	ds_read_b128 v[184:187], v247 offset:22528
	ds_read_b128 v[188:191], v247 offset:23552
	global_load_lds_dwordx4 v[204:205], off
	s_add_i32 m0, s59, 0x2000
	s_add_u32 s66, s88, 0xb0000
	v_lshl_add_u64 v[206:207], s[88:89], 0, v[198:199]
	s_addc_u32 s67, s89, 0
	s_add_i32 s59, s27, s15
	global_load_lds_dwordx4 v[206:207], off
	v_lshl_add_u64 v[208:209], s[66:67], 0, v[194:195]
	s_mov_b32 m0, s59
	global_load_lds_dwordx4 v[208:209], off
	s_add_i32 m0, s59, 0x2000
	v_lshl_add_u64 v[208:209], s[66:67], 0, v[198:199]
	global_load_lds_dwordx4 v[208:209], off
	s_mov_b32 m0, s16
	v_lshl_add_u64 v[208:209], s[90:91], 0, v[192:193]
	global_load_lds_dwordx4 v[208:209], off
	s_mov_b32 m0, s17
	v_lshl_add_u64 v[210:211], s[90:91], 0, v[196:197]
	global_load_lds_dwordx4 v[210:211], off
	s_waitcnt vmcnt(8) lgkmcnt(0)
	s_barrier
	s_setprio 1
	v_mfma_f32_16x16x32_bf16 v[60:63], v[120:123], v[160:163], v[60:63]
	v_mfma_f32_16x16x32_bf16 v[60:63], v[124:127], v[164:167], v[60:63]
	v_mfma_f32_16x16x32_bf16 v[56:59], v[128:131], v[160:163], v[56:59]
	v_mfma_f32_16x16x32_bf16 v[56:59], v[132:135], v[164:167], v[56:59]
	v_mfma_f32_16x16x32_bf16 v[44:47], v[120:123], v[168:171], v[44:47]
	v_mfma_f32_16x16x32_bf16 v[44:47], v[124:127], v[172:175], v[44:47]
	v_mfma_f32_16x16x32_bf16 v[40:43], v[128:131], v[168:171], v[40:43]
	v_mfma_f32_16x16x32_bf16 v[40:43], v[132:135], v[172:175], v[40:43]
	v_mfma_f32_16x16x32_bf16 v[28:31], v[120:123], v[176:179], v[28:31]
	v_mfma_f32_16x16x32_bf16 v[28:31], v[124:127], v[180:183], v[28:31]
	v_mfma_f32_16x16x32_bf16 v[24:27], v[128:131], v[176:179], v[24:27]
	v_mfma_f32_16x16x32_bf16 v[24:27], v[132:135], v[180:183], v[24:27]
	v_mfma_f32_16x16x32_bf16 v[12:15], v[120:123], v[184:187], v[12:15]
	v_mfma_f32_16x16x32_bf16 v[12:15], v[124:127], v[188:191], v[12:15]
	v_mfma_f32_16x16x32_bf16 v[8:11], v[128:131], v[184:187], v[8:11]
	v_mfma_f32_16x16x32_bf16 v[8:11], v[132:135], v[188:191], v[8:11]
	v_mfma_f32_16x16x32_bf16 v[52:55], v[144:147], v[160:163], v[52:55]
	v_mfma_f32_16x16x32_bf16 v[52:55], v[148:151], v[164:167], v[52:55]
	v_mfma_f32_16x16x32_bf16 v[48:51], v[152:155], v[160:163], v[48:51]
	v_mfma_f32_16x16x32_bf16 v[48:51], v[156:159], v[164:167], v[48:51]
	v_mfma_f32_16x16x32_bf16 v[36:39], v[144:147], v[168:171], v[36:39]
	v_mfma_f32_16x16x32_bf16 v[36:39], v[148:151], v[172:175], v[36:39]
	v_mfma_f32_16x16x32_bf16 v[32:35], v[152:155], v[168:171], v[32:35]
	v_mfma_f32_16x16x32_bf16 v[32:35], v[156:159], v[172:175], v[32:35]
	v_mfma_f32_16x16x32_bf16 v[20:23], v[144:147], v[176:179], v[20:23]
	v_mfma_f32_16x16x32_bf16 v[20:23], v[148:151], v[180:183], v[20:23]
	v_mfma_f32_16x16x32_bf16 v[16:19], v[152:155], v[176:179], v[16:19]
	v_mfma_f32_16x16x32_bf16 v[16:19], v[156:159], v[180:183], v[16:19]
	v_mfma_f32_16x16x32_bf16 v[4:7], v[144:147], v[184:187], v[4:7]
	v_mfma_f32_16x16x32_bf16 v[4:7], v[148:151], v[188:191], v[4:7]
	s_setprio 3
	s_barrier
	v_mfma_f32_16x16x32_bf16 v[0:3], v[152:155], v[184:187], v[0:3]
	v_mfma_f32_16x16x32_bf16 v[0:3], v[156:159], v[188:191], v[0:3]
	s_setprio 0
	s_add_i32 s59, 0, 0x18000
	s_add_i32 s68, 0, 0x1c000
	v_add_u32_e32 v132, s59, v243
	v_add_u32_e32 v156, s68, v243
	ds_read_b128 v[120:123], v132
	ds_read_b128 v[124:127], v132 offset:1024
	ds_read_b128 v[128:131], v132 offset:2048
	ds_read_b128 v[132:135], v132 offset:3072
	ds_read_b128 v[144:147], v156
	ds_read_b128 v[148:151], v156 offset:1024
	ds_read_b128 v[152:155], v156 offset:2048
	ds_read_b128 v[156:159], v156 offset:3072
	s_add_u32 s66, s90, 0xb0000
	s_addc_u32 s67, s91, 0
	s_mov_b32 m0, s18
	v_lshl_add_u64 v[212:213], s[66:67], 0, v[192:193]
	ds_read_b128 v[160:163], v247 offset:32768
	ds_read_b128 v[164:167], v247 offset:33792
	ds_read_b128 v[168:171], v247 offset:34816
	ds_read_b128 v[172:175], v247 offset:35840
	ds_read_b128 v[176:179], v247 offset:36864
	ds_read_b128 v[180:183], v247 offset:37888
	ds_read_b128 v[184:187], v247 offset:38912
	ds_read_b128 v[188:191], v247 offset:39936
	global_load_lds_dwordx4 v[212:213], off
	s_mov_b32 m0, s19
	v_lshl_add_u64 v[212:213], s[66:67], 0, v[196:197]
	global_load_lds_dwordx4 v[212:213], off
	s_waitcnt vmcnt(8) lgkmcnt(0)
	s_barrier
	s_setprio 1
	v_mfma_f32_16x16x32_bf16 v[140:143], v[120:123], v[160:163], v[140:143]
	v_mfma_f32_16x16x32_bf16 v[140:143], v[124:127], v[164:167], v[140:143]
	v_mfma_f32_16x16x32_bf16 v[136:139], v[128:131], v[160:163], v[136:139]
	v_mfma_f32_16x16x32_bf16 v[136:139], v[132:135], v[164:167], v[136:139]
	v_mfma_f32_16x16x32_bf16 v[108:111], v[120:123], v[168:171], v[108:111]
	v_mfma_f32_16x16x32_bf16 v[108:111], v[124:127], v[172:175], v[108:111]
	v_mfma_f32_16x16x32_bf16 v[104:107], v[128:131], v[168:171], v[104:107]
	v_mfma_f32_16x16x32_bf16 v[104:107], v[132:135], v[172:175], v[104:107]
	v_mfma_f32_16x16x32_bf16 v[92:95], v[120:123], v[176:179], v[92:95]
	v_mfma_f32_16x16x32_bf16 v[92:95], v[124:127], v[180:183], v[92:95]
	v_mfma_f32_16x16x32_bf16 v[88:91], v[128:131], v[176:179], v[88:91]
	v_mfma_f32_16x16x32_bf16 v[88:91], v[132:135], v[180:183], v[88:91]
	v_mfma_f32_16x16x32_bf16 v[76:79], v[120:123], v[184:187], v[76:79]
	v_mfma_f32_16x16x32_bf16 v[76:79], v[124:127], v[188:191], v[76:79]
	v_mfma_f32_16x16x32_bf16 v[72:75], v[128:131], v[184:187], v[72:75]
	v_mfma_f32_16x16x32_bf16 v[72:75], v[132:135], v[188:191], v[72:75]
	v_mfma_f32_16x16x32_bf16 v[116:119], v[144:147], v[160:163], v[116:119]
	v_mfma_f32_16x16x32_bf16 v[116:119], v[148:151], v[164:167], v[116:119]
	v_mfma_f32_16x16x32_bf16 v[112:115], v[152:155], v[160:163], v[112:115]
	v_mfma_f32_16x16x32_bf16 v[112:115], v[156:159], v[164:167], v[112:115]
	v_mfma_f32_16x16x32_bf16 v[100:103], v[144:147], v[168:171], v[100:103]
	v_mfma_f32_16x16x32_bf16 v[100:103], v[148:151], v[172:175], v[100:103]
	v_mfma_f32_16x16x32_bf16 v[96:99], v[152:155], v[168:171], v[96:99]
	v_mfma_f32_16x16x32_bf16 v[96:99], v[156:159], v[172:175], v[96:99]
	v_mfma_f32_16x16x32_bf16 v[84:87], v[144:147], v[176:179], v[84:87]
	v_mfma_f32_16x16x32_bf16 v[84:87], v[148:151], v[180:183], v[84:87]
	v_mfma_f32_16x16x32_bf16 v[80:83], v[152:155], v[176:179], v[80:83]
	v_mfma_f32_16x16x32_bf16 v[80:83], v[156:159], v[180:183], v[80:83]
	v_mfma_f32_16x16x32_bf16 v[68:71], v[144:147], v[184:187], v[68:71]
	v_mfma_f32_16x16x32_bf16 v[68:71], v[148:151], v[188:191], v[68:71]
	s_setprio 3
	s_barrier
	v_mfma_f32_16x16x32_bf16 v[64:67], v[152:155], v[184:187], v[64:67]
	v_mfma_f32_16x16x32_bf16 v[64:67], v[156:159], v[188:191], v[64:67]
	s_setprio 0
	s_add_i32 s59, s59, s15
	v_lshl_add_u64 v[204:205], v[204:205], 0, s[80:81]
	s_mov_b32 m0, s59
	ds_read_b128 v[160:163], v247 offset:49152
	ds_read_b128 v[164:167], v247 offset:50176
	ds_read_b128 v[168:171], v247 offset:51200
	ds_read_b128 v[172:175], v247 offset:52224
	ds_read_b128 v[176:179], v247 offset:53248
	ds_read_b128 v[180:183], v247 offset:54272
	ds_read_b128 v[184:187], v247 offset:55296
	ds_read_b128 v[188:191], v247 offset:56320
	global_load_lds_dwordx4 v[204:205], off
	s_add_i32 m0, s59, 0x2000
	s_add_u32 s66, s88, 0xb0080
	v_lshl_add_u64 v[204:205], v[206:207], 0, s[80:81]
	s_addc_u32 s67, s89, 0
	s_add_i32 s59, s68, s15
	global_load_lds_dwordx4 v[204:205], off
	s_mov_b32 m0, s59
	v_lshl_add_u64 v[204:205], s[66:67], 0, v[194:195]
	global_load_lds_dwordx4 v[204:205], off
	s_add_i32 m0, s59, 0x2000
	v_lshl_add_u64 v[204:205], s[66:67], 0, v[198:199]
	global_load_lds_dwordx4 v[204:205], off
	s_mov_b32 m0, s21
	v_lshl_add_u64 v[204:205], v[208:209], 0, s[80:81]
	global_load_lds_dwordx4 v[204:205], off
	s_mov_b32 m0, s22
	v_lshl_add_u64 v[204:205], v[210:211], 0, s[80:81]
	global_load_lds_dwordx4 v[204:205], off
	s_waitcnt vmcnt(8) lgkmcnt(0)
	s_barrier
	s_setprio 1
	v_mfma_f32_16x16x32_bf16 v[60:63], v[120:123], v[160:163], v[60:63]
	v_mfma_f32_16x16x32_bf16 v[60:63], v[124:127], v[164:167], v[60:63]
	v_mfma_f32_16x16x32_bf16 v[56:59], v[128:131], v[160:163], v[56:59]
	v_mfma_f32_16x16x32_bf16 v[56:59], v[132:135], v[164:167], v[56:59]
	v_mfma_f32_16x16x32_bf16 v[44:47], v[120:123], v[168:171], v[44:47]
	v_mfma_f32_16x16x32_bf16 v[44:47], v[124:127], v[172:175], v[44:47]
	v_mfma_f32_16x16x32_bf16 v[40:43], v[128:131], v[168:171], v[40:43]
	v_mfma_f32_16x16x32_bf16 v[40:43], v[132:135], v[172:175], v[40:43]
	v_mfma_f32_16x16x32_bf16 v[28:31], v[120:123], v[176:179], v[28:31]
	v_mfma_f32_16x16x32_bf16 v[28:31], v[124:127], v[180:183], v[28:31]
	v_mfma_f32_16x16x32_bf16 v[24:27], v[128:131], v[176:179], v[24:27]
	v_mfma_f32_16x16x32_bf16 v[24:27], v[132:135], v[180:183], v[24:27]
	v_mfma_f32_16x16x32_bf16 v[12:15], v[120:123], v[184:187], v[12:15]
	v_mfma_f32_16x16x32_bf16 v[12:15], v[124:127], v[188:191], v[12:15]
	v_mfma_f32_16x16x32_bf16 v[8:11], v[128:131], v[184:187], v[8:11]
	v_mfma_f32_16x16x32_bf16 v[8:11], v[132:135], v[188:191], v[8:11]
	v_mfma_f32_16x16x32_bf16 v[52:55], v[144:147], v[160:163], v[52:55]
	v_mfma_f32_16x16x32_bf16 v[52:55], v[148:151], v[164:167], v[52:55]
	v_mfma_f32_16x16x32_bf16 v[48:51], v[152:155], v[160:163], v[48:51]
	v_mfma_f32_16x16x32_bf16 v[48:51], v[156:159], v[164:167], v[48:51]
	v_mfma_f32_16x16x32_bf16 v[36:39], v[144:147], v[168:171], v[36:39]
	v_mfma_f32_16x16x32_bf16 v[36:39], v[148:151], v[172:175], v[36:39]
	v_mfma_f32_16x16x32_bf16 v[32:35], v[152:155], v[168:171], v[32:35]
	v_mfma_f32_16x16x32_bf16 v[32:35], v[156:159], v[172:175], v[32:35]
	v_mfma_f32_16x16x32_bf16 v[20:23], v[144:147], v[176:179], v[20:23]
	v_mfma_f32_16x16x32_bf16 v[20:23], v[148:151], v[180:183], v[20:23]
	v_mfma_f32_16x16x32_bf16 v[16:19], v[152:155], v[176:179], v[16:19]
	v_mfma_f32_16x16x32_bf16 v[16:19], v[156:159], v[180:183], v[16:19]
	v_mfma_f32_16x16x32_bf16 v[4:7], v[144:147], v[184:187], v[4:7]
	v_mfma_f32_16x16x32_bf16 v[4:7], v[148:151], v[188:191], v[4:7]
	s_setprio 3
	s_barrier
	v_mfma_f32_16x16x32_bf16 v[0:3], v[152:155], v[184:187], v[0:3]
	v_mfma_f32_16x16x32_bf16 v[0:3], v[156:159], v[188:191], v[0:3]
	s_setprio 0
	s_add_i32 s58, s58, 2
	s_add_u32 s86, s86, 0x100
	s_addc_u32 s87, s87, 0
	s_add_u32 s56, s56, 0x100
	s_addc_u32 s57, s57, 0
	s_cmp_gt_u32 s58, 41
	s_cbranch_scc0 .LBB0_272
	s_and_b64 vcc, exec, s[82:83]
	s_cbranch_vccz .LBB0_275
	s_barrier

.LBB0_428:
	s_ashr_i32 s95, s94, 31
	s_lshl_b64 s[16:17], s[94:95], 19
	s_add_u32 s96, s12, s16
	s_addc_u32 s97, s13, s17
	s_and_b64 s[16:17], s[8:9], exec
	s_cselect_b32 s15, s97, s89
	s_cselect_b32 s16, s96, s88
	s_ashr_i32 s85, s84, 31
	s_lshl_b64 s[18:19], s[84:85], 19
	s_add_u32 s90, s54, s18
	s_addc_u32 s91, s55, s19
	s_and_b64 s[18:19], s[8:9], exec
	s_cselect_b32 s17, s91, s7
	s_cselect_b32 s18, s90, s6
	s_add_u32 s88, s88, 0x40080
	s_addc_u32 s89, s89, 0
	s_add_u32 s19, s6, 0x100
	v_mov_b32_e32 v0, 0
	s_addc_u32 s20, s7, 0
	s_mov_b32 s21, -2
	s_waitcnt lgkmcnt(0)
	ds_read_b128 v[128:131], v203
	ds_read_b128 v[132:135], v203 offset:1024
	ds_read_b128 v[136:139], v203 offset:2048
	ds_read_b128 v[164:167], v203 offset:3072
	ds_read_b128 v[168:171], v204
	ds_read_b128 v[172:175], v204 offset:1024
	ds_read_b128 v[176:179], v204 offset:2048
	ds_read_b128 v[180:183], v204 offset:3072
	s_add_u32 s6, s88, 0xfffc0080
	s_addc_u32 s7, s89, -1
	s_cmp_eq_u32 s21, 12
	s_cselect_b32 vcc_hi, s15, s7
	s_cselect_b32 vcc_lo, s16, s6
	s_cselect_b32 s7, s17, s20
	s_cselect_b32 s6, s18, s19
	v_lshl_add_u64 v[196:197], s[88:89], 0, v[156:157]
	s_add_i32 m0, s58, 0xc000
	ds_read_b128 v[184:187], v205
	ds_read_b128 v[188:191], v205 offset:1024
	ds_read_b128 v[192:195], v205 offset:2048
	ds_read_b128 v[212:215], v205 offset:3072
	ds_read_b128 v[216:219], v205 offset:4096
	ds_read_b128 v[220:223], v205 offset:5120
	ds_read_b128 v[224:227], v205 offset:6144
	ds_read_b128 v[228:231], v205 offset:7168
	global_load_lds_dwordx4 v[196:197], off
	s_add_i32 m0, s58, 0xe000
	v_lshl_add_u64 v[196:197], s[88:89], 0, v[158:159]
	global_load_lds_dwordx4 v[196:197], off
	s_waitcnt vmcnt(8) lgkmcnt(0)
	s_barrier
	s_setprio 1
	v_mfma_f32_16x16x32_bf16 v[124:127], v[128:131], v[184:187], 0
	v_mfma_f32_16x16x32_bf16 v[124:127], v[132:135], v[188:191], v[124:127]
	v_mfma_f32_16x16x32_bf16 v[116:119], v[136:139], v[184:187], 0
	v_mfma_f32_16x16x32_bf16 v[116:119], v[164:167], v[188:191], v[116:119]
	v_mfma_f32_16x16x32_bf16 v[108:111], v[128:131], v[192:195], 0
	v_mfma_f32_16x16x32_bf16 v[108:111], v[132:135], v[212:215], v[108:111]
	v_mfma_f32_16x16x32_bf16 v[100:103], v[136:139], v[192:195], 0
	v_mfma_f32_16x16x32_bf16 v[100:103], v[164:167], v[212:215], v[100:103]
	v_mfma_f32_16x16x32_bf16 v[92:95], v[128:131], v[216:219], 0
	v_mfma_f32_16x16x32_bf16 v[92:95], v[132:135], v[220:223], v[92:95]
	v_mfma_f32_16x16x32_bf16 v[84:87], v[136:139], v[216:219], 0
	v_mfma_f32_16x16x32_bf16 v[84:87], v[164:167], v[220:223], v[84:87]
	v_mfma_f32_16x16x32_bf16 v[76:79], v[128:131], v[224:227], 0
	v_mfma_f32_16x16x32_bf16 v[76:79], v[132:135], v[228:231], v[76:79]
	v_mfma_f32_16x16x32_bf16 v[68:71], v[136:139], v[224:227], 0
	v_mfma_f32_16x16x32_bf16 v[68:71], v[164:167], v[228:231], v[68:71]
	v_mfma_f32_16x16x32_bf16 v[120:123], v[168:171], v[184:187], 0
	v_mfma_f32_16x16x32_bf16 v[120:123], v[172:175], v[188:191], v[120:123]
	v_mfma_f32_16x16x32_bf16 v[112:115], v[176:179], v[184:187], 0
	v_mfma_f32_16x16x32_bf16 v[112:115], v[180:183], v[188:191], v[112:115]
	v_mfma_f32_16x16x32_bf16 v[104:107], v[168:171], v[192:195], 0
	v_mfma_f32_16x16x32_bf16 v[104:107], v[172:175], v[212:215], v[104:107]
	v_mfma_f32_16x16x32_bf16 v[96:99], v[176:179], v[192:195], 0
	v_mfma_f32_16x16x32_bf16 v[96:99], v[180:183], v[212:215], v[96:99]
	v_mfma_f32_16x16x32_bf16 v[88:91], v[168:171], v[216:219], 0
	v_mfma_f32_16x16x32_bf16 v[88:91], v[172:175], v[220:223], v[88:91]
	v_mfma_f32_16x16x32_bf16 v[80:83], v[176:179], v[216:219], 0
	v_mfma_f32_16x16x32_bf16 v[80:83], v[180:183], v[220:223], v[80:83]
	v_mfma_f32_16x16x32_bf16 v[72:75], v[168:171], v[224:227], 0
	v_mfma_f32_16x16x32_bf16 v[72:75], v[172:175], v[228:231], v[72:75]
	s_setprio 3
	s_barrier
	v_mfma_f32_16x16x32_bf16 v[64:67], v[176:179], v[224:227], 0
	v_mfma_f32_16x16x32_bf16 v[64:67], v[180:183], v[228:231], v[64:67]
	s_setprio 0
	s_add_i32 s22, s76, s57
	v_lshl_add_u64 v[196:197], s[6:7], 0, v[142:143]
	s_mov_b32 m0, s22
	ds_read_b128 v[184:187], v205 offset:16384
	ds_read_b128 v[188:191], v205 offset:17408
	ds_read_b128 v[192:195], v205 offset:18432
	ds_read_b128 v[212:215], v205 offset:19456
	ds_read_b128 v[216:219], v205 offset:20480
	ds_read_b128 v[220:223], v205 offset:21504
	ds_read_b128 v[224:227], v205 offset:22528
	ds_read_b128 v[228:231], v205 offset:23552
	global_load_lds_dwordx4 v[196:197], off
	s_add_i32 m0, s22, 0x2000
	s_add_u32 s22, s6, 0x40000
	v_lshl_add_u64 v[232:233], s[6:7], 0, v[146:147]
	s_addc_u32 s23, s7, 0
	s_add_i32 s24, s77, s57
	global_load_lds_dwordx4 v[232:233], off
	v_lshl_add_u64 v[234:235], s[22:23], 0, v[142:143]
	s_mov_b32 m0, s24
	global_load_lds_dwordx4 v[234:235], off
	s_add_i32 m0, s24, 0x2000
	v_lshl_add_u64 v[234:235], s[22:23], 0, v[146:147]
	global_load_lds_dwordx4 v[234:235], off
	s_mov_b32 m0, s58
	v_lshl_add_u64 v[234:235], vcc, 0, v[140:141]
	global_load_lds_dwordx4 v[234:235], off
	s_mov_b32 m0, s59
	v_lshl_add_u64 v[236:237], vcc, 0, v[144:145]
	global_load_lds_dwordx4 v[236:237], off
	s_waitcnt vmcnt(8) lgkmcnt(0)
	s_barrier
	s_setprio 1
	v_mfma_f32_16x16x32_bf16 v[60:63], v[128:131], v[184:187], 0
	v_mfma_f32_16x16x32_bf16 v[60:63], v[132:135], v[188:191], v[60:63]
	v_mfma_f32_16x16x32_bf16 v[52:55], v[136:139], v[184:187], 0
	v_mfma_f32_16x16x32_bf16 v[52:55], v[164:167], v[188:191], v[52:55]
	v_mfma_f32_16x16x32_bf16 v[44:47], v[128:131], v[192:195], 0
	v_mfma_f32_16x16x32_bf16 v[44:47], v[132:135], v[212:215], v[44:47]
	v_mfma_f32_16x16x32_bf16 v[36:39], v[136:139], v[192:195], 0
	v_mfma_f32_16x16x32_bf16 v[36:39], v[164:167], v[212:215], v[36:39]
	v_mfma_f32_16x16x32_bf16 v[28:31], v[128:131], v[216:219], 0
	v_mfma_f32_16x16x32_bf16 v[28:31], v[132:135], v[220:223], v[28:31]
	v_mfma_f32_16x16x32_bf16 v[20:23], v[136:139], v[216:219], 0
	v_mfma_f32_16x16x32_bf16 v[20:23], v[164:167], v[220:223], v[20:23]
	v_mfma_f32_16x16x32_bf16 v[12:15], v[128:131], v[224:227], 0
	v_mfma_f32_16x16x32_bf16 v[12:15], v[132:135], v[228:231], v[12:15]
	v_mfma_f32_16x16x32_bf16 v[4:7], v[136:139], v[224:227], 0
	v_mfma_f32_16x16x32_bf16 v[4:7], v[164:167], v[228:231], v[4:7]
	v_mfma_f32_16x16x32_bf16 v[56:59], v[168:171], v[184:187], 0
	v_mfma_f32_16x16x32_bf16 v[56:59], v[172:175], v[188:191], v[56:59]
	v_mfma_f32_16x16x32_bf16 v[48:51], v[176:179], v[184:187], 0
	v_mfma_f32_16x16x32_bf16 v[48:51], v[180:183], v[188:191], v[48:51]
	v_mfma_f32_16x16x32_bf16 v[40:43], v[168:171], v[192:195], 0
	v_mfma_f32_16x16x32_bf16 v[40:43], v[172:175], v[212:215], v[40:43]
	v_mfma_f32_16x16x32_bf16 v[32:35], v[176:179], v[192:195], 0
	v_mfma_f32_16x16x32_bf16 v[32:35], v[180:183], v[212:215], v[32:35]
	v_mfma_f32_16x16x32_bf16 v[24:27], v[168:171], v[216:219], 0
	v_mfma_f32_16x16x32_bf16 v[24:27], v[172:175], v[220:223], v[24:27]
	v_mfma_f32_16x16x32_bf16 v[16:19], v[176:179], v[216:219], 0
	v_mfma_f32_16x16x32_bf16 v[16:19], v[180:183], v[220:223], v[16:19]
	v_mfma_f32_16x16x32_bf16 v[8:11], v[168:171], v[224:227], 0
	v_mfma_f32_16x16x32_bf16 v[8:11], v[172:175], v[228:231], v[8:11]
	s_setprio 3
	s_barrier
	v_mfma_f32_16x16x32_bf16 v[0:3], v[176:179], v[224:227], 0
	v_mfma_f32_16x16x32_bf16 v[0:3], v[180:183], v[228:231], v[0:3]
	s_setprio 0
	s_add_i32 s24, 0, 0x18000
	v_add_u32_e32 v150, s24, v200
	s_add_i32 s25, 0, 0x1c000
	ds_read_b128 v[128:131], v150
	ds_read_b128 v[132:135], v150 offset:1024
	ds_read_b128 v[136:139], v150 offset:2048
	ds_read_b128 v[164:167], v150 offset:3072
	v_add_u32_e32 v150, s25, v200
	ds_read_b128 v[168:171], v150
	ds_read_b128 v[172:175], v150 offset:1024
	ds_read_b128 v[176:179], v150 offset:2048
	ds_read_b128 v[180:183], v150 offset:3072
	s_add_u32 s22, vcc_lo, 0x40000
	s_addc_u32 s23, vcc_hi, 0
	s_mov_b32 m0, s66
	v_lshl_add_u64 v[238:239], s[22:23], 0, v[140:141]
	ds_read_b128 v[184:187], v205 offset:32768
	ds_read_b128 v[188:191], v205 offset:33792
	ds_read_b128 v[192:195], v205 offset:34816
	ds_read_b128 v[212:215], v205 offset:35840
	ds_read_b128 v[216:219], v205 offset:36864
	ds_read_b128 v[220:223], v205 offset:37888
	ds_read_b128 v[224:227], v205 offset:38912
	ds_read_b128 v[228:231], v205 offset:39936
	global_load_lds_dwordx4 v[238:239], off
	s_mov_b32 m0, s67
	v_lshl_add_u64 v[238:239], s[22:23], 0, v[144:145]
	global_load_lds_dwordx4 v[238:239], off
	s_waitcnt vmcnt(8) lgkmcnt(0)
	s_barrier
	s_setprio 1
	v_mfma_f32_16x16x32_bf16 v[124:127], v[128:131], v[184:187], v[124:127]
	v_mfma_f32_16x16x32_bf16 v[124:127], v[132:135], v[188:191], v[124:127]
	v_mfma_f32_16x16x32_bf16 v[116:119], v[136:139], v[184:187], v[116:119]
	v_mfma_f32_16x16x32_bf16 v[116:119], v[164:167], v[188:191], v[116:119]
	v_mfma_f32_16x16x32_bf16 v[108:111], v[128:131], v[192:195], v[108:111]
	v_mfma_f32_16x16x32_bf16 v[108:111], v[132:135], v[212:215], v[108:111]
	v_mfma_f32_16x16x32_bf16 v[100:103], v[136:139], v[192:195], v[100:103]
	v_mfma_f32_16x16x32_bf16 v[100:103], v[164:167], v[212:215], v[100:103]
	v_mfma_f32_16x16x32_bf16 v[92:95], v[128:131], v[216:219], v[92:95]
	v_mfma_f32_16x16x32_bf16 v[92:95], v[132:135], v[220:223], v[92:95]
	v_mfma_f32_16x16x32_bf16 v[84:87], v[136:139], v[216:219], v[84:87]
	v_mfma_f32_16x16x32_bf16 v[84:87], v[164:167], v[220:223], v[84:87]
	v_mfma_f32_16x16x32_bf16 v[76:79], v[128:131], v[224:227], v[76:79]
	v_mfma_f32_16x16x32_bf16 v[76:79], v[132:135], v[228:231], v[76:79]
	v_mfma_f32_16x16x32_bf16 v[68:71], v[136:139], v[224:227], v[68:71]
	v_mfma_f32_16x16x32_bf16 v[68:71], v[164:167], v[228:231], v[68:71]
	v_mfma_f32_16x16x32_bf16 v[120:123], v[168:171], v[184:187], v[120:123]
	v_mfma_f32_16x16x32_bf16 v[120:123], v[172:175], v[188:191], v[120:123]
	v_mfma_f32_16x16x32_bf16 v[112:115], v[176:179], v[184:187], v[112:115]
	v_mfma_f32_16x16x32_bf16 v[112:115], v[180:183], v[188:191], v[112:115]
	v_mfma_f32_16x16x32_bf16 v[104:107], v[168:171], v[192:195], v[104:107]
	v_mfma_f32_16x16x32_bf16 v[104:107], v[172:175], v[212:215], v[104:107]
	v_mfma_f32_16x16x32_bf16 v[96:99], v[176:179], v[192:195], v[96:99]
	v_mfma_f32_16x16x32_bf16 v[96:99], v[180:183], v[212:215], v[96:99]
	v_mfma_f32_16x16x32_bf16 v[88:91], v[168:171], v[216:219], v[88:91]
	v_mfma_f32_16x16x32_bf16 v[88:91], v[172:175], v[220:223], v[88:91]
	v_mfma_f32_16x16x32_bf16 v[80:83], v[176:179], v[216:219], v[80:83]
	v_mfma_f32_16x16x32_bf16 v[80:83], v[180:183], v[220:223], v[80:83]
	v_mfma_f32_16x16x32_bf16 v[72:75], v[168:171], v[224:227], v[72:75]
	v_mfma_f32_16x16x32_bf16 v[72:75], v[172:175], v[228:231], v[72:75]
	s_setprio 3
	s_barrier
	v_mfma_f32_16x16x32_bf16 v[64:67], v[176:179], v[224:227], v[64:67]
	v_mfma_f32_16x16x32_bf16 v[64:67], v[180:183], v[228:231], v[64:67]
	s_setprio 0
	s_add_i32 s22, s24, s57
	v_lshl_add_u64 v[196:197], v[196:197], 0, s[80:81]
	s_mov_b32 m0, s22
	ds_read_b128 v[184:187], v205 offset:49152
	ds_read_b128 v[188:191], v205 offset:50176
	ds_read_b128 v[192:195], v205 offset:51200
	ds_read_b128 v[212:215], v205 offset:52224
	ds_read_b128 v[216:219], v205 offset:53248
	ds_read_b128 v[220:223], v205 offset:54272
	ds_read_b128 v[224:227], v205 offset:55296
	ds_read_b128 v[228:231], v205 offset:56320
	global_load_lds_dwordx4 v[196:197], off
	s_add_i32 m0, s22, 0x2000
	s_add_u32 s6, s6, 0x40080
	v_lshl_add_u64 v[196:197], v[232:233], 0, s[80:81]
	s_addc_u32 s7, s7, 0
	s_add_i32 s22, s25, s57
	global_load_lds_dwordx4 v[196:197], off
	s_mov_b32 m0, s22
	v_lshl_add_u64 v[196:197], s[6:7], 0, v[142:143]
	global_load_lds_dwordx4 v[196:197], off
	s_add_i32 m0, s22, 0x2000
	v_lshl_add_u64 v[196:197], s[6:7], 0, v[146:147]
	global_load_lds_dwordx4 v[196:197], off
	s_mov_b32 m0, s93
	v_lshl_add_u64 v[196:197], v[234:235], 0, s[80:81]
	global_load_lds_dwordx4 v[196:197], off
	s_mov_b32 m0, s69
	v_lshl_add_u64 v[196:197], v[236:237], 0, s[80:81]
	global_load_lds_dwordx4 v[196:197], off
	s_waitcnt vmcnt(8) lgkmcnt(0)
	s_barrier
	s_setprio 1
	v_mfma_f32_16x16x32_bf16 v[60:63], v[128:131], v[184:187], v[60:63]
	v_mfma_f32_16x16x32_bf16 v[60:63], v[132:135], v[188:191], v[60:63]
	v_mfma_f32_16x16x32_bf16 v[52:55], v[136:139], v[184:187], v[52:55]
	v_mfma_f32_16x16x32_bf16 v[52:55], v[164:167], v[188:191], v[52:55]
	v_mfma_f32_16x16x32_bf16 v[44:47], v[128:131], v[192:195], v[44:47]
	v_mfma_f32_16x16x32_bf16 v[44:47], v[132:135], v[212:215], v[44:47]
	v_mfma_f32_16x16x32_bf16 v[36:39], v[136:139], v[192:195], v[36:39]
	v_mfma_f32_16x16x32_bf16 v[36:39], v[164:167], v[212:215], v[36:39]
	v_mfma_f32_16x16x32_bf16 v[28:31], v[128:131], v[216:219], v[28:31]
	v_mfma_f32_16x16x32_bf16 v[28:31], v[132:135], v[220:223], v[28:31]
	v_mfma_f32_16x16x32_bf16 v[20:23], v[136:139], v[216:219], v[20:23]
	v_mfma_f32_16x16x32_bf16 v[20:23], v[164:167], v[220:223], v[20:23]
	v_mfma_f32_16x16x32_bf16 v[12:15], v[128:131], v[224:227], v[12:15]
	v_mfma_f32_16x16x32_bf16 v[12:15], v[132:135], v[228:231], v[12:15]
	v_mfma_f32_16x16x32_bf16 v[4:7], v[136:139], v[224:227], v[4:7]
	v_mfma_f32_16x16x32_bf16 v[4:7], v[164:167], v[228:231], v[4:7]
	v_mfma_f32_16x16x32_bf16 v[56:59], v[168:171], v[184:187], v[56:59]
	v_mfma_f32_16x16x32_bf16 v[56:59], v[172:175], v[188:191], v[56:59]
	v_mfma_f32_16x16x32_bf16 v[48:51], v[176:179], v[184:187], v[48:51]
	v_mfma_f32_16x16x32_bf16 v[48:51], v[180:183], v[188:191], v[48:51]
	v_mfma_f32_16x16x32_bf16 v[40:43], v[168:171], v[192:195], v[40:43]
	v_mfma_f32_16x16x32_bf16 v[40:43], v[172:175], v[212:215], v[40:43]
	v_mfma_f32_16x16x32_bf16 v[32:35], v[176:179], v[192:195], v[32:35]
	v_mfma_f32_16x16x32_bf16 v[32:35], v[180:183], v[212:215], v[32:35]
	v_mfma_f32_16x16x32_bf16 v[24:27], v[168:171], v[216:219], v[24:27]
	v_mfma_f32_16x16x32_bf16 v[24:27], v[172:175], v[220:223], v[24:27]
	v_mfma_f32_16x16x32_bf16 v[16:19], v[176:179], v[216:219], v[16:19]
	v_mfma_f32_16x16x32_bf16 v[16:19], v[180:183], v[220:223], v[16:19]
	v_mfma_f32_16x16x32_bf16 v[8:11], v[168:171], v[224:227], v[8:11]
	v_mfma_f32_16x16x32_bf16 v[8:11], v[172:175], v[228:231], v[8:11]
	s_setprio 3
	s_barrier
	v_mfma_f32_16x16x32_bf16 v[0:3], v[176:179], v[224:227], v[0:3]
	v_mfma_f32_16x16x32_bf16 v[0:3], v[180:183], v[228:231], v[0:3]
	s_setprio 0
	s_add_i32 s21, s21, 2
	s_add_u32 s88, s88, 0x100
	s_addc_u32 s89, s89, 0
	s_add_u32 s19, s19, 0x100
	s_addc_u32 s20, s20, 0
	s_cmp_gt_u32 s21, 13
.LBB0_429:
	ds_read_b128 v[128:131], v203
	ds_read_b128 v[132:135], v203 offset:1024
	ds_read_b128 v[136:139], v203 offset:2048
	ds_read_b128 v[164:167], v203 offset:3072
	ds_read_b128 v[168:171], v204
	ds_read_b128 v[172:175], v204 offset:1024
	ds_read_b128 v[176:179], v204 offset:2048
	ds_read_b128 v[180:183], v204 offset:3072
	s_add_u32 s6, s88, 0xfffc0080
	s_addc_u32 s7, s89, -1
	s_cmp_eq_u32 s21, 12
	s_cselect_b32 vcc_hi, s15, s7
	s_cselect_b32 vcc_lo, s16, s6
	s_cselect_b32 s7, s17, s20
	s_cselect_b32 s6, s18, s19
	v_lshl_add_u64 v[196:197], s[88:89], 0, v[156:157]
	s_add_i32 m0, s58, 0xc000
	ds_read_b128 v[184:187], v205
	ds_read_b128 v[188:191], v205 offset:1024
	ds_read_b128 v[192:195], v205 offset:2048
	ds_read_b128 v[212:215], v205 offset:3072
	ds_read_b128 v[216:219], v205 offset:4096
	ds_read_b128 v[220:223], v205 offset:5120
	ds_read_b128 v[224:227], v205 offset:6144
	ds_read_b128 v[228:231], v205 offset:7168
	global_load_lds_dwordx4 v[196:197], off
	s_add_i32 m0, s58, 0xe000
	v_lshl_add_u64 v[196:197], s[88:89], 0, v[158:159]
	global_load_lds_dwordx4 v[196:197], off
	s_waitcnt vmcnt(8) lgkmcnt(0)
	s_barrier
	s_setprio 1
	v_mfma_f32_16x16x32_bf16 v[124:127], v[128:131], v[184:187], v[124:127]
	v_mfma_f32_16x16x32_bf16 v[124:127], v[132:135], v[188:191], v[124:127]
	v_mfma_f32_16x16x32_bf16 v[116:119], v[136:139], v[184:187], v[116:119]
	v_mfma_f32_16x16x32_bf16 v[116:119], v[164:167], v[188:191], v[116:119]
	v_mfma_f32_16x16x32_bf16 v[108:111], v[128:131], v[192:195], v[108:111]
	v_mfma_f32_16x16x32_bf16 v[108:111], v[132:135], v[212:215], v[108:111]
	v_mfma_f32_16x16x32_bf16 v[100:103], v[136:139], v[192:195], v[100:103]
	v_mfma_f32_16x16x32_bf16 v[100:103], v[164:167], v[212:215], v[100:103]
	v_mfma_f32_16x16x32_bf16 v[92:95], v[128:131], v[216:219], v[92:95]
	v_mfma_f32_16x16x32_bf16 v[92:95], v[132:135], v[220:223], v[92:95]
	v_mfma_f32_16x16x32_bf16 v[84:87], v[136:139], v[216:219], v[84:87]
	v_mfma_f32_16x16x32_bf16 v[84:87], v[164:167], v[220:223], v[84:87]
	v_mfma_f32_16x16x32_bf16 v[76:79], v[128:131], v[224:227], v[76:79]
	v_mfma_f32_16x16x32_bf16 v[76:79], v[132:135], v[228:231], v[76:79]
	v_mfma_f32_16x16x32_bf16 v[68:71], v[136:139], v[224:227], v[68:71]
	v_mfma_f32_16x16x32_bf16 v[68:71], v[164:167], v[228:231], v[68:71]
	v_mfma_f32_16x16x32_bf16 v[120:123], v[168:171], v[184:187], v[120:123]
	v_mfma_f32_16x16x32_bf16 v[120:123], v[172:175], v[188:191], v[120:123]
	v_mfma_f32_16x16x32_bf16 v[112:115], v[176:179], v[184:187], v[112:115]
	v_mfma_f32_16x16x32_bf16 v[112:115], v[180:183], v[188:191], v[112:115]
	v_mfma_f32_16x16x32_bf16 v[104:107], v[168:171], v[192:195], v[104:107]
	v_mfma_f32_16x16x32_bf16 v[104:107], v[172:175], v[212:215], v[104:107]
	v_mfma_f32_16x16x32_bf16 v[96:99], v[176:179], v[192:195], v[96:99]
	v_mfma_f32_16x16x32_bf16 v[96:99], v[180:183], v[212:215], v[96:99]
	v_mfma_f32_16x16x32_bf16 v[88:91], v[168:171], v[216:219], v[88:91]
	v_mfma_f32_16x16x32_bf16 v[88:91], v[172:175], v[220:223], v[88:91]
	v_mfma_f32_16x16x32_bf16 v[80:83], v[176:179], v[216:219], v[80:83]
	v_mfma_f32_16x16x32_bf16 v[80:83], v[180:183], v[220:223], v[80:83]
	v_mfma_f32_16x16x32_bf16 v[72:75], v[168:171], v[224:227], v[72:75]
	v_mfma_f32_16x16x32_bf16 v[72:75], v[172:175], v[228:231], v[72:75]
	s_setprio 3
	s_barrier
	v_mfma_f32_16x16x32_bf16 v[64:67], v[176:179], v[224:227], v[64:67]
	v_mfma_f32_16x16x32_bf16 v[64:67], v[180:183], v[228:231], v[64:67]
	s_setprio 0
	s_add_i32 s22, s76, s57
	v_lshl_add_u64 v[196:197], s[6:7], 0, v[142:143]
	s_mov_b32 m0, s22
	ds_read_b128 v[184:187], v205 offset:16384
	ds_read_b128 v[188:191], v205 offset:17408
	ds_read_b128 v[192:195], v205 offset:18432
	ds_read_b128 v[212:215], v205 offset:19456
	ds_read_b128 v[216:219], v205 offset:20480
	ds_read_b128 v[220:223], v205 offset:21504
	ds_read_b128 v[224:227], v205 offset:22528
	ds_read_b128 v[228:231], v205 offset:23552
	global_load_lds_dwordx4 v[196:197], off
	s_add_i32 m0, s22, 0x2000
	s_add_u32 s22, s6, 0x40000
	v_lshl_add_u64 v[232:233], s[6:7], 0, v[146:147]
	s_addc_u32 s23, s7, 0
	s_add_i32 s24, s77, s57
	global_load_lds_dwordx4 v[232:233], off
	v_lshl_add_u64 v[234:235], s[22:23], 0, v[142:143]
	s_mov_b32 m0, s24
	global_load_lds_dwordx4 v[234:235], off
	s_add_i32 m0, s24, 0x2000
	v_lshl_add_u64 v[234:235], s[22:23], 0, v[146:147]
	global_load_lds_dwordx4 v[234:235], off
	s_mov_b32 m0, s58
	v_lshl_add_u64 v[234:235], vcc, 0, v[140:141]
	global_load_lds_dwordx4 v[234:235], off
	s_mov_b32 m0, s59
	v_lshl_add_u64 v[236:237], vcc, 0, v[144:145]
	global_load_lds_dwordx4 v[236:237], off
	s_waitcnt vmcnt(8) lgkmcnt(0)
	s_barrier
	s_setprio 1
	v_mfma_f32_16x16x32_bf16 v[60:63], v[128:131], v[184:187], v[60:63]
	v_mfma_f32_16x16x32_bf16 v[60:63], v[132:135], v[188:191], v[60:63]
	v_mfma_f32_16x16x32_bf16 v[52:55], v[136:139], v[184:187], v[52:55]
	v_mfma_f32_16x16x32_bf16 v[52:55], v[164:167], v[188:191], v[52:55]
	v_mfma_f32_16x16x32_bf16 v[44:47], v[128:131], v[192:195], v[44:47]
	v_mfma_f32_16x16x32_bf16 v[44:47], v[132:135], v[212:215], v[44:47]
	v_mfma_f32_16x16x32_bf16 v[36:39], v[136:139], v[192:195], v[36:39]
	v_mfma_f32_16x16x32_bf16 v[36:39], v[164:167], v[212:215], v[36:39]
	v_mfma_f32_16x16x32_bf16 v[28:31], v[128:131], v[216:219], v[28:31]
	v_mfma_f32_16x16x32_bf16 v[28:31], v[132:135], v[220:223], v[28:31]
	v_mfma_f32_16x16x32_bf16 v[20:23], v[136:139], v[216:219], v[20:23]
	v_mfma_f32_16x16x32_bf16 v[20:23], v[164:167], v[220:223], v[20:23]
	v_mfma_f32_16x16x32_bf16 v[12:15], v[128:131], v[224:227], v[12:15]
	v_mfma_f32_16x16x32_bf16 v[12:15], v[132:135], v[228:231], v[12:15]
	v_mfma_f32_16x16x32_bf16 v[4:7], v[136:139], v[224:227], v[4:7]
	v_mfma_f32_16x16x32_bf16 v[4:7], v[164:167], v[228:231], v[4:7]
	v_mfma_f32_16x16x32_bf16 v[56:59], v[168:171], v[184:187], v[56:59]
	v_mfma_f32_16x16x32_bf16 v[56:59], v[172:175], v[188:191], v[56:59]
	v_mfma_f32_16x16x32_bf16 v[48:51], v[176:179], v[184:187], v[48:51]
	v_mfma_f32_16x16x32_bf16 v[48:51], v[180:183], v[188:191], v[48:51]
	v_mfma_f32_16x16x32_bf16 v[40:43], v[168:171], v[192:195], v[40:43]
	v_mfma_f32_16x16x32_bf16 v[40:43], v[172:175], v[212:215], v[40:43]
	v_mfma_f32_16x16x32_bf16 v[32:35], v[176:179], v[192:195], v[32:35]
	v_mfma_f32_16x16x32_bf16 v[32:35], v[180:183], v[212:215], v[32:35]
	v_mfma_f32_16x16x32_bf16 v[24:27], v[168:171], v[216:219], v[24:27]
	v_mfma_f32_16x16x32_bf16 v[24:27], v[172:175], v[220:223], v[24:27]
	v_mfma_f32_16x16x32_bf16 v[16:19], v[176:179], v[216:219], v[16:19]
	v_mfma_f32_16x16x32_bf16 v[16:19], v[180:183], v[220:223], v[16:19]
	v_mfma_f32_16x16x32_bf16 v[8:11], v[168:171], v[224:227], v[8:11]
	v_mfma_f32_16x16x32_bf16 v[8:11], v[172:175], v[228:231], v[8:11]
	s_setprio 3
	s_barrier
	v_mfma_f32_16x16x32_bf16 v[0:3], v[176:179], v[224:227], v[0:3]
	v_mfma_f32_16x16x32_bf16 v[0:3], v[180:183], v[228:231], v[0:3]
	s_setprio 0
	s_add_i32 s24, 0, 0x18000
	v_add_u32_e32 v150, s24, v200
	s_add_i32 s25, 0, 0x1c000
	ds_read_b128 v[128:131], v150
	ds_read_b128 v[132:135], v150 offset:1024
	ds_read_b128 v[136:139], v150 offset:2048
	ds_read_b128 v[164:167], v150 offset:3072
	v_add_u32_e32 v150, s25, v200
	ds_read_b128 v[168:171], v150
	ds_read_b128 v[172:175], v150 offset:1024
	ds_read_b128 v[176:179], v150 offset:2048
	ds_read_b128 v[180:183], v150 offset:3072
	s_add_u32 s22, vcc_lo, 0x40000
	s_addc_u32 s23, vcc_hi, 0
	s_mov_b32 m0, s66
	v_lshl_add_u64 v[238:239], s[22:23], 0, v[140:141]
	ds_read_b128 v[184:187], v205 offset:32768
	ds_read_b128 v[188:191], v205 offset:33792
	ds_read_b128 v[192:195], v205 offset:34816
	ds_read_b128 v[212:215], v205 offset:35840
	ds_read_b128 v[216:219], v205 offset:36864
	ds_read_b128 v[220:223], v205 offset:37888
	ds_read_b128 v[224:227], v205 offset:38912
	ds_read_b128 v[228:231], v205 offset:39936
	global_load_lds_dwordx4 v[238:239], off
	s_mov_b32 m0, s67
	v_lshl_add_u64 v[238:239], s[22:23], 0, v[144:145]
	global_load_lds_dwordx4 v[238:239], off
	s_waitcnt vmcnt(8) lgkmcnt(0)
	s_barrier
	s_setprio 1
	v_mfma_f32_16x16x32_bf16 v[124:127], v[128:131], v[184:187], v[124:127]
	v_mfma_f32_16x16x32_bf16 v[124:127], v[132:135], v[188:191], v[124:127]
	v_mfma_f32_16x16x32_bf16 v[116:119], v[136:139], v[184:187], v[116:119]
	v_mfma_f32_16x16x32_bf16 v[116:119], v[164:167], v[188:191], v[116:119]
	v_mfma_f32_16x16x32_bf16 v[108:111], v[128:131], v[192:195], v[108:111]
	v_mfma_f32_16x16x32_bf16 v[108:111], v[132:135], v[212:215], v[108:111]
	v_mfma_f32_16x16x32_bf16 v[100:103], v[136:139], v[192:195], v[100:103]
	v_mfma_f32_16x16x32_bf16 v[100:103], v[164:167], v[212:215], v[100:103]
	v_mfma_f32_16x16x32_bf16 v[92:95], v[128:131], v[216:219], v[92:95]
	v_mfma_f32_16x16x32_bf16 v[92:95], v[132:135], v[220:223], v[92:95]
	v_mfma_f32_16x16x32_bf16 v[84:87], v[136:139], v[216:219], v[84:87]
	v_mfma_f32_16x16x32_bf16 v[84:87], v[164:167], v[220:223], v[84:87]
	v_mfma_f32_16x16x32_bf16 v[76:79], v[128:131], v[224:227], v[76:79]
	v_mfma_f32_16x16x32_bf16 v[76:79], v[132:135], v[228:231], v[76:79]
	v_mfma_f32_16x16x32_bf16 v[68:71], v[136:139], v[224:227], v[68:71]
	v_mfma_f32_16x16x32_bf16 v[68:71], v[164:167], v[228:231], v[68:71]
	v_mfma_f32_16x16x32_bf16 v[120:123], v[168:171], v[184:187], v[120:123]
	v_mfma_f32_16x16x32_bf16 v[120:123], v[172:175], v[188:191], v[120:123]
	v_mfma_f32_16x16x32_bf16 v[112:115], v[176:179], v[184:187], v[112:115]
	v_mfma_f32_16x16x32_bf16 v[112:115], v[180:183], v[188:191], v[112:115]
	v_mfma_f32_16x16x32_bf16 v[104:107], v[168:171], v[192:195], v[104:107]
	v_mfma_f32_16x16x32_bf16 v[104:107], v[172:175], v[212:215], v[104:107]
	v_mfma_f32_16x16x32_bf16 v[96:99], v[176:179], v[192:195], v[96:99]
	v_mfma_f32_16x16x32_bf16 v[96:99], v[180:183], v[212:215], v[96:99]
	v_mfma_f32_16x16x32_bf16 v[88:91], v[168:171], v[216:219], v[88:91]
	v_mfma_f32_16x16x32_bf16 v[88:91], v[172:175], v[220:223], v[88:91]
	v_mfma_f32_16x16x32_bf16 v[80:83], v[176:179], v[216:219], v[80:83]
	v_mfma_f32_16x16x32_bf16 v[80:83], v[180:183], v[220:223], v[80:83]
	v_mfma_f32_16x16x32_bf16 v[72:75], v[168:171], v[224:227], v[72:75]
	v_mfma_f32_16x16x32_bf16 v[72:75], v[172:175], v[228:231], v[72:75]
	s_setprio 3
	s_barrier
	v_mfma_f32_16x16x32_bf16 v[64:67], v[176:179], v[224:227], v[64:67]
	v_mfma_f32_16x16x32_bf16 v[64:67], v[180:183], v[228:231], v[64:67]
	s_setprio 0
	s_add_i32 s22, s24, s57
	v_lshl_add_u64 v[196:197], v[196:197], 0, s[80:81]
	s_mov_b32 m0, s22
	ds_read_b128 v[184:187], v205 offset:49152
	ds_read_b128 v[188:191], v205 offset:50176
	ds_read_b128 v[192:195], v205 offset:51200
	ds_read_b128 v[212:215], v205 offset:52224
	ds_read_b128 v[216:219], v205 offset:53248
	ds_read_b128 v[220:223], v205 offset:54272
	ds_read_b128 v[224:227], v205 offset:55296
	ds_read_b128 v[228:231], v205 offset:56320
	global_load_lds_dwordx4 v[196:197], off
	s_add_i32 m0, s22, 0x2000
	s_add_u32 s6, s6, 0x40080
	v_lshl_add_u64 v[196:197], v[232:233], 0, s[80:81]
	s_addc_u32 s7, s7, 0
	s_add_i32 s22, s25, s57
	global_load_lds_dwordx4 v[196:197], off
	s_mov_b32 m0, s22
	v_lshl_add_u64 v[196:197], s[6:7], 0, v[142:143]
	global_load_lds_dwordx4 v[196:197], off
	s_add_i32 m0, s22, 0x2000
	v_lshl_add_u64 v[196:197], s[6:7], 0, v[146:147]
	global_load_lds_dwordx4 v[196:197], off
	s_mov_b32 m0, s93
	v_lshl_add_u64 v[196:197], v[234:235], 0, s[80:81]
	global_load_lds_dwordx4 v[196:197], off
	s_mov_b32 m0, s69
	v_lshl_add_u64 v[196:197], v[236:237], 0, s[80:81]
	global_load_lds_dwordx4 v[196:197], off
	s_waitcnt vmcnt(8) lgkmcnt(0)
	s_barrier
	s_setprio 1
	v_mfma_f32_16x16x32_bf16 v[60:63], v[128:131], v[184:187], v[60:63]
	v_mfma_f32_16x16x32_bf16 v[60:63], v[132:135], v[188:191], v[60:63]
	v_mfma_f32_16x16x32_bf16 v[52:55], v[136:139], v[184:187], v[52:55]
	v_mfma_f32_16x16x32_bf16 v[52:55], v[164:167], v[188:191], v[52:55]
	v_mfma_f32_16x16x32_bf16 v[44:47], v[128:131], v[192:195], v[44:47]
	v_mfma_f32_16x16x32_bf16 v[44:47], v[132:135], v[212:215], v[44:47]
	v_mfma_f32_16x16x32_bf16 v[36:39], v[136:139], v[192:195], v[36:39]
	v_mfma_f32_16x16x32_bf16 v[36:39], v[164:167], v[212:215], v[36:39]
	v_mfma_f32_16x16x32_bf16 v[28:31], v[128:131], v[216:219], v[28:31]
	v_mfma_f32_16x16x32_bf16 v[28:31], v[132:135], v[220:223], v[28:31]
	v_mfma_f32_16x16x32_bf16 v[20:23], v[136:139], v[216:219], v[20:23]
	v_mfma_f32_16x16x32_bf16 v[20:23], v[164:167], v[220:223], v[20:23]
	v_mfma_f32_16x16x32_bf16 v[12:15], v[128:131], v[224:227], v[12:15]
	v_mfma_f32_16x16x32_bf16 v[12:15], v[132:135], v[228:231], v[12:15]
	v_mfma_f32_16x16x32_bf16 v[4:7], v[136:139], v[224:227], v[4:7]
	v_mfma_f32_16x16x32_bf16 v[4:7], v[164:167], v[228:231], v[4:7]
	v_mfma_f32_16x16x32_bf16 v[56:59], v[168:171], v[184:187], v[56:59]
	v_mfma_f32_16x16x32_bf16 v[56:59], v[172:175], v[188:191], v[56:59]
	v_mfma_f32_16x16x32_bf16 v[48:51], v[176:179], v[184:187], v[48:51]
	v_mfma_f32_16x16x32_bf16 v[48:51], v[180:183], v[188:191], v[48:51]
	v_mfma_f32_16x16x32_bf16 v[40:43], v[168:171], v[192:195], v[40:43]
	v_mfma_f32_16x16x32_bf16 v[40:43], v[172:175], v[212:215], v[40:43]
	v_mfma_f32_16x16x32_bf16 v[32:35], v[176:179], v[192:195], v[32:35]
	v_mfma_f32_16x16x32_bf16 v[32:35], v[180:183], v[212:215], v[32:35]
	v_mfma_f32_16x16x32_bf16 v[24:27], v[168:171], v[216:219], v[24:27]
	v_mfma_f32_16x16x32_bf16 v[24:27], v[172:175], v[220:223], v[24:27]
	v_mfma_f32_16x16x32_bf16 v[16:19], v[176:179], v[216:219], v[16:19]
	v_mfma_f32_16x16x32_bf16 v[16:19], v[180:183], v[220:223], v[16:19]
	v_mfma_f32_16x16x32_bf16 v[8:11], v[168:171], v[224:227], v[8:11]
	v_mfma_f32_16x16x32_bf16 v[8:11], v[172:175], v[228:231], v[8:11]
	s_setprio 3
	s_barrier
	v_mfma_f32_16x16x32_bf16 v[0:3], v[176:179], v[224:227], v[0:3]
	v_mfma_f32_16x16x32_bf16 v[0:3], v[180:183], v[228:231], v[0:3]
	s_setprio 0
	s_add_i32 s21, s21, 2
	s_add_u32 s88, s88, 0x100
	s_addc_u32 s89, s89, 0
	s_add_u32 s19, s19, 0x100
	s_addc_u32 s20, s20, 0
	s_cmp_gt_u32 s21, 13
	s_cbranch_scc0 .LBB0_429
	s_and_b64 vcc, exec, s[82:83]
	s_cbranch_vccz .LBB0_432
	s_barrier

.LBB0_992:
	s_ashr_i32 s53, s52, 31
	s_lshl_b64 s[54:55], s[52:53], 19
	s_add_u32 s76, s42, s54
	s_addc_u32 s77, s43, s55
	s_and_b64 s[54:55], s[6:7], exec
	s_cselect_b32 s53, s77, s83
	s_cselect_b32 s54, s76, s82
	s_ashr_i32 s51, s50, 31
	s_lshl_b64 s[56:57], s[50:51], 19
	s_add_u32 s78, s3, s56
	s_addc_u32 s79, s14, s57
	s_and_b64 s[56:57], s[6:7], exec
	s_cselect_b32 s51, s79, s85
	s_cselect_b32 s55, s78, s84
	s_add_u32 s82, s82, 0x40080
	s_addc_u32 s83, s83, 0
	s_add_u32 s56, s84, 0x100
	v_mov_b32_e32 v0, 0
	s_addc_u32 s57, s85, 0
	s_mov_b32 s58, -2
	ds_read_b128 v[120:123], v245
	ds_read_b128 v[124:127], v245 offset:1024
	ds_read_b128 v[128:131], v245 offset:2048
	ds_read_b128 v[132:135], v245 offset:3072
	ds_read_b128 v[144:147], v246
	ds_read_b128 v[148:151], v246 offset:1024
	ds_read_b128 v[152:155], v246 offset:2048
	ds_read_b128 v[156:159], v246 offset:3072
	s_add_u32 s59, s82, 0xfffc0080
	s_addc_u32 s66, s83, -1
	s_cmp_eq_u32 s58, 12
	s_cselect_b32 s87, s53, s66
	s_cselect_b32 s86, s54, s59
	s_cselect_b32 s85, s51, s57
	s_cselect_b32 s84, s55, s56
	v_lshl_add_u64 v[204:205], s[82:83], 0, v[200:201]
	s_add_i32 m0, s16, 0xc000
	ds_read_b128 v[160:163], v247
	ds_read_b128 v[164:167], v247 offset:1024
	ds_read_b128 v[168:171], v247 offset:2048
	ds_read_b128 v[172:175], v247 offset:3072
	ds_read_b128 v[176:179], v247 offset:4096
	ds_read_b128 v[180:183], v247 offset:5120
	ds_read_b128 v[184:187], v247 offset:6144
	ds_read_b128 v[188:191], v247 offset:7168
	global_load_lds_dwordx4 v[204:205], off
	s_add_i32 m0, s16, 0xe000
	v_lshl_add_u64 v[204:205], s[82:83], 0, v[202:203]
	global_load_lds_dwordx4 v[204:205], off
	s_waitcnt vmcnt(8) lgkmcnt(0)
	s_barrier
	s_setprio 1
	v_mfma_f32_16x16x32_bf16 v[140:143], v[120:123], v[160:163], 0
	v_mfma_f32_16x16x32_bf16 v[140:143], v[124:127], v[164:167], v[140:143]
	v_mfma_f32_16x16x32_bf16 v[136:139], v[128:131], v[160:163], 0
	v_mfma_f32_16x16x32_bf16 v[136:139], v[132:135], v[164:167], v[136:139]
	v_mfma_f32_16x16x32_bf16 v[108:111], v[120:123], v[168:171], 0
	v_mfma_f32_16x16x32_bf16 v[108:111], v[124:127], v[172:175], v[108:111]
	v_mfma_f32_16x16x32_bf16 v[104:107], v[128:131], v[168:171], 0
	v_mfma_f32_16x16x32_bf16 v[104:107], v[132:135], v[172:175], v[104:107]
	v_mfma_f32_16x16x32_bf16 v[92:95], v[120:123], v[176:179], 0
	v_mfma_f32_16x16x32_bf16 v[92:95], v[124:127], v[180:183], v[92:95]
	v_mfma_f32_16x16x32_bf16 v[88:91], v[128:131], v[176:179], 0
	v_mfma_f32_16x16x32_bf16 v[88:91], v[132:135], v[180:183], v[88:91]
	v_mfma_f32_16x16x32_bf16 v[76:79], v[120:123], v[184:187], 0
	v_mfma_f32_16x16x32_bf16 v[76:79], v[124:127], v[188:191], v[76:79]
	v_mfma_f32_16x16x32_bf16 v[72:75], v[128:131], v[184:187], 0
	v_mfma_f32_16x16x32_bf16 v[72:75], v[132:135], v[188:191], v[72:75]
	v_mfma_f32_16x16x32_bf16 v[116:119], v[144:147], v[160:163], 0
	v_mfma_f32_16x16x32_bf16 v[116:119], v[148:151], v[164:167], v[116:119]
	v_mfma_f32_16x16x32_bf16 v[112:115], v[152:155], v[160:163], 0
	v_mfma_f32_16x16x32_bf16 v[112:115], v[156:159], v[164:167], v[112:115]
	v_mfma_f32_16x16x32_bf16 v[100:103], v[144:147], v[168:171], 0
	v_mfma_f32_16x16x32_bf16 v[100:103], v[148:151], v[172:175], v[100:103]
	v_mfma_f32_16x16x32_bf16 v[96:99], v[152:155], v[168:171], 0
	v_mfma_f32_16x16x32_bf16 v[96:99], v[156:159], v[172:175], v[96:99]
	v_mfma_f32_16x16x32_bf16 v[84:87], v[144:147], v[176:179], 0
	v_mfma_f32_16x16x32_bf16 v[84:87], v[148:151], v[180:183], v[84:87]
	v_mfma_f32_16x16x32_bf16 v[80:83], v[152:155], v[176:179], 0
	v_mfma_f32_16x16x32_bf16 v[80:83], v[156:159], v[180:183], v[80:83]
	v_mfma_f32_16x16x32_bf16 v[68:71], v[144:147], v[184:187], 0
	v_mfma_f32_16x16x32_bf16 v[68:71], v[148:151], v[188:191], v[68:71]
	s_setprio 3
	s_barrier
	v_mfma_f32_16x16x32_bf16 v[64:67], v[152:155], v[184:187], 0
	v_mfma_f32_16x16x32_bf16 v[64:67], v[156:159], v[188:191], v[64:67]
	s_setprio 0
	s_add_i32 s59, s26, s15
	v_lshl_add_u64 v[204:205], s[84:85], 0, v[194:195]
	s_mov_b32 m0, s59
	ds_read_b128 v[160:163], v247 offset:16384
	ds_read_b128 v[164:167], v247 offset:17408
	ds_read_b128 v[168:171], v247 offset:18432
	ds_read_b128 v[172:175], v247 offset:19456
	ds_read_b128 v[176:179], v247 offset:20480
	ds_read_b128 v[180:183], v247 offset:21504
	ds_read_b128 v[184:187], v247 offset:22528
	ds_read_b128 v[188:191], v247 offset:23552
	global_load_lds_dwordx4 v[204:205], off
	s_add_i32 m0, s59, 0x2000
	s_add_u32 s66, s84, 0x40000
	v_lshl_add_u64 v[206:207], s[84:85], 0, v[198:199]
	s_addc_u32 s67, s85, 0
	s_add_i32 s59, s27, s15
	global_load_lds_dwordx4 v[206:207], off
	v_lshl_add_u64 v[208:209], s[66:67], 0, v[194:195]
	s_mov_b32 m0, s59
	global_load_lds_dwordx4 v[208:209], off
	s_add_i32 m0, s59, 0x2000
	v_lshl_add_u64 v[208:209], s[66:67], 0, v[198:199]
	global_load_lds_dwordx4 v[208:209], off
	s_mov_b32 m0, s16
	v_lshl_add_u64 v[208:209], s[86:87], 0, v[192:193]
	global_load_lds_dwordx4 v[208:209], off
	s_mov_b32 m0, s17
	v_lshl_add_u64 v[210:211], s[86:87], 0, v[196:197]
	global_load_lds_dwordx4 v[210:211], off
	s_waitcnt vmcnt(8) lgkmcnt(0)
	s_barrier
	s_setprio 1
	v_mfma_f32_16x16x32_bf16 v[60:63], v[120:123], v[160:163], 0
	v_mfma_f32_16x16x32_bf16 v[60:63], v[124:127], v[164:167], v[60:63]
	v_mfma_f32_16x16x32_bf16 v[56:59], v[128:131], v[160:163], 0
	v_mfma_f32_16x16x32_bf16 v[56:59], v[132:135], v[164:167], v[56:59]
	v_mfma_f32_16x16x32_bf16 v[44:47], v[120:123], v[168:171], 0
	v_mfma_f32_16x16x32_bf16 v[44:47], v[124:127], v[172:175], v[44:47]
	v_mfma_f32_16x16x32_bf16 v[40:43], v[128:131], v[168:171], 0
	v_mfma_f32_16x16x32_bf16 v[40:43], v[132:135], v[172:175], v[40:43]
	v_mfma_f32_16x16x32_bf16 v[28:31], v[120:123], v[176:179], 0
	v_mfma_f32_16x16x32_bf16 v[28:31], v[124:127], v[180:183], v[28:31]
	v_mfma_f32_16x16x32_bf16 v[24:27], v[128:131], v[176:179], 0
	v_mfma_f32_16x16x32_bf16 v[24:27], v[132:135], v[180:183], v[24:27]
	v_mfma_f32_16x16x32_bf16 v[12:15], v[120:123], v[184:187], 0
	v_mfma_f32_16x16x32_bf16 v[12:15], v[124:127], v[188:191], v[12:15]
	v_mfma_f32_16x16x32_bf16 v[8:11], v[128:131], v[184:187], 0
	v_mfma_f32_16x16x32_bf16 v[8:11], v[132:135], v[188:191], v[8:11]
	v_mfma_f32_16x16x32_bf16 v[52:55], v[144:147], v[160:163], 0
	v_mfma_f32_16x16x32_bf16 v[52:55], v[148:151], v[164:167], v[52:55]
	v_mfma_f32_16x16x32_bf16 v[48:51], v[152:155], v[160:163], 0
	v_mfma_f32_16x16x32_bf16 v[48:51], v[156:159], v[164:167], v[48:51]
	v_mfma_f32_16x16x32_bf16 v[36:39], v[144:147], v[168:171], 0
	v_mfma_f32_16x16x32_bf16 v[36:39], v[148:151], v[172:175], v[36:39]
	v_mfma_f32_16x16x32_bf16 v[32:35], v[152:155], v[168:171], 0
	v_mfma_f32_16x16x32_bf16 v[32:35], v[156:159], v[172:175], v[32:35]
	v_mfma_f32_16x16x32_bf16 v[20:23], v[144:147], v[176:179], 0
	v_mfma_f32_16x16x32_bf16 v[20:23], v[148:151], v[180:183], v[20:23]
	v_mfma_f32_16x16x32_bf16 v[16:19], v[152:155], v[176:179], 0
	v_mfma_f32_16x16x32_bf16 v[16:19], v[156:159], v[180:183], v[16:19]
	v_mfma_f32_16x16x32_bf16 v[4:7], v[144:147], v[184:187], 0
	v_mfma_f32_16x16x32_bf16 v[4:7], v[148:151], v[188:191], v[4:7]
	s_setprio 3
	s_barrier
	v_mfma_f32_16x16x32_bf16 v[0:3], v[152:155], v[184:187], 0
	v_mfma_f32_16x16x32_bf16 v[0:3], v[156:159], v[188:191], v[0:3]
	s_setprio 0
	s_add_i32 s59, 0, 0x18000
	s_add_i32 s68, 0, 0x1c000
	v_add_u32_e32 v132, s59, v243
	v_add_u32_e32 v156, s68, v243
	ds_read_b128 v[120:123], v132
	ds_read_b128 v[124:127], v132 offset:1024
	ds_read_b128 v[128:131], v132 offset:2048
	ds_read_b128 v[132:135], v132 offset:3072
	ds_read_b128 v[144:147], v156
	ds_read_b128 v[148:151], v156 offset:1024
	ds_read_b128 v[152:155], v156 offset:2048
	ds_read_b128 v[156:159], v156 offset:3072
	s_add_u32 s66, s86, 0x40000
	s_addc_u32 s67, s87, 0
	s_mov_b32 m0, s18
	v_lshl_add_u64 v[212:213], s[66:67], 0, v[192:193]
	ds_read_b128 v[160:163], v247 offset:32768
	ds_read_b128 v[164:167], v247 offset:33792
	ds_read_b128 v[168:171], v247 offset:34816
	ds_read_b128 v[172:175], v247 offset:35840
	ds_read_b128 v[176:179], v247 offset:36864
	ds_read_b128 v[180:183], v247 offset:37888
	ds_read_b128 v[184:187], v247 offset:38912
	ds_read_b128 v[188:191], v247 offset:39936
	global_load_lds_dwordx4 v[212:213], off
	s_mov_b32 m0, s19
	v_lshl_add_u64 v[212:213], s[66:67], 0, v[196:197]
	global_load_lds_dwordx4 v[212:213], off
	s_waitcnt vmcnt(8) lgkmcnt(0)
	s_barrier
	s_setprio 1
	v_mfma_f32_16x16x32_bf16 v[140:143], v[120:123], v[160:163], v[140:143]
	v_mfma_f32_16x16x32_bf16 v[140:143], v[124:127], v[164:167], v[140:143]
	v_mfma_f32_16x16x32_bf16 v[136:139], v[128:131], v[160:163], v[136:139]
	v_mfma_f32_16x16x32_bf16 v[136:139], v[132:135], v[164:167], v[136:139]
	v_mfma_f32_16x16x32_bf16 v[108:111], v[120:123], v[168:171], v[108:111]
	v_mfma_f32_16x16x32_bf16 v[108:111], v[124:127], v[172:175], v[108:111]
	v_mfma_f32_16x16x32_bf16 v[104:107], v[128:131], v[168:171], v[104:107]
	v_mfma_f32_16x16x32_bf16 v[104:107], v[132:135], v[172:175], v[104:107]
	v_mfma_f32_16x16x32_bf16 v[92:95], v[120:123], v[176:179], v[92:95]
	v_mfma_f32_16x16x32_bf16 v[92:95], v[124:127], v[180:183], v[92:95]
	v_mfma_f32_16x16x32_bf16 v[88:91], v[128:131], v[176:179], v[88:91]
	v_mfma_f32_16x16x32_bf16 v[88:91], v[132:135], v[180:183], v[88:91]
	v_mfma_f32_16x16x32_bf16 v[76:79], v[120:123], v[184:187], v[76:79]
	v_mfma_f32_16x16x32_bf16 v[76:79], v[124:127], v[188:191], v[76:79]
	v_mfma_f32_16x16x32_bf16 v[72:75], v[128:131], v[184:187], v[72:75]
	v_mfma_f32_16x16x32_bf16 v[72:75], v[132:135], v[188:191], v[72:75]
	v_mfma_f32_16x16x32_bf16 v[116:119], v[144:147], v[160:163], v[116:119]
	v_mfma_f32_16x16x32_bf16 v[116:119], v[148:151], v[164:167], v[116:119]
	v_mfma_f32_16x16x32_bf16 v[112:115], v[152:155], v[160:163], v[112:115]
	v_mfma_f32_16x16x32_bf16 v[112:115], v[156:159], v[164:167], v[112:115]
	v_mfma_f32_16x16x32_bf16 v[100:103], v[144:147], v[168:171], v[100:103]
	v_mfma_f32_16x16x32_bf16 v[100:103], v[148:151], v[172:175], v[100:103]
	v_mfma_f32_16x16x32_bf16 v[96:99], v[152:155], v[168:171], v[96:99]
	v_mfma_f32_16x16x32_bf16 v[96:99], v[156:159], v[172:175], v[96:99]
	v_mfma_f32_16x16x32_bf16 v[84:87], v[144:147], v[176:179], v[84:87]
	v_mfma_f32_16x16x32_bf16 v[84:87], v[148:151], v[180:183], v[84:87]
	v_mfma_f32_16x16x32_bf16 v[80:83], v[152:155], v[176:179], v[80:83]
	v_mfma_f32_16x16x32_bf16 v[80:83], v[156:159], v[180:183], v[80:83]
	v_mfma_f32_16x16x32_bf16 v[68:71], v[144:147], v[184:187], v[68:71]
	v_mfma_f32_16x16x32_bf16 v[68:71], v[148:151], v[188:191], v[68:71]
	s_setprio 3
	s_barrier
	v_mfma_f32_16x16x32_bf16 v[64:67], v[152:155], v[184:187], v[64:67]
	v_mfma_f32_16x16x32_bf16 v[64:67], v[156:159], v[188:191], v[64:67]
	s_setprio 0
	s_add_i32 s59, s59, s15
	v_lshl_add_u64 v[204:205], v[204:205], 0, s[46:47]
	s_mov_b32 m0, s59
	ds_read_b128 v[160:163], v247 offset:49152
	ds_read_b128 v[164:167], v247 offset:50176
	ds_read_b128 v[168:171], v247 offset:51200
	ds_read_b128 v[172:175], v247 offset:52224
	ds_read_b128 v[176:179], v247 offset:53248
	ds_read_b128 v[180:183], v247 offset:54272
	ds_read_b128 v[184:187], v247 offset:55296
	ds_read_b128 v[188:191], v247 offset:56320
	global_load_lds_dwordx4 v[204:205], off
	s_add_i32 m0, s59, 0x2000
	s_add_u32 s66, s84, 0x40080
	v_lshl_add_u64 v[204:205], v[206:207], 0, s[46:47]
	s_addc_u32 s67, s85, 0
	s_add_i32 s59, s68, s15
	global_load_lds_dwordx4 v[204:205], off
	s_mov_b32 m0, s59
	v_lshl_add_u64 v[204:205], s[66:67], 0, v[194:195]
	global_load_lds_dwordx4 v[204:205], off
	s_add_i32 m0, s59, 0x2000
	v_lshl_add_u64 v[204:205], s[66:67], 0, v[198:199]
	global_load_lds_dwordx4 v[204:205], off
	s_mov_b32 m0, s21
	v_lshl_add_u64 v[204:205], v[208:209], 0, s[46:47]
	global_load_lds_dwordx4 v[204:205], off
	s_mov_b32 m0, s22
	v_lshl_add_u64 v[204:205], v[210:211], 0, s[46:47]
	global_load_lds_dwordx4 v[204:205], off
	s_waitcnt vmcnt(8) lgkmcnt(0)
	s_barrier
	s_setprio 1
	v_mfma_f32_16x16x32_bf16 v[60:63], v[120:123], v[160:163], v[60:63]
	v_mfma_f32_16x16x32_bf16 v[60:63], v[124:127], v[164:167], v[60:63]
	v_mfma_f32_16x16x32_bf16 v[56:59], v[128:131], v[160:163], v[56:59]
	v_mfma_f32_16x16x32_bf16 v[56:59], v[132:135], v[164:167], v[56:59]
	v_mfma_f32_16x16x32_bf16 v[44:47], v[120:123], v[168:171], v[44:47]
	v_mfma_f32_16x16x32_bf16 v[44:47], v[124:127], v[172:175], v[44:47]
	v_mfma_f32_16x16x32_bf16 v[40:43], v[128:131], v[168:171], v[40:43]
	v_mfma_f32_16x16x32_bf16 v[40:43], v[132:135], v[172:175], v[40:43]
	v_mfma_f32_16x16x32_bf16 v[28:31], v[120:123], v[176:179], v[28:31]
	v_mfma_f32_16x16x32_bf16 v[28:31], v[124:127], v[180:183], v[28:31]
	v_mfma_f32_16x16x32_bf16 v[24:27], v[128:131], v[176:179], v[24:27]
	v_mfma_f32_16x16x32_bf16 v[24:27], v[132:135], v[180:183], v[24:27]
	v_mfma_f32_16x16x32_bf16 v[12:15], v[120:123], v[184:187], v[12:15]
	v_mfma_f32_16x16x32_bf16 v[12:15], v[124:127], v[188:191], v[12:15]
	v_mfma_f32_16x16x32_bf16 v[8:11], v[128:131], v[184:187], v[8:11]
	v_mfma_f32_16x16x32_bf16 v[8:11], v[132:135], v[188:191], v[8:11]
	v_mfma_f32_16x16x32_bf16 v[52:55], v[144:147], v[160:163], v[52:55]
	v_mfma_f32_16x16x32_bf16 v[52:55], v[148:151], v[164:167], v[52:55]
	v_mfma_f32_16x16x32_bf16 v[48:51], v[152:155], v[160:163], v[48:51]
	v_mfma_f32_16x16x32_bf16 v[48:51], v[156:159], v[164:167], v[48:51]
	v_mfma_f32_16x16x32_bf16 v[36:39], v[144:147], v[168:171], v[36:39]
	v_mfma_f32_16x16x32_bf16 v[36:39], v[148:151], v[172:175], v[36:39]
	v_mfma_f32_16x16x32_bf16 v[32:35], v[152:155], v[168:171], v[32:35]
	v_mfma_f32_16x16x32_bf16 v[32:35], v[156:159], v[172:175], v[32:35]
	v_mfma_f32_16x16x32_bf16 v[20:23], v[144:147], v[176:179], v[20:23]
	v_mfma_f32_16x16x32_bf16 v[20:23], v[148:151], v[180:183], v[20:23]
	v_mfma_f32_16x16x32_bf16 v[16:19], v[152:155], v[176:179], v[16:19]
	v_mfma_f32_16x16x32_bf16 v[16:19], v[156:159], v[180:183], v[16:19]
	v_mfma_f32_16x16x32_bf16 v[4:7], v[144:147], v[184:187], v[4:7]
	v_mfma_f32_16x16x32_bf16 v[4:7], v[148:151], v[188:191], v[4:7]
	s_setprio 3
	s_barrier
	v_mfma_f32_16x16x32_bf16 v[0:3], v[152:155], v[184:187], v[0:3]
	v_mfma_f32_16x16x32_bf16 v[0:3], v[156:159], v[188:191], v[0:3]
	s_setprio 0
	s_add_i32 s58, s58, 2
	s_add_u32 s82, s82, 0x100
	s_addc_u32 s83, s83, 0
	s_add_u32 s56, s56, 0x100
	s_addc_u32 s57, s57, 0
	s_cmp_gt_u32 s58, 13
.LBB0_993:
	ds_read_b128 v[120:123], v245
	ds_read_b128 v[124:127], v245 offset:1024
	ds_read_b128 v[128:131], v245 offset:2048
	ds_read_b128 v[132:135], v245 offset:3072
	ds_read_b128 v[144:147], v246
	ds_read_b128 v[148:151], v246 offset:1024
	ds_read_b128 v[152:155], v246 offset:2048
	ds_read_b128 v[156:159], v246 offset:3072
	s_add_u32 s59, s82, 0xfffc0080
	s_addc_u32 s66, s83, -1
	s_cmp_eq_u32 s58, 12
	s_cselect_b32 s87, s53, s66
	s_cselect_b32 s86, s54, s59
	s_cselect_b32 s85, s51, s57
	s_cselect_b32 s84, s55, s56
	v_lshl_add_u64 v[204:205], s[82:83], 0, v[200:201]
	s_add_i32 m0, s16, 0xc000
	ds_read_b128 v[160:163], v247
	ds_read_b128 v[164:167], v247 offset:1024
	ds_read_b128 v[168:171], v247 offset:2048
	ds_read_b128 v[172:175], v247 offset:3072
	ds_read_b128 v[176:179], v247 offset:4096
	ds_read_b128 v[180:183], v247 offset:5120
	ds_read_b128 v[184:187], v247 offset:6144
	ds_read_b128 v[188:191], v247 offset:7168
	global_load_lds_dwordx4 v[204:205], off
	s_add_i32 m0, s16, 0xe000
	v_lshl_add_u64 v[204:205], s[82:83], 0, v[202:203]
	global_load_lds_dwordx4 v[204:205], off
	s_waitcnt vmcnt(8) lgkmcnt(0)
	s_barrier
	s_setprio 1
	v_mfma_f32_16x16x32_bf16 v[140:143], v[120:123], v[160:163], v[140:143]
	v_mfma_f32_16x16x32_bf16 v[140:143], v[124:127], v[164:167], v[140:143]
	v_mfma_f32_16x16x32_bf16 v[136:139], v[128:131], v[160:163], v[136:139]
	v_mfma_f32_16x16x32_bf16 v[136:139], v[132:135], v[164:167], v[136:139]
	v_mfma_f32_16x16x32_bf16 v[108:111], v[120:123], v[168:171], v[108:111]
	v_mfma_f32_16x16x32_bf16 v[108:111], v[124:127], v[172:175], v[108:111]
	v_mfma_f32_16x16x32_bf16 v[104:107], v[128:131], v[168:171], v[104:107]
	v_mfma_f32_16x16x32_bf16 v[104:107], v[132:135], v[172:175], v[104:107]
	v_mfma_f32_16x16x32_bf16 v[92:95], v[120:123], v[176:179], v[92:95]
	v_mfma_f32_16x16x32_bf16 v[92:95], v[124:127], v[180:183], v[92:95]
	v_mfma_f32_16x16x32_bf16 v[88:91], v[128:131], v[176:179], v[88:91]
	v_mfma_f32_16x16x32_bf16 v[88:91], v[132:135], v[180:183], v[88:91]
	v_mfma_f32_16x16x32_bf16 v[76:79], v[120:123], v[184:187], v[76:79]
	v_mfma_f32_16x16x32_bf16 v[76:79], v[124:127], v[188:191], v[76:79]
	v_mfma_f32_16x16x32_bf16 v[72:75], v[128:131], v[184:187], v[72:75]
	v_mfma_f32_16x16x32_bf16 v[72:75], v[132:135], v[188:191], v[72:75]
	v_mfma_f32_16x16x32_bf16 v[116:119], v[144:147], v[160:163], v[116:119]
	v_mfma_f32_16x16x32_bf16 v[116:119], v[148:151], v[164:167], v[116:119]
	v_mfma_f32_16x16x32_bf16 v[112:115], v[152:155], v[160:163], v[112:115]
	v_mfma_f32_16x16x32_bf16 v[112:115], v[156:159], v[164:167], v[112:115]
	v_mfma_f32_16x16x32_bf16 v[100:103], v[144:147], v[168:171], v[100:103]
	v_mfma_f32_16x16x32_bf16 v[100:103], v[148:151], v[172:175], v[100:103]
	v_mfma_f32_16x16x32_bf16 v[96:99], v[152:155], v[168:171], v[96:99]
	v_mfma_f32_16x16x32_bf16 v[96:99], v[156:159], v[172:175], v[96:99]
	v_mfma_f32_16x16x32_bf16 v[84:87], v[144:147], v[176:179], v[84:87]
	v_mfma_f32_16x16x32_bf16 v[84:87], v[148:151], v[180:183], v[84:87]
	v_mfma_f32_16x16x32_bf16 v[80:83], v[152:155], v[176:179], v[80:83]
	v_mfma_f32_16x16x32_bf16 v[80:83], v[156:159], v[180:183], v[80:83]
	v_mfma_f32_16x16x32_bf16 v[68:71], v[144:147], v[184:187], v[68:71]
	v_mfma_f32_16x16x32_bf16 v[68:71], v[148:151], v[188:191], v[68:71]
	s_setprio 3
	s_barrier
	v_mfma_f32_16x16x32_bf16 v[64:67], v[152:155], v[184:187], v[64:67]
	v_mfma_f32_16x16x32_bf16 v[64:67], v[156:159], v[188:191], v[64:67]
	s_setprio 0
	s_add_i32 s59, s26, s15
	v_lshl_add_u64 v[204:205], s[84:85], 0, v[194:195]
	s_mov_b32 m0, s59
	ds_read_b128 v[160:163], v247 offset:16384
	ds_read_b128 v[164:167], v247 offset:17408
	ds_read_b128 v[168:171], v247 offset:18432
	ds_read_b128 v[172:175], v247 offset:19456
	ds_read_b128 v[176:179], v247 offset:20480
	ds_read_b128 v[180:183], v247 offset:21504
	ds_read_b128 v[184:187], v247 offset:22528
	ds_read_b128 v[188:191], v247 offset:23552
	global_load_lds_dwordx4 v[204:205], off
	s_add_i32 m0, s59, 0x2000
	s_add_u32 s66, s84, 0x40000
	v_lshl_add_u64 v[206:207], s[84:85], 0, v[198:199]
	s_addc_u32 s67, s85, 0
	s_add_i32 s59, s27, s15
	global_load_lds_dwordx4 v[206:207], off
	v_lshl_add_u64 v[208:209], s[66:67], 0, v[194:195]
	s_mov_b32 m0, s59
	global_load_lds_dwordx4 v[208:209], off
	s_add_i32 m0, s59, 0x2000
	v_lshl_add_u64 v[208:209], s[66:67], 0, v[198:199]
	global_load_lds_dwordx4 v[208:209], off
	s_mov_b32 m0, s16
	v_lshl_add_u64 v[208:209], s[86:87], 0, v[192:193]
	global_load_lds_dwordx4 v[208:209], off
	s_mov_b32 m0, s17
	v_lshl_add_u64 v[210:211], s[86:87], 0, v[196:197]
	global_load_lds_dwordx4 v[210:211], off
	s_waitcnt vmcnt(8) lgkmcnt(0)
	s_barrier
	s_setprio 1
	v_mfma_f32_16x16x32_bf16 v[60:63], v[120:123], v[160:163], v[60:63]
	v_mfma_f32_16x16x32_bf16 v[60:63], v[124:127], v[164:167], v[60:63]
	v_mfma_f32_16x16x32_bf16 v[56:59], v[128:131], v[160:163], v[56:59]
	v_mfma_f32_16x16x32_bf16 v[56:59], v[132:135], v[164:167], v[56:59]
	v_mfma_f32_16x16x32_bf16 v[44:47], v[120:123], v[168:171], v[44:47]
	v_mfma_f32_16x16x32_bf16 v[44:47], v[124:127], v[172:175], v[44:47]
	v_mfma_f32_16x16x32_bf16 v[40:43], v[128:131], v[168:171], v[40:43]
	v_mfma_f32_16x16x32_bf16 v[40:43], v[132:135], v[172:175], v[40:43]
	v_mfma_f32_16x16x32_bf16 v[28:31], v[120:123], v[176:179], v[28:31]
	v_mfma_f32_16x16x32_bf16 v[28:31], v[124:127], v[180:183], v[28:31]
	v_mfma_f32_16x16x32_bf16 v[24:27], v[128:131], v[176:179], v[24:27]
	v_mfma_f32_16x16x32_bf16 v[24:27], v[132:135], v[180:183], v[24:27]
	v_mfma_f32_16x16x32_bf16 v[12:15], v[120:123], v[184:187], v[12:15]
	v_mfma_f32_16x16x32_bf16 v[12:15], v[124:127], v[188:191], v[12:15]
	v_mfma_f32_16x16x32_bf16 v[8:11], v[128:131], v[184:187], v[8:11]
	v_mfma_f32_16x16x32_bf16 v[8:11], v[132:135], v[188:191], v[8:11]
	v_mfma_f32_16x16x32_bf16 v[52:55], v[144:147], v[160:163], v[52:55]
	v_mfma_f32_16x16x32_bf16 v[52:55], v[148:151], v[164:167], v[52:55]
	v_mfma_f32_16x16x32_bf16 v[48:51], v[152:155], v[160:163], v[48:51]
	v_mfma_f32_16x16x32_bf16 v[48:51], v[156:159], v[164:167], v[48:51]
	v_mfma_f32_16x16x32_bf16 v[36:39], v[144:147], v[168:171], v[36:39]
	v_mfma_f32_16x16x32_bf16 v[36:39], v[148:151], v[172:175], v[36:39]
	v_mfma_f32_16x16x32_bf16 v[32:35], v[152:155], v[168:171], v[32:35]
	v_mfma_f32_16x16x32_bf16 v[32:35], v[156:159], v[172:175], v[32:35]
	v_mfma_f32_16x16x32_bf16 v[20:23], v[144:147], v[176:179], v[20:23]
	v_mfma_f32_16x16x32_bf16 v[20:23], v[148:151], v[180:183], v[20:23]
	v_mfma_f32_16x16x32_bf16 v[16:19], v[152:155], v[176:179], v[16:19]
	v_mfma_f32_16x16x32_bf16 v[16:19], v[156:159], v[180:183], v[16:19]
	v_mfma_f32_16x16x32_bf16 v[4:7], v[144:147], v[184:187], v[4:7]
	v_mfma_f32_16x16x32_bf16 v[4:7], v[148:151], v[188:191], v[4:7]
	s_setprio 3
	s_barrier
	v_mfma_f32_16x16x32_bf16 v[0:3], v[152:155], v[184:187], v[0:3]
	v_mfma_f32_16x16x32_bf16 v[0:3], v[156:159], v[188:191], v[0:3]
	s_setprio 0
	s_add_i32 s59, 0, 0x18000
	s_add_i32 s68, 0, 0x1c000
	v_add_u32_e32 v132, s59, v243
	v_add_u32_e32 v156, s68, v243
	ds_read_b128 v[120:123], v132
	ds_read_b128 v[124:127], v132 offset:1024
	ds_read_b128 v[128:131], v132 offset:2048
	ds_read_b128 v[132:135], v132 offset:3072
	ds_read_b128 v[144:147], v156
	ds_read_b128 v[148:151], v156 offset:1024
	ds_read_b128 v[152:155], v156 offset:2048
	ds_read_b128 v[156:159], v156 offset:3072
	s_add_u32 s66, s86, 0x40000
	s_addc_u32 s67, s87, 0
	s_mov_b32 m0, s18
	v_lshl_add_u64 v[212:213], s[66:67], 0, v[192:193]
	ds_read_b128 v[160:163], v247 offset:32768
	ds_read_b128 v[164:167], v247 offset:33792
	ds_read_b128 v[168:171], v247 offset:34816
	ds_read_b128 v[172:175], v247 offset:35840
	ds_read_b128 v[176:179], v247 offset:36864
	ds_read_b128 v[180:183], v247 offset:37888
	ds_read_b128 v[184:187], v247 offset:38912
	ds_read_b128 v[188:191], v247 offset:39936
	global_load_lds_dwordx4 v[212:213], off
	s_mov_b32 m0, s19
	v_lshl_add_u64 v[212:213], s[66:67], 0, v[196:197]
	global_load_lds_dwordx4 v[212:213], off
	s_waitcnt vmcnt(8) lgkmcnt(0)
	s_barrier
	s_setprio 1
	v_mfma_f32_16x16x32_bf16 v[140:143], v[120:123], v[160:163], v[140:143]
	v_mfma_f32_16x16x32_bf16 v[140:143], v[124:127], v[164:167], v[140:143]
	v_mfma_f32_16x16x32_bf16 v[136:139], v[128:131], v[160:163], v[136:139]
	v_mfma_f32_16x16x32_bf16 v[136:139], v[132:135], v[164:167], v[136:139]
	v_mfma_f32_16x16x32_bf16 v[108:111], v[120:123], v[168:171], v[108:111]
	v_mfma_f32_16x16x32_bf16 v[108:111], v[124:127], v[172:175], v[108:111]
	v_mfma_f32_16x16x32_bf16 v[104:107], v[128:131], v[168:171], v[104:107]
	v_mfma_f32_16x16x32_bf16 v[104:107], v[132:135], v[172:175], v[104:107]
	v_mfma_f32_16x16x32_bf16 v[92:95], v[120:123], v[176:179], v[92:95]
	v_mfma_f32_16x16x32_bf16 v[92:95], v[124:127], v[180:183], v[92:95]
	v_mfma_f32_16x16x32_bf16 v[88:91], v[128:131], v[176:179], v[88:91]
	v_mfma_f32_16x16x32_bf16 v[88:91], v[132:135], v[180:183], v[88:91]
	v_mfma_f32_16x16x32_bf16 v[76:79], v[120:123], v[184:187], v[76:79]
	v_mfma_f32_16x16x32_bf16 v[76:79], v[124:127], v[188:191], v[76:79]
	v_mfma_f32_16x16x32_bf16 v[72:75], v[128:131], v[184:187], v[72:75]
	v_mfma_f32_16x16x32_bf16 v[72:75], v[132:135], v[188:191], v[72:75]
	v_mfma_f32_16x16x32_bf16 v[116:119], v[144:147], v[160:163], v[116:119]
	v_mfma_f32_16x16x32_bf16 v[116:119], v[148:151], v[164:167], v[116:119]
	v_mfma_f32_16x16x32_bf16 v[112:115], v[152:155], v[160:163], v[112:115]
	v_mfma_f32_16x16x32_bf16 v[112:115], v[156:159], v[164:167], v[112:115]
	v_mfma_f32_16x16x32_bf16 v[100:103], v[144:147], v[168:171], v[100:103]
	v_mfma_f32_16x16x32_bf16 v[100:103], v[148:151], v[172:175], v[100:103]
	v_mfma_f32_16x16x32_bf16 v[96:99], v[152:155], v[168:171], v[96:99]
	v_mfma_f32_16x16x32_bf16 v[96:99], v[156:159], v[172:175], v[96:99]
	v_mfma_f32_16x16x32_bf16 v[84:87], v[144:147], v[176:179], v[84:87]
	v_mfma_f32_16x16x32_bf16 v[84:87], v[148:151], v[180:183], v[84:87]
	v_mfma_f32_16x16x32_bf16 v[80:83], v[152:155], v[176:179], v[80:83]
	v_mfma_f32_16x16x32_bf16 v[80:83], v[156:159], v[180:183], v[80:83]
	v_mfma_f32_16x16x32_bf16 v[68:71], v[144:147], v[184:187], v[68:71]
	v_mfma_f32_16x16x32_bf16 v[68:71], v[148:151], v[188:191], v[68:71]
	s_setprio 3
	s_barrier
	v_mfma_f32_16x16x32_bf16 v[64:67], v[152:155], v[184:187], v[64:67]
	v_mfma_f32_16x16x32_bf16 v[64:67], v[156:159], v[188:191], v[64:67]
	s_setprio 0
	s_add_i32 s59, s59, s15
	v_lshl_add_u64 v[204:205], v[204:205], 0, s[46:47]
	s_mov_b32 m0, s59
	ds_read_b128 v[160:163], v247 offset:49152
	ds_read_b128 v[164:167], v247 offset:50176
	ds_read_b128 v[168:171], v247 offset:51200
	ds_read_b128 v[172:175], v247 offset:52224
	ds_read_b128 v[176:179], v247 offset:53248
	ds_read_b128 v[180:183], v247 offset:54272
	ds_read_b128 v[184:187], v247 offset:55296
	ds_read_b128 v[188:191], v247 offset:56320
	global_load_lds_dwordx4 v[204:205], off
	s_add_i32 m0, s59, 0x2000
	s_add_u32 s66, s84, 0x40080
	v_lshl_add_u64 v[204:205], v[206:207], 0, s[46:47]
	s_addc_u32 s67, s85, 0
	s_add_i32 s59, s68, s15
	global_load_lds_dwordx4 v[204:205], off
	s_mov_b32 m0, s59
	v_lshl_add_u64 v[204:205], s[66:67], 0, v[194:195]
	global_load_lds_dwordx4 v[204:205], off
	s_add_i32 m0, s59, 0x2000
	v_lshl_add_u64 v[204:205], s[66:67], 0, v[198:199]
	global_load_lds_dwordx4 v[204:205], off
	s_mov_b32 m0, s21
	v_lshl_add_u64 v[204:205], v[208:209], 0, s[46:47]
	global_load_lds_dwordx4 v[204:205], off
	s_mov_b32 m0, s22
	v_lshl_add_u64 v[204:205], v[210:211], 0, s[46:47]
	global_load_lds_dwordx4 v[204:205], off
	s_waitcnt vmcnt(8) lgkmcnt(0)
	s_barrier
	s_setprio 1
	v_mfma_f32_16x16x32_bf16 v[60:63], v[120:123], v[160:163], v[60:63]
	v_mfma_f32_16x16x32_bf16 v[60:63], v[124:127], v[164:167], v[60:63]
	v_mfma_f32_16x16x32_bf16 v[56:59], v[128:131], v[160:163], v[56:59]
	v_mfma_f32_16x16x32_bf16 v[56:59], v[132:135], v[164:167], v[56:59]
	v_mfma_f32_16x16x32_bf16 v[44:47], v[120:123], v[168:171], v[44:47]
	v_mfma_f32_16x16x32_bf16 v[44:47], v[124:127], v[172:175], v[44:47]
	v_mfma_f32_16x16x32_bf16 v[40:43], v[128:131], v[168:171], v[40:43]
	v_mfma_f32_16x16x32_bf16 v[40:43], v[132:135], v[172:175], v[40:43]
	v_mfma_f32_16x16x32_bf16 v[28:31], v[120:123], v[176:179], v[28:31]
	v_mfma_f32_16x16x32_bf16 v[28:31], v[124:127], v[180:183], v[28:31]
	v_mfma_f32_16x16x32_bf16 v[24:27], v[128:131], v[176:179], v[24:27]
	v_mfma_f32_16x16x32_bf16 v[24:27], v[132:135], v[180:183], v[24:27]
	v_mfma_f32_16x16x32_bf16 v[12:15], v[120:123], v[184:187], v[12:15]
	v_mfma_f32_16x16x32_bf16 v[12:15], v[124:127], v[188:191], v[12:15]
	v_mfma_f32_16x16x32_bf16 v[8:11], v[128:131], v[184:187], v[8:11]
	v_mfma_f32_16x16x32_bf16 v[8:11], v[132:135], v[188:191], v[8:11]
	v_mfma_f32_16x16x32_bf16 v[52:55], v[144:147], v[160:163], v[52:55]
	v_mfma_f32_16x16x32_bf16 v[52:55], v[148:151], v[164:167], v[52:55]
	v_mfma_f32_16x16x32_bf16 v[48:51], v[152:155], v[160:163], v[48:51]
	v_mfma_f32_16x16x32_bf16 v[48:51], v[156:159], v[164:167], v[48:51]
	v_mfma_f32_16x16x32_bf16 v[36:39], v[144:147], v[168:171], v[36:39]
	v_mfma_f32_16x16x32_bf16 v[36:39], v[148:151], v[172:175], v[36:39]
	v_mfma_f32_16x16x32_bf16 v[32:35], v[152:155], v[168:171], v[32:35]
	v_mfma_f32_16x16x32_bf16 v[32:35], v[156:159], v[172:175], v[32:35]
	v_mfma_f32_16x16x32_bf16 v[20:23], v[144:147], v[176:179], v[20:23]
	v_mfma_f32_16x16x32_bf16 v[20:23], v[148:151], v[180:183], v[20:23]
	v_mfma_f32_16x16x32_bf16 v[16:19], v[152:155], v[176:179], v[16:19]
	v_mfma_f32_16x16x32_bf16 v[16:19], v[156:159], v[180:183], v[16:19]
	v_mfma_f32_16x16x32_bf16 v[4:7], v[144:147], v[184:187], v[4:7]
	v_mfma_f32_16x16x32_bf16 v[4:7], v[148:151], v[188:191], v[4:7]
	s_setprio 3
	s_barrier
	v_mfma_f32_16x16x32_bf16 v[0:3], v[152:155], v[184:187], v[0:3]
	v_mfma_f32_16x16x32_bf16 v[0:3], v[156:159], v[188:191], v[0:3]
	s_setprio 0
	s_add_i32 s58, s58, 2
	s_add_u32 s82, s82, 0x100
	s_addc_u32 s83, s83, 0
	s_add_u32 s56, s56, 0x100
	s_addc_u32 s57, s57, 0
	s_cmp_gt_u32 s58, 13
	s_cbranch_scc0 .LBB0_993
	s_and_b64 vcc, exec, s[48:49]
	s_cbranch_vccz .LBB0_996
	s_barrier

.LBB0_1147:
	s_ashr_i32 s49, s48, 31
	s_lshl_b64 s[50:51], s[48:49], 19
	s_add_u32 s50, s12, s50
	s_addc_u32 s51, s13, s51
	s_and_b64 s[52:53], s[4:5], exec
	s_cselect_b32 s49, s51, s79
	s_cselect_b32 s54, s50, s78
	s_ashr_i32 s47, s46, 31
	s_lshl_b64 s[52:53], s[46:47], 19
	s_add_u32 s52, s14, s52
	s_addc_u32 s53, s15, s53
	s_and_b64 s[58:59], s[4:5], exec
	s_cselect_b32 s47, s53, s81
	s_cselect_b32 s55, s52, s80
	s_add_u32 s78, s78, 0x40080
	s_addc_u32 s79, s79, 0
	s_add_u32 s58, s80, 0x100
	v_mov_b32_e32 v0, 0
	s_addc_u32 s59, s81, 0
	s_mov_b32 s66, -2
	s_waitcnt lgkmcnt(0)
	ds_read_b128 v[146:149], v174
	ds_read_b128 v[150:153], v174 offset:1024
	ds_read_b128 v[154:157], v174 offset:2048
	ds_read_b128 v[158:161], v174 offset:3072
	ds_read_b128 v[162:165], v175
	ds_read_b128 v[178:181], v175 offset:1024
	ds_read_b128 v[182:185], v175 offset:2048
	ds_read_b128 v[186:189], v175 offset:3072
	s_add_u32 s67, s78, 0xfffc0080
	s_addc_u32 s68, s79, -1
	s_cmp_eq_u32 s66, 12
	s_cselect_b32 s83, s49, s68
	s_cselect_b32 s82, s54, s67
	s_cselect_b32 s81, s47, s59
	s_cselect_b32 s80, s55, s58
	v_lshl_add_u64 v[166:167], s[78:79], 0, v[136:137]
	s_add_i32 m0, s17, 0xc000
	ds_read_b128 v[190:193], v176
	ds_read_b128 v[194:197], v176 offset:1024
	ds_read_b128 v[198:201], v176 offset:2048
	ds_read_b128 v[202:205], v176 offset:3072
	ds_read_b128 v[206:209], v176 offset:4096
	ds_read_b128 v[210:213], v176 offset:5120
	ds_read_b128 v[214:217], v176 offset:6144
	ds_read_b128 v[218:221], v176 offset:7168
	global_load_lds_dwordx4 v[166:167], off
	s_add_i32 m0, s17, 0xe000
	v_lshl_add_u64 v[166:167], s[78:79], 0, v[140:141]
	global_load_lds_dwordx4 v[166:167], off
	s_waitcnt vmcnt(8) lgkmcnt(0)
	s_barrier
	s_setprio 1
	v_mfma_f32_16x16x32_bf16 v[124:127], v[146:149], v[190:193], 0
	v_mfma_f32_16x16x32_bf16 v[124:127], v[150:153], v[194:197], v[124:127]
	v_mfma_f32_16x16x32_bf16 v[116:119], v[154:157], v[190:193], 0
	v_mfma_f32_16x16x32_bf16 v[116:119], v[158:161], v[194:197], v[116:119]
	v_mfma_f32_16x16x32_bf16 v[108:111], v[146:149], v[198:201], 0
	v_mfma_f32_16x16x32_bf16 v[108:111], v[150:153], v[202:205], v[108:111]
	v_mfma_f32_16x16x32_bf16 v[100:103], v[154:157], v[198:201], 0
	v_mfma_f32_16x16x32_bf16 v[100:103], v[158:161], v[202:205], v[100:103]
	v_mfma_f32_16x16x32_bf16 v[92:95], v[146:149], v[206:209], 0
	v_mfma_f32_16x16x32_bf16 v[92:95], v[150:153], v[210:213], v[92:95]
	v_mfma_f32_16x16x32_bf16 v[84:87], v[154:157], v[206:209], 0
	v_mfma_f32_16x16x32_bf16 v[84:87], v[158:161], v[210:213], v[84:87]
	v_mfma_f32_16x16x32_bf16 v[76:79], v[146:149], v[214:217], 0
	v_mfma_f32_16x16x32_bf16 v[76:79], v[150:153], v[218:221], v[76:79]
	v_mfma_f32_16x16x32_bf16 v[68:71], v[154:157], v[214:217], 0
	v_mfma_f32_16x16x32_bf16 v[68:71], v[158:161], v[218:221], v[68:71]
	v_mfma_f32_16x16x32_bf16 v[120:123], v[162:165], v[190:193], 0
	v_mfma_f32_16x16x32_bf16 v[120:123], v[178:181], v[194:197], v[120:123]
	v_mfma_f32_16x16x32_bf16 v[112:115], v[182:185], v[190:193], 0
	v_mfma_f32_16x16x32_bf16 v[112:115], v[186:189], v[194:197], v[112:115]
	v_mfma_f32_16x16x32_bf16 v[104:107], v[162:165], v[198:201], 0
	v_mfma_f32_16x16x32_bf16 v[104:107], v[178:181], v[202:205], v[104:107]
	v_mfma_f32_16x16x32_bf16 v[96:99], v[182:185], v[198:201], 0
	v_mfma_f32_16x16x32_bf16 v[96:99], v[186:189], v[202:205], v[96:99]
	v_mfma_f32_16x16x32_bf16 v[88:91], v[162:165], v[206:209], 0
	v_mfma_f32_16x16x32_bf16 v[88:91], v[178:181], v[210:213], v[88:91]
	v_mfma_f32_16x16x32_bf16 v[80:83], v[182:185], v[206:209], 0
	v_mfma_f32_16x16x32_bf16 v[80:83], v[186:189], v[210:213], v[80:83]
	v_mfma_f32_16x16x32_bf16 v[72:75], v[162:165], v[214:217], 0
	v_mfma_f32_16x16x32_bf16 v[72:75], v[178:181], v[218:221], v[72:75]
	s_setprio 3
	s_barrier
	v_mfma_f32_16x16x32_bf16 v[64:67], v[182:185], v[214:217], 0
	v_mfma_f32_16x16x32_bf16 v[64:67], v[186:189], v[218:221], v[64:67]
	s_setprio 0
	s_add_i32 s67, s25, s16
	v_lshl_add_u64 v[166:167], s[80:81], 0, v[132:133]
	s_mov_b32 m0, s67
	ds_read_b128 v[190:193], v176 offset:16384
	ds_read_b128 v[194:197], v176 offset:17408
	ds_read_b128 v[198:201], v176 offset:18432
	ds_read_b128 v[202:205], v176 offset:19456
	ds_read_b128 v[206:209], v176 offset:20480
	ds_read_b128 v[210:213], v176 offset:21504
	ds_read_b128 v[214:217], v176 offset:22528
	ds_read_b128 v[218:221], v176 offset:23552
	global_load_lds_dwordx4 v[166:167], off
	s_add_i32 m0, s67, 0x2000
	s_add_u32 s68, s80, 0x40000
	v_lshl_add_u64 v[222:223], s[80:81], 0, v[128:129]
	s_addc_u32 s69, s81, 0
	s_add_i32 s67, s26, s16
	global_load_lds_dwordx4 v[222:223], off
	v_lshl_add_u64 v[224:225], s[68:69], 0, v[132:133]
	s_mov_b32 m0, s67
	global_load_lds_dwordx4 v[224:225], off
	s_add_i32 m0, s67, 0x2000
	v_lshl_add_u64 v[224:225], s[68:69], 0, v[128:129]
	global_load_lds_dwordx4 v[224:225], off
	s_mov_b32 m0, s17
	v_lshl_add_u64 v[224:225], s[82:83], 0, v[134:135]
	global_load_lds_dwordx4 v[224:225], off
	s_mov_b32 m0, s18
	v_lshl_add_u64 v[226:227], s[82:83], 0, v[130:131]
	global_load_lds_dwordx4 v[226:227], off
	s_waitcnt vmcnt(8) lgkmcnt(0)
	s_barrier
	s_setprio 1
	v_mfma_f32_16x16x32_bf16 v[60:63], v[146:149], v[190:193], 0
	v_mfma_f32_16x16x32_bf16 v[60:63], v[150:153], v[194:197], v[60:63]
	v_mfma_f32_16x16x32_bf16 v[52:55], v[154:157], v[190:193], 0
	v_mfma_f32_16x16x32_bf16 v[52:55], v[158:161], v[194:197], v[52:55]
	v_mfma_f32_16x16x32_bf16 v[44:47], v[146:149], v[198:201], 0
	v_mfma_f32_16x16x32_bf16 v[44:47], v[150:153], v[202:205], v[44:47]
	v_mfma_f32_16x16x32_bf16 v[36:39], v[154:157], v[198:201], 0
	v_mfma_f32_16x16x32_bf16 v[36:39], v[158:161], v[202:205], v[36:39]
	v_mfma_f32_16x16x32_bf16 v[28:31], v[146:149], v[206:209], 0
	v_mfma_f32_16x16x32_bf16 v[28:31], v[150:153], v[210:213], v[28:31]
	v_mfma_f32_16x16x32_bf16 v[20:23], v[154:157], v[206:209], 0
	v_mfma_f32_16x16x32_bf16 v[20:23], v[158:161], v[210:213], v[20:23]
	v_mfma_f32_16x16x32_bf16 v[12:15], v[146:149], v[214:217], 0
	v_mfma_f32_16x16x32_bf16 v[12:15], v[150:153], v[218:221], v[12:15]
	v_mfma_f32_16x16x32_bf16 v[4:7], v[154:157], v[214:217], 0
	v_mfma_f32_16x16x32_bf16 v[4:7], v[158:161], v[218:221], v[4:7]
	v_mfma_f32_16x16x32_bf16 v[56:59], v[162:165], v[190:193], 0
	v_mfma_f32_16x16x32_bf16 v[56:59], v[178:181], v[194:197], v[56:59]
	v_mfma_f32_16x16x32_bf16 v[48:51], v[182:185], v[190:193], 0
	v_mfma_f32_16x16x32_bf16 v[48:51], v[186:189], v[194:197], v[48:51]
	v_mfma_f32_16x16x32_bf16 v[40:43], v[162:165], v[198:201], 0
	v_mfma_f32_16x16x32_bf16 v[40:43], v[178:181], v[202:205], v[40:43]
	v_mfma_f32_16x16x32_bf16 v[32:35], v[182:185], v[198:201], 0
	v_mfma_f32_16x16x32_bf16 v[32:35], v[186:189], v[202:205], v[32:35]
	v_mfma_f32_16x16x32_bf16 v[24:27], v[162:165], v[206:209], 0
	v_mfma_f32_16x16x32_bf16 v[24:27], v[178:181], v[210:213], v[24:27]
	v_mfma_f32_16x16x32_bf16 v[16:19], v[182:185], v[206:209], 0
	v_mfma_f32_16x16x32_bf16 v[16:19], v[186:189], v[210:213], v[16:19]
	v_mfma_f32_16x16x32_bf16 v[8:11], v[162:165], v[214:217], 0
	v_mfma_f32_16x16x32_bf16 v[8:11], v[178:181], v[218:221], v[8:11]
	s_setprio 3
	s_barrier
	v_mfma_f32_16x16x32_bf16 v[0:3], v[182:185], v[214:217], 0
	v_mfma_f32_16x16x32_bf16 v[0:3], v[186:189], v[218:221], v[0:3]
	s_setprio 0
	s_add_i32 s67, 0, 0x18000
	s_add_i32 s73, 0, 0x1c000
	v_add_u32_e32 v158, s67, v171
	v_add_u32_e32 v186, s73, v171
	ds_read_b128 v[146:149], v158
	ds_read_b128 v[150:153], v158 offset:1024
	ds_read_b128 v[154:157], v158 offset:2048
	ds_read_b128 v[158:161], v158 offset:3072
	ds_read_b128 v[162:165], v186
	ds_read_b128 v[178:181], v186 offset:1024
	ds_read_b128 v[182:185], v186 offset:2048
	ds_read_b128 v[186:189], v186 offset:3072
	s_add_u32 s68, s82, 0x40000
	s_addc_u32 s69, s83, 0
	s_mov_b32 m0, s19
	v_lshl_add_u64 v[228:229], s[68:69], 0, v[134:135]
	ds_read_b128 v[190:193], v176 offset:32768
	ds_read_b128 v[194:197], v176 offset:33792
	ds_read_b128 v[198:201], v176 offset:34816
	ds_read_b128 v[202:205], v176 offset:35840
	ds_read_b128 v[206:209], v176 offset:36864
	ds_read_b128 v[210:213], v176 offset:37888
	ds_read_b128 v[214:217], v176 offset:38912
	ds_read_b128 v[218:221], v176 offset:39936
	global_load_lds_dwordx4 v[228:229], off
	s_mov_b32 m0, s20
	v_lshl_add_u64 v[228:229], s[68:69], 0, v[130:131]
	global_load_lds_dwordx4 v[228:229], off
	s_waitcnt vmcnt(8) lgkmcnt(0)
	s_barrier
	s_setprio 1
	v_mfma_f32_16x16x32_bf16 v[124:127], v[146:149], v[190:193], v[124:127]
	v_mfma_f32_16x16x32_bf16 v[124:127], v[150:153], v[194:197], v[124:127]
	v_mfma_f32_16x16x32_bf16 v[116:119], v[154:157], v[190:193], v[116:119]
	v_mfma_f32_16x16x32_bf16 v[116:119], v[158:161], v[194:197], v[116:119]
	v_mfma_f32_16x16x32_bf16 v[108:111], v[146:149], v[198:201], v[108:111]
	v_mfma_f32_16x16x32_bf16 v[108:111], v[150:153], v[202:205], v[108:111]
	v_mfma_f32_16x16x32_bf16 v[100:103], v[154:157], v[198:201], v[100:103]
	v_mfma_f32_16x16x32_bf16 v[100:103], v[158:161], v[202:205], v[100:103]
	v_mfma_f32_16x16x32_bf16 v[92:95], v[146:149], v[206:209], v[92:95]
	v_mfma_f32_16x16x32_bf16 v[92:95], v[150:153], v[210:213], v[92:95]
	v_mfma_f32_16x16x32_bf16 v[84:87], v[154:157], v[206:209], v[84:87]
	v_mfma_f32_16x16x32_bf16 v[84:87], v[158:161], v[210:213], v[84:87]
	v_mfma_f32_16x16x32_bf16 v[76:79], v[146:149], v[214:217], v[76:79]
	v_mfma_f32_16x16x32_bf16 v[76:79], v[150:153], v[218:221], v[76:79]
	v_mfma_f32_16x16x32_bf16 v[68:71], v[154:157], v[214:217], v[68:71]
	v_mfma_f32_16x16x32_bf16 v[68:71], v[158:161], v[218:221], v[68:71]
	v_mfma_f32_16x16x32_bf16 v[120:123], v[162:165], v[190:193], v[120:123]
	v_mfma_f32_16x16x32_bf16 v[120:123], v[178:181], v[194:197], v[120:123]
	v_mfma_f32_16x16x32_bf16 v[112:115], v[182:185], v[190:193], v[112:115]
	v_mfma_f32_16x16x32_bf16 v[112:115], v[186:189], v[194:197], v[112:115]
	v_mfma_f32_16x16x32_bf16 v[104:107], v[162:165], v[198:201], v[104:107]
	v_mfma_f32_16x16x32_bf16 v[104:107], v[178:181], v[202:205], v[104:107]
	v_mfma_f32_16x16x32_bf16 v[96:99], v[182:185], v[198:201], v[96:99]
	v_mfma_f32_16x16x32_bf16 v[96:99], v[186:189], v[202:205], v[96:99]
	v_mfma_f32_16x16x32_bf16 v[88:91], v[162:165], v[206:209], v[88:91]
	v_mfma_f32_16x16x32_bf16 v[88:91], v[178:181], v[210:213], v[88:91]
	v_mfma_f32_16x16x32_bf16 v[80:83], v[182:185], v[206:209], v[80:83]
	v_mfma_f32_16x16x32_bf16 v[80:83], v[186:189], v[210:213], v[80:83]
	v_mfma_f32_16x16x32_bf16 v[72:75], v[162:165], v[214:217], v[72:75]
	v_mfma_f32_16x16x32_bf16 v[72:75], v[178:181], v[218:221], v[72:75]
	s_setprio 3
	s_barrier
	v_mfma_f32_16x16x32_bf16 v[64:67], v[182:185], v[214:217], v[64:67]
	v_mfma_f32_16x16x32_bf16 v[64:67], v[186:189], v[218:221], v[64:67]
	s_setprio 0
	s_add_i32 s67, s67, s16
	v_lshl_add_u64 v[166:167], v[166:167], 0, s[10:11]
	s_mov_b32 m0, s67
	ds_read_b128 v[190:193], v176 offset:49152
	ds_read_b128 v[194:197], v176 offset:50176
	ds_read_b128 v[198:201], v176 offset:51200
	ds_read_b128 v[202:205], v176 offset:52224
	ds_read_b128 v[206:209], v176 offset:53248
	ds_read_b128 v[210:213], v176 offset:54272
	ds_read_b128 v[214:217], v176 offset:55296
	ds_read_b128 v[218:221], v176 offset:56320
	global_load_lds_dwordx4 v[166:167], off
	s_add_i32 m0, s67, 0x2000
	s_add_u32 s68, s80, 0x40080
	v_lshl_add_u64 v[166:167], v[222:223], 0, s[10:11]
	s_addc_u32 s69, s81, 0
	s_add_i32 s67, s73, s16
	global_load_lds_dwordx4 v[166:167], off
	s_mov_b32 m0, s67
	v_lshl_add_u64 v[166:167], s[68:69], 0, v[132:133]
	global_load_lds_dwordx4 v[166:167], off
	s_add_i32 m0, s67, 0x2000
	v_lshl_add_u64 v[166:167], s[68:69], 0, v[128:129]
	global_load_lds_dwordx4 v[166:167], off
	s_mov_b32 m0, s23
	v_lshl_add_u64 v[166:167], v[224:225], 0, s[10:11]
	global_load_lds_dwordx4 v[166:167], off
	s_mov_b32 m0, s24
	v_lshl_add_u64 v[166:167], v[226:227], 0, s[10:11]
	global_load_lds_dwordx4 v[166:167], off
	s_waitcnt vmcnt(8) lgkmcnt(0)
	s_barrier
	s_setprio 1
	v_mfma_f32_16x16x32_bf16 v[60:63], v[146:149], v[190:193], v[60:63]
	v_mfma_f32_16x16x32_bf16 v[60:63], v[150:153], v[194:197], v[60:63]
	v_mfma_f32_16x16x32_bf16 v[52:55], v[154:157], v[190:193], v[52:55]
	v_mfma_f32_16x16x32_bf16 v[52:55], v[158:161], v[194:197], v[52:55]
	v_mfma_f32_16x16x32_bf16 v[44:47], v[146:149], v[198:201], v[44:47]
	v_mfma_f32_16x16x32_bf16 v[44:47], v[150:153], v[202:205], v[44:47]
	v_mfma_f32_16x16x32_bf16 v[36:39], v[154:157], v[198:201], v[36:39]
	v_mfma_f32_16x16x32_bf16 v[36:39], v[158:161], v[202:205], v[36:39]
	v_mfma_f32_16x16x32_bf16 v[28:31], v[146:149], v[206:209], v[28:31]
	v_mfma_f32_16x16x32_bf16 v[28:31], v[150:153], v[210:213], v[28:31]
	v_mfma_f32_16x16x32_bf16 v[20:23], v[154:157], v[206:209], v[20:23]
	v_mfma_f32_16x16x32_bf16 v[20:23], v[158:161], v[210:213], v[20:23]
	v_mfma_f32_16x16x32_bf16 v[12:15], v[146:149], v[214:217], v[12:15]
	v_mfma_f32_16x16x32_bf16 v[12:15], v[150:153], v[218:221], v[12:15]
	v_mfma_f32_16x16x32_bf16 v[4:7], v[154:157], v[214:217], v[4:7]
	v_mfma_f32_16x16x32_bf16 v[4:7], v[158:161], v[218:221], v[4:7]
	v_mfma_f32_16x16x32_bf16 v[56:59], v[162:165], v[190:193], v[56:59]
	v_mfma_f32_16x16x32_bf16 v[56:59], v[178:181], v[194:197], v[56:59]
	v_mfma_f32_16x16x32_bf16 v[48:51], v[182:185], v[190:193], v[48:51]
	v_mfma_f32_16x16x32_bf16 v[48:51], v[186:189], v[194:197], v[48:51]
	v_mfma_f32_16x16x32_bf16 v[40:43], v[162:165], v[198:201], v[40:43]
	v_mfma_f32_16x16x32_bf16 v[40:43], v[178:181], v[202:205], v[40:43]
	v_mfma_f32_16x16x32_bf16 v[32:35], v[182:185], v[198:201], v[32:35]
	v_mfma_f32_16x16x32_bf16 v[32:35], v[186:189], v[202:205], v[32:35]
	v_mfma_f32_16x16x32_bf16 v[24:27], v[162:165], v[206:209], v[24:27]
	v_mfma_f32_16x16x32_bf16 v[24:27], v[178:181], v[210:213], v[24:27]
	v_mfma_f32_16x16x32_bf16 v[16:19], v[182:185], v[206:209], v[16:19]
	v_mfma_f32_16x16x32_bf16 v[16:19], v[186:189], v[210:213], v[16:19]
	v_mfma_f32_16x16x32_bf16 v[8:11], v[162:165], v[214:217], v[8:11]
	v_mfma_f32_16x16x32_bf16 v[8:11], v[178:181], v[218:221], v[8:11]
	s_setprio 3
	s_barrier
	v_mfma_f32_16x16x32_bf16 v[0:3], v[182:185], v[214:217], v[0:3]
	v_mfma_f32_16x16x32_bf16 v[0:3], v[186:189], v[218:221], v[0:3]
	s_setprio 0
	s_add_i32 s66, s66, 2
	s_add_u32 s78, s78, 0x100
	s_addc_u32 s79, s79, 0
	s_add_u32 s58, s58, 0x100
	s_addc_u32 s59, s59, 0
	s_cmp_gt_u32 s66, 13
.LBB0_1148:
	ds_read_b128 v[146:149], v174
	ds_read_b128 v[150:153], v174 offset:1024
	ds_read_b128 v[154:157], v174 offset:2048
	ds_read_b128 v[158:161], v174 offset:3072
	ds_read_b128 v[162:165], v175
	ds_read_b128 v[178:181], v175 offset:1024
	ds_read_b128 v[182:185], v175 offset:2048
	ds_read_b128 v[186:189], v175 offset:3072
	s_add_u32 s67, s78, 0xfffc0080
	s_addc_u32 s68, s79, -1
	s_cmp_eq_u32 s66, 12
	s_cselect_b32 s83, s49, s68
	s_cselect_b32 s82, s54, s67
	s_cselect_b32 s81, s47, s59
	s_cselect_b32 s80, s55, s58
	v_lshl_add_u64 v[166:167], s[78:79], 0, v[136:137]
	s_add_i32 m0, s17, 0xc000
	ds_read_b128 v[190:193], v176
	ds_read_b128 v[194:197], v176 offset:1024
	ds_read_b128 v[198:201], v176 offset:2048
	ds_read_b128 v[202:205], v176 offset:3072
	ds_read_b128 v[206:209], v176 offset:4096
	ds_read_b128 v[210:213], v176 offset:5120
	ds_read_b128 v[214:217], v176 offset:6144
	ds_read_b128 v[218:221], v176 offset:7168
	global_load_lds_dwordx4 v[166:167], off
	s_add_i32 m0, s17, 0xe000
	v_lshl_add_u64 v[166:167], s[78:79], 0, v[140:141]
	global_load_lds_dwordx4 v[166:167], off
	s_waitcnt vmcnt(8) lgkmcnt(0)
	s_barrier
	s_setprio 1
	v_mfma_f32_16x16x32_bf16 v[124:127], v[146:149], v[190:193], v[124:127]
	v_mfma_f32_16x16x32_bf16 v[124:127], v[150:153], v[194:197], v[124:127]
	v_mfma_f32_16x16x32_bf16 v[116:119], v[154:157], v[190:193], v[116:119]
	v_mfma_f32_16x16x32_bf16 v[116:119], v[158:161], v[194:197], v[116:119]
	v_mfma_f32_16x16x32_bf16 v[108:111], v[146:149], v[198:201], v[108:111]
	v_mfma_f32_16x16x32_bf16 v[108:111], v[150:153], v[202:205], v[108:111]
	v_mfma_f32_16x16x32_bf16 v[100:103], v[154:157], v[198:201], v[100:103]
	v_mfma_f32_16x16x32_bf16 v[100:103], v[158:161], v[202:205], v[100:103]
	v_mfma_f32_16x16x32_bf16 v[92:95], v[146:149], v[206:209], v[92:95]
	v_mfma_f32_16x16x32_bf16 v[92:95], v[150:153], v[210:213], v[92:95]
	v_mfma_f32_16x16x32_bf16 v[84:87], v[154:157], v[206:209], v[84:87]
	v_mfma_f32_16x16x32_bf16 v[84:87], v[158:161], v[210:213], v[84:87]
	v_mfma_f32_16x16x32_bf16 v[76:79], v[146:149], v[214:217], v[76:79]
	v_mfma_f32_16x16x32_bf16 v[76:79], v[150:153], v[218:221], v[76:79]
	v_mfma_f32_16x16x32_bf16 v[68:71], v[154:157], v[214:217], v[68:71]
	v_mfma_f32_16x16x32_bf16 v[68:71], v[158:161], v[218:221], v[68:71]
	v_mfma_f32_16x16x32_bf16 v[120:123], v[162:165], v[190:193], v[120:123]
	v_mfma_f32_16x16x32_bf16 v[120:123], v[178:181], v[194:197], v[120:123]
	v_mfma_f32_16x16x32_bf16 v[112:115], v[182:185], v[190:193], v[112:115]
	v_mfma_f32_16x16x32_bf16 v[112:115], v[186:189], v[194:197], v[112:115]
	v_mfma_f32_16x16x32_bf16 v[104:107], v[162:165], v[198:201], v[104:107]
	v_mfma_f32_16x16x32_bf16 v[104:107], v[178:181], v[202:205], v[104:107]
	v_mfma_f32_16x16x32_bf16 v[96:99], v[182:185], v[198:201], v[96:99]
	v_mfma_f32_16x16x32_bf16 v[96:99], v[186:189], v[202:205], v[96:99]
	v_mfma_f32_16x16x32_bf16 v[88:91], v[162:165], v[206:209], v[88:91]
	v_mfma_f32_16x16x32_bf16 v[88:91], v[178:181], v[210:213], v[88:91]
	v_mfma_f32_16x16x32_bf16 v[80:83], v[182:185], v[206:209], v[80:83]
	v_mfma_f32_16x16x32_bf16 v[80:83], v[186:189], v[210:213], v[80:83]
	v_mfma_f32_16x16x32_bf16 v[72:75], v[162:165], v[214:217], v[72:75]
	v_mfma_f32_16x16x32_bf16 v[72:75], v[178:181], v[218:221], v[72:75]
	s_setprio 3
	s_barrier
	v_mfma_f32_16x16x32_bf16 v[64:67], v[182:185], v[214:217], v[64:67]
	v_mfma_f32_16x16x32_bf16 v[64:67], v[186:189], v[218:221], v[64:67]
	s_setprio 0
	s_add_i32 s67, s25, s16
	v_lshl_add_u64 v[166:167], s[80:81], 0, v[132:133]
	s_mov_b32 m0, s67
	ds_read_b128 v[190:193], v176 offset:16384
	ds_read_b128 v[194:197], v176 offset:17408
	ds_read_b128 v[198:201], v176 offset:18432
	ds_read_b128 v[202:205], v176 offset:19456
	ds_read_b128 v[206:209], v176 offset:20480
	ds_read_b128 v[210:213], v176 offset:21504
	ds_read_b128 v[214:217], v176 offset:22528
	ds_read_b128 v[218:221], v176 offset:23552
	global_load_lds_dwordx4 v[166:167], off
	s_add_i32 m0, s67, 0x2000
	s_add_u32 s68, s80, 0x40000
	v_lshl_add_u64 v[222:223], s[80:81], 0, v[128:129]
	s_addc_u32 s69, s81, 0
	s_add_i32 s67, s26, s16
	global_load_lds_dwordx4 v[222:223], off
	v_lshl_add_u64 v[224:225], s[68:69], 0, v[132:133]
	s_mov_b32 m0, s67
	global_load_lds_dwordx4 v[224:225], off
	s_add_i32 m0, s67, 0x2000
	v_lshl_add_u64 v[224:225], s[68:69], 0, v[128:129]
	global_load_lds_dwordx4 v[224:225], off
	s_mov_b32 m0, s17
	v_lshl_add_u64 v[224:225], s[82:83], 0, v[134:135]
	global_load_lds_dwordx4 v[224:225], off
	s_mov_b32 m0, s18
	v_lshl_add_u64 v[226:227], s[82:83], 0, v[130:131]
	global_load_lds_dwordx4 v[226:227], off
	s_waitcnt vmcnt(8) lgkmcnt(0)
	s_barrier
	s_setprio 1
	v_mfma_f32_16x16x32_bf16 v[60:63], v[146:149], v[190:193], v[60:63]
	v_mfma_f32_16x16x32_bf16 v[60:63], v[150:153], v[194:197], v[60:63]
	v_mfma_f32_16x16x32_bf16 v[52:55], v[154:157], v[190:193], v[52:55]
	v_mfma_f32_16x16x32_bf16 v[52:55], v[158:161], v[194:197], v[52:55]
	v_mfma_f32_16x16x32_bf16 v[44:47], v[146:149], v[198:201], v[44:47]
	v_mfma_f32_16x16x32_bf16 v[44:47], v[150:153], v[202:205], v[44:47]
	v_mfma_f32_16x16x32_bf16 v[36:39], v[154:157], v[198:201], v[36:39]
	v_mfma_f32_16x16x32_bf16 v[36:39], v[158:161], v[202:205], v[36:39]
	v_mfma_f32_16x16x32_bf16 v[28:31], v[146:149], v[206:209], v[28:31]
	v_mfma_f32_16x16x32_bf16 v[28:31], v[150:153], v[210:213], v[28:31]
	v_mfma_f32_16x16x32_bf16 v[20:23], v[154:157], v[206:209], v[20:23]
	v_mfma_f32_16x16x32_bf16 v[20:23], v[158:161], v[210:213], v[20:23]
	v_mfma_f32_16x16x32_bf16 v[12:15], v[146:149], v[214:217], v[12:15]
	v_mfma_f32_16x16x32_bf16 v[12:15], v[150:153], v[218:221], v[12:15]
	v_mfma_f32_16x16x32_bf16 v[4:7], v[154:157], v[214:217], v[4:7]
	v_mfma_f32_16x16x32_bf16 v[4:7], v[158:161], v[218:221], v[4:7]
	v_mfma_f32_16x16x32_bf16 v[56:59], v[162:165], v[190:193], v[56:59]
	v_mfma_f32_16x16x32_bf16 v[56:59], v[178:181], v[194:197], v[56:59]
	v_mfma_f32_16x16x32_bf16 v[48:51], v[182:185], v[190:193], v[48:51]
	v_mfma_f32_16x16x32_bf16 v[48:51], v[186:189], v[194:197], v[48:51]
	v_mfma_f32_16x16x32_bf16 v[40:43], v[162:165], v[198:201], v[40:43]
	v_mfma_f32_16x16x32_bf16 v[40:43], v[178:181], v[202:205], v[40:43]
	v_mfma_f32_16x16x32_bf16 v[32:35], v[182:185], v[198:201], v[32:35]
	v_mfma_f32_16x16x32_bf16 v[32:35], v[186:189], v[202:205], v[32:35]
	v_mfma_f32_16x16x32_bf16 v[24:27], v[162:165], v[206:209], v[24:27]
	v_mfma_f32_16x16x32_bf16 v[24:27], v[178:181], v[210:213], v[24:27]
	v_mfma_f32_16x16x32_bf16 v[16:19], v[182:185], v[206:209], v[16:19]
	v_mfma_f32_16x16x32_bf16 v[16:19], v[186:189], v[210:213], v[16:19]
	v_mfma_f32_16x16x32_bf16 v[8:11], v[162:165], v[214:217], v[8:11]
	v_mfma_f32_16x16x32_bf16 v[8:11], v[178:181], v[218:221], v[8:11]
	s_setprio 3
	s_barrier
	v_mfma_f32_16x16x32_bf16 v[0:3], v[182:185], v[214:217], v[0:3]
	v_mfma_f32_16x16x32_bf16 v[0:3], v[186:189], v[218:221], v[0:3]
	s_setprio 0
	s_add_i32 s67, 0, 0x18000
	s_add_i32 s73, 0, 0x1c000
	v_add_u32_e32 v158, s67, v171
	v_add_u32_e32 v186, s73, v171
	ds_read_b128 v[146:149], v158
	ds_read_b128 v[150:153], v158 offset:1024
	ds_read_b128 v[154:157], v158 offset:2048
	ds_read_b128 v[158:161], v158 offset:3072
	ds_read_b128 v[162:165], v186
	ds_read_b128 v[178:181], v186 offset:1024
	ds_read_b128 v[182:185], v186 offset:2048
	ds_read_b128 v[186:189], v186 offset:3072
	s_add_u32 s68, s82, 0x40000
	s_addc_u32 s69, s83, 0
	s_mov_b32 m0, s19
	v_lshl_add_u64 v[228:229], s[68:69], 0, v[134:135]
	ds_read_b128 v[190:193], v176 offset:32768
	ds_read_b128 v[194:197], v176 offset:33792
	ds_read_b128 v[198:201], v176 offset:34816
	ds_read_b128 v[202:205], v176 offset:35840
	ds_read_b128 v[206:209], v176 offset:36864
	ds_read_b128 v[210:213], v176 offset:37888
	ds_read_b128 v[214:217], v176 offset:38912
	ds_read_b128 v[218:221], v176 offset:39936
	global_load_lds_dwordx4 v[228:229], off
	s_mov_b32 m0, s20
	v_lshl_add_u64 v[228:229], s[68:69], 0, v[130:131]
	global_load_lds_dwordx4 v[228:229], off
	s_waitcnt vmcnt(8) lgkmcnt(0)
	s_barrier
	s_setprio 1
	v_mfma_f32_16x16x32_bf16 v[124:127], v[146:149], v[190:193], v[124:127]
	v_mfma_f32_16x16x32_bf16 v[124:127], v[150:153], v[194:197], v[124:127]
	v_mfma_f32_16x16x32_bf16 v[116:119], v[154:157], v[190:193], v[116:119]
	v_mfma_f32_16x16x32_bf16 v[116:119], v[158:161], v[194:197], v[116:119]
	v_mfma_f32_16x16x32_bf16 v[108:111], v[146:149], v[198:201], v[108:111]
	v_mfma_f32_16x16x32_bf16 v[108:111], v[150:153], v[202:205], v[108:111]
	v_mfma_f32_16x16x32_bf16 v[100:103], v[154:157], v[198:201], v[100:103]
	v_mfma_f32_16x16x32_bf16 v[100:103], v[158:161], v[202:205], v[100:103]
	v_mfma_f32_16x16x32_bf16 v[92:95], v[146:149], v[206:209], v[92:95]
	v_mfma_f32_16x16x32_bf16 v[92:95], v[150:153], v[210:213], v[92:95]
	v_mfma_f32_16x16x32_bf16 v[84:87], v[154:157], v[206:209], v[84:87]
	v_mfma_f32_16x16x32_bf16 v[84:87], v[158:161], v[210:213], v[84:87]
	v_mfma_f32_16x16x32_bf16 v[76:79], v[146:149], v[214:217], v[76:79]
	v_mfma_f32_16x16x32_bf16 v[76:79], v[150:153], v[218:221], v[76:79]
	v_mfma_f32_16x16x32_bf16 v[68:71], v[154:157], v[214:217], v[68:71]
	v_mfma_f32_16x16x32_bf16 v[68:71], v[158:161], v[218:221], v[68:71]
	v_mfma_f32_16x16x32_bf16 v[120:123], v[162:165], v[190:193], v[120:123]
	v_mfma_f32_16x16x32_bf16 v[120:123], v[178:181], v[194:197], v[120:123]
	v_mfma_f32_16x16x32_bf16 v[112:115], v[182:185], v[190:193], v[112:115]
	v_mfma_f32_16x16x32_bf16 v[112:115], v[186:189], v[194:197], v[112:115]
	v_mfma_f32_16x16x32_bf16 v[104:107], v[162:165], v[198:201], v[104:107]
	v_mfma_f32_16x16x32_bf16 v[104:107], v[178:181], v[202:205], v[104:107]
	v_mfma_f32_16x16x32_bf16 v[96:99], v[182:185], v[198:201], v[96:99]
	v_mfma_f32_16x16x32_bf16 v[96:99], v[186:189], v[202:205], v[96:99]
	v_mfma_f32_16x16x32_bf16 v[88:91], v[162:165], v[206:209], v[88:91]
	v_mfma_f32_16x16x32_bf16 v[88:91], v[178:181], v[210:213], v[88:91]
	v_mfma_f32_16x16x32_bf16 v[80:83], v[182:185], v[206:209], v[80:83]
	v_mfma_f32_16x16x32_bf16 v[80:83], v[186:189], v[210:213], v[80:83]
	v_mfma_f32_16x16x32_bf16 v[72:75], v[162:165], v[214:217], v[72:75]
	v_mfma_f32_16x16x32_bf16 v[72:75], v[178:181], v[218:221], v[72:75]
	s_setprio 3
	s_barrier
	v_mfma_f32_16x16x32_bf16 v[64:67], v[182:185], v[214:217], v[64:67]
	v_mfma_f32_16x16x32_bf16 v[64:67], v[186:189], v[218:221], v[64:67]
	s_setprio 0
	s_add_i32 s67, s67, s16
	v_lshl_add_u64 v[166:167], v[166:167], 0, s[10:11]
	s_mov_b32 m0, s67
	ds_read_b128 v[190:193], v176 offset:49152
	ds_read_b128 v[194:197], v176 offset:50176
	ds_read_b128 v[198:201], v176 offset:51200
	ds_read_b128 v[202:205], v176 offset:52224
	ds_read_b128 v[206:209], v176 offset:53248
	ds_read_b128 v[210:213], v176 offset:54272
	ds_read_b128 v[214:217], v176 offset:55296
	ds_read_b128 v[218:221], v176 offset:56320
	global_load_lds_dwordx4 v[166:167], off
	s_add_i32 m0, s67, 0x2000
	s_add_u32 s68, s80, 0x40080
	v_lshl_add_u64 v[166:167], v[222:223], 0, s[10:11]
	s_addc_u32 s69, s81, 0
	s_add_i32 s67, s73, s16
	global_load_lds_dwordx4 v[166:167], off
	s_mov_b32 m0, s67
	v_lshl_add_u64 v[166:167], s[68:69], 0, v[132:133]
	global_load_lds_dwordx4 v[166:167], off
	s_add_i32 m0, s67, 0x2000
	v_lshl_add_u64 v[166:167], s[68:69], 0, v[128:129]
	global_load_lds_dwordx4 v[166:167], off
	s_mov_b32 m0, s23
	v_lshl_add_u64 v[166:167], v[224:225], 0, s[10:11]
	global_load_lds_dwordx4 v[166:167], off
	s_mov_b32 m0, s24
	v_lshl_add_u64 v[166:167], v[226:227], 0, s[10:11]
	global_load_lds_dwordx4 v[166:167], off
	s_waitcnt vmcnt(8) lgkmcnt(0)
	s_barrier
	s_setprio 1
	v_mfma_f32_16x16x32_bf16 v[60:63], v[146:149], v[190:193], v[60:63]
	v_mfma_f32_16x16x32_bf16 v[60:63], v[150:153], v[194:197], v[60:63]
	v_mfma_f32_16x16x32_bf16 v[52:55], v[154:157], v[190:193], v[52:55]
	v_mfma_f32_16x16x32_bf16 v[52:55], v[158:161], v[194:197], v[52:55]
	v_mfma_f32_16x16x32_bf16 v[44:47], v[146:149], v[198:201], v[44:47]
	v_mfma_f32_16x16x32_bf16 v[44:47], v[150:153], v[202:205], v[44:47]
	v_mfma_f32_16x16x32_bf16 v[36:39], v[154:157], v[198:201], v[36:39]
	v_mfma_f32_16x16x32_bf16 v[36:39], v[158:161], v[202:205], v[36:39]
	v_mfma_f32_16x16x32_bf16 v[28:31], v[146:149], v[206:209], v[28:31]
	v_mfma_f32_16x16x32_bf16 v[28:31], v[150:153], v[210:213], v[28:31]
	v_mfma_f32_16x16x32_bf16 v[20:23], v[154:157], v[206:209], v[20:23]
	v_mfma_f32_16x16x32_bf16 v[20:23], v[158:161], v[210:213], v[20:23]
	v_mfma_f32_16x16x32_bf16 v[12:15], v[146:149], v[214:217], v[12:15]
	v_mfma_f32_16x16x32_bf16 v[12:15], v[150:153], v[218:221], v[12:15]
	v_mfma_f32_16x16x32_bf16 v[4:7], v[154:157], v[214:217], v[4:7]
	v_mfma_f32_16x16x32_bf16 v[4:7], v[158:161], v[218:221], v[4:7]
	v_mfma_f32_16x16x32_bf16 v[56:59], v[162:165], v[190:193], v[56:59]
	v_mfma_f32_16x16x32_bf16 v[56:59], v[178:181], v[194:197], v[56:59]
	v_mfma_f32_16x16x32_bf16 v[48:51], v[182:185], v[190:193], v[48:51]
	v_mfma_f32_16x16x32_bf16 v[48:51], v[186:189], v[194:197], v[48:51]
	v_mfma_f32_16x16x32_bf16 v[40:43], v[162:165], v[198:201], v[40:43]
	v_mfma_f32_16x16x32_bf16 v[40:43], v[178:181], v[202:205], v[40:43]
	v_mfma_f32_16x16x32_bf16 v[32:35], v[182:185], v[198:201], v[32:35]
	v_mfma_f32_16x16x32_bf16 v[32:35], v[186:189], v[202:205], v[32:35]
	v_mfma_f32_16x16x32_bf16 v[24:27], v[162:165], v[206:209], v[24:27]
	v_mfma_f32_16x16x32_bf16 v[24:27], v[178:181], v[210:213], v[24:27]
	v_mfma_f32_16x16x32_bf16 v[16:19], v[182:185], v[206:209], v[16:19]
	v_mfma_f32_16x16x32_bf16 v[16:19], v[186:189], v[210:213], v[16:19]
	v_mfma_f32_16x16x32_bf16 v[8:11], v[162:165], v[214:217], v[8:11]
	v_mfma_f32_16x16x32_bf16 v[8:11], v[178:181], v[218:221], v[8:11]
	s_setprio 3
	s_barrier
	v_mfma_f32_16x16x32_bf16 v[0:3], v[182:185], v[214:217], v[0:3]
	v_mfma_f32_16x16x32_bf16 v[0:3], v[186:189], v[218:221], v[0:3]
	s_setprio 0
	s_add_i32 s66, s66, 2
	s_add_u32 s78, s78, 0x100
	s_addc_u32 s79, s79, 0
	s_add_u32 s58, s58, 0x100
	s_addc_u32 s59, s59, 0
	s_cmp_gt_u32 s66, 13
	s_cbranch_scc0 .LBB0_1148
	s_and_b64 vcc, exec, s[44:45]
	s_cbranch_vccz .LBB0_1151
	s_barrier

.LBB0_1298:
	s_add_u32 s76, s76, 0xb0080
	s_addc_u32 s77, s77, 0
	s_add_u32 s55, s78, 0x100
	v_mov_b32_e32 v0, 0
	s_addc_u32 s58, s79, 0
	s_mov_b32 s59, -2
	ds_read_b128 v[120:123], v245
	ds_read_b128 v[124:127], v245 offset:1024
	ds_read_b128 v[128:131], v245 offset:2048
	ds_read_b128 v[132:135], v245 offset:3072
	ds_read_b128 v[144:147], v246
	ds_read_b128 v[148:151], v246 offset:1024
	ds_read_b128 v[152:155], v246 offset:2048
	ds_read_b128 v[156:159], v246 offset:3072
	s_add_u32 s66, s76, 0xfff50080
	s_addc_u32 s67, s77, -1
	s_cmp_eq_u32 s59, 40
	s_cselect_b32 s81, s9, s67
	s_cselect_b32 s80, s8, s66
	s_cselect_b32 s79, s53, s58
	s_cselect_b32 s78, s52, s55
	v_lshl_add_u64 v[204:205], s[76:77], 0, v[200:201]
	s_add_i32 m0, s16, 0xc000
	ds_read_b128 v[160:163], v247
	ds_read_b128 v[164:167], v247 offset:1024
	ds_read_b128 v[168:171], v247 offset:2048
	ds_read_b128 v[172:175], v247 offset:3072
	ds_read_b128 v[176:179], v247 offset:4096
	ds_read_b128 v[180:183], v247 offset:5120
	ds_read_b128 v[184:187], v247 offset:6144
	ds_read_b128 v[188:191], v247 offset:7168
	global_load_lds_dwordx4 v[204:205], off
	s_add_i32 m0, s16, 0xe000
	v_lshl_add_u64 v[204:205], s[76:77], 0, v[202:203]
	global_load_lds_dwordx4 v[204:205], off
	s_waitcnt vmcnt(8) lgkmcnt(0)
	s_barrier
	s_setprio 1
	v_mfma_f32_16x16x32_bf16 v[140:143], v[120:123], v[160:163], 0
	v_mfma_f32_16x16x32_bf16 v[140:143], v[124:127], v[164:167], v[140:143]
	v_mfma_f32_16x16x32_bf16 v[136:139], v[128:131], v[160:163], 0
	v_mfma_f32_16x16x32_bf16 v[136:139], v[132:135], v[164:167], v[136:139]
	v_mfma_f32_16x16x32_bf16 v[108:111], v[120:123], v[168:171], 0
	v_mfma_f32_16x16x32_bf16 v[108:111], v[124:127], v[172:175], v[108:111]
	v_mfma_f32_16x16x32_bf16 v[104:107], v[128:131], v[168:171], 0
	v_mfma_f32_16x16x32_bf16 v[104:107], v[132:135], v[172:175], v[104:107]
	v_mfma_f32_16x16x32_bf16 v[92:95], v[120:123], v[176:179], 0
	v_mfma_f32_16x16x32_bf16 v[92:95], v[124:127], v[180:183], v[92:95]
	v_mfma_f32_16x16x32_bf16 v[88:91], v[128:131], v[176:179], 0
	v_mfma_f32_16x16x32_bf16 v[88:91], v[132:135], v[180:183], v[88:91]
	v_mfma_f32_16x16x32_bf16 v[76:79], v[120:123], v[184:187], 0
	v_mfma_f32_16x16x32_bf16 v[76:79], v[124:127], v[188:191], v[76:79]
	v_mfma_f32_16x16x32_bf16 v[72:75], v[128:131], v[184:187], 0
	v_mfma_f32_16x16x32_bf16 v[72:75], v[132:135], v[188:191], v[72:75]
	v_mfma_f32_16x16x32_bf16 v[116:119], v[144:147], v[160:163], 0
	v_mfma_f32_16x16x32_bf16 v[116:119], v[148:151], v[164:167], v[116:119]
	v_mfma_f32_16x16x32_bf16 v[112:115], v[152:155], v[160:163], 0
	v_mfma_f32_16x16x32_bf16 v[112:115], v[156:159], v[164:167], v[112:115]
	v_mfma_f32_16x16x32_bf16 v[100:103], v[144:147], v[168:171], 0
	v_mfma_f32_16x16x32_bf16 v[100:103], v[148:151], v[172:175], v[100:103]
	v_mfma_f32_16x16x32_bf16 v[96:99], v[152:155], v[168:171], 0
	v_mfma_f32_16x16x32_bf16 v[96:99], v[156:159], v[172:175], v[96:99]
	v_mfma_f32_16x16x32_bf16 v[84:87], v[144:147], v[176:179], 0
	v_mfma_f32_16x16x32_bf16 v[84:87], v[148:151], v[180:183], v[84:87]
	v_mfma_f32_16x16x32_bf16 v[80:83], v[152:155], v[176:179], 0
	v_mfma_f32_16x16x32_bf16 v[80:83], v[156:159], v[180:183], v[80:83]
	v_mfma_f32_16x16x32_bf16 v[68:71], v[144:147], v[184:187], 0
	v_mfma_f32_16x16x32_bf16 v[68:71], v[148:151], v[188:191], v[68:71]
	s_setprio 3
	s_barrier
	v_mfma_f32_16x16x32_bf16 v[64:67], v[152:155], v[184:187], 0
	v_mfma_f32_16x16x32_bf16 v[64:67], v[156:159], v[188:191], v[64:67]
	s_setprio 0
	s_add_i32 s66, s26, s15
	v_lshl_add_u64 v[204:205], s[78:79], 0, v[194:195]
	s_mov_b32 m0, s66
	ds_read_b128 v[160:163], v247 offset:16384
	ds_read_b128 v[164:167], v247 offset:17408
	ds_read_b128 v[168:171], v247 offset:18432
	ds_read_b128 v[172:175], v247 offset:19456
	ds_read_b128 v[176:179], v247 offset:20480
	ds_read_b128 v[180:183], v247 offset:21504
	ds_read_b128 v[184:187], v247 offset:22528
	ds_read_b128 v[188:191], v247 offset:23552
	global_load_lds_dwordx4 v[204:205], off
	s_add_i32 m0, s66, 0x2000
	s_add_u32 s66, s78, 0xb0000
	v_lshl_add_u64 v[206:207], s[78:79], 0, v[198:199]
	s_addc_u32 s67, s79, 0
	s_add_i32 s68, s27, s15
	global_load_lds_dwordx4 v[206:207], off
	v_lshl_add_u64 v[208:209], s[66:67], 0, v[194:195]
	s_mov_b32 m0, s68
	global_load_lds_dwordx4 v[208:209], off
	s_add_i32 m0, s68, 0x2000
	v_lshl_add_u64 v[208:209], s[66:67], 0, v[198:199]
	global_load_lds_dwordx4 v[208:209], off
	s_mov_b32 m0, s16
	v_lshl_add_u64 v[208:209], s[80:81], 0, v[192:193]
	global_load_lds_dwordx4 v[208:209], off
	s_mov_b32 m0, s17
	v_lshl_add_u64 v[210:211], s[80:81], 0, v[196:197]
	global_load_lds_dwordx4 v[210:211], off
	s_waitcnt vmcnt(8) lgkmcnt(0)
	s_barrier
	s_setprio 1
	v_mfma_f32_16x16x32_bf16 v[60:63], v[120:123], v[160:163], 0
	v_mfma_f32_16x16x32_bf16 v[60:63], v[124:127], v[164:167], v[60:63]
	v_mfma_f32_16x16x32_bf16 v[56:59], v[128:131], v[160:163], 0
	v_mfma_f32_16x16x32_bf16 v[56:59], v[132:135], v[164:167], v[56:59]
	v_mfma_f32_16x16x32_bf16 v[44:47], v[120:123], v[168:171], 0
	v_mfma_f32_16x16x32_bf16 v[44:47], v[124:127], v[172:175], v[44:47]
	v_mfma_f32_16x16x32_bf16 v[40:43], v[128:131], v[168:171], 0
	v_mfma_f32_16x16x32_bf16 v[40:43], v[132:135], v[172:175], v[40:43]
	v_mfma_f32_16x16x32_bf16 v[28:31], v[120:123], v[176:179], 0
	v_mfma_f32_16x16x32_bf16 v[28:31], v[124:127], v[180:183], v[28:31]
	v_mfma_f32_16x16x32_bf16 v[24:27], v[128:131], v[176:179], 0
	v_mfma_f32_16x16x32_bf16 v[24:27], v[132:135], v[180:183], v[24:27]
	v_mfma_f32_16x16x32_bf16 v[12:15], v[120:123], v[184:187], 0
	v_mfma_f32_16x16x32_bf16 v[12:15], v[124:127], v[188:191], v[12:15]
	v_mfma_f32_16x16x32_bf16 v[8:11], v[128:131], v[184:187], 0
	v_mfma_f32_16x16x32_bf16 v[8:11], v[132:135], v[188:191], v[8:11]
	v_mfma_f32_16x16x32_bf16 v[52:55], v[144:147], v[160:163], 0
	v_mfma_f32_16x16x32_bf16 v[52:55], v[148:151], v[164:167], v[52:55]
	v_mfma_f32_16x16x32_bf16 v[48:51], v[152:155], v[160:163], 0
	v_mfma_f32_16x16x32_bf16 v[48:51], v[156:159], v[164:167], v[48:51]
	v_mfma_f32_16x16x32_bf16 v[36:39], v[144:147], v[168:171], 0
	v_mfma_f32_16x16x32_bf16 v[36:39], v[148:151], v[172:175], v[36:39]
	v_mfma_f32_16x16x32_bf16 v[32:35], v[152:155], v[168:171], 0
	v_mfma_f32_16x16x32_bf16 v[32:35], v[156:159], v[172:175], v[32:35]
	v_mfma_f32_16x16x32_bf16 v[20:23], v[144:147], v[176:179], 0
	v_mfma_f32_16x16x32_bf16 v[20:23], v[148:151], v[180:183], v[20:23]
	v_mfma_f32_16x16x32_bf16 v[16:19], v[152:155], v[176:179], 0
	v_mfma_f32_16x16x32_bf16 v[16:19], v[156:159], v[180:183], v[16:19]
	v_mfma_f32_16x16x32_bf16 v[4:7], v[144:147], v[184:187], 0
	v_mfma_f32_16x16x32_bf16 v[4:7], v[148:151], v[188:191], v[4:7]
	s_setprio 3
	s_barrier
	v_mfma_f32_16x16x32_bf16 v[0:3], v[152:155], v[184:187], 0
	v_mfma_f32_16x16x32_bf16 v[0:3], v[156:159], v[188:191], v[0:3]
	s_setprio 0
	s_add_i32 s68, 0, 0x18000
	s_add_i32 s69, 0, 0x1c000
	v_add_u32_e32 v132, s68, v243
	v_add_u32_e32 v156, s69, v243
	ds_read_b128 v[120:123], v132
	ds_read_b128 v[124:127], v132 offset:1024
	ds_read_b128 v[128:131], v132 offset:2048
	ds_read_b128 v[132:135], v132 offset:3072
	ds_read_b128 v[144:147], v156
	ds_read_b128 v[148:151], v156 offset:1024
	ds_read_b128 v[152:155], v156 offset:2048
	ds_read_b128 v[156:159], v156 offset:3072
	s_add_u32 s66, s80, 0xb0000
	s_addc_u32 s67, s81, 0
	s_mov_b32 m0, s18
	v_lshl_add_u64 v[212:213], s[66:67], 0, v[192:193]
	ds_read_b128 v[160:163], v247 offset:32768
	ds_read_b128 v[164:167], v247 offset:33792
	ds_read_b128 v[168:171], v247 offset:34816
	ds_read_b128 v[172:175], v247 offset:35840
	ds_read_b128 v[176:179], v247 offset:36864
	ds_read_b128 v[180:183], v247 offset:37888
	ds_read_b128 v[184:187], v247 offset:38912
	ds_read_b128 v[188:191], v247 offset:39936
	global_load_lds_dwordx4 v[212:213], off
	s_mov_b32 m0, s19
	v_lshl_add_u64 v[212:213], s[66:67], 0, v[196:197]
	global_load_lds_dwordx4 v[212:213], off
	s_waitcnt vmcnt(8) lgkmcnt(0)
	s_barrier
	s_setprio 1
	v_mfma_f32_16x16x32_bf16 v[140:143], v[120:123], v[160:163], v[140:143]
	v_mfma_f32_16x16x32_bf16 v[140:143], v[124:127], v[164:167], v[140:143]
	v_mfma_f32_16x16x32_bf16 v[136:139], v[128:131], v[160:163], v[136:139]
	v_mfma_f32_16x16x32_bf16 v[136:139], v[132:135], v[164:167], v[136:139]
	v_mfma_f32_16x16x32_bf16 v[108:111], v[120:123], v[168:171], v[108:111]
	v_mfma_f32_16x16x32_bf16 v[108:111], v[124:127], v[172:175], v[108:111]
	v_mfma_f32_16x16x32_bf16 v[104:107], v[128:131], v[168:171], v[104:107]
	v_mfma_f32_16x16x32_bf16 v[104:107], v[132:135], v[172:175], v[104:107]
	v_mfma_f32_16x16x32_bf16 v[92:95], v[120:123], v[176:179], v[92:95]
	v_mfma_f32_16x16x32_bf16 v[92:95], v[124:127], v[180:183], v[92:95]
	v_mfma_f32_16x16x32_bf16 v[88:91], v[128:131], v[176:179], v[88:91]
	v_mfma_f32_16x16x32_bf16 v[88:91], v[132:135], v[180:183], v[88:91]
	v_mfma_f32_16x16x32_bf16 v[76:79], v[120:123], v[184:187], v[76:79]
	v_mfma_f32_16x16x32_bf16 v[76:79], v[124:127], v[188:191], v[76:79]
	v_mfma_f32_16x16x32_bf16 v[72:75], v[128:131], v[184:187], v[72:75]
	v_mfma_f32_16x16x32_bf16 v[72:75], v[132:135], v[188:191], v[72:75]
	v_mfma_f32_16x16x32_bf16 v[116:119], v[144:147], v[160:163], v[116:119]
	v_mfma_f32_16x16x32_bf16 v[116:119], v[148:151], v[164:167], v[116:119]
	v_mfma_f32_16x16x32_bf16 v[112:115], v[152:155], v[160:163], v[112:115]
	v_mfma_f32_16x16x32_bf16 v[112:115], v[156:159], v[164:167], v[112:115]
	v_mfma_f32_16x16x32_bf16 v[100:103], v[144:147], v[168:171], v[100:103]
	v_mfma_f32_16x16x32_bf16 v[100:103], v[148:151], v[172:175], v[100:103]
	v_mfma_f32_16x16x32_bf16 v[96:99], v[152:155], v[168:171], v[96:99]
	v_mfma_f32_16x16x32_bf16 v[96:99], v[156:159], v[172:175], v[96:99]
	v_mfma_f32_16x16x32_bf16 v[84:87], v[144:147], v[176:179], v[84:87]
	v_mfma_f32_16x16x32_bf16 v[84:87], v[148:151], v[180:183], v[84:87]
	v_mfma_f32_16x16x32_bf16 v[80:83], v[152:155], v[176:179], v[80:83]
	v_mfma_f32_16x16x32_bf16 v[80:83], v[156:159], v[180:183], v[80:83]
	v_mfma_f32_16x16x32_bf16 v[68:71], v[144:147], v[184:187], v[68:71]
	v_mfma_f32_16x16x32_bf16 v[68:71], v[148:151], v[188:191], v[68:71]
	s_setprio 3
	s_barrier
	v_mfma_f32_16x16x32_bf16 v[64:67], v[152:155], v[184:187], v[64:67]
	v_mfma_f32_16x16x32_bf16 v[64:67], v[156:159], v[188:191], v[64:67]
	s_setprio 0
	s_add_i32 s66, s68, s15
	v_lshl_add_u64 v[204:205], v[204:205], 0, s[48:49]
	s_mov_b32 m0, s66
	ds_read_b128 v[160:163], v247 offset:49152
	ds_read_b128 v[164:167], v247 offset:50176
	ds_read_b128 v[168:171], v247 offset:51200
	ds_read_b128 v[172:175], v247 offset:52224
	ds_read_b128 v[176:179], v247 offset:53248
	ds_read_b128 v[180:183], v247 offset:54272
	ds_read_b128 v[184:187], v247 offset:55296
	ds_read_b128 v[188:191], v247 offset:56320
	global_load_lds_dwordx4 v[204:205], off
	s_add_i32 m0, s66, 0x2000
	s_add_u32 s66, s78, 0xb0080
	v_lshl_add_u64 v[204:205], v[206:207], 0, s[48:49]
	s_addc_u32 s67, s79, 0
	s_add_i32 s68, s69, s15
	global_load_lds_dwordx4 v[204:205], off
	s_mov_b32 m0, s68
	v_lshl_add_u64 v[204:205], s[66:67], 0, v[194:195]
	global_load_lds_dwordx4 v[204:205], off
	s_add_i32 m0, s68, 0x2000
	v_lshl_add_u64 v[204:205], s[66:67], 0, v[198:199]
	global_load_lds_dwordx4 v[204:205], off
	s_mov_b32 m0, s21
	v_lshl_add_u64 v[204:205], v[208:209], 0, s[48:49]
	global_load_lds_dwordx4 v[204:205], off
	s_mov_b32 m0, s22
	v_lshl_add_u64 v[204:205], v[210:211], 0, s[48:49]
	global_load_lds_dwordx4 v[204:205], off
	s_waitcnt vmcnt(8) lgkmcnt(0)
	s_barrier
	s_setprio 1
	v_mfma_f32_16x16x32_bf16 v[60:63], v[120:123], v[160:163], v[60:63]
	v_mfma_f32_16x16x32_bf16 v[60:63], v[124:127], v[164:167], v[60:63]
	v_mfma_f32_16x16x32_bf16 v[56:59], v[128:131], v[160:163], v[56:59]
	v_mfma_f32_16x16x32_bf16 v[56:59], v[132:135], v[164:167], v[56:59]
	v_mfma_f32_16x16x32_bf16 v[44:47], v[120:123], v[168:171], v[44:47]
	v_mfma_f32_16x16x32_bf16 v[44:47], v[124:127], v[172:175], v[44:47]
	v_mfma_f32_16x16x32_bf16 v[40:43], v[128:131], v[168:171], v[40:43]
	v_mfma_f32_16x16x32_bf16 v[40:43], v[132:135], v[172:175], v[40:43]
	v_mfma_f32_16x16x32_bf16 v[28:31], v[120:123], v[176:179], v[28:31]
	v_mfma_f32_16x16x32_bf16 v[28:31], v[124:127], v[180:183], v[28:31]
	v_mfma_f32_16x16x32_bf16 v[24:27], v[128:131], v[176:179], v[24:27]
	v_mfma_f32_16x16x32_bf16 v[24:27], v[132:135], v[180:183], v[24:27]
	v_mfma_f32_16x16x32_bf16 v[12:15], v[120:123], v[184:187], v[12:15]
	v_mfma_f32_16x16x32_bf16 v[12:15], v[124:127], v[188:191], v[12:15]
	v_mfma_f32_16x16x32_bf16 v[8:11], v[128:131], v[184:187], v[8:11]
	v_mfma_f32_16x16x32_bf16 v[8:11], v[132:135], v[188:191], v[8:11]
	v_mfma_f32_16x16x32_bf16 v[52:55], v[144:147], v[160:163], v[52:55]
	v_mfma_f32_16x16x32_bf16 v[52:55], v[148:151], v[164:167], v[52:55]
	v_mfma_f32_16x16x32_bf16 v[48:51], v[152:155], v[160:163], v[48:51]
	v_mfma_f32_16x16x32_bf16 v[48:51], v[156:159], v[164:167], v[48:51]
	v_mfma_f32_16x16x32_bf16 v[36:39], v[144:147], v[168:171], v[36:39]
	v_mfma_f32_16x16x32_bf16 v[36:39], v[148:151], v[172:175], v[36:39]
	v_mfma_f32_16x16x32_bf16 v[32:35], v[152:155], v[168:171], v[32:35]
	v_mfma_f32_16x16x32_bf16 v[32:35], v[156:159], v[172:175], v[32:35]
	v_mfma_f32_16x16x32_bf16 v[20:23], v[144:147], v[176:179], v[20:23]
	v_mfma_f32_16x16x32_bf16 v[20:23], v[148:151], v[180:183], v[20:23]
	v_mfma_f32_16x16x32_bf16 v[16:19], v[152:155], v[176:179], v[16:19]
	v_mfma_f32_16x16x32_bf16 v[16:19], v[156:159], v[180:183], v[16:19]
	v_mfma_f32_16x16x32_bf16 v[4:7], v[144:147], v[184:187], v[4:7]
	v_mfma_f32_16x16x32_bf16 v[4:7], v[148:151], v[188:191], v[4:7]
	s_setprio 3
	s_barrier
	v_mfma_f32_16x16x32_bf16 v[0:3], v[152:155], v[184:187], v[0:3]
	v_mfma_f32_16x16x32_bf16 v[0:3], v[156:159], v[188:191], v[0:3]
	s_setprio 0
	s_add_i32 s59, s59, 2
	s_add_u32 s76, s76, 0x100
	s_addc_u32 s77, s77, 0
	s_add_u32 s55, s55, 0x100
	s_addc_u32 s58, s58, 0
	s_cmp_gt_u32 s59, 41
.LBB0_1299:
	ds_read_b128 v[120:123], v245
	ds_read_b128 v[124:127], v245 offset:1024
	ds_read_b128 v[128:131], v245 offset:2048
	ds_read_b128 v[132:135], v245 offset:3072
	ds_read_b128 v[144:147], v246
	ds_read_b128 v[148:151], v246 offset:1024
	ds_read_b128 v[152:155], v246 offset:2048
	ds_read_b128 v[156:159], v246 offset:3072
	s_add_u32 s66, s76, 0xfff50080
	s_addc_u32 s67, s77, -1
	s_cmp_eq_u32 s59, 40
	s_cselect_b32 s81, s9, s67
	s_cselect_b32 s80, s8, s66
	s_cselect_b32 s79, s53, s58
	s_cselect_b32 s78, s52, s55
	v_lshl_add_u64 v[204:205], s[76:77], 0, v[200:201]
	s_add_i32 m0, s16, 0xc000
	ds_read_b128 v[160:163], v247
	ds_read_b128 v[164:167], v247 offset:1024
	ds_read_b128 v[168:171], v247 offset:2048
	ds_read_b128 v[172:175], v247 offset:3072
	ds_read_b128 v[176:179], v247 offset:4096
	ds_read_b128 v[180:183], v247 offset:5120
	ds_read_b128 v[184:187], v247 offset:6144
	ds_read_b128 v[188:191], v247 offset:7168
	global_load_lds_dwordx4 v[204:205], off
	s_add_i32 m0, s16, 0xe000
	v_lshl_add_u64 v[204:205], s[76:77], 0, v[202:203]
	global_load_lds_dwordx4 v[204:205], off
	s_waitcnt vmcnt(8) lgkmcnt(0)
	s_barrier
	s_setprio 1
	v_mfma_f32_16x16x32_bf16 v[140:143], v[120:123], v[160:163], v[140:143]
	v_mfma_f32_16x16x32_bf16 v[140:143], v[124:127], v[164:167], v[140:143]
	v_mfma_f32_16x16x32_bf16 v[136:139], v[128:131], v[160:163], v[136:139]
	v_mfma_f32_16x16x32_bf16 v[136:139], v[132:135], v[164:167], v[136:139]
	v_mfma_f32_16x16x32_bf16 v[108:111], v[120:123], v[168:171], v[108:111]
	v_mfma_f32_16x16x32_bf16 v[108:111], v[124:127], v[172:175], v[108:111]
	v_mfma_f32_16x16x32_bf16 v[104:107], v[128:131], v[168:171], v[104:107]
	v_mfma_f32_16x16x32_bf16 v[104:107], v[132:135], v[172:175], v[104:107]
	v_mfma_f32_16x16x32_bf16 v[92:95], v[120:123], v[176:179], v[92:95]
	v_mfma_f32_16x16x32_bf16 v[92:95], v[124:127], v[180:183], v[92:95]
	v_mfma_f32_16x16x32_bf16 v[88:91], v[128:131], v[176:179], v[88:91]
	v_mfma_f32_16x16x32_bf16 v[88:91], v[132:135], v[180:183], v[88:91]
	v_mfma_f32_16x16x32_bf16 v[76:79], v[120:123], v[184:187], v[76:79]
	v_mfma_f32_16x16x32_bf16 v[76:79], v[124:127], v[188:191], v[76:79]
	v_mfma_f32_16x16x32_bf16 v[72:75], v[128:131], v[184:187], v[72:75]
	v_mfma_f32_16x16x32_bf16 v[72:75], v[132:135], v[188:191], v[72:75]
	v_mfma_f32_16x16x32_bf16 v[116:119], v[144:147], v[160:163], v[116:119]
	v_mfma_f32_16x16x32_bf16 v[116:119], v[148:151], v[164:167], v[116:119]
	v_mfma_f32_16x16x32_bf16 v[112:115], v[152:155], v[160:163], v[112:115]
	v_mfma_f32_16x16x32_bf16 v[112:115], v[156:159], v[164:167], v[112:115]
	v_mfma_f32_16x16x32_bf16 v[100:103], v[144:147], v[168:171], v[100:103]
	v_mfma_f32_16x16x32_bf16 v[100:103], v[148:151], v[172:175], v[100:103]
	v_mfma_f32_16x16x32_bf16 v[96:99], v[152:155], v[168:171], v[96:99]
	v_mfma_f32_16x16x32_bf16 v[96:99], v[156:159], v[172:175], v[96:99]
	v_mfma_f32_16x16x32_bf16 v[84:87], v[144:147], v[176:179], v[84:87]
	v_mfma_f32_16x16x32_bf16 v[84:87], v[148:151], v[180:183], v[84:87]
	v_mfma_f32_16x16x32_bf16 v[80:83], v[152:155], v[176:179], v[80:83]
	v_mfma_f32_16x16x32_bf16 v[80:83], v[156:159], v[180:183], v[80:83]
	v_mfma_f32_16x16x32_bf16 v[68:71], v[144:147], v[184:187], v[68:71]
	v_mfma_f32_16x16x32_bf16 v[68:71], v[148:151], v[188:191], v[68:71]
	s_setprio 3
	s_barrier
	v_mfma_f32_16x16x32_bf16 v[64:67], v[152:155], v[184:187], v[64:67]
	v_mfma_f32_16x16x32_bf16 v[64:67], v[156:159], v[188:191], v[64:67]
	s_setprio 0
	s_add_i32 s66, s26, s15
	v_lshl_add_u64 v[204:205], s[78:79], 0, v[194:195]
	s_mov_b32 m0, s66
	ds_read_b128 v[160:163], v247 offset:16384
	ds_read_b128 v[164:167], v247 offset:17408
	ds_read_b128 v[168:171], v247 offset:18432
	ds_read_b128 v[172:175], v247 offset:19456
	ds_read_b128 v[176:179], v247 offset:20480
	ds_read_b128 v[180:183], v247 offset:21504
	ds_read_b128 v[184:187], v247 offset:22528
	ds_read_b128 v[188:191], v247 offset:23552
	global_load_lds_dwordx4 v[204:205], off
	s_add_i32 m0, s66, 0x2000
	s_add_u32 s66, s78, 0xb0000
	v_lshl_add_u64 v[206:207], s[78:79], 0, v[198:199]
	s_addc_u32 s67, s79, 0
	s_add_i32 s68, s27, s15
	global_load_lds_dwordx4 v[206:207], off
	v_lshl_add_u64 v[208:209], s[66:67], 0, v[194:195]
	s_mov_b32 m0, s68
	global_load_lds_dwordx4 v[208:209], off
	s_add_i32 m0, s68, 0x2000
	v_lshl_add_u64 v[208:209], s[66:67], 0, v[198:199]
	global_load_lds_dwordx4 v[208:209], off
	s_mov_b32 m0, s16
	v_lshl_add_u64 v[208:209], s[80:81], 0, v[192:193]
	global_load_lds_dwordx4 v[208:209], off
	s_mov_b32 m0, s17
	v_lshl_add_u64 v[210:211], s[80:81], 0, v[196:197]
	global_load_lds_dwordx4 v[210:211], off
	s_waitcnt vmcnt(8) lgkmcnt(0)
	s_barrier
	s_setprio 1
	v_mfma_f32_16x16x32_bf16 v[60:63], v[120:123], v[160:163], v[60:63]
	v_mfma_f32_16x16x32_bf16 v[60:63], v[124:127], v[164:167], v[60:63]
	v_mfma_f32_16x16x32_bf16 v[56:59], v[128:131], v[160:163], v[56:59]
	v_mfma_f32_16x16x32_bf16 v[56:59], v[132:135], v[164:167], v[56:59]
	v_mfma_f32_16x16x32_bf16 v[44:47], v[120:123], v[168:171], v[44:47]
	v_mfma_f32_16x16x32_bf16 v[44:47], v[124:127], v[172:175], v[44:47]
	v_mfma_f32_16x16x32_bf16 v[40:43], v[128:131], v[168:171], v[40:43]
	v_mfma_f32_16x16x32_bf16 v[40:43], v[132:135], v[172:175], v[40:43]
	v_mfma_f32_16x16x32_bf16 v[28:31], v[120:123], v[176:179], v[28:31]
	v_mfma_f32_16x16x32_bf16 v[28:31], v[124:127], v[180:183], v[28:31]
	v_mfma_f32_16x16x32_bf16 v[24:27], v[128:131], v[176:179], v[24:27]
	v_mfma_f32_16x16x32_bf16 v[24:27], v[132:135], v[180:183], v[24:27]
	v_mfma_f32_16x16x32_bf16 v[12:15], v[120:123], v[184:187], v[12:15]
	v_mfma_f32_16x16x32_bf16 v[12:15], v[124:127], v[188:191], v[12:15]
	v_mfma_f32_16x16x32_bf16 v[8:11], v[128:131], v[184:187], v[8:11]
	v_mfma_f32_16x16x32_bf16 v[8:11], v[132:135], v[188:191], v[8:11]
	v_mfma_f32_16x16x32_bf16 v[52:55], v[144:147], v[160:163], v[52:55]
	v_mfma_f32_16x16x32_bf16 v[52:55], v[148:151], v[164:167], v[52:55]
	v_mfma_f32_16x16x32_bf16 v[48:51], v[152:155], v[160:163], v[48:51]
	v_mfma_f32_16x16x32_bf16 v[48:51], v[156:159], v[164:167], v[48:51]
	v_mfma_f32_16x16x32_bf16 v[36:39], v[144:147], v[168:171], v[36:39]
	v_mfma_f32_16x16x32_bf16 v[36:39], v[148:151], v[172:175], v[36:39]
	v_mfma_f32_16x16x32_bf16 v[32:35], v[152:155], v[168:171], v[32:35]
	v_mfma_f32_16x16x32_bf16 v[32:35], v[156:159], v[172:175], v[32:35]
	v_mfma_f32_16x16x32_bf16 v[20:23], v[144:147], v[176:179], v[20:23]
	v_mfma_f32_16x16x32_bf16 v[20:23], v[148:151], v[180:183], v[20:23]
	v_mfma_f32_16x16x32_bf16 v[16:19], v[152:155], v[176:179], v[16:19]
	v_mfma_f32_16x16x32_bf16 v[16:19], v[156:159], v[180:183], v[16:19]
	v_mfma_f32_16x16x32_bf16 v[4:7], v[144:147], v[184:187], v[4:7]
	v_mfma_f32_16x16x32_bf16 v[4:7], v[148:151], v[188:191], v[4:7]
	s_setprio 3
	s_barrier
	v_mfma_f32_16x16x32_bf16 v[0:3], v[152:155], v[184:187], v[0:3]
	v_mfma_f32_16x16x32_bf16 v[0:3], v[156:159], v[188:191], v[0:3]
	s_setprio 0
	s_add_i32 s68, 0, 0x18000
	s_add_i32 s69, 0, 0x1c000
	v_add_u32_e32 v132, s68, v243
	v_add_u32_e32 v156, s69, v243
	ds_read_b128 v[120:123], v132
	ds_read_b128 v[124:127], v132 offset:1024
	ds_read_b128 v[128:131], v132 offset:2048
	ds_read_b128 v[132:135], v132 offset:3072
	ds_read_b128 v[144:147], v156
	ds_read_b128 v[148:151], v156 offset:1024
	ds_read_b128 v[152:155], v156 offset:2048
	ds_read_b128 v[156:159], v156 offset:3072
	s_add_u32 s66, s80, 0xb0000
	s_addc_u32 s67, s81, 0
	s_mov_b32 m0, s18
	v_lshl_add_u64 v[212:213], s[66:67], 0, v[192:193]
	ds_read_b128 v[160:163], v247 offset:32768
	ds_read_b128 v[164:167], v247 offset:33792
	ds_read_b128 v[168:171], v247 offset:34816
	ds_read_b128 v[172:175], v247 offset:35840
	ds_read_b128 v[176:179], v247 offset:36864
	ds_read_b128 v[180:183], v247 offset:37888
	ds_read_b128 v[184:187], v247 offset:38912
	ds_read_b128 v[188:191], v247 offset:39936
	global_load_lds_dwordx4 v[212:213], off
	s_mov_b32 m0, s19
	v_lshl_add_u64 v[212:213], s[66:67], 0, v[196:197]
	global_load_lds_dwordx4 v[212:213], off
	s_waitcnt vmcnt(8) lgkmcnt(0)
	s_barrier
	s_setprio 1
	v_mfma_f32_16x16x32_bf16 v[140:143], v[120:123], v[160:163], v[140:143]
	v_mfma_f32_16x16x32_bf16 v[140:143], v[124:127], v[164:167], v[140:143]
	v_mfma_f32_16x16x32_bf16 v[136:139], v[128:131], v[160:163], v[136:139]
	v_mfma_f32_16x16x32_bf16 v[136:139], v[132:135], v[164:167], v[136:139]
	v_mfma_f32_16x16x32_bf16 v[108:111], v[120:123], v[168:171], v[108:111]
	v_mfma_f32_16x16x32_bf16 v[108:111], v[124:127], v[172:175], v[108:111]
	v_mfma_f32_16x16x32_bf16 v[104:107], v[128:131], v[168:171], v[104:107]
	v_mfma_f32_16x16x32_bf16 v[104:107], v[132:135], v[172:175], v[104:107]
	v_mfma_f32_16x16x32_bf16 v[92:95], v[120:123], v[176:179], v[92:95]
	v_mfma_f32_16x16x32_bf16 v[92:95], v[124:127], v[180:183], v[92:95]
	v_mfma_f32_16x16x32_bf16 v[88:91], v[128:131], v[176:179], v[88:91]
	v_mfma_f32_16x16x32_bf16 v[88:91], v[132:135], v[180:183], v[88:91]
	v_mfma_f32_16x16x32_bf16 v[76:79], v[120:123], v[184:187], v[76:79]
	v_mfma_f32_16x16x32_bf16 v[76:79], v[124:127], v[188:191], v[76:79]
	v_mfma_f32_16x16x32_bf16 v[72:75], v[128:131], v[184:187], v[72:75]
	v_mfma_f32_16x16x32_bf16 v[72:75], v[132:135], v[188:191], v[72:75]
	v_mfma_f32_16x16x32_bf16 v[116:119], v[144:147], v[160:163], v[116:119]
	v_mfma_f32_16x16x32_bf16 v[116:119], v[148:151], v[164:167], v[116:119]
	v_mfma_f32_16x16x32_bf16 v[112:115], v[152:155], v[160:163], v[112:115]
	v_mfma_f32_16x16x32_bf16 v[112:115], v[156:159], v[164:167], v[112:115]
	v_mfma_f32_16x16x32_bf16 v[100:103], v[144:147], v[168:171], v[100:103]
	v_mfma_f32_16x16x32_bf16 v[100:103], v[148:151], v[172:175], v[100:103]
	v_mfma_f32_16x16x32_bf16 v[96:99], v[152:155], v[168:171], v[96:99]
	v_mfma_f32_16x16x32_bf16 v[96:99], v[156:159], v[172:175], v[96:99]
	v_mfma_f32_16x16x32_bf16 v[84:87], v[144:147], v[176:179], v[84:87]
	v_mfma_f32_16x16x32_bf16 v[84:87], v[148:151], v[180:183], v[84:87]
	v_mfma_f32_16x16x32_bf16 v[80:83], v[152:155], v[176:179], v[80:83]
	v_mfma_f32_16x16x32_bf16 v[80:83], v[156:159], v[180:183], v[80:83]
	v_mfma_f32_16x16x32_bf16 v[68:71], v[144:147], v[184:187], v[68:71]
	v_mfma_f32_16x16x32_bf16 v[68:71], v[148:151], v[188:191], v[68:71]
	s_setprio 3
	s_barrier
	v_mfma_f32_16x16x32_bf16 v[64:67], v[152:155], v[184:187], v[64:67]
	v_mfma_f32_16x16x32_bf16 v[64:67], v[156:159], v[188:191], v[64:67]
	s_setprio 0
	s_add_i32 s66, s68, s15
	v_lshl_add_u64 v[204:205], v[204:205], 0, s[48:49]
	s_mov_b32 m0, s66
	ds_read_b128 v[160:163], v247 offset:49152
	ds_read_b128 v[164:167], v247 offset:50176
	ds_read_b128 v[168:171], v247 offset:51200
	ds_read_b128 v[172:175], v247 offset:52224
	ds_read_b128 v[176:179], v247 offset:53248
	ds_read_b128 v[180:183], v247 offset:54272
	ds_read_b128 v[184:187], v247 offset:55296
	ds_read_b128 v[188:191], v247 offset:56320
	global_load_lds_dwordx4 v[204:205], off
	s_add_i32 m0, s66, 0x2000
	s_add_u32 s66, s78, 0xb0080
	v_lshl_add_u64 v[204:205], v[206:207], 0, s[48:49]
	s_addc_u32 s67, s79, 0
	s_add_i32 s68, s69, s15
	global_load_lds_dwordx4 v[204:205], off
	s_mov_b32 m0, s68
	v_lshl_add_u64 v[204:205], s[66:67], 0, v[194:195]
	global_load_lds_dwordx4 v[204:205], off
	s_add_i32 m0, s68, 0x2000
	v_lshl_add_u64 v[204:205], s[66:67], 0, v[198:199]
	global_load_lds_dwordx4 v[204:205], off
	s_mov_b32 m0, s21
	v_lshl_add_u64 v[204:205], v[208:209], 0, s[48:49]
	global_load_lds_dwordx4 v[204:205], off
	s_mov_b32 m0, s22
	v_lshl_add_u64 v[204:205], v[210:211], 0, s[48:49]
	global_load_lds_dwordx4 v[204:205], off
	s_waitcnt vmcnt(8) lgkmcnt(0)
	s_barrier
	s_setprio 1
	v_mfma_f32_16x16x32_bf16 v[60:63], v[120:123], v[160:163], v[60:63]
	v_mfma_f32_16x16x32_bf16 v[60:63], v[124:127], v[164:167], v[60:63]
	v_mfma_f32_16x16x32_bf16 v[56:59], v[128:131], v[160:163], v[56:59]
	v_mfma_f32_16x16x32_bf16 v[56:59], v[132:135], v[164:167], v[56:59]
	v_mfma_f32_16x16x32_bf16 v[44:47], v[120:123], v[168:171], v[44:47]
	v_mfma_f32_16x16x32_bf16 v[44:47], v[124:127], v[172:175], v[44:47]
	v_mfma_f32_16x16x32_bf16 v[40:43], v[128:131], v[168:171], v[40:43]
	v_mfma_f32_16x16x32_bf16 v[40:43], v[132:135], v[172:175], v[40:43]
	v_mfma_f32_16x16x32_bf16 v[28:31], v[120:123], v[176:179], v[28:31]
	v_mfma_f32_16x16x32_bf16 v[28:31], v[124:127], v[180:183], v[28:31]
	v_mfma_f32_16x16x32_bf16 v[24:27], v[128:131], v[176:179], v[24:27]
	v_mfma_f32_16x16x32_bf16 v[24:27], v[132:135], v[180:183], v[24:27]
	v_mfma_f32_16x16x32_bf16 v[12:15], v[120:123], v[184:187], v[12:15]
	v_mfma_f32_16x16x32_bf16 v[12:15], v[124:127], v[188:191], v[12:15]
	v_mfma_f32_16x16x32_bf16 v[8:11], v[128:131], v[184:187], v[8:11]
	v_mfma_f32_16x16x32_bf16 v[8:11], v[132:135], v[188:191], v[8:11]
	v_mfma_f32_16x16x32_bf16 v[52:55], v[144:147], v[160:163], v[52:55]
	v_mfma_f32_16x16x32_bf16 v[52:55], v[148:151], v[164:167], v[52:55]
	v_mfma_f32_16x16x32_bf16 v[48:51], v[152:155], v[160:163], v[48:51]
	v_mfma_f32_16x16x32_bf16 v[48:51], v[156:159], v[164:167], v[48:51]
	v_mfma_f32_16x16x32_bf16 v[36:39], v[144:147], v[168:171], v[36:39]
	v_mfma_f32_16x16x32_bf16 v[36:39], v[148:151], v[172:175], v[36:39]
	v_mfma_f32_16x16x32_bf16 v[32:35], v[152:155], v[168:171], v[32:35]
	v_mfma_f32_16x16x32_bf16 v[32:35], v[156:159], v[172:175], v[32:35]
	v_mfma_f32_16x16x32_bf16 v[20:23], v[144:147], v[176:179], v[20:23]
	v_mfma_f32_16x16x32_bf16 v[20:23], v[148:151], v[180:183], v[20:23]
	v_mfma_f32_16x16x32_bf16 v[16:19], v[152:155], v[176:179], v[16:19]
	v_mfma_f32_16x16x32_bf16 v[16:19], v[156:159], v[180:183], v[16:19]
	v_mfma_f32_16x16x32_bf16 v[4:7], v[144:147], v[184:187], v[4:7]
	v_mfma_f32_16x16x32_bf16 v[4:7], v[148:151], v[188:191], v[4:7]
	s_setprio 3
	s_barrier
	v_mfma_f32_16x16x32_bf16 v[0:3], v[152:155], v[184:187], v[0:3]
	v_mfma_f32_16x16x32_bf16 v[0:3], v[156:159], v[188:191], v[0:3]
	s_setprio 0
	s_add_i32 s59, s59, 2
	s_add_u32 s76, s76, 0x100
	s_addc_u32 s77, s77, 0
	s_add_u32 s55, s55, 0x100
	s_addc_u32 s58, s58, 0
	s_cmp_gt_u32 s59, 41
	s_cbranch_scc0 .LBB0_1299
	s_and_b64 vcc, exec, s[50:51]
	s_cbranch_vccz .LBB0_1302
	s_barrier

.LBB0_1759:
	s_ashr_i32 s49, s48, 31
	s_lshl_b64 s[50:51], s[48:49], 19
	s_add_u32 s50, s12, s50
	s_addc_u32 s51, s13, s51
	s_and_b64 s[52:53], s[4:5], exec
	s_cselect_b32 s49, s51, s79
	s_cselect_b32 s54, s50, s78
	s_ashr_i32 s47, s46, 31
	s_lshl_b64 s[52:53], s[46:47], 19
	s_add_u32 s52, s14, s52
	s_addc_u32 s53, s15, s53
	s_and_b64 s[66:67], s[4:5], exec
	s_cselect_b32 s47, s53, s81
	s_cselect_b32 s55, s52, s80
	s_add_u32 s78, s78, 0x40080
	s_addc_u32 s79, s79, 0
	s_add_u32 s66, s80, 0x100
	v_mov_b32_e32 v0, 0
	s_addc_u32 s67, s81, 0
	s_mov_b32 s68, -2
	s_waitcnt lgkmcnt(0)
	ds_read_b128 v[128:131], v181
	ds_read_b128 v[132:135], v181 offset:1024
	ds_read_b128 v[136:139], v181 offset:2048
	ds_read_b128 v[160:163], v181 offset:3072
	ds_read_b128 v[164:167], v182
	ds_read_b128 v[168:171], v182 offset:1024
	ds_read_b128 v[186:189], v182 offset:2048
	ds_read_b128 v[190:193], v182 offset:3072
	s_add_u32 s69, s78, 0xfffc0080
	s_addc_u32 s73, s79, -1
	s_cmp_eq_u32 s68, 12
	s_cselect_b32 s83, s49, s73
	s_cselect_b32 s82, s54, s69
	s_cselect_b32 s81, s47, s67
	s_cselect_b32 s80, s55, s66
	v_lshl_add_u64 v[172:173], s[78:79], 0, v[152:153]
	s_add_i32 m0, s18, 0xc000
	ds_read_b128 v[194:197], v183
	ds_read_b128 v[198:201], v183 offset:1024
	ds_read_b128 v[202:205], v183 offset:2048
	ds_read_b128 v[206:209], v183 offset:3072
	ds_read_b128 v[210:213], v183 offset:4096
	ds_read_b128 v[214:217], v183 offset:5120
	ds_read_b128 v[218:221], v183 offset:6144
	ds_read_b128 v[222:225], v183 offset:7168
	global_load_lds_dwordx4 v[172:173], off
	s_add_i32 m0, s18, 0xe000
	v_lshl_add_u64 v[172:173], s[78:79], 0, v[154:155]
	global_load_lds_dwordx4 v[172:173], off
	s_waitcnt vmcnt(8) lgkmcnt(0)
	s_barrier
	s_setprio 1
	v_mfma_f32_16x16x32_bf16 v[124:127], v[128:131], v[194:197], 0
	v_mfma_f32_16x16x32_bf16 v[124:127], v[132:135], v[198:201], v[124:127]
	v_mfma_f32_16x16x32_bf16 v[120:123], v[136:139], v[194:197], 0
	v_mfma_f32_16x16x32_bf16 v[120:123], v[160:163], v[198:201], v[120:123]
	v_mfma_f32_16x16x32_bf16 v[108:111], v[128:131], v[202:205], 0
	v_mfma_f32_16x16x32_bf16 v[108:111], v[132:135], v[206:209], v[108:111]
	v_mfma_f32_16x16x32_bf16 v[104:107], v[136:139], v[202:205], 0
	v_mfma_f32_16x16x32_bf16 v[104:107], v[160:163], v[206:209], v[104:107]
	v_mfma_f32_16x16x32_bf16 v[92:95], v[128:131], v[210:213], 0
	v_mfma_f32_16x16x32_bf16 v[92:95], v[132:135], v[214:217], v[92:95]
	v_mfma_f32_16x16x32_bf16 v[88:91], v[136:139], v[210:213], 0
	v_mfma_f32_16x16x32_bf16 v[88:91], v[160:163], v[214:217], v[88:91]
	v_mfma_f32_16x16x32_bf16 v[76:79], v[128:131], v[218:221], 0
	v_mfma_f32_16x16x32_bf16 v[76:79], v[132:135], v[222:225], v[76:79]
	v_mfma_f32_16x16x32_bf16 v[72:75], v[136:139], v[218:221], 0
	v_mfma_f32_16x16x32_bf16 v[72:75], v[160:163], v[222:225], v[72:75]
	v_mfma_f32_16x16x32_bf16 v[116:119], v[164:167], v[194:197], 0
	v_mfma_f32_16x16x32_bf16 v[116:119], v[168:171], v[198:201], v[116:119]
	v_mfma_f32_16x16x32_bf16 v[112:115], v[186:189], v[194:197], 0
	v_mfma_f32_16x16x32_bf16 v[112:115], v[190:193], v[198:201], v[112:115]
	v_mfma_f32_16x16x32_bf16 v[100:103], v[164:167], v[202:205], 0
	v_mfma_f32_16x16x32_bf16 v[100:103], v[168:171], v[206:209], v[100:103]
	v_mfma_f32_16x16x32_bf16 v[96:99], v[186:189], v[202:205], 0
	v_mfma_f32_16x16x32_bf16 v[96:99], v[190:193], v[206:209], v[96:99]
	v_mfma_f32_16x16x32_bf16 v[84:87], v[164:167], v[210:213], 0
	v_mfma_f32_16x16x32_bf16 v[84:87], v[168:171], v[214:217], v[84:87]
	v_mfma_f32_16x16x32_bf16 v[80:83], v[186:189], v[210:213], 0
	v_mfma_f32_16x16x32_bf16 v[80:83], v[190:193], v[214:217], v[80:83]
	v_mfma_f32_16x16x32_bf16 v[68:71], v[164:167], v[218:221], 0
	v_mfma_f32_16x16x32_bf16 v[68:71], v[168:171], v[222:225], v[68:71]
	s_setprio 3
	s_barrier
	v_mfma_f32_16x16x32_bf16 v[64:67], v[186:189], v[218:221], 0
	v_mfma_f32_16x16x32_bf16 v[64:67], v[190:193], v[222:225], v[64:67]
	s_setprio 0
	s_add_i32 s69, s25, s17
	v_lshl_add_u64 v[172:173], s[80:81], 0, v[142:143]
	s_mov_b32 m0, s69
	ds_read_b128 v[194:197], v183 offset:16384
	ds_read_b128 v[198:201], v183 offset:17408
	ds_read_b128 v[202:205], v183 offset:18432
	ds_read_b128 v[206:209], v183 offset:19456
	ds_read_b128 v[210:213], v183 offset:20480
	ds_read_b128 v[214:217], v183 offset:21504
	ds_read_b128 v[218:221], v183 offset:22528
	ds_read_b128 v[222:225], v183 offset:23552
	global_load_lds_dwordx4 v[172:173], off
	s_add_i32 m0, s69, 0x2000
	s_add_u32 s84, s80, 0x40000
	v_lshl_add_u64 v[226:227], s[80:81], 0, v[146:147]
	s_addc_u32 s85, s81, 0
	s_add_i32 s69, s26, s17
	global_load_lds_dwordx4 v[226:227], off
	v_lshl_add_u64 v[228:229], s[84:85], 0, v[142:143]
	s_mov_b32 m0, s69
	global_load_lds_dwordx4 v[228:229], off
	s_add_i32 m0, s69, 0x2000
	v_lshl_add_u64 v[228:229], s[84:85], 0, v[146:147]
	global_load_lds_dwordx4 v[228:229], off
	s_mov_b32 m0, s18
	v_lshl_add_u64 v[228:229], s[82:83], 0, v[140:141]
	global_load_lds_dwordx4 v[228:229], off
	s_mov_b32 m0, s19
	v_lshl_add_u64 v[230:231], s[82:83], 0, v[144:145]
	global_load_lds_dwordx4 v[230:231], off
	s_waitcnt vmcnt(8) lgkmcnt(0)
	s_barrier
	s_setprio 1
	v_mfma_f32_16x16x32_bf16 v[60:63], v[128:131], v[194:197], 0
	v_mfma_f32_16x16x32_bf16 v[60:63], v[132:135], v[198:201], v[60:63]
	v_mfma_f32_16x16x32_bf16 v[56:59], v[136:139], v[194:197], 0
	v_mfma_f32_16x16x32_bf16 v[56:59], v[160:163], v[198:201], v[56:59]
	v_mfma_f32_16x16x32_bf16 v[44:47], v[128:131], v[202:205], 0
	v_mfma_f32_16x16x32_bf16 v[44:47], v[132:135], v[206:209], v[44:47]
	v_mfma_f32_16x16x32_bf16 v[40:43], v[136:139], v[202:205], 0
	v_mfma_f32_16x16x32_bf16 v[40:43], v[160:163], v[206:209], v[40:43]
	v_mfma_f32_16x16x32_bf16 v[28:31], v[128:131], v[210:213], 0
	v_mfma_f32_16x16x32_bf16 v[28:31], v[132:135], v[214:217], v[28:31]
	v_mfma_f32_16x16x32_bf16 v[24:27], v[136:139], v[210:213], 0
	v_mfma_f32_16x16x32_bf16 v[24:27], v[160:163], v[214:217], v[24:27]
	v_mfma_f32_16x16x32_bf16 v[12:15], v[128:131], v[218:221], 0
	v_mfma_f32_16x16x32_bf16 v[12:15], v[132:135], v[222:225], v[12:15]
	v_mfma_f32_16x16x32_bf16 v[8:11], v[136:139], v[218:221], 0
	v_mfma_f32_16x16x32_bf16 v[8:11], v[160:163], v[222:225], v[8:11]
	v_mfma_f32_16x16x32_bf16 v[52:55], v[164:167], v[194:197], 0
	v_mfma_f32_16x16x32_bf16 v[52:55], v[168:171], v[198:201], v[52:55]
	v_mfma_f32_16x16x32_bf16 v[48:51], v[186:189], v[194:197], 0
	v_mfma_f32_16x16x32_bf16 v[48:51], v[190:193], v[198:201], v[48:51]
	v_mfma_f32_16x16x32_bf16 v[36:39], v[164:167], v[202:205], 0
	v_mfma_f32_16x16x32_bf16 v[36:39], v[168:171], v[206:209], v[36:39]
	v_mfma_f32_16x16x32_bf16 v[32:35], v[186:189], v[202:205], 0
	v_mfma_f32_16x16x32_bf16 v[32:35], v[190:193], v[206:209], v[32:35]
	v_mfma_f32_16x16x32_bf16 v[20:23], v[164:167], v[210:213], 0
	v_mfma_f32_16x16x32_bf16 v[20:23], v[168:171], v[214:217], v[20:23]
	v_mfma_f32_16x16x32_bf16 v[16:19], v[186:189], v[210:213], 0
	v_mfma_f32_16x16x32_bf16 v[16:19], v[190:193], v[214:217], v[16:19]
	v_mfma_f32_16x16x32_bf16 v[4:7], v[164:167], v[218:221], 0
	v_mfma_f32_16x16x32_bf16 v[4:7], v[168:171], v[222:225], v[4:7]
	s_setprio 3
	s_barrier
	v_mfma_f32_16x16x32_bf16 v[0:3], v[186:189], v[218:221], 0
	v_mfma_f32_16x16x32_bf16 v[0:3], v[190:193], v[222:225], v[0:3]
	s_setprio 0
	s_add_i32 s69, 0, 0x18000
	v_add_u32_e32 v148, s69, v177
	s_add_i32 s73, 0, 0x1c000
	ds_read_b128 v[128:131], v148
	ds_read_b128 v[132:135], v148 offset:1024
	ds_read_b128 v[136:139], v148 offset:2048
	ds_read_b128 v[160:163], v148 offset:3072
	v_add_u32_e32 v148, s73, v177
	ds_read_b128 v[164:167], v148
	ds_read_b128 v[168:171], v148 offset:1024
	ds_read_b128 v[186:189], v148 offset:2048
	ds_read_b128 v[190:193], v148 offset:3072
	s_add_u32 s82, s82, 0x40000
	s_addc_u32 s83, s83, 0
	s_mov_b32 m0, s20
	v_lshl_add_u64 v[232:233], s[82:83], 0, v[140:141]
	ds_read_b128 v[194:197], v183 offset:32768
	ds_read_b128 v[198:201], v183 offset:33792
	ds_read_b128 v[202:205], v183 offset:34816
	ds_read_b128 v[206:209], v183 offset:35840
	ds_read_b128 v[210:213], v183 offset:36864
	ds_read_b128 v[214:217], v183 offset:37888
	ds_read_b128 v[218:221], v183 offset:38912
	ds_read_b128 v[222:225], v183 offset:39936
	global_load_lds_dwordx4 v[232:233], off
	s_mov_b32 m0, s21
	v_lshl_add_u64 v[232:233], s[82:83], 0, v[144:145]
	global_load_lds_dwordx4 v[232:233], off
	s_waitcnt vmcnt(8) lgkmcnt(0)
	s_barrier
	s_setprio 1
	v_mfma_f32_16x16x32_bf16 v[124:127], v[128:131], v[194:197], v[124:127]
	v_mfma_f32_16x16x32_bf16 v[124:127], v[132:135], v[198:201], v[124:127]
	v_mfma_f32_16x16x32_bf16 v[120:123], v[136:139], v[194:197], v[120:123]
	v_mfma_f32_16x16x32_bf16 v[120:123], v[160:163], v[198:201], v[120:123]
	v_mfma_f32_16x16x32_bf16 v[108:111], v[128:131], v[202:205], v[108:111]
	v_mfma_f32_16x16x32_bf16 v[108:111], v[132:135], v[206:209], v[108:111]
	v_mfma_f32_16x16x32_bf16 v[104:107], v[136:139], v[202:205], v[104:107]
	v_mfma_f32_16x16x32_bf16 v[104:107], v[160:163], v[206:209], v[104:107]
	v_mfma_f32_16x16x32_bf16 v[92:95], v[128:131], v[210:213], v[92:95]
	v_mfma_f32_16x16x32_bf16 v[92:95], v[132:135], v[214:217], v[92:95]
	v_mfma_f32_16x16x32_bf16 v[88:91], v[136:139], v[210:213], v[88:91]
	v_mfma_f32_16x16x32_bf16 v[88:91], v[160:163], v[214:217], v[88:91]
	v_mfma_f32_16x16x32_bf16 v[76:79], v[128:131], v[218:221], v[76:79]
	v_mfma_f32_16x16x32_bf16 v[76:79], v[132:135], v[222:225], v[76:79]
	v_mfma_f32_16x16x32_bf16 v[72:75], v[136:139], v[218:221], v[72:75]
	v_mfma_f32_16x16x32_bf16 v[72:75], v[160:163], v[222:225], v[72:75]
	v_mfma_f32_16x16x32_bf16 v[116:119], v[164:167], v[194:197], v[116:119]
	v_mfma_f32_16x16x32_bf16 v[116:119], v[168:171], v[198:201], v[116:119]
	v_mfma_f32_16x16x32_bf16 v[112:115], v[186:189], v[194:197], v[112:115]
	v_mfma_f32_16x16x32_bf16 v[112:115], v[190:193], v[198:201], v[112:115]
	v_mfma_f32_16x16x32_bf16 v[100:103], v[164:167], v[202:205], v[100:103]
	v_mfma_f32_16x16x32_bf16 v[100:103], v[168:171], v[206:209], v[100:103]
	v_mfma_f32_16x16x32_bf16 v[96:99], v[186:189], v[202:205], v[96:99]
	v_mfma_f32_16x16x32_bf16 v[96:99], v[190:193], v[206:209], v[96:99]
	v_mfma_f32_16x16x32_bf16 v[84:87], v[164:167], v[210:213], v[84:87]
	v_mfma_f32_16x16x32_bf16 v[84:87], v[168:171], v[214:217], v[84:87]
	v_mfma_f32_16x16x32_bf16 v[80:83], v[186:189], v[210:213], v[80:83]
	v_mfma_f32_16x16x32_bf16 v[80:83], v[190:193], v[214:217], v[80:83]
	v_mfma_f32_16x16x32_bf16 v[68:71], v[164:167], v[218:221], v[68:71]
	v_mfma_f32_16x16x32_bf16 v[68:71], v[168:171], v[222:225], v[68:71]
	s_setprio 3
	s_barrier
	v_mfma_f32_16x16x32_bf16 v[64:67], v[186:189], v[218:221], v[64:67]
	v_mfma_f32_16x16x32_bf16 v[64:67], v[190:193], v[222:225], v[64:67]
	s_setprio 0
	s_add_i32 s69, s69, s17
	v_lshl_add_u64 v[172:173], v[172:173], 0, s[10:11]
	s_mov_b32 m0, s69
	ds_read_b128 v[194:197], v183 offset:49152
	ds_read_b128 v[198:201], v183 offset:50176
	ds_read_b128 v[202:205], v183 offset:51200
	ds_read_b128 v[206:209], v183 offset:52224
	ds_read_b128 v[210:213], v183 offset:53248
	ds_read_b128 v[214:217], v183 offset:54272
	ds_read_b128 v[218:221], v183 offset:55296
	ds_read_b128 v[222:225], v183 offset:56320
	global_load_lds_dwordx4 v[172:173], off
	s_add_i32 m0, s69, 0x2000
	s_add_u32 s80, s80, 0x40080
	v_lshl_add_u64 v[172:173], v[226:227], 0, s[10:11]
	s_addc_u32 s81, s81, 0
	s_add_i32 s69, s73, s17
	global_load_lds_dwordx4 v[172:173], off
	s_mov_b32 m0, s69
	v_lshl_add_u64 v[172:173], s[80:81], 0, v[142:143]
	global_load_lds_dwordx4 v[172:173], off
	s_add_i32 m0, s69, 0x2000
	v_lshl_add_u64 v[172:173], s[80:81], 0, v[146:147]
	global_load_lds_dwordx4 v[172:173], off
	s_mov_b32 m0, s23
	v_lshl_add_u64 v[172:173], v[228:229], 0, s[10:11]
	global_load_lds_dwordx4 v[172:173], off
	s_mov_b32 m0, s24
	v_lshl_add_u64 v[172:173], v[230:231], 0, s[10:11]
	global_load_lds_dwordx4 v[172:173], off
	s_waitcnt vmcnt(8) lgkmcnt(0)
	s_barrier
	s_setprio 1
	v_mfma_f32_16x16x32_bf16 v[60:63], v[128:131], v[194:197], v[60:63]
	v_mfma_f32_16x16x32_bf16 v[60:63], v[132:135], v[198:201], v[60:63]
	v_mfma_f32_16x16x32_bf16 v[56:59], v[136:139], v[194:197], v[56:59]
	v_mfma_f32_16x16x32_bf16 v[56:59], v[160:163], v[198:201], v[56:59]
	v_mfma_f32_16x16x32_bf16 v[44:47], v[128:131], v[202:205], v[44:47]
	v_mfma_f32_16x16x32_bf16 v[44:47], v[132:135], v[206:209], v[44:47]
	v_mfma_f32_16x16x32_bf16 v[40:43], v[136:139], v[202:205], v[40:43]
	v_mfma_f32_16x16x32_bf16 v[40:43], v[160:163], v[206:209], v[40:43]
	v_mfma_f32_16x16x32_bf16 v[28:31], v[128:131], v[210:213], v[28:31]
	v_mfma_f32_16x16x32_bf16 v[28:31], v[132:135], v[214:217], v[28:31]
	v_mfma_f32_16x16x32_bf16 v[24:27], v[136:139], v[210:213], v[24:27]
	v_mfma_f32_16x16x32_bf16 v[24:27], v[160:163], v[214:217], v[24:27]
	v_mfma_f32_16x16x32_bf16 v[12:15], v[128:131], v[218:221], v[12:15]
	v_mfma_f32_16x16x32_bf16 v[12:15], v[132:135], v[222:225], v[12:15]
	v_mfma_f32_16x16x32_bf16 v[8:11], v[136:139], v[218:221], v[8:11]
	v_mfma_f32_16x16x32_bf16 v[8:11], v[160:163], v[222:225], v[8:11]
	v_mfma_f32_16x16x32_bf16 v[52:55], v[164:167], v[194:197], v[52:55]
	v_mfma_f32_16x16x32_bf16 v[52:55], v[168:171], v[198:201], v[52:55]
	v_mfma_f32_16x16x32_bf16 v[48:51], v[186:189], v[194:197], v[48:51]
	v_mfma_f32_16x16x32_bf16 v[48:51], v[190:193], v[198:201], v[48:51]
	v_mfma_f32_16x16x32_bf16 v[36:39], v[164:167], v[202:205], v[36:39]
	v_mfma_f32_16x16x32_bf16 v[36:39], v[168:171], v[206:209], v[36:39]
	v_mfma_f32_16x16x32_bf16 v[32:35], v[186:189], v[202:205], v[32:35]
	v_mfma_f32_16x16x32_bf16 v[32:35], v[190:193], v[206:209], v[32:35]
	v_mfma_f32_16x16x32_bf16 v[20:23], v[164:167], v[210:213], v[20:23]
	v_mfma_f32_16x16x32_bf16 v[20:23], v[168:171], v[214:217], v[20:23]
	v_mfma_f32_16x16x32_bf16 v[16:19], v[186:189], v[210:213], v[16:19]
	v_mfma_f32_16x16x32_bf16 v[16:19], v[190:193], v[214:217], v[16:19]
	v_mfma_f32_16x16x32_bf16 v[4:7], v[164:167], v[218:221], v[4:7]
	v_mfma_f32_16x16x32_bf16 v[4:7], v[168:171], v[222:225], v[4:7]
	s_setprio 3
	s_barrier
	v_mfma_f32_16x16x32_bf16 v[0:3], v[186:189], v[218:221], v[0:3]
	v_mfma_f32_16x16x32_bf16 v[0:3], v[190:193], v[222:225], v[0:3]
	s_setprio 0
	s_add_i32 s68, s68, 2
	s_add_u32 s78, s78, 0x100
	s_addc_u32 s79, s79, 0
	s_add_u32 s66, s66, 0x100
	s_addc_u32 s67, s67, 0
	s_cmp_gt_u32 s68, 13
.LBB0_1760:
	ds_read_b128 v[128:131], v181
	ds_read_b128 v[132:135], v181 offset:1024
	ds_read_b128 v[136:139], v181 offset:2048
	ds_read_b128 v[160:163], v181 offset:3072
	ds_read_b128 v[164:167], v182
	ds_read_b128 v[168:171], v182 offset:1024
	ds_read_b128 v[186:189], v182 offset:2048
	ds_read_b128 v[190:193], v182 offset:3072
	s_add_u32 s69, s78, 0xfffc0080
	s_addc_u32 s73, s79, -1
	s_cmp_eq_u32 s68, 12
	s_cselect_b32 s83, s49, s73
	s_cselect_b32 s82, s54, s69
	s_cselect_b32 s81, s47, s67
	s_cselect_b32 s80, s55, s66
	v_lshl_add_u64 v[172:173], s[78:79], 0, v[152:153]
	s_add_i32 m0, s18, 0xc000
	ds_read_b128 v[194:197], v183
	ds_read_b128 v[198:201], v183 offset:1024
	ds_read_b128 v[202:205], v183 offset:2048
	ds_read_b128 v[206:209], v183 offset:3072
	ds_read_b128 v[210:213], v183 offset:4096
	ds_read_b128 v[214:217], v183 offset:5120
	ds_read_b128 v[218:221], v183 offset:6144
	ds_read_b128 v[222:225], v183 offset:7168
	global_load_lds_dwordx4 v[172:173], off
	s_add_i32 m0, s18, 0xe000
	v_lshl_add_u64 v[172:173], s[78:79], 0, v[154:155]
	global_load_lds_dwordx4 v[172:173], off
	s_waitcnt vmcnt(8) lgkmcnt(0)
	s_barrier
	s_setprio 1
	v_mfma_f32_16x16x32_bf16 v[124:127], v[128:131], v[194:197], v[124:127]
	v_mfma_f32_16x16x32_bf16 v[124:127], v[132:135], v[198:201], v[124:127]
	v_mfma_f32_16x16x32_bf16 v[120:123], v[136:139], v[194:197], v[120:123]
	v_mfma_f32_16x16x32_bf16 v[120:123], v[160:163], v[198:201], v[120:123]
	v_mfma_f32_16x16x32_bf16 v[108:111], v[128:131], v[202:205], v[108:111]
	v_mfma_f32_16x16x32_bf16 v[108:111], v[132:135], v[206:209], v[108:111]
	v_mfma_f32_16x16x32_bf16 v[104:107], v[136:139], v[202:205], v[104:107]
	v_mfma_f32_16x16x32_bf16 v[104:107], v[160:163], v[206:209], v[104:107]
	v_mfma_f32_16x16x32_bf16 v[92:95], v[128:131], v[210:213], v[92:95]
	v_mfma_f32_16x16x32_bf16 v[92:95], v[132:135], v[214:217], v[92:95]
	v_mfma_f32_16x16x32_bf16 v[88:91], v[136:139], v[210:213], v[88:91]
	v_mfma_f32_16x16x32_bf16 v[88:91], v[160:163], v[214:217], v[88:91]
	v_mfma_f32_16x16x32_bf16 v[76:79], v[128:131], v[218:221], v[76:79]
	v_mfma_f32_16x16x32_bf16 v[76:79], v[132:135], v[222:225], v[76:79]
	v_mfma_f32_16x16x32_bf16 v[72:75], v[136:139], v[218:221], v[72:75]
	v_mfma_f32_16x16x32_bf16 v[72:75], v[160:163], v[222:225], v[72:75]
	v_mfma_f32_16x16x32_bf16 v[116:119], v[164:167], v[194:197], v[116:119]
	v_mfma_f32_16x16x32_bf16 v[116:119], v[168:171], v[198:201], v[116:119]
	v_mfma_f32_16x16x32_bf16 v[112:115], v[186:189], v[194:197], v[112:115]
	v_mfma_f32_16x16x32_bf16 v[112:115], v[190:193], v[198:201], v[112:115]
	v_mfma_f32_16x16x32_bf16 v[100:103], v[164:167], v[202:205], v[100:103]
	v_mfma_f32_16x16x32_bf16 v[100:103], v[168:171], v[206:209], v[100:103]
	v_mfma_f32_16x16x32_bf16 v[96:99], v[186:189], v[202:205], v[96:99]
	v_mfma_f32_16x16x32_bf16 v[96:99], v[190:193], v[206:209], v[96:99]
	v_mfma_f32_16x16x32_bf16 v[84:87], v[164:167], v[210:213], v[84:87]
	v_mfma_f32_16x16x32_bf16 v[84:87], v[168:171], v[214:217], v[84:87]
	v_mfma_f32_16x16x32_bf16 v[80:83], v[186:189], v[210:213], v[80:83]
	v_mfma_f32_16x16x32_bf16 v[80:83], v[190:193], v[214:217], v[80:83]
	v_mfma_f32_16x16x32_bf16 v[68:71], v[164:167], v[218:221], v[68:71]
	v_mfma_f32_16x16x32_bf16 v[68:71], v[168:171], v[222:225], v[68:71]
	s_setprio 3
	s_barrier
	v_mfma_f32_16x16x32_bf16 v[64:67], v[186:189], v[218:221], v[64:67]
	v_mfma_f32_16x16x32_bf16 v[64:67], v[190:193], v[222:225], v[64:67]
	s_setprio 0
	s_add_i32 s69, s25, s17
	v_lshl_add_u64 v[172:173], s[80:81], 0, v[142:143]
	s_mov_b32 m0, s69
	ds_read_b128 v[194:197], v183 offset:16384
	ds_read_b128 v[198:201], v183 offset:17408
	ds_read_b128 v[202:205], v183 offset:18432
	ds_read_b128 v[206:209], v183 offset:19456
	ds_read_b128 v[210:213], v183 offset:20480
	ds_read_b128 v[214:217], v183 offset:21504
	ds_read_b128 v[218:221], v183 offset:22528
	ds_read_b128 v[222:225], v183 offset:23552
	global_load_lds_dwordx4 v[172:173], off
	s_add_i32 m0, s69, 0x2000
	s_add_u32 s84, s80, 0x40000
	v_lshl_add_u64 v[226:227], s[80:81], 0, v[146:147]
	s_addc_u32 s85, s81, 0
	s_add_i32 s69, s26, s17
	global_load_lds_dwordx4 v[226:227], off
	v_lshl_add_u64 v[228:229], s[84:85], 0, v[142:143]
	s_mov_b32 m0, s69
	global_load_lds_dwordx4 v[228:229], off
	s_add_i32 m0, s69, 0x2000
	v_lshl_add_u64 v[228:229], s[84:85], 0, v[146:147]
	global_load_lds_dwordx4 v[228:229], off
	s_mov_b32 m0, s18
	v_lshl_add_u64 v[228:229], s[82:83], 0, v[140:141]
	global_load_lds_dwordx4 v[228:229], off
	s_mov_b32 m0, s19
	v_lshl_add_u64 v[230:231], s[82:83], 0, v[144:145]
	global_load_lds_dwordx4 v[230:231], off
	s_waitcnt vmcnt(8) lgkmcnt(0)
	s_barrier
	s_setprio 1
	v_mfma_f32_16x16x32_bf16 v[60:63], v[128:131], v[194:197], v[60:63]
	v_mfma_f32_16x16x32_bf16 v[60:63], v[132:135], v[198:201], v[60:63]
	v_mfma_f32_16x16x32_bf16 v[56:59], v[136:139], v[194:197], v[56:59]
	v_mfma_f32_16x16x32_bf16 v[56:59], v[160:163], v[198:201], v[56:59]
	v_mfma_f32_16x16x32_bf16 v[44:47], v[128:131], v[202:205], v[44:47]
	v_mfma_f32_16x16x32_bf16 v[44:47], v[132:135], v[206:209], v[44:47]
	v_mfma_f32_16x16x32_bf16 v[40:43], v[136:139], v[202:205], v[40:43]
	v_mfma_f32_16x16x32_bf16 v[40:43], v[160:163], v[206:209], v[40:43]
	v_mfma_f32_16x16x32_bf16 v[28:31], v[128:131], v[210:213], v[28:31]
	v_mfma_f32_16x16x32_bf16 v[28:31], v[132:135], v[214:217], v[28:31]
	v_mfma_f32_16x16x32_bf16 v[24:27], v[136:139], v[210:213], v[24:27]
	v_mfma_f32_16x16x32_bf16 v[24:27], v[160:163], v[214:217], v[24:27]
	v_mfma_f32_16x16x32_bf16 v[12:15], v[128:131], v[218:221], v[12:15]
	v_mfma_f32_16x16x32_bf16 v[12:15], v[132:135], v[222:225], v[12:15]
	v_mfma_f32_16x16x32_bf16 v[8:11], v[136:139], v[218:221], v[8:11]
	v_mfma_f32_16x16x32_bf16 v[8:11], v[160:163], v[222:225], v[8:11]
	v_mfma_f32_16x16x32_bf16 v[52:55], v[164:167], v[194:197], v[52:55]
	v_mfma_f32_16x16x32_bf16 v[52:55], v[168:171], v[198:201], v[52:55]
	v_mfma_f32_16x16x32_bf16 v[48:51], v[186:189], v[194:197], v[48:51]
	v_mfma_f32_16x16x32_bf16 v[48:51], v[190:193], v[198:201], v[48:51]
	v_mfma_f32_16x16x32_bf16 v[36:39], v[164:167], v[202:205], v[36:39]
	v_mfma_f32_16x16x32_bf16 v[36:39], v[168:171], v[206:209], v[36:39]
	v_mfma_f32_16x16x32_bf16 v[32:35], v[186:189], v[202:205], v[32:35]
	v_mfma_f32_16x16x32_bf16 v[32:35], v[190:193], v[206:209], v[32:35]
	v_mfma_f32_16x16x32_bf16 v[20:23], v[164:167], v[210:213], v[20:23]
	v_mfma_f32_16x16x32_bf16 v[20:23], v[168:171], v[214:217], v[20:23]
	v_mfma_f32_16x16x32_bf16 v[16:19], v[186:189], v[210:213], v[16:19]
	v_mfma_f32_16x16x32_bf16 v[16:19], v[190:193], v[214:217], v[16:19]
	v_mfma_f32_16x16x32_bf16 v[4:7], v[164:167], v[218:221], v[4:7]
	v_mfma_f32_16x16x32_bf16 v[4:7], v[168:171], v[222:225], v[4:7]
	s_setprio 3
	s_barrier
	v_mfma_f32_16x16x32_bf16 v[0:3], v[186:189], v[218:221], v[0:3]
	v_mfma_f32_16x16x32_bf16 v[0:3], v[190:193], v[222:225], v[0:3]
	s_setprio 0
	s_add_i32 s69, 0, 0x18000
	v_add_u32_e32 v148, s69, v177
	s_add_i32 s73, 0, 0x1c000
	ds_read_b128 v[128:131], v148
	ds_read_b128 v[132:135], v148 offset:1024
	ds_read_b128 v[136:139], v148 offset:2048
	ds_read_b128 v[160:163], v148 offset:3072
	v_add_u32_e32 v148, s73, v177
	ds_read_b128 v[164:167], v148
	ds_read_b128 v[168:171], v148 offset:1024
	ds_read_b128 v[186:189], v148 offset:2048
	ds_read_b128 v[190:193], v148 offset:3072
	s_add_u32 s82, s82, 0x40000
	s_addc_u32 s83, s83, 0
	s_mov_b32 m0, s20
	v_lshl_add_u64 v[232:233], s[82:83], 0, v[140:141]
	ds_read_b128 v[194:197], v183 offset:32768
	ds_read_b128 v[198:201], v183 offset:33792
	ds_read_b128 v[202:205], v183 offset:34816
	ds_read_b128 v[206:209], v183 offset:35840
	ds_read_b128 v[210:213], v183 offset:36864
	ds_read_b128 v[214:217], v183 offset:37888
	ds_read_b128 v[218:221], v183 offset:38912
	ds_read_b128 v[222:225], v183 offset:39936
	global_load_lds_dwordx4 v[232:233], off
	s_mov_b32 m0, s21
	v_lshl_add_u64 v[232:233], s[82:83], 0, v[144:145]
	global_load_lds_dwordx4 v[232:233], off
	s_waitcnt vmcnt(8) lgkmcnt(0)
	s_barrier
	s_setprio 1
	v_mfma_f32_16x16x32_bf16 v[124:127], v[128:131], v[194:197], v[124:127]
	v_mfma_f32_16x16x32_bf16 v[124:127], v[132:135], v[198:201], v[124:127]
	v_mfma_f32_16x16x32_bf16 v[120:123], v[136:139], v[194:197], v[120:123]
	v_mfma_f32_16x16x32_bf16 v[120:123], v[160:163], v[198:201], v[120:123]
	v_mfma_f32_16x16x32_bf16 v[108:111], v[128:131], v[202:205], v[108:111]
	v_mfma_f32_16x16x32_bf16 v[108:111], v[132:135], v[206:209], v[108:111]
	v_mfma_f32_16x16x32_bf16 v[104:107], v[136:139], v[202:205], v[104:107]
	v_mfma_f32_16x16x32_bf16 v[104:107], v[160:163], v[206:209], v[104:107]
	v_mfma_f32_16x16x32_bf16 v[92:95], v[128:131], v[210:213], v[92:95]
	v_mfma_f32_16x16x32_bf16 v[92:95], v[132:135], v[214:217], v[92:95]
	v_mfma_f32_16x16x32_bf16 v[88:91], v[136:139], v[210:213], v[88:91]
	v_mfma_f32_16x16x32_bf16 v[88:91], v[160:163], v[214:217], v[88:91]
	v_mfma_f32_16x16x32_bf16 v[76:79], v[128:131], v[218:221], v[76:79]
	v_mfma_f32_16x16x32_bf16 v[76:79], v[132:135], v[222:225], v[76:79]
	v_mfma_f32_16x16x32_bf16 v[72:75], v[136:139], v[218:221], v[72:75]
	v_mfma_f32_16x16x32_bf16 v[72:75], v[160:163], v[222:225], v[72:75]
	v_mfma_f32_16x16x32_bf16 v[116:119], v[164:167], v[194:197], v[116:119]
	v_mfma_f32_16x16x32_bf16 v[116:119], v[168:171], v[198:201], v[116:119]
	v_mfma_f32_16x16x32_bf16 v[112:115], v[186:189], v[194:197], v[112:115]
	v_mfma_f32_16x16x32_bf16 v[112:115], v[190:193], v[198:201], v[112:115]
	v_mfma_f32_16x16x32_bf16 v[100:103], v[164:167], v[202:205], v[100:103]
	v_mfma_f32_16x16x32_bf16 v[100:103], v[168:171], v[206:209], v[100:103]
	v_mfma_f32_16x16x32_bf16 v[96:99], v[186:189], v[202:205], v[96:99]
	v_mfma_f32_16x16x32_bf16 v[96:99], v[190:193], v[206:209], v[96:99]
	v_mfma_f32_16x16x32_bf16 v[84:87], v[164:167], v[210:213], v[84:87]
	v_mfma_f32_16x16x32_bf16 v[84:87], v[168:171], v[214:217], v[84:87]
	v_mfma_f32_16x16x32_bf16 v[80:83], v[186:189], v[210:213], v[80:83]
	v_mfma_f32_16x16x32_bf16 v[80:83], v[190:193], v[214:217], v[80:83]
	v_mfma_f32_16x16x32_bf16 v[68:71], v[164:167], v[218:221], v[68:71]
	v_mfma_f32_16x16x32_bf16 v[68:71], v[168:171], v[222:225], v[68:71]
	s_setprio 3
	s_barrier
	v_mfma_f32_16x16x32_bf16 v[64:67], v[186:189], v[218:221], v[64:67]
	v_mfma_f32_16x16x32_bf16 v[64:67], v[190:193], v[222:225], v[64:67]
	s_setprio 0
	s_add_i32 s69, s69, s17
	v_lshl_add_u64 v[172:173], v[172:173], 0, s[10:11]
	s_mov_b32 m0, s69
	ds_read_b128 v[194:197], v183 offset:49152
	ds_read_b128 v[198:201], v183 offset:50176
	ds_read_b128 v[202:205], v183 offset:51200
	ds_read_b128 v[206:209], v183 offset:52224
	ds_read_b128 v[210:213], v183 offset:53248
	ds_read_b128 v[214:217], v183 offset:54272
	ds_read_b128 v[218:221], v183 offset:55296
	ds_read_b128 v[222:225], v183 offset:56320
	global_load_lds_dwordx4 v[172:173], off
	s_add_i32 m0, s69, 0x2000
	s_add_u32 s80, s80, 0x40080
	v_lshl_add_u64 v[172:173], v[226:227], 0, s[10:11]
	s_addc_u32 s81, s81, 0
	s_add_i32 s69, s73, s17
	global_load_lds_dwordx4 v[172:173], off
	s_mov_b32 m0, s69
	v_lshl_add_u64 v[172:173], s[80:81], 0, v[142:143]
	global_load_lds_dwordx4 v[172:173], off
	s_add_i32 m0, s69, 0x2000
	v_lshl_add_u64 v[172:173], s[80:81], 0, v[146:147]
	global_load_lds_dwordx4 v[172:173], off
	s_mov_b32 m0, s23
	v_lshl_add_u64 v[172:173], v[228:229], 0, s[10:11]
	global_load_lds_dwordx4 v[172:173], off
	s_mov_b32 m0, s24
	v_lshl_add_u64 v[172:173], v[230:231], 0, s[10:11]
	global_load_lds_dwordx4 v[172:173], off
	s_waitcnt vmcnt(8) lgkmcnt(0)
	s_barrier
	s_setprio 1
	v_mfma_f32_16x16x32_bf16 v[60:63], v[128:131], v[194:197], v[60:63]
	v_mfma_f32_16x16x32_bf16 v[60:63], v[132:135], v[198:201], v[60:63]
	v_mfma_f32_16x16x32_bf16 v[56:59], v[136:139], v[194:197], v[56:59]
	v_mfma_f32_16x16x32_bf16 v[56:59], v[160:163], v[198:201], v[56:59]
	v_mfma_f32_16x16x32_bf16 v[44:47], v[128:131], v[202:205], v[44:47]
	v_mfma_f32_16x16x32_bf16 v[44:47], v[132:135], v[206:209], v[44:47]
	v_mfma_f32_16x16x32_bf16 v[40:43], v[136:139], v[202:205], v[40:43]
	v_mfma_f32_16x16x32_bf16 v[40:43], v[160:163], v[206:209], v[40:43]
	v_mfma_f32_16x16x32_bf16 v[28:31], v[128:131], v[210:213], v[28:31]
	v_mfma_f32_16x16x32_bf16 v[28:31], v[132:135], v[214:217], v[28:31]
	v_mfma_f32_16x16x32_bf16 v[24:27], v[136:139], v[210:213], v[24:27]
	v_mfma_f32_16x16x32_bf16 v[24:27], v[160:163], v[214:217], v[24:27]
	v_mfma_f32_16x16x32_bf16 v[12:15], v[128:131], v[218:221], v[12:15]
	v_mfma_f32_16x16x32_bf16 v[12:15], v[132:135], v[222:225], v[12:15]
	v_mfma_f32_16x16x32_bf16 v[8:11], v[136:139], v[218:221], v[8:11]
	v_mfma_f32_16x16x32_bf16 v[8:11], v[160:163], v[222:225], v[8:11]
	v_mfma_f32_16x16x32_bf16 v[52:55], v[164:167], v[194:197], v[52:55]
	v_mfma_f32_16x16x32_bf16 v[52:55], v[168:171], v[198:201], v[52:55]
	v_mfma_f32_16x16x32_bf16 v[48:51], v[186:189], v[194:197], v[48:51]
	v_mfma_f32_16x16x32_bf16 v[48:51], v[190:193], v[198:201], v[48:51]
	v_mfma_f32_16x16x32_bf16 v[36:39], v[164:167], v[202:205], v[36:39]
	v_mfma_f32_16x16x32_bf16 v[36:39], v[168:171], v[206:209], v[36:39]
	v_mfma_f32_16x16x32_bf16 v[32:35], v[186:189], v[202:205], v[32:35]
	v_mfma_f32_16x16x32_bf16 v[32:35], v[190:193], v[206:209], v[32:35]
	v_mfma_f32_16x16x32_bf16 v[20:23], v[164:167], v[210:213], v[20:23]
	v_mfma_f32_16x16x32_bf16 v[20:23], v[168:171], v[214:217], v[20:23]
	v_mfma_f32_16x16x32_bf16 v[16:19], v[186:189], v[210:213], v[16:19]
	v_mfma_f32_16x16x32_bf16 v[16:19], v[190:193], v[214:217], v[16:19]
	v_mfma_f32_16x16x32_bf16 v[4:7], v[164:167], v[218:221], v[4:7]
	v_mfma_f32_16x16x32_bf16 v[4:7], v[168:171], v[222:225], v[4:7]
	s_setprio 3
	s_barrier
	v_mfma_f32_16x16x32_bf16 v[0:3], v[186:189], v[218:221], v[0:3]
	v_mfma_f32_16x16x32_bf16 v[0:3], v[190:193], v[222:225], v[0:3]
	s_setprio 0
	s_add_i32 s68, s68, 2
	s_add_u32 s78, s78, 0x100
	s_addc_u32 s79, s79, 0
	s_add_u32 s66, s66, 0x100
	s_addc_u32 s67, s67, 0
	s_cmp_gt_u32 s68, 13
	s_cbranch_scc0 .LBB0_1760
	s_and_b64 vcc, exec, s[44:45]
	s_cbranch_vccz .LBB0_1763
	s_barrier

.LBB0_2036:
	s_ashr_i32 s53, s52, 31
	s_lshl_b64 s[54:55], s[52:53], 19
	s_add_u32 s58, s42, s54
	s_addc_u32 s59, s43, s55
	s_and_b64 s[54:55], s[6:7], exec
	s_cselect_b32 s53, s59, s77
	s_cselect_b32 s54, s58, s76
	s_ashr_i32 s51, s50, 31
	s_lshl_b64 s[56:57], s[50:51], 19
	s_add_u32 s72, s3, s56
	s_addc_u32 s73, s14, s57
	s_and_b64 s[56:57], s[6:7], exec
	s_cselect_b32 s51, s73, s79
	s_cselect_b32 s55, s72, s78
	s_add_u32 s76, s76, 0x40080
	s_addc_u32 s77, s77, 0
	s_add_u32 s56, s78, 0x100
	v_mov_b32_e32 v0, 0
	s_addc_u32 s57, s79, 0
	s_mov_b32 s66, -2
	ds_read_b128 v[120:123], v245
	ds_read_b128 v[124:127], v245 offset:1024
	ds_read_b128 v[128:131], v245 offset:2048
	ds_read_b128 v[132:135], v245 offset:3072
	ds_read_b128 v[144:147], v246
	ds_read_b128 v[148:151], v246 offset:1024
	ds_read_b128 v[152:155], v246 offset:2048
	ds_read_b128 v[156:159], v246 offset:3072
	s_add_u32 s67, s76, 0xfffc0080
	s_addc_u32 s68, s77, -1
	s_cmp_eq_u32 s66, 12
	s_cselect_b32 s81, s53, s68
	s_cselect_b32 s80, s54, s67
	s_cselect_b32 s79, s51, s57
	s_cselect_b32 s78, s55, s56
	v_lshl_add_u64 v[204:205], s[76:77], 0, v[200:201]
	s_add_i32 m0, s16, 0xc000
	ds_read_b128 v[160:163], v247
	ds_read_b128 v[164:167], v247 offset:1024
	ds_read_b128 v[168:171], v247 offset:2048
	ds_read_b128 v[172:175], v247 offset:3072
	ds_read_b128 v[176:179], v247 offset:4096
	ds_read_b128 v[180:183], v247 offset:5120
	ds_read_b128 v[184:187], v247 offset:6144
	ds_read_b128 v[188:191], v247 offset:7168
	global_load_lds_dwordx4 v[204:205], off
	s_add_i32 m0, s16, 0xe000
	v_lshl_add_u64 v[204:205], s[76:77], 0, v[202:203]
	global_load_lds_dwordx4 v[204:205], off
	s_waitcnt vmcnt(8) lgkmcnt(0)
	s_barrier
	s_setprio 1
	v_mfma_f32_16x16x32_bf16 v[140:143], v[120:123], v[160:163], 0
	v_mfma_f32_16x16x32_bf16 v[140:143], v[124:127], v[164:167], v[140:143]
	v_mfma_f32_16x16x32_bf16 v[136:139], v[128:131], v[160:163], 0
	v_mfma_f32_16x16x32_bf16 v[136:139], v[132:135], v[164:167], v[136:139]
	v_mfma_f32_16x16x32_bf16 v[108:111], v[120:123], v[168:171], 0
	v_mfma_f32_16x16x32_bf16 v[108:111], v[124:127], v[172:175], v[108:111]
	v_mfma_f32_16x16x32_bf16 v[104:107], v[128:131], v[168:171], 0
	v_mfma_f32_16x16x32_bf16 v[104:107], v[132:135], v[172:175], v[104:107]
	v_mfma_f32_16x16x32_bf16 v[92:95], v[120:123], v[176:179], 0
	v_mfma_f32_16x16x32_bf16 v[92:95], v[124:127], v[180:183], v[92:95]
	v_mfma_f32_16x16x32_bf16 v[88:91], v[128:131], v[176:179], 0
	v_mfma_f32_16x16x32_bf16 v[88:91], v[132:135], v[180:183], v[88:91]
	v_mfma_f32_16x16x32_bf16 v[76:79], v[120:123], v[184:187], 0
	v_mfma_f32_16x16x32_bf16 v[76:79], v[124:127], v[188:191], v[76:79]
	v_mfma_f32_16x16x32_bf16 v[72:75], v[128:131], v[184:187], 0
	v_mfma_f32_16x16x32_bf16 v[72:75], v[132:135], v[188:191], v[72:75]
	v_mfma_f32_16x16x32_bf16 v[116:119], v[144:147], v[160:163], 0
	v_mfma_f32_16x16x32_bf16 v[116:119], v[148:151], v[164:167], v[116:119]
	v_mfma_f32_16x16x32_bf16 v[112:115], v[152:155], v[160:163], 0
	v_mfma_f32_16x16x32_bf16 v[112:115], v[156:159], v[164:167], v[112:115]
	v_mfma_f32_16x16x32_bf16 v[100:103], v[144:147], v[168:171], 0
	v_mfma_f32_16x16x32_bf16 v[100:103], v[148:151], v[172:175], v[100:103]
	v_mfma_f32_16x16x32_bf16 v[96:99], v[152:155], v[168:171], 0
	v_mfma_f32_16x16x32_bf16 v[96:99], v[156:159], v[172:175], v[96:99]
	v_mfma_f32_16x16x32_bf16 v[84:87], v[144:147], v[176:179], 0
	v_mfma_f32_16x16x32_bf16 v[84:87], v[148:151], v[180:183], v[84:87]
	v_mfma_f32_16x16x32_bf16 v[80:83], v[152:155], v[176:179], 0
	v_mfma_f32_16x16x32_bf16 v[80:83], v[156:159], v[180:183], v[80:83]
	v_mfma_f32_16x16x32_bf16 v[68:71], v[144:147], v[184:187], 0
	v_mfma_f32_16x16x32_bf16 v[68:71], v[148:151], v[188:191], v[68:71]
	s_setprio 3
	s_barrier
	v_mfma_f32_16x16x32_bf16 v[64:67], v[152:155], v[184:187], 0
	v_mfma_f32_16x16x32_bf16 v[64:67], v[156:159], v[188:191], v[64:67]
	s_setprio 0
	s_add_i32 s67, s26, s15
	v_lshl_add_u64 v[204:205], s[78:79], 0, v[194:195]
	s_mov_b32 m0, s67
	ds_read_b128 v[160:163], v247 offset:16384
	ds_read_b128 v[164:167], v247 offset:17408
	ds_read_b128 v[168:171], v247 offset:18432
	ds_read_b128 v[172:175], v247 offset:19456
	ds_read_b128 v[176:179], v247 offset:20480
	ds_read_b128 v[180:183], v247 offset:21504
	ds_read_b128 v[184:187], v247 offset:22528
	ds_read_b128 v[188:191], v247 offset:23552
	global_load_lds_dwordx4 v[204:205], off
	s_add_i32 m0, s67, 0x2000
	s_add_u32 s68, s78, 0x40000
	v_lshl_add_u64 v[206:207], s[78:79], 0, v[198:199]
	s_addc_u32 s69, s79, 0
	s_add_i32 s67, s27, s15
	global_load_lds_dwordx4 v[206:207], off
	v_lshl_add_u64 v[208:209], s[68:69], 0, v[194:195]
	s_mov_b32 m0, s67
	global_load_lds_dwordx4 v[208:209], off
	s_add_i32 m0, s67, 0x2000
	v_lshl_add_u64 v[208:209], s[68:69], 0, v[198:199]
	global_load_lds_dwordx4 v[208:209], off
	s_mov_b32 m0, s16
	v_lshl_add_u64 v[208:209], s[80:81], 0, v[192:193]
	global_load_lds_dwordx4 v[208:209], off
	s_mov_b32 m0, s17
	v_lshl_add_u64 v[210:211], s[80:81], 0, v[196:197]
	global_load_lds_dwordx4 v[210:211], off
	s_waitcnt vmcnt(8) lgkmcnt(0)
	s_barrier
	s_setprio 1
	v_mfma_f32_16x16x32_bf16 v[60:63], v[120:123], v[160:163], 0
	v_mfma_f32_16x16x32_bf16 v[60:63], v[124:127], v[164:167], v[60:63]
	v_mfma_f32_16x16x32_bf16 v[56:59], v[128:131], v[160:163], 0
	v_mfma_f32_16x16x32_bf16 v[56:59], v[132:135], v[164:167], v[56:59]
	v_mfma_f32_16x16x32_bf16 v[44:47], v[120:123], v[168:171], 0
	v_mfma_f32_16x16x32_bf16 v[44:47], v[124:127], v[172:175], v[44:47]
	v_mfma_f32_16x16x32_bf16 v[40:43], v[128:131], v[168:171], 0
	v_mfma_f32_16x16x32_bf16 v[40:43], v[132:135], v[172:175], v[40:43]
	v_mfma_f32_16x16x32_bf16 v[28:31], v[120:123], v[176:179], 0
	v_mfma_f32_16x16x32_bf16 v[28:31], v[124:127], v[180:183], v[28:31]
	v_mfma_f32_16x16x32_bf16 v[24:27], v[128:131], v[176:179], 0
	v_mfma_f32_16x16x32_bf16 v[24:27], v[132:135], v[180:183], v[24:27]
	v_mfma_f32_16x16x32_bf16 v[12:15], v[120:123], v[184:187], 0
	v_mfma_f32_16x16x32_bf16 v[12:15], v[124:127], v[188:191], v[12:15]
	v_mfma_f32_16x16x32_bf16 v[8:11], v[128:131], v[184:187], 0
	v_mfma_f32_16x16x32_bf16 v[8:11], v[132:135], v[188:191], v[8:11]
	v_mfma_f32_16x16x32_bf16 v[52:55], v[144:147], v[160:163], 0
	v_mfma_f32_16x16x32_bf16 v[52:55], v[148:151], v[164:167], v[52:55]
	v_mfma_f32_16x16x32_bf16 v[48:51], v[152:155], v[160:163], 0
	v_mfma_f32_16x16x32_bf16 v[48:51], v[156:159], v[164:167], v[48:51]
	v_mfma_f32_16x16x32_bf16 v[36:39], v[144:147], v[168:171], 0
	v_mfma_f32_16x16x32_bf16 v[36:39], v[148:151], v[172:175], v[36:39]
	v_mfma_f32_16x16x32_bf16 v[32:35], v[152:155], v[168:171], 0
	v_mfma_f32_16x16x32_bf16 v[32:35], v[156:159], v[172:175], v[32:35]
	v_mfma_f32_16x16x32_bf16 v[20:23], v[144:147], v[176:179], 0
	v_mfma_f32_16x16x32_bf16 v[20:23], v[148:151], v[180:183], v[20:23]
	v_mfma_f32_16x16x32_bf16 v[16:19], v[152:155], v[176:179], 0
	v_mfma_f32_16x16x32_bf16 v[16:19], v[156:159], v[180:183], v[16:19]
	v_mfma_f32_16x16x32_bf16 v[4:7], v[144:147], v[184:187], 0
	v_mfma_f32_16x16x32_bf16 v[4:7], v[148:151], v[188:191], v[4:7]
	s_setprio 3
	s_barrier
	v_mfma_f32_16x16x32_bf16 v[0:3], v[152:155], v[184:187], 0
	v_mfma_f32_16x16x32_bf16 v[0:3], v[156:159], v[188:191], v[0:3]
	s_setprio 0
	s_add_i32 s67, 0, 0x18000
	s_add_i32 s75, 0, 0x1c000
	v_add_u32_e32 v132, s67, v243
	v_add_u32_e32 v156, s75, v243
	ds_read_b128 v[120:123], v132
	ds_read_b128 v[124:127], v132 offset:1024
	ds_read_b128 v[128:131], v132 offset:2048
	ds_read_b128 v[132:135], v132 offset:3072
	ds_read_b128 v[144:147], v156
	ds_read_b128 v[148:151], v156 offset:1024
	ds_read_b128 v[152:155], v156 offset:2048
	ds_read_b128 v[156:159], v156 offset:3072
	s_add_u32 s68, s80, 0x40000
	s_addc_u32 s69, s81, 0
	s_mov_b32 m0, s18
	v_lshl_add_u64 v[212:213], s[68:69], 0, v[192:193]
	ds_read_b128 v[160:163], v247 offset:32768
	ds_read_b128 v[164:167], v247 offset:33792
	ds_read_b128 v[168:171], v247 offset:34816
	ds_read_b128 v[172:175], v247 offset:35840
	ds_read_b128 v[176:179], v247 offset:36864
	ds_read_b128 v[180:183], v247 offset:37888
	ds_read_b128 v[184:187], v247 offset:38912
	ds_read_b128 v[188:191], v247 offset:39936
	global_load_lds_dwordx4 v[212:213], off
	s_mov_b32 m0, s19
	v_lshl_add_u64 v[212:213], s[68:69], 0, v[196:197]
	global_load_lds_dwordx4 v[212:213], off
	s_waitcnt vmcnt(8) lgkmcnt(0)
	s_barrier
	s_setprio 1
	v_mfma_f32_16x16x32_bf16 v[140:143], v[120:123], v[160:163], v[140:143]
	v_mfma_f32_16x16x32_bf16 v[140:143], v[124:127], v[164:167], v[140:143]
	v_mfma_f32_16x16x32_bf16 v[136:139], v[128:131], v[160:163], v[136:139]
	v_mfma_f32_16x16x32_bf16 v[136:139], v[132:135], v[164:167], v[136:139]
	v_mfma_f32_16x16x32_bf16 v[108:111], v[120:123], v[168:171], v[108:111]
	v_mfma_f32_16x16x32_bf16 v[108:111], v[124:127], v[172:175], v[108:111]
	v_mfma_f32_16x16x32_bf16 v[104:107], v[128:131], v[168:171], v[104:107]
	v_mfma_f32_16x16x32_bf16 v[104:107], v[132:135], v[172:175], v[104:107]
	v_mfma_f32_16x16x32_bf16 v[92:95], v[120:123], v[176:179], v[92:95]
	v_mfma_f32_16x16x32_bf16 v[92:95], v[124:127], v[180:183], v[92:95]
	v_mfma_f32_16x16x32_bf16 v[88:91], v[128:131], v[176:179], v[88:91]
	v_mfma_f32_16x16x32_bf16 v[88:91], v[132:135], v[180:183], v[88:91]
	v_mfma_f32_16x16x32_bf16 v[76:79], v[120:123], v[184:187], v[76:79]
	v_mfma_f32_16x16x32_bf16 v[76:79], v[124:127], v[188:191], v[76:79]
	v_mfma_f32_16x16x32_bf16 v[72:75], v[128:131], v[184:187], v[72:75]
	v_mfma_f32_16x16x32_bf16 v[72:75], v[132:135], v[188:191], v[72:75]
	v_mfma_f32_16x16x32_bf16 v[116:119], v[144:147], v[160:163], v[116:119]
	v_mfma_f32_16x16x32_bf16 v[116:119], v[148:151], v[164:167], v[116:119]
	v_mfma_f32_16x16x32_bf16 v[112:115], v[152:155], v[160:163], v[112:115]
	v_mfma_f32_16x16x32_bf16 v[112:115], v[156:159], v[164:167], v[112:115]
	v_mfma_f32_16x16x32_bf16 v[100:103], v[144:147], v[168:171], v[100:103]
	v_mfma_f32_16x16x32_bf16 v[100:103], v[148:151], v[172:175], v[100:103]
	v_mfma_f32_16x16x32_bf16 v[96:99], v[152:155], v[168:171], v[96:99]
	v_mfma_f32_16x16x32_bf16 v[96:99], v[156:159], v[172:175], v[96:99]
	v_mfma_f32_16x16x32_bf16 v[84:87], v[144:147], v[176:179], v[84:87]
	v_mfma_f32_16x16x32_bf16 v[84:87], v[148:151], v[180:183], v[84:87]
	v_mfma_f32_16x16x32_bf16 v[80:83], v[152:155], v[176:179], v[80:83]
	v_mfma_f32_16x16x32_bf16 v[80:83], v[156:159], v[180:183], v[80:83]
	v_mfma_f32_16x16x32_bf16 v[68:71], v[144:147], v[184:187], v[68:71]
	v_mfma_f32_16x16x32_bf16 v[68:71], v[148:151], v[188:191], v[68:71]
	s_setprio 3
	s_barrier
	v_mfma_f32_16x16x32_bf16 v[64:67], v[152:155], v[184:187], v[64:67]
	v_mfma_f32_16x16x32_bf16 v[64:67], v[156:159], v[188:191], v[64:67]
	s_setprio 0
	s_add_i32 s67, s67, s15
	v_lshl_add_u64 v[204:205], v[204:205], 0, s[46:47]
	s_mov_b32 m0, s67
	ds_read_b128 v[160:163], v247 offset:49152
	ds_read_b128 v[164:167], v247 offset:50176
	ds_read_b128 v[168:171], v247 offset:51200
	ds_read_b128 v[172:175], v247 offset:52224
	ds_read_b128 v[176:179], v247 offset:53248
	ds_read_b128 v[180:183], v247 offset:54272
	ds_read_b128 v[184:187], v247 offset:55296
	ds_read_b128 v[188:191], v247 offset:56320
	global_load_lds_dwordx4 v[204:205], off
	s_add_i32 m0, s67, 0x2000
	s_add_u32 s68, s78, 0x40080
	v_lshl_add_u64 v[204:205], v[206:207], 0, s[46:47]
	s_addc_u32 s69, s79, 0
	s_add_i32 s67, s75, s15
	global_load_lds_dwordx4 v[204:205], off
	s_mov_b32 m0, s67
	v_lshl_add_u64 v[204:205], s[68:69], 0, v[194:195]
	global_load_lds_dwordx4 v[204:205], off
	s_add_i32 m0, s67, 0x2000
	v_lshl_add_u64 v[204:205], s[68:69], 0, v[198:199]
	global_load_lds_dwordx4 v[204:205], off
	s_mov_b32 m0, s21
	v_lshl_add_u64 v[204:205], v[208:209], 0, s[46:47]
	global_load_lds_dwordx4 v[204:205], off
	s_mov_b32 m0, s22
	v_lshl_add_u64 v[204:205], v[210:211], 0, s[46:47]
	global_load_lds_dwordx4 v[204:205], off
	s_waitcnt vmcnt(8) lgkmcnt(0)
	s_barrier
	s_setprio 1
	v_mfma_f32_16x16x32_bf16 v[60:63], v[120:123], v[160:163], v[60:63]
	v_mfma_f32_16x16x32_bf16 v[60:63], v[124:127], v[164:167], v[60:63]
	v_mfma_f32_16x16x32_bf16 v[56:59], v[128:131], v[160:163], v[56:59]
	v_mfma_f32_16x16x32_bf16 v[56:59], v[132:135], v[164:167], v[56:59]
	v_mfma_f32_16x16x32_bf16 v[44:47], v[120:123], v[168:171], v[44:47]
	v_mfma_f32_16x16x32_bf16 v[44:47], v[124:127], v[172:175], v[44:47]
	v_mfma_f32_16x16x32_bf16 v[40:43], v[128:131], v[168:171], v[40:43]
	v_mfma_f32_16x16x32_bf16 v[40:43], v[132:135], v[172:175], v[40:43]
	v_mfma_f32_16x16x32_bf16 v[28:31], v[120:123], v[176:179], v[28:31]
	v_mfma_f32_16x16x32_bf16 v[28:31], v[124:127], v[180:183], v[28:31]
	v_mfma_f32_16x16x32_bf16 v[24:27], v[128:131], v[176:179], v[24:27]
	v_mfma_f32_16x16x32_bf16 v[24:27], v[132:135], v[180:183], v[24:27]
	v_mfma_f32_16x16x32_bf16 v[12:15], v[120:123], v[184:187], v[12:15]
	v_mfma_f32_16x16x32_bf16 v[12:15], v[124:127], v[188:191], v[12:15]
	v_mfma_f32_16x16x32_bf16 v[8:11], v[128:131], v[184:187], v[8:11]
	v_mfma_f32_16x16x32_bf16 v[8:11], v[132:135], v[188:191], v[8:11]
	v_mfma_f32_16x16x32_bf16 v[52:55], v[144:147], v[160:163], v[52:55]
	v_mfma_f32_16x16x32_bf16 v[52:55], v[148:151], v[164:167], v[52:55]
	v_mfma_f32_16x16x32_bf16 v[48:51], v[152:155], v[160:163], v[48:51]
	v_mfma_f32_16x16x32_bf16 v[48:51], v[156:159], v[164:167], v[48:51]
	v_mfma_f32_16x16x32_bf16 v[36:39], v[144:147], v[168:171], v[36:39]
	v_mfma_f32_16x16x32_bf16 v[36:39], v[148:151], v[172:175], v[36:39]
	v_mfma_f32_16x16x32_bf16 v[32:35], v[152:155], v[168:171], v[32:35]
	v_mfma_f32_16x16x32_bf16 v[32:35], v[156:159], v[172:175], v[32:35]
	v_mfma_f32_16x16x32_bf16 v[20:23], v[144:147], v[176:179], v[20:23]
	v_mfma_f32_16x16x32_bf16 v[20:23], v[148:151], v[180:183], v[20:23]
	v_mfma_f32_16x16x32_bf16 v[16:19], v[152:155], v[176:179], v[16:19]
	v_mfma_f32_16x16x32_bf16 v[16:19], v[156:159], v[180:183], v[16:19]
	v_mfma_f32_16x16x32_bf16 v[4:7], v[144:147], v[184:187], v[4:7]
	v_mfma_f32_16x16x32_bf16 v[4:7], v[148:151], v[188:191], v[4:7]
	s_setprio 3
	s_barrier
	v_mfma_f32_16x16x32_bf16 v[0:3], v[152:155], v[184:187], v[0:3]
	v_mfma_f32_16x16x32_bf16 v[0:3], v[156:159], v[188:191], v[0:3]
	s_setprio 0
	s_add_i32 s66, s66, 2
	s_add_u32 s76, s76, 0x100
	s_addc_u32 s77, s77, 0
	s_add_u32 s56, s56, 0x100
	s_addc_u32 s57, s57, 0
	s_cmp_gt_u32 s66, 13
.LBB0_2037:
	ds_read_b128 v[120:123], v245
	ds_read_b128 v[124:127], v245 offset:1024
	ds_read_b128 v[128:131], v245 offset:2048
	ds_read_b128 v[132:135], v245 offset:3072
	ds_read_b128 v[144:147], v246
	ds_read_b128 v[148:151], v246 offset:1024
	ds_read_b128 v[152:155], v246 offset:2048
	ds_read_b128 v[156:159], v246 offset:3072
	s_add_u32 s67, s76, 0xfffc0080
	s_addc_u32 s68, s77, -1
	s_cmp_eq_u32 s66, 12
	s_cselect_b32 s81, s53, s68
	s_cselect_b32 s80, s54, s67
	s_cselect_b32 s79, s51, s57
	s_cselect_b32 s78, s55, s56
	v_lshl_add_u64 v[204:205], s[76:77], 0, v[200:201]
	s_add_i32 m0, s16, 0xc000
	ds_read_b128 v[160:163], v247
	ds_read_b128 v[164:167], v247 offset:1024
	ds_read_b128 v[168:171], v247 offset:2048
	ds_read_b128 v[172:175], v247 offset:3072
	ds_read_b128 v[176:179], v247 offset:4096
	ds_read_b128 v[180:183], v247 offset:5120
	ds_read_b128 v[184:187], v247 offset:6144
	ds_read_b128 v[188:191], v247 offset:7168
	global_load_lds_dwordx4 v[204:205], off
	s_add_i32 m0, s16, 0xe000
	v_lshl_add_u64 v[204:205], s[76:77], 0, v[202:203]
	global_load_lds_dwordx4 v[204:205], off
	s_waitcnt vmcnt(8) lgkmcnt(0)
	s_barrier
	s_setprio 1
	v_mfma_f32_16x16x32_bf16 v[140:143], v[120:123], v[160:163], v[140:143]
	v_mfma_f32_16x16x32_bf16 v[140:143], v[124:127], v[164:167], v[140:143]
	v_mfma_f32_16x16x32_bf16 v[136:139], v[128:131], v[160:163], v[136:139]
	v_mfma_f32_16x16x32_bf16 v[136:139], v[132:135], v[164:167], v[136:139]
	v_mfma_f32_16x16x32_bf16 v[108:111], v[120:123], v[168:171], v[108:111]
	v_mfma_f32_16x16x32_bf16 v[108:111], v[124:127], v[172:175], v[108:111]
	v_mfma_f32_16x16x32_bf16 v[104:107], v[128:131], v[168:171], v[104:107]
	v_mfma_f32_16x16x32_bf16 v[104:107], v[132:135], v[172:175], v[104:107]
	v_mfma_f32_16x16x32_bf16 v[92:95], v[120:123], v[176:179], v[92:95]
	v_mfma_f32_16x16x32_bf16 v[92:95], v[124:127], v[180:183], v[92:95]
	v_mfma_f32_16x16x32_bf16 v[88:91], v[128:131], v[176:179], v[88:91]
	v_mfma_f32_16x16x32_bf16 v[88:91], v[132:135], v[180:183], v[88:91]
	v_mfma_f32_16x16x32_bf16 v[76:79], v[120:123], v[184:187], v[76:79]
	v_mfma_f32_16x16x32_bf16 v[76:79], v[124:127], v[188:191], v[76:79]
	v_mfma_f32_16x16x32_bf16 v[72:75], v[128:131], v[184:187], v[72:75]
	v_mfma_f32_16x16x32_bf16 v[72:75], v[132:135], v[188:191], v[72:75]
	v_mfma_f32_16x16x32_bf16 v[116:119], v[144:147], v[160:163], v[116:119]
	v_mfma_f32_16x16x32_bf16 v[116:119], v[148:151], v[164:167], v[116:119]
	v_mfma_f32_16x16x32_bf16 v[112:115], v[152:155], v[160:163], v[112:115]
	v_mfma_f32_16x16x32_bf16 v[112:115], v[156:159], v[164:167], v[112:115]
	v_mfma_f32_16x16x32_bf16 v[100:103], v[144:147], v[168:171], v[100:103]
	v_mfma_f32_16x16x32_bf16 v[100:103], v[148:151], v[172:175], v[100:103]
	v_mfma_f32_16x16x32_bf16 v[96:99], v[152:155], v[168:171], v[96:99]
	v_mfma_f32_16x16x32_bf16 v[96:99], v[156:159], v[172:175], v[96:99]
	v_mfma_f32_16x16x32_bf16 v[84:87], v[144:147], v[176:179], v[84:87]
	v_mfma_f32_16x16x32_bf16 v[84:87], v[148:151], v[180:183], v[84:87]
	v_mfma_f32_16x16x32_bf16 v[80:83], v[152:155], v[176:179], v[80:83]
	v_mfma_f32_16x16x32_bf16 v[80:83], v[156:159], v[180:183], v[80:83]
	v_mfma_f32_16x16x32_bf16 v[68:71], v[144:147], v[184:187], v[68:71]
	v_mfma_f32_16x16x32_bf16 v[68:71], v[148:151], v[188:191], v[68:71]
	s_setprio 3
	s_barrier
	v_mfma_f32_16x16x32_bf16 v[64:67], v[152:155], v[184:187], v[64:67]
	v_mfma_f32_16x16x32_bf16 v[64:67], v[156:159], v[188:191], v[64:67]
	s_setprio 0
	s_add_i32 s67, s26, s15
	v_lshl_add_u64 v[204:205], s[78:79], 0, v[194:195]
	s_mov_b32 m0, s67
	ds_read_b128 v[160:163], v247 offset:16384
	ds_read_b128 v[164:167], v247 offset:17408
	ds_read_b128 v[168:171], v247 offset:18432
	ds_read_b128 v[172:175], v247 offset:19456
	ds_read_b128 v[176:179], v247 offset:20480
	ds_read_b128 v[180:183], v247 offset:21504
	ds_read_b128 v[184:187], v247 offset:22528
	ds_read_b128 v[188:191], v247 offset:23552
	global_load_lds_dwordx4 v[204:205], off
	s_add_i32 m0, s67, 0x2000
	s_add_u32 s68, s78, 0x40000
	v_lshl_add_u64 v[206:207], s[78:79], 0, v[198:199]
	s_addc_u32 s69, s79, 0
	s_add_i32 s67, s27, s15
	global_load_lds_dwordx4 v[206:207], off
	v_lshl_add_u64 v[208:209], s[68:69], 0, v[194:195]
	s_mov_b32 m0, s67
	global_load_lds_dwordx4 v[208:209], off
	s_add_i32 m0, s67, 0x2000
	v_lshl_add_u64 v[208:209], s[68:69], 0, v[198:199]
	global_load_lds_dwordx4 v[208:209], off
	s_mov_b32 m0, s16
	v_lshl_add_u64 v[208:209], s[80:81], 0, v[192:193]
	global_load_lds_dwordx4 v[208:209], off
	s_mov_b32 m0, s17
	v_lshl_add_u64 v[210:211], s[80:81], 0, v[196:197]
	global_load_lds_dwordx4 v[210:211], off
	s_waitcnt vmcnt(8) lgkmcnt(0)
	s_barrier
	s_setprio 1
	v_mfma_f32_16x16x32_bf16 v[60:63], v[120:123], v[160:163], v[60:63]
	v_mfma_f32_16x16x32_bf16 v[60:63], v[124:127], v[164:167], v[60:63]
	v_mfma_f32_16x16x32_bf16 v[56:59], v[128:131], v[160:163], v[56:59]
	v_mfma_f32_16x16x32_bf16 v[56:59], v[132:135], v[164:167], v[56:59]
	v_mfma_f32_16x16x32_bf16 v[44:47], v[120:123], v[168:171], v[44:47]
	v_mfma_f32_16x16x32_bf16 v[44:47], v[124:127], v[172:175], v[44:47]
	v_mfma_f32_16x16x32_bf16 v[40:43], v[128:131], v[168:171], v[40:43]
	v_mfma_f32_16x16x32_bf16 v[40:43], v[132:135], v[172:175], v[40:43]
	v_mfma_f32_16x16x32_bf16 v[28:31], v[120:123], v[176:179], v[28:31]
	v_mfma_f32_16x16x32_bf16 v[28:31], v[124:127], v[180:183], v[28:31]
	v_mfma_f32_16x16x32_bf16 v[24:27], v[128:131], v[176:179], v[24:27]
	v_mfma_f32_16x16x32_bf16 v[24:27], v[132:135], v[180:183], v[24:27]
	v_mfma_f32_16x16x32_bf16 v[12:15], v[120:123], v[184:187], v[12:15]
	v_mfma_f32_16x16x32_bf16 v[12:15], v[124:127], v[188:191], v[12:15]
	v_mfma_f32_16x16x32_bf16 v[8:11], v[128:131], v[184:187], v[8:11]
	v_mfma_f32_16x16x32_bf16 v[8:11], v[132:135], v[188:191], v[8:11]
	v_mfma_f32_16x16x32_bf16 v[52:55], v[144:147], v[160:163], v[52:55]
	v_mfma_f32_16x16x32_bf16 v[52:55], v[148:151], v[164:167], v[52:55]
	v_mfma_f32_16x16x32_bf16 v[48:51], v[152:155], v[160:163], v[48:51]
	v_mfma_f32_16x16x32_bf16 v[48:51], v[156:159], v[164:167], v[48:51]
	v_mfma_f32_16x16x32_bf16 v[36:39], v[144:147], v[168:171], v[36:39]
	v_mfma_f32_16x16x32_bf16 v[36:39], v[148:151], v[172:175], v[36:39]
	v_mfma_f32_16x16x32_bf16 v[32:35], v[152:155], v[168:171], v[32:35]
	v_mfma_f32_16x16x32_bf16 v[32:35], v[156:159], v[172:175], v[32:35]
	v_mfma_f32_16x16x32_bf16 v[20:23], v[144:147], v[176:179], v[20:23]
	v_mfma_f32_16x16x32_bf16 v[20:23], v[148:151], v[180:183], v[20:23]
	v_mfma_f32_16x16x32_bf16 v[16:19], v[152:155], v[176:179], v[16:19]
	v_mfma_f32_16x16x32_bf16 v[16:19], v[156:159], v[180:183], v[16:19]
	v_mfma_f32_16x16x32_bf16 v[4:7], v[144:147], v[184:187], v[4:7]
	v_mfma_f32_16x16x32_bf16 v[4:7], v[148:151], v[188:191], v[4:7]
	s_setprio 3
	s_barrier
	v_mfma_f32_16x16x32_bf16 v[0:3], v[152:155], v[184:187], v[0:3]
	v_mfma_f32_16x16x32_bf16 v[0:3], v[156:159], v[188:191], v[0:3]
	s_setprio 0
	s_add_i32 s67, 0, 0x18000
	s_add_i32 s75, 0, 0x1c000
	v_add_u32_e32 v132, s67, v243
	v_add_u32_e32 v156, s75, v243
	ds_read_b128 v[120:123], v132
	ds_read_b128 v[124:127], v132 offset:1024
	ds_read_b128 v[128:131], v132 offset:2048
	ds_read_b128 v[132:135], v132 offset:3072
	ds_read_b128 v[144:147], v156
	ds_read_b128 v[148:151], v156 offset:1024
	ds_read_b128 v[152:155], v156 offset:2048
	ds_read_b128 v[156:159], v156 offset:3072
	s_add_u32 s68, s80, 0x40000
	s_addc_u32 s69, s81, 0
	s_mov_b32 m0, s18
	v_lshl_add_u64 v[212:213], s[68:69], 0, v[192:193]
	ds_read_b128 v[160:163], v247 offset:32768
	ds_read_b128 v[164:167], v247 offset:33792
	ds_read_b128 v[168:171], v247 offset:34816
	ds_read_b128 v[172:175], v247 offset:35840
	ds_read_b128 v[176:179], v247 offset:36864
	ds_read_b128 v[180:183], v247 offset:37888
	ds_read_b128 v[184:187], v247 offset:38912
	ds_read_b128 v[188:191], v247 offset:39936
	global_load_lds_dwordx4 v[212:213], off
	s_mov_b32 m0, s19
	v_lshl_add_u64 v[212:213], s[68:69], 0, v[196:197]
	global_load_lds_dwordx4 v[212:213], off
	s_waitcnt vmcnt(8) lgkmcnt(0)
	s_barrier
	s_setprio 1
	v_mfma_f32_16x16x32_bf16 v[140:143], v[120:123], v[160:163], v[140:143]
	v_mfma_f32_16x16x32_bf16 v[140:143], v[124:127], v[164:167], v[140:143]
	v_mfma_f32_16x16x32_bf16 v[136:139], v[128:131], v[160:163], v[136:139]
	v_mfma_f32_16x16x32_bf16 v[136:139], v[132:135], v[164:167], v[136:139]
	v_mfma_f32_16x16x32_bf16 v[108:111], v[120:123], v[168:171], v[108:111]
	v_mfma_f32_16x16x32_bf16 v[108:111], v[124:127], v[172:175], v[108:111]
	v_mfma_f32_16x16x32_bf16 v[104:107], v[128:131], v[168:171], v[104:107]
	v_mfma_f32_16x16x32_bf16 v[104:107], v[132:135], v[172:175], v[104:107]
	v_mfma_f32_16x16x32_bf16 v[92:95], v[120:123], v[176:179], v[92:95]
	v_mfma_f32_16x16x32_bf16 v[92:95], v[124:127], v[180:183], v[92:95]
	v_mfma_f32_16x16x32_bf16 v[88:91], v[128:131], v[176:179], v[88:91]
	v_mfma_f32_16x16x32_bf16 v[88:91], v[132:135], v[180:183], v[88:91]
	v_mfma_f32_16x16x32_bf16 v[76:79], v[120:123], v[184:187], v[76:79]
	v_mfma_f32_16x16x32_bf16 v[76:79], v[124:127], v[188:191], v[76:79]
	v_mfma_f32_16x16x32_bf16 v[72:75], v[128:131], v[184:187], v[72:75]
	v_mfma_f32_16x16x32_bf16 v[72:75], v[132:135], v[188:191], v[72:75]
	v_mfma_f32_16x16x32_bf16 v[116:119], v[144:147], v[160:163], v[116:119]
	v_mfma_f32_16x16x32_bf16 v[116:119], v[148:151], v[164:167], v[116:119]
	v_mfma_f32_16x16x32_bf16 v[112:115], v[152:155], v[160:163], v[112:115]
	v_mfma_f32_16x16x32_bf16 v[112:115], v[156:159], v[164:167], v[112:115]
	v_mfma_f32_16x16x32_bf16 v[100:103], v[144:147], v[168:171], v[100:103]
	v_mfma_f32_16x16x32_bf16 v[100:103], v[148:151], v[172:175], v[100:103]
	v_mfma_f32_16x16x32_bf16 v[96:99], v[152:155], v[168:171], v[96:99]
	v_mfma_f32_16x16x32_bf16 v[96:99], v[156:159], v[172:175], v[96:99]
	v_mfma_f32_16x16x32_bf16 v[84:87], v[144:147], v[176:179], v[84:87]
	v_mfma_f32_16x16x32_bf16 v[84:87], v[148:151], v[180:183], v[84:87]
	v_mfma_f32_16x16x32_bf16 v[80:83], v[152:155], v[176:179], v[80:83]
	v_mfma_f32_16x16x32_bf16 v[80:83], v[156:159], v[180:183], v[80:83]
	v_mfma_f32_16x16x32_bf16 v[68:71], v[144:147], v[184:187], v[68:71]
	v_mfma_f32_16x16x32_bf16 v[68:71], v[148:151], v[188:191], v[68:71]
	s_setprio 3
	s_barrier
	v_mfma_f32_16x16x32_bf16 v[64:67], v[152:155], v[184:187], v[64:67]
	v_mfma_f32_16x16x32_bf16 v[64:67], v[156:159], v[188:191], v[64:67]
	s_setprio 0
	s_add_i32 s67, s67, s15
	v_lshl_add_u64 v[204:205], v[204:205], 0, s[46:47]
	s_mov_b32 m0, s67
	ds_read_b128 v[160:163], v247 offset:49152
	ds_read_b128 v[164:167], v247 offset:50176
	ds_read_b128 v[168:171], v247 offset:51200
	ds_read_b128 v[172:175], v247 offset:52224
	ds_read_b128 v[176:179], v247 offset:53248
	ds_read_b128 v[180:183], v247 offset:54272
	ds_read_b128 v[184:187], v247 offset:55296
	ds_read_b128 v[188:191], v247 offset:56320
	global_load_lds_dwordx4 v[204:205], off
	s_add_i32 m0, s67, 0x2000
	s_add_u32 s68, s78, 0x40080
	v_lshl_add_u64 v[204:205], v[206:207], 0, s[46:47]
	s_addc_u32 s69, s79, 0
	s_add_i32 s67, s75, s15
	global_load_lds_dwordx4 v[204:205], off
	s_mov_b32 m0, s67
	v_lshl_add_u64 v[204:205], s[68:69], 0, v[194:195]
	global_load_lds_dwordx4 v[204:205], off
	s_add_i32 m0, s67, 0x2000
	v_lshl_add_u64 v[204:205], s[68:69], 0, v[198:199]
	global_load_lds_dwordx4 v[204:205], off
	s_mov_b32 m0, s21
	v_lshl_add_u64 v[204:205], v[208:209], 0, s[46:47]
	global_load_lds_dwordx4 v[204:205], off
	s_mov_b32 m0, s22
	v_lshl_add_u64 v[204:205], v[210:211], 0, s[46:47]
	global_load_lds_dwordx4 v[204:205], off
	s_waitcnt vmcnt(8) lgkmcnt(0)
	s_barrier
	s_setprio 1
	v_mfma_f32_16x16x32_bf16 v[60:63], v[120:123], v[160:163], v[60:63]
	v_mfma_f32_16x16x32_bf16 v[60:63], v[124:127], v[164:167], v[60:63]
	v_mfma_f32_16x16x32_bf16 v[56:59], v[128:131], v[160:163], v[56:59]
	v_mfma_f32_16x16x32_bf16 v[56:59], v[132:135], v[164:167], v[56:59]
	v_mfma_f32_16x16x32_bf16 v[44:47], v[120:123], v[168:171], v[44:47]
	v_mfma_f32_16x16x32_bf16 v[44:47], v[124:127], v[172:175], v[44:47]
	v_mfma_f32_16x16x32_bf16 v[40:43], v[128:131], v[168:171], v[40:43]
	v_mfma_f32_16x16x32_bf16 v[40:43], v[132:135], v[172:175], v[40:43]
	v_mfma_f32_16x16x32_bf16 v[28:31], v[120:123], v[176:179], v[28:31]
	v_mfma_f32_16x16x32_bf16 v[28:31], v[124:127], v[180:183], v[28:31]
	v_mfma_f32_16x16x32_bf16 v[24:27], v[128:131], v[176:179], v[24:27]
	v_mfma_f32_16x16x32_bf16 v[24:27], v[132:135], v[180:183], v[24:27]
	v_mfma_f32_16x16x32_bf16 v[12:15], v[120:123], v[184:187], v[12:15]
	v_mfma_f32_16x16x32_bf16 v[12:15], v[124:127], v[188:191], v[12:15]
	v_mfma_f32_16x16x32_bf16 v[8:11], v[128:131], v[184:187], v[8:11]
	v_mfma_f32_16x16x32_bf16 v[8:11], v[132:135], v[188:191], v[8:11]
	v_mfma_f32_16x16x32_bf16 v[52:55], v[144:147], v[160:163], v[52:55]
	v_mfma_f32_16x16x32_bf16 v[52:55], v[148:151], v[164:167], v[52:55]
	v_mfma_f32_16x16x32_bf16 v[48:51], v[152:155], v[160:163], v[48:51]
	v_mfma_f32_16x16x32_bf16 v[48:51], v[156:159], v[164:167], v[48:51]
	v_mfma_f32_16x16x32_bf16 v[36:39], v[144:147], v[168:171], v[36:39]
	v_mfma_f32_16x16x32_bf16 v[36:39], v[148:151], v[172:175], v[36:39]
	v_mfma_f32_16x16x32_bf16 v[32:35], v[152:155], v[168:171], v[32:35]
	v_mfma_f32_16x16x32_bf16 v[32:35], v[156:159], v[172:175], v[32:35]
	v_mfma_f32_16x16x32_bf16 v[20:23], v[144:147], v[176:179], v[20:23]
	v_mfma_f32_16x16x32_bf16 v[20:23], v[148:151], v[180:183], v[20:23]
	v_mfma_f32_16x16x32_bf16 v[16:19], v[152:155], v[176:179], v[16:19]
	v_mfma_f32_16x16x32_bf16 v[16:19], v[156:159], v[180:183], v[16:19]
	v_mfma_f32_16x16x32_bf16 v[4:7], v[144:147], v[184:187], v[4:7]
	v_mfma_f32_16x16x32_bf16 v[4:7], v[148:151], v[188:191], v[4:7]
	s_setprio 3
	s_barrier
	v_mfma_f32_16x16x32_bf16 v[0:3], v[152:155], v[184:187], v[0:3]
	v_mfma_f32_16x16x32_bf16 v[0:3], v[156:159], v[188:191], v[0:3]
	s_setprio 0
	s_add_i32 s66, s66, 2
	s_add_u32 s76, s76, 0x100
	s_addc_u32 s77, s77, 0
	s_add_u32 s56, s56, 0x100
	s_addc_u32 s57, s57, 0
	s_cmp_gt_u32 s66, 13
	s_cbranch_scc0 .LBB0_2037
	s_and_b64 vcc, exec, s[48:49]
	s_cbranch_vccz .LBB0_2040
	s_barrier

.LBB0_2191:
	s_ashr_i32 s47, s46, 31
	s_lshl_b64 s[48:49], s[46:47], 19
	s_add_u32 s48, s12, s48
	s_addc_u32 s49, s13, s49
	s_and_b64 s[50:51], s[4:5], exec
	s_cselect_b32 s47, s49, s59
	s_cselect_b32 s53, s48, s58
	s_ashr_i32 s45, s44, 31
	s_lshl_b64 s[50:51], s[44:45], 19
	s_add_u32 s50, s14, s50
	s_addc_u32 s51, s15, s51
	s_and_b64 s[66:67], s[4:5], exec
	s_cselect_b32 s45, s51, s73
	s_cselect_b32 s66, s50, s72
	s_add_u32 s58, s58, 0x40080
	s_addc_u32 s59, s59, 0
	s_add_u32 s67, s72, 0x100
	v_mov_b32_e32 v0, 0
	s_addc_u32 s68, s73, 0
	s_mov_b32 s69, -2
	s_waitcnt lgkmcnt(0)
	ds_read_b128 v[146:149], v174
	ds_read_b128 v[150:153], v174 offset:1024
	ds_read_b128 v[154:157], v174 offset:2048
	ds_read_b128 v[158:161], v174 offset:3072
	ds_read_b128 v[162:165], v175
	ds_read_b128 v[178:181], v175 offset:1024
	ds_read_b128 v[182:185], v175 offset:2048
	ds_read_b128 v[186:189], v175 offset:3072
	s_add_u32 s70, s58, 0xfffc0080
	s_addc_u32 s71, s59, -1
	s_cmp_eq_u32 s69, 12
	s_cselect_b32 s73, s47, s71
	s_cselect_b32 s72, s53, s70
	s_cselect_b32 s71, s45, s68
	s_cselect_b32 s70, s66, s67
	v_lshl_add_u64 v[166:167], s[58:59], 0, v[136:137]
	s_add_i32 m0, s17, 0xc000
	ds_read_b128 v[190:193], v176
	ds_read_b128 v[194:197], v176 offset:1024
	ds_read_b128 v[198:201], v176 offset:2048
	ds_read_b128 v[202:205], v176 offset:3072
	ds_read_b128 v[206:209], v176 offset:4096
	ds_read_b128 v[210:213], v176 offset:5120
	ds_read_b128 v[214:217], v176 offset:6144
	ds_read_b128 v[218:221], v176 offset:7168
	global_load_lds_dwordx4 v[166:167], off
	s_add_i32 m0, s17, 0xe000
	v_lshl_add_u64 v[166:167], s[58:59], 0, v[140:141]
	global_load_lds_dwordx4 v[166:167], off
	s_waitcnt vmcnt(8) lgkmcnt(0)
	s_barrier
	s_setprio 1
	v_mfma_f32_16x16x32_bf16 v[124:127], v[146:149], v[190:193], 0
	v_mfma_f32_16x16x32_bf16 v[124:127], v[150:153], v[194:197], v[124:127]
	v_mfma_f32_16x16x32_bf16 v[116:119], v[154:157], v[190:193], 0
	v_mfma_f32_16x16x32_bf16 v[116:119], v[158:161], v[194:197], v[116:119]
	v_mfma_f32_16x16x32_bf16 v[108:111], v[146:149], v[198:201], 0
	v_mfma_f32_16x16x32_bf16 v[108:111], v[150:153], v[202:205], v[108:111]
	v_mfma_f32_16x16x32_bf16 v[100:103], v[154:157], v[198:201], 0
	v_mfma_f32_16x16x32_bf16 v[100:103], v[158:161], v[202:205], v[100:103]
	v_mfma_f32_16x16x32_bf16 v[92:95], v[146:149], v[206:209], 0
	v_mfma_f32_16x16x32_bf16 v[92:95], v[150:153], v[210:213], v[92:95]
	v_mfma_f32_16x16x32_bf16 v[84:87], v[154:157], v[206:209], 0
	v_mfma_f32_16x16x32_bf16 v[84:87], v[158:161], v[210:213], v[84:87]
	v_mfma_f32_16x16x32_bf16 v[76:79], v[146:149], v[214:217], 0
	v_mfma_f32_16x16x32_bf16 v[76:79], v[150:153], v[218:221], v[76:79]
	v_mfma_f32_16x16x32_bf16 v[68:71], v[154:157], v[214:217], 0
	v_mfma_f32_16x16x32_bf16 v[68:71], v[158:161], v[218:221], v[68:71]
	v_mfma_f32_16x16x32_bf16 v[120:123], v[162:165], v[190:193], 0
	v_mfma_f32_16x16x32_bf16 v[120:123], v[178:181], v[194:197], v[120:123]
	v_mfma_f32_16x16x32_bf16 v[112:115], v[182:185], v[190:193], 0
	v_mfma_f32_16x16x32_bf16 v[112:115], v[186:189], v[194:197], v[112:115]
	v_mfma_f32_16x16x32_bf16 v[104:107], v[162:165], v[198:201], 0
	v_mfma_f32_16x16x32_bf16 v[104:107], v[178:181], v[202:205], v[104:107]
	v_mfma_f32_16x16x32_bf16 v[96:99], v[182:185], v[198:201], 0
	v_mfma_f32_16x16x32_bf16 v[96:99], v[186:189], v[202:205], v[96:99]
	v_mfma_f32_16x16x32_bf16 v[88:91], v[162:165], v[206:209], 0
	v_mfma_f32_16x16x32_bf16 v[88:91], v[178:181], v[210:213], v[88:91]
	v_mfma_f32_16x16x32_bf16 v[80:83], v[182:185], v[206:209], 0
	v_mfma_f32_16x16x32_bf16 v[80:83], v[186:189], v[210:213], v[80:83]
	v_mfma_f32_16x16x32_bf16 v[72:75], v[162:165], v[214:217], 0
	v_mfma_f32_16x16x32_bf16 v[72:75], v[178:181], v[218:221], v[72:75]
	s_setprio 3
	s_barrier
	v_mfma_f32_16x16x32_bf16 v[64:67], v[182:185], v[214:217], 0
	v_mfma_f32_16x16x32_bf16 v[64:67], v[186:189], v[218:221], v[64:67]
	s_setprio 0
	s_add_i32 s74, s26, s16
	v_lshl_add_u64 v[166:167], s[70:71], 0, v[132:133]
	s_mov_b32 m0, s74
	ds_read_b128 v[190:193], v176 offset:16384
	ds_read_b128 v[194:197], v176 offset:17408
	ds_read_b128 v[198:201], v176 offset:18432
	ds_read_b128 v[202:205], v176 offset:19456
	ds_read_b128 v[206:209], v176 offset:20480
	ds_read_b128 v[210:213], v176 offset:21504
	ds_read_b128 v[214:217], v176 offset:22528
	ds_read_b128 v[218:221], v176 offset:23552
	global_load_lds_dwordx4 v[166:167], off
	s_add_i32 m0, s74, 0x2000
	s_add_u32 s74, s70, 0x40000
	v_lshl_add_u64 v[222:223], s[70:71], 0, v[128:129]
	s_addc_u32 s75, s71, 0
	s_add_i32 s76, s27, s16
	global_load_lds_dwordx4 v[222:223], off
	v_lshl_add_u64 v[224:225], s[74:75], 0, v[132:133]
	s_mov_b32 m0, s76
	global_load_lds_dwordx4 v[224:225], off
	s_add_i32 m0, s76, 0x2000
	v_lshl_add_u64 v[224:225], s[74:75], 0, v[128:129]
	global_load_lds_dwordx4 v[224:225], off
	s_mov_b32 m0, s17
	v_lshl_add_u64 v[224:225], s[72:73], 0, v[134:135]
	global_load_lds_dwordx4 v[224:225], off
	s_mov_b32 m0, s18
	v_lshl_add_u64 v[226:227], s[72:73], 0, v[130:131]
	global_load_lds_dwordx4 v[226:227], off
	s_waitcnt vmcnt(8) lgkmcnt(0)
	s_barrier
	s_setprio 1
	v_mfma_f32_16x16x32_bf16 v[60:63], v[146:149], v[190:193], 0
	v_mfma_f32_16x16x32_bf16 v[60:63], v[150:153], v[194:197], v[60:63]
	v_mfma_f32_16x16x32_bf16 v[52:55], v[154:157], v[190:193], 0
	v_mfma_f32_16x16x32_bf16 v[52:55], v[158:161], v[194:197], v[52:55]
	v_mfma_f32_16x16x32_bf16 v[44:47], v[146:149], v[198:201], 0
	v_mfma_f32_16x16x32_bf16 v[44:47], v[150:153], v[202:205], v[44:47]
	v_mfma_f32_16x16x32_bf16 v[36:39], v[154:157], v[198:201], 0
	v_mfma_f32_16x16x32_bf16 v[36:39], v[158:161], v[202:205], v[36:39]
	v_mfma_f32_16x16x32_bf16 v[28:31], v[146:149], v[206:209], 0
	v_mfma_f32_16x16x32_bf16 v[28:31], v[150:153], v[210:213], v[28:31]
	v_mfma_f32_16x16x32_bf16 v[20:23], v[154:157], v[206:209], 0
	v_mfma_f32_16x16x32_bf16 v[20:23], v[158:161], v[210:213], v[20:23]
	v_mfma_f32_16x16x32_bf16 v[12:15], v[146:149], v[214:217], 0
	v_mfma_f32_16x16x32_bf16 v[12:15], v[150:153], v[218:221], v[12:15]
	v_mfma_f32_16x16x32_bf16 v[4:7], v[154:157], v[214:217], 0
	v_mfma_f32_16x16x32_bf16 v[4:7], v[158:161], v[218:221], v[4:7]
	v_mfma_f32_16x16x32_bf16 v[56:59], v[162:165], v[190:193], 0
	v_mfma_f32_16x16x32_bf16 v[56:59], v[178:181], v[194:197], v[56:59]
	v_mfma_f32_16x16x32_bf16 v[48:51], v[182:185], v[190:193], 0
	v_mfma_f32_16x16x32_bf16 v[48:51], v[186:189], v[194:197], v[48:51]
	v_mfma_f32_16x16x32_bf16 v[40:43], v[162:165], v[198:201], 0
	v_mfma_f32_16x16x32_bf16 v[40:43], v[178:181], v[202:205], v[40:43]
	v_mfma_f32_16x16x32_bf16 v[32:35], v[182:185], v[198:201], 0
	v_mfma_f32_16x16x32_bf16 v[32:35], v[186:189], v[202:205], v[32:35]
	v_mfma_f32_16x16x32_bf16 v[24:27], v[162:165], v[206:209], 0
	v_mfma_f32_16x16x32_bf16 v[24:27], v[178:181], v[210:213], v[24:27]
	v_mfma_f32_16x16x32_bf16 v[16:19], v[182:185], v[206:209], 0
	v_mfma_f32_16x16x32_bf16 v[16:19], v[186:189], v[210:213], v[16:19]
	v_mfma_f32_16x16x32_bf16 v[8:11], v[162:165], v[214:217], 0
	v_mfma_f32_16x16x32_bf16 v[8:11], v[178:181], v[218:221], v[8:11]
	s_setprio 3
	s_barrier
	v_mfma_f32_16x16x32_bf16 v[0:3], v[182:185], v[214:217], 0
	v_mfma_f32_16x16x32_bf16 v[0:3], v[186:189], v[218:221], v[0:3]
	s_setprio 0
	s_add_i32 s74, 0, 0x18000
	s_add_i32 s75, 0, 0x1c000
	v_add_u32_e32 v158, s74, v171
	v_add_u32_e32 v186, s75, v171
	ds_read_b128 v[146:149], v158
	ds_read_b128 v[150:153], v158 offset:1024
	ds_read_b128 v[154:157], v158 offset:2048
	ds_read_b128 v[158:161], v158 offset:3072
	ds_read_b128 v[162:165], v186
	ds_read_b128 v[178:181], v186 offset:1024
	ds_read_b128 v[182:185], v186 offset:2048
	ds_read_b128 v[186:189], v186 offset:3072
	s_add_u32 s72, s72, 0x40000
	s_addc_u32 s73, s73, 0
	s_mov_b32 m0, s19
	v_lshl_add_u64 v[228:229], s[72:73], 0, v[134:135]
	ds_read_b128 v[190:193], v176 offset:32768
	ds_read_b128 v[194:197], v176 offset:33792
	ds_read_b128 v[198:201], v176 offset:34816
	ds_read_b128 v[202:205], v176 offset:35840
	ds_read_b128 v[206:209], v176 offset:36864
	ds_read_b128 v[210:213], v176 offset:37888
	ds_read_b128 v[214:217], v176 offset:38912
	ds_read_b128 v[218:221], v176 offset:39936
	global_load_lds_dwordx4 v[228:229], off
	s_mov_b32 m0, s20
	v_lshl_add_u64 v[228:229], s[72:73], 0, v[130:131]
	global_load_lds_dwordx4 v[228:229], off
	s_waitcnt vmcnt(8) lgkmcnt(0)
	s_barrier
	s_setprio 1
	v_mfma_f32_16x16x32_bf16 v[124:127], v[146:149], v[190:193], v[124:127]
	v_mfma_f32_16x16x32_bf16 v[124:127], v[150:153], v[194:197], v[124:127]
	v_mfma_f32_16x16x32_bf16 v[116:119], v[154:157], v[190:193], v[116:119]
	v_mfma_f32_16x16x32_bf16 v[116:119], v[158:161], v[194:197], v[116:119]
	v_mfma_f32_16x16x32_bf16 v[108:111], v[146:149], v[198:201], v[108:111]
	v_mfma_f32_16x16x32_bf16 v[108:111], v[150:153], v[202:205], v[108:111]
	v_mfma_f32_16x16x32_bf16 v[100:103], v[154:157], v[198:201], v[100:103]
	v_mfma_f32_16x16x32_bf16 v[100:103], v[158:161], v[202:205], v[100:103]
	v_mfma_f32_16x16x32_bf16 v[92:95], v[146:149], v[206:209], v[92:95]
	v_mfma_f32_16x16x32_bf16 v[92:95], v[150:153], v[210:213], v[92:95]
	v_mfma_f32_16x16x32_bf16 v[84:87], v[154:157], v[206:209], v[84:87]
	v_mfma_f32_16x16x32_bf16 v[84:87], v[158:161], v[210:213], v[84:87]
	v_mfma_f32_16x16x32_bf16 v[76:79], v[146:149], v[214:217], v[76:79]
	v_mfma_f32_16x16x32_bf16 v[76:79], v[150:153], v[218:221], v[76:79]
	v_mfma_f32_16x16x32_bf16 v[68:71], v[154:157], v[214:217], v[68:71]
	v_mfma_f32_16x16x32_bf16 v[68:71], v[158:161], v[218:221], v[68:71]
	v_mfma_f32_16x16x32_bf16 v[120:123], v[162:165], v[190:193], v[120:123]
	v_mfma_f32_16x16x32_bf16 v[120:123], v[178:181], v[194:197], v[120:123]
	v_mfma_f32_16x16x32_bf16 v[112:115], v[182:185], v[190:193], v[112:115]
	v_mfma_f32_16x16x32_bf16 v[112:115], v[186:189], v[194:197], v[112:115]
	v_mfma_f32_16x16x32_bf16 v[104:107], v[162:165], v[198:201], v[104:107]
	v_mfma_f32_16x16x32_bf16 v[104:107], v[178:181], v[202:205], v[104:107]
	v_mfma_f32_16x16x32_bf16 v[96:99], v[182:185], v[198:201], v[96:99]
	v_mfma_f32_16x16x32_bf16 v[96:99], v[186:189], v[202:205], v[96:99]
	v_mfma_f32_16x16x32_bf16 v[88:91], v[162:165], v[206:209], v[88:91]
	v_mfma_f32_16x16x32_bf16 v[88:91], v[178:181], v[210:213], v[88:91]
	v_mfma_f32_16x16x32_bf16 v[80:83], v[182:185], v[206:209], v[80:83]
	v_mfma_f32_16x16x32_bf16 v[80:83], v[186:189], v[210:213], v[80:83]
	v_mfma_f32_16x16x32_bf16 v[72:75], v[162:165], v[214:217], v[72:75]
	v_mfma_f32_16x16x32_bf16 v[72:75], v[178:181], v[218:221], v[72:75]
	s_setprio 3
	s_barrier
	v_mfma_f32_16x16x32_bf16 v[64:67], v[182:185], v[214:217], v[64:67]
	v_mfma_f32_16x16x32_bf16 v[64:67], v[186:189], v[218:221], v[64:67]
	s_setprio 0
	s_add_i32 s72, s74, s16
	v_lshl_add_u64 v[166:167], v[166:167], 0, s[10:11]
	s_mov_b32 m0, s72
	ds_read_b128 v[190:193], v176 offset:49152
	ds_read_b128 v[194:197], v176 offset:50176
	ds_read_b128 v[198:201], v176 offset:51200
	ds_read_b128 v[202:205], v176 offset:52224
	ds_read_b128 v[206:209], v176 offset:53248
	ds_read_b128 v[210:213], v176 offset:54272
	ds_read_b128 v[214:217], v176 offset:55296
	ds_read_b128 v[218:221], v176 offset:56320
	global_load_lds_dwordx4 v[166:167], off
	s_add_i32 m0, s72, 0x2000
	s_add_u32 s70, s70, 0x40080
	v_lshl_add_u64 v[166:167], v[222:223], 0, s[10:11]
	s_addc_u32 s71, s71, 0
	s_add_i32 s72, s75, s16
	global_load_lds_dwordx4 v[166:167], off
	s_mov_b32 m0, s72
	v_lshl_add_u64 v[166:167], s[70:71], 0, v[132:133]
	global_load_lds_dwordx4 v[166:167], off
	s_add_i32 m0, s72, 0x2000
	v_lshl_add_u64 v[166:167], s[70:71], 0, v[128:129]
	global_load_lds_dwordx4 v[166:167], off
	s_mov_b32 m0, s23
	v_lshl_add_u64 v[166:167], v[224:225], 0, s[10:11]
	global_load_lds_dwordx4 v[166:167], off
	s_mov_b32 m0, s24
	v_lshl_add_u64 v[166:167], v[226:227], 0, s[10:11]
	global_load_lds_dwordx4 v[166:167], off
	s_waitcnt vmcnt(8) lgkmcnt(0)
	s_barrier
	s_setprio 1
	v_mfma_f32_16x16x32_bf16 v[60:63], v[146:149], v[190:193], v[60:63]
	v_mfma_f32_16x16x32_bf16 v[60:63], v[150:153], v[194:197], v[60:63]
	v_mfma_f32_16x16x32_bf16 v[52:55], v[154:157], v[190:193], v[52:55]
	v_mfma_f32_16x16x32_bf16 v[52:55], v[158:161], v[194:197], v[52:55]
	v_mfma_f32_16x16x32_bf16 v[44:47], v[146:149], v[198:201], v[44:47]
	v_mfma_f32_16x16x32_bf16 v[44:47], v[150:153], v[202:205], v[44:47]
	v_mfma_f32_16x16x32_bf16 v[36:39], v[154:157], v[198:201], v[36:39]
	v_mfma_f32_16x16x32_bf16 v[36:39], v[158:161], v[202:205], v[36:39]
	v_mfma_f32_16x16x32_bf16 v[28:31], v[146:149], v[206:209], v[28:31]
	v_mfma_f32_16x16x32_bf16 v[28:31], v[150:153], v[210:213], v[28:31]
	v_mfma_f32_16x16x32_bf16 v[20:23], v[154:157], v[206:209], v[20:23]
	v_mfma_f32_16x16x32_bf16 v[20:23], v[158:161], v[210:213], v[20:23]
	v_mfma_f32_16x16x32_bf16 v[12:15], v[146:149], v[214:217], v[12:15]
	v_mfma_f32_16x16x32_bf16 v[12:15], v[150:153], v[218:221], v[12:15]
	v_mfma_f32_16x16x32_bf16 v[4:7], v[154:157], v[214:217], v[4:7]
	v_mfma_f32_16x16x32_bf16 v[4:7], v[158:161], v[218:221], v[4:7]
	v_mfma_f32_16x16x32_bf16 v[56:59], v[162:165], v[190:193], v[56:59]
	v_mfma_f32_16x16x32_bf16 v[56:59], v[178:181], v[194:197], v[56:59]
	v_mfma_f32_16x16x32_bf16 v[48:51], v[182:185], v[190:193], v[48:51]
	v_mfma_f32_16x16x32_bf16 v[48:51], v[186:189], v[194:197], v[48:51]
	v_mfma_f32_16x16x32_bf16 v[40:43], v[162:165], v[198:201], v[40:43]
	v_mfma_f32_16x16x32_bf16 v[40:43], v[178:181], v[202:205], v[40:43]
	v_mfma_f32_16x16x32_bf16 v[32:35], v[182:185], v[198:201], v[32:35]
	v_mfma_f32_16x16x32_bf16 v[32:35], v[186:189], v[202:205], v[32:35]
	v_mfma_f32_16x16x32_bf16 v[24:27], v[162:165], v[206:209], v[24:27]
	v_mfma_f32_16x16x32_bf16 v[24:27], v[178:181], v[210:213], v[24:27]
	v_mfma_f32_16x16x32_bf16 v[16:19], v[182:185], v[206:209], v[16:19]
	v_mfma_f32_16x16x32_bf16 v[16:19], v[186:189], v[210:213], v[16:19]
	v_mfma_f32_16x16x32_bf16 v[8:11], v[162:165], v[214:217], v[8:11]
	v_mfma_f32_16x16x32_bf16 v[8:11], v[178:181], v[218:221], v[8:11]
	s_setprio 3
	s_barrier
	v_mfma_f32_16x16x32_bf16 v[0:3], v[182:185], v[214:217], v[0:3]
	v_mfma_f32_16x16x32_bf16 v[0:3], v[186:189], v[218:221], v[0:3]
	s_setprio 0
	s_add_i32 s69, s69, 2
	s_add_u32 s58, s58, 0x100
	s_addc_u32 s59, s59, 0
	s_add_u32 s67, s67, 0x100
	s_addc_u32 s68, s68, 0
	s_cmp_gt_u32 s69, 13
.LBB0_2192:
	ds_read_b128 v[146:149], v174
	ds_read_b128 v[150:153], v174 offset:1024
	ds_read_b128 v[154:157], v174 offset:2048
	ds_read_b128 v[158:161], v174 offset:3072
	ds_read_b128 v[162:165], v175
	ds_read_b128 v[178:181], v175 offset:1024
	ds_read_b128 v[182:185], v175 offset:2048
	ds_read_b128 v[186:189], v175 offset:3072
	s_add_u32 s70, s58, 0xfffc0080
	s_addc_u32 s71, s59, -1
	s_cmp_eq_u32 s69, 12
	s_cselect_b32 s73, s47, s71
	s_cselect_b32 s72, s53, s70
	s_cselect_b32 s71, s45, s68
	s_cselect_b32 s70, s66, s67
	v_lshl_add_u64 v[166:167], s[58:59], 0, v[136:137]
	s_add_i32 m0, s17, 0xc000
	ds_read_b128 v[190:193], v176
	ds_read_b128 v[194:197], v176 offset:1024
	ds_read_b128 v[198:201], v176 offset:2048
	ds_read_b128 v[202:205], v176 offset:3072
	ds_read_b128 v[206:209], v176 offset:4096
	ds_read_b128 v[210:213], v176 offset:5120
	ds_read_b128 v[214:217], v176 offset:6144
	ds_read_b128 v[218:221], v176 offset:7168
	global_load_lds_dwordx4 v[166:167], off
	s_add_i32 m0, s17, 0xe000
	v_lshl_add_u64 v[166:167], s[58:59], 0, v[140:141]
	global_load_lds_dwordx4 v[166:167], off
	s_waitcnt vmcnt(8) lgkmcnt(0)
	s_barrier
	s_setprio 1
	v_mfma_f32_16x16x32_bf16 v[124:127], v[146:149], v[190:193], v[124:127]
	v_mfma_f32_16x16x32_bf16 v[124:127], v[150:153], v[194:197], v[124:127]
	v_mfma_f32_16x16x32_bf16 v[116:119], v[154:157], v[190:193], v[116:119]
	v_mfma_f32_16x16x32_bf16 v[116:119], v[158:161], v[194:197], v[116:119]
	v_mfma_f32_16x16x32_bf16 v[108:111], v[146:149], v[198:201], v[108:111]
	v_mfma_f32_16x16x32_bf16 v[108:111], v[150:153], v[202:205], v[108:111]
	v_mfma_f32_16x16x32_bf16 v[100:103], v[154:157], v[198:201], v[100:103]
	v_mfma_f32_16x16x32_bf16 v[100:103], v[158:161], v[202:205], v[100:103]
	v_mfma_f32_16x16x32_bf16 v[92:95], v[146:149], v[206:209], v[92:95]
	v_mfma_f32_16x16x32_bf16 v[92:95], v[150:153], v[210:213], v[92:95]
	v_mfma_f32_16x16x32_bf16 v[84:87], v[154:157], v[206:209], v[84:87]
	v_mfma_f32_16x16x32_bf16 v[84:87], v[158:161], v[210:213], v[84:87]
	v_mfma_f32_16x16x32_bf16 v[76:79], v[146:149], v[214:217], v[76:79]
	v_mfma_f32_16x16x32_bf16 v[76:79], v[150:153], v[218:221], v[76:79]
	v_mfma_f32_16x16x32_bf16 v[68:71], v[154:157], v[214:217], v[68:71]
	v_mfma_f32_16x16x32_bf16 v[68:71], v[158:161], v[218:221], v[68:71]
	v_mfma_f32_16x16x32_bf16 v[120:123], v[162:165], v[190:193], v[120:123]
	v_mfma_f32_16x16x32_bf16 v[120:123], v[178:181], v[194:197], v[120:123]
	v_mfma_f32_16x16x32_bf16 v[112:115], v[182:185], v[190:193], v[112:115]
	v_mfma_f32_16x16x32_bf16 v[112:115], v[186:189], v[194:197], v[112:115]
	v_mfma_f32_16x16x32_bf16 v[104:107], v[162:165], v[198:201], v[104:107]
	v_mfma_f32_16x16x32_bf16 v[104:107], v[178:181], v[202:205], v[104:107]
	v_mfma_f32_16x16x32_bf16 v[96:99], v[182:185], v[198:201], v[96:99]
	v_mfma_f32_16x16x32_bf16 v[96:99], v[186:189], v[202:205], v[96:99]
	v_mfma_f32_16x16x32_bf16 v[88:91], v[162:165], v[206:209], v[88:91]
	v_mfma_f32_16x16x32_bf16 v[88:91], v[178:181], v[210:213], v[88:91]
	v_mfma_f32_16x16x32_bf16 v[80:83], v[182:185], v[206:209], v[80:83]
	v_mfma_f32_16x16x32_bf16 v[80:83], v[186:189], v[210:213], v[80:83]
	v_mfma_f32_16x16x32_bf16 v[72:75], v[162:165], v[214:217], v[72:75]
	v_mfma_f32_16x16x32_bf16 v[72:75], v[178:181], v[218:221], v[72:75]
	s_setprio 3
	s_barrier
	v_mfma_f32_16x16x32_bf16 v[64:67], v[182:185], v[214:217], v[64:67]
	v_mfma_f32_16x16x32_bf16 v[64:67], v[186:189], v[218:221], v[64:67]
	s_setprio 0
	s_add_i32 s74, s26, s16
	v_lshl_add_u64 v[166:167], s[70:71], 0, v[132:133]
	s_mov_b32 m0, s74
	ds_read_b128 v[190:193], v176 offset:16384
	ds_read_b128 v[194:197], v176 offset:17408
	ds_read_b128 v[198:201], v176 offset:18432
	ds_read_b128 v[202:205], v176 offset:19456
	ds_read_b128 v[206:209], v176 offset:20480
	ds_read_b128 v[210:213], v176 offset:21504
	ds_read_b128 v[214:217], v176 offset:22528
	ds_read_b128 v[218:221], v176 offset:23552
	global_load_lds_dwordx4 v[166:167], off
	s_add_i32 m0, s74, 0x2000
	s_add_u32 s74, s70, 0x40000
	v_lshl_add_u64 v[222:223], s[70:71], 0, v[128:129]
	s_addc_u32 s75, s71, 0
	s_add_i32 s76, s27, s16
	global_load_lds_dwordx4 v[222:223], off
	v_lshl_add_u64 v[224:225], s[74:75], 0, v[132:133]
	s_mov_b32 m0, s76
	global_load_lds_dwordx4 v[224:225], off
	s_add_i32 m0, s76, 0x2000
	v_lshl_add_u64 v[224:225], s[74:75], 0, v[128:129]
	global_load_lds_dwordx4 v[224:225], off
	s_mov_b32 m0, s17
	v_lshl_add_u64 v[224:225], s[72:73], 0, v[134:135]
	global_load_lds_dwordx4 v[224:225], off
	s_mov_b32 m0, s18
	v_lshl_add_u64 v[226:227], s[72:73], 0, v[130:131]
	global_load_lds_dwordx4 v[226:227], off
	s_waitcnt vmcnt(8) lgkmcnt(0)
	s_barrier
	s_setprio 1
	v_mfma_f32_16x16x32_bf16 v[60:63], v[146:149], v[190:193], v[60:63]
	v_mfma_f32_16x16x32_bf16 v[60:63], v[150:153], v[194:197], v[60:63]
	v_mfma_f32_16x16x32_bf16 v[52:55], v[154:157], v[190:193], v[52:55]
	v_mfma_f32_16x16x32_bf16 v[52:55], v[158:161], v[194:197], v[52:55]
	v_mfma_f32_16x16x32_bf16 v[44:47], v[146:149], v[198:201], v[44:47]
	v_mfma_f32_16x16x32_bf16 v[44:47], v[150:153], v[202:205], v[44:47]
	v_mfma_f32_16x16x32_bf16 v[36:39], v[154:157], v[198:201], v[36:39]
	v_mfma_f32_16x16x32_bf16 v[36:39], v[158:161], v[202:205], v[36:39]
	v_mfma_f32_16x16x32_bf16 v[28:31], v[146:149], v[206:209], v[28:31]
	v_mfma_f32_16x16x32_bf16 v[28:31], v[150:153], v[210:213], v[28:31]
	v_mfma_f32_16x16x32_bf16 v[20:23], v[154:157], v[206:209], v[20:23]
	v_mfma_f32_16x16x32_bf16 v[20:23], v[158:161], v[210:213], v[20:23]
	v_mfma_f32_16x16x32_bf16 v[12:15], v[146:149], v[214:217], v[12:15]
	v_mfma_f32_16x16x32_bf16 v[12:15], v[150:153], v[218:221], v[12:15]
	v_mfma_f32_16x16x32_bf16 v[4:7], v[154:157], v[214:217], v[4:7]
	v_mfma_f32_16x16x32_bf16 v[4:7], v[158:161], v[218:221], v[4:7]
	v_mfma_f32_16x16x32_bf16 v[56:59], v[162:165], v[190:193], v[56:59]
	v_mfma_f32_16x16x32_bf16 v[56:59], v[178:181], v[194:197], v[56:59]
	v_mfma_f32_16x16x32_bf16 v[48:51], v[182:185], v[190:193], v[48:51]
	v_mfma_f32_16x16x32_bf16 v[48:51], v[186:189], v[194:197], v[48:51]
	v_mfma_f32_16x16x32_bf16 v[40:43], v[162:165], v[198:201], v[40:43]
	v_mfma_f32_16x16x32_bf16 v[40:43], v[178:181], v[202:205], v[40:43]
	v_mfma_f32_16x16x32_bf16 v[32:35], v[182:185], v[198:201], v[32:35]
	v_mfma_f32_16x16x32_bf16 v[32:35], v[186:189], v[202:205], v[32:35]
	v_mfma_f32_16x16x32_bf16 v[24:27], v[162:165], v[206:209], v[24:27]
	v_mfma_f32_16x16x32_bf16 v[24:27], v[178:181], v[210:213], v[24:27]
	v_mfma_f32_16x16x32_bf16 v[16:19], v[182:185], v[206:209], v[16:19]
	v_mfma_f32_16x16x32_bf16 v[16:19], v[186:189], v[210:213], v[16:19]
	v_mfma_f32_16x16x32_bf16 v[8:11], v[162:165], v[214:217], v[8:11]
	v_mfma_f32_16x16x32_bf16 v[8:11], v[178:181], v[218:221], v[8:11]
	s_setprio 3
	s_barrier
	v_mfma_f32_16x16x32_bf16 v[0:3], v[182:185], v[214:217], v[0:3]
	v_mfma_f32_16x16x32_bf16 v[0:3], v[186:189], v[218:221], v[0:3]
	s_setprio 0
	s_add_i32 s74, 0, 0x18000
	s_add_i32 s75, 0, 0x1c000
	v_add_u32_e32 v158, s74, v171
	v_add_u32_e32 v186, s75, v171
	ds_read_b128 v[146:149], v158
	ds_read_b128 v[150:153], v158 offset:1024
	ds_read_b128 v[154:157], v158 offset:2048
	ds_read_b128 v[158:161], v158 offset:3072
	ds_read_b128 v[162:165], v186
	ds_read_b128 v[178:181], v186 offset:1024
	ds_read_b128 v[182:185], v186 offset:2048
	ds_read_b128 v[186:189], v186 offset:3072
	s_add_u32 s72, s72, 0x40000
	s_addc_u32 s73, s73, 0
	s_mov_b32 m0, s19
	v_lshl_add_u64 v[228:229], s[72:73], 0, v[134:135]
	ds_read_b128 v[190:193], v176 offset:32768
	ds_read_b128 v[194:197], v176 offset:33792
	ds_read_b128 v[198:201], v176 offset:34816
	ds_read_b128 v[202:205], v176 offset:35840
	ds_read_b128 v[206:209], v176 offset:36864
	ds_read_b128 v[210:213], v176 offset:37888
	ds_read_b128 v[214:217], v176 offset:38912
	ds_read_b128 v[218:221], v176 offset:39936
	global_load_lds_dwordx4 v[228:229], off
	s_mov_b32 m0, s20
	v_lshl_add_u64 v[228:229], s[72:73], 0, v[130:131]
	global_load_lds_dwordx4 v[228:229], off
	s_waitcnt vmcnt(8) lgkmcnt(0)
	s_barrier
	s_setprio 1
	v_mfma_f32_16x16x32_bf16 v[124:127], v[146:149], v[190:193], v[124:127]
	v_mfma_f32_16x16x32_bf16 v[124:127], v[150:153], v[194:197], v[124:127]
	v_mfma_f32_16x16x32_bf16 v[116:119], v[154:157], v[190:193], v[116:119]
	v_mfma_f32_16x16x32_bf16 v[116:119], v[158:161], v[194:197], v[116:119]
	v_mfma_f32_16x16x32_bf16 v[108:111], v[146:149], v[198:201], v[108:111]
	v_mfma_f32_16x16x32_bf16 v[108:111], v[150:153], v[202:205], v[108:111]
	v_mfma_f32_16x16x32_bf16 v[100:103], v[154:157], v[198:201], v[100:103]
	v_mfma_f32_16x16x32_bf16 v[100:103], v[158:161], v[202:205], v[100:103]
	v_mfma_f32_16x16x32_bf16 v[92:95], v[146:149], v[206:209], v[92:95]
	v_mfma_f32_16x16x32_bf16 v[92:95], v[150:153], v[210:213], v[92:95]
	v_mfma_f32_16x16x32_bf16 v[84:87], v[154:157], v[206:209], v[84:87]
	v_mfma_f32_16x16x32_bf16 v[84:87], v[158:161], v[210:213], v[84:87]
	v_mfma_f32_16x16x32_bf16 v[76:79], v[146:149], v[214:217], v[76:79]
	v_mfma_f32_16x16x32_bf16 v[76:79], v[150:153], v[218:221], v[76:79]
	v_mfma_f32_16x16x32_bf16 v[68:71], v[154:157], v[214:217], v[68:71]
	v_mfma_f32_16x16x32_bf16 v[68:71], v[158:161], v[218:221], v[68:71]
	v_mfma_f32_16x16x32_bf16 v[120:123], v[162:165], v[190:193], v[120:123]
	v_mfma_f32_16x16x32_bf16 v[120:123], v[178:181], v[194:197], v[120:123]
	v_mfma_f32_16x16x32_bf16 v[112:115], v[182:185], v[190:193], v[112:115]
	v_mfma_f32_16x16x32_bf16 v[112:115], v[186:189], v[194:197], v[112:115]
	v_mfma_f32_16x16x32_bf16 v[104:107], v[162:165], v[198:201], v[104:107]
	v_mfma_f32_16x16x32_bf16 v[104:107], v[178:181], v[202:205], v[104:107]
	v_mfma_f32_16x16x32_bf16 v[96:99], v[182:185], v[198:201], v[96:99]
	v_mfma_f32_16x16x32_bf16 v[96:99], v[186:189], v[202:205], v[96:99]
	v_mfma_f32_16x16x32_bf16 v[88:91], v[162:165], v[206:209], v[88:91]
	v_mfma_f32_16x16x32_bf16 v[88:91], v[178:181], v[210:213], v[88:91]
	v_mfma_f32_16x16x32_bf16 v[80:83], v[182:185], v[206:209], v[80:83]
	v_mfma_f32_16x16x32_bf16 v[80:83], v[186:189], v[210:213], v[80:83]
	v_mfma_f32_16x16x32_bf16 v[72:75], v[162:165], v[214:217], v[72:75]
	v_mfma_f32_16x16x32_bf16 v[72:75], v[178:181], v[218:221], v[72:75]
	s_setprio 3
	s_barrier
	v_mfma_f32_16x16x32_bf16 v[64:67], v[182:185], v[214:217], v[64:67]
	v_mfma_f32_16x16x32_bf16 v[64:67], v[186:189], v[218:221], v[64:67]
	s_setprio 0
	s_add_i32 s72, s74, s16
	v_lshl_add_u64 v[166:167], v[166:167], 0, s[10:11]
	s_mov_b32 m0, s72
	ds_read_b128 v[190:193], v176 offset:49152
	ds_read_b128 v[194:197], v176 offset:50176
	ds_read_b128 v[198:201], v176 offset:51200
	ds_read_b128 v[202:205], v176 offset:52224
	ds_read_b128 v[206:209], v176 offset:53248
	ds_read_b128 v[210:213], v176 offset:54272
	ds_read_b128 v[214:217], v176 offset:55296
	ds_read_b128 v[218:221], v176 offset:56320
	global_load_lds_dwordx4 v[166:167], off
	s_add_i32 m0, s72, 0x2000
	s_add_u32 s70, s70, 0x40080
	v_lshl_add_u64 v[166:167], v[222:223], 0, s[10:11]
	s_addc_u32 s71, s71, 0
	s_add_i32 s72, s75, s16
	global_load_lds_dwordx4 v[166:167], off
	s_mov_b32 m0, s72
	v_lshl_add_u64 v[166:167], s[70:71], 0, v[132:133]
	global_load_lds_dwordx4 v[166:167], off
	s_add_i32 m0, s72, 0x2000
	v_lshl_add_u64 v[166:167], s[70:71], 0, v[128:129]
	global_load_lds_dwordx4 v[166:167], off
	s_mov_b32 m0, s23
	v_lshl_add_u64 v[166:167], v[224:225], 0, s[10:11]
	global_load_lds_dwordx4 v[166:167], off
	s_mov_b32 m0, s24
	v_lshl_add_u64 v[166:167], v[226:227], 0, s[10:11]
	global_load_lds_dwordx4 v[166:167], off
	s_waitcnt vmcnt(8) lgkmcnt(0)
	s_barrier
	s_setprio 1
	v_mfma_f32_16x16x32_bf16 v[60:63], v[146:149], v[190:193], v[60:63]
	v_mfma_f32_16x16x32_bf16 v[60:63], v[150:153], v[194:197], v[60:63]
	v_mfma_f32_16x16x32_bf16 v[52:55], v[154:157], v[190:193], v[52:55]
	v_mfma_f32_16x16x32_bf16 v[52:55], v[158:161], v[194:197], v[52:55]
	v_mfma_f32_16x16x32_bf16 v[44:47], v[146:149], v[198:201], v[44:47]
	v_mfma_f32_16x16x32_bf16 v[44:47], v[150:153], v[202:205], v[44:47]
	v_mfma_f32_16x16x32_bf16 v[36:39], v[154:157], v[198:201], v[36:39]
	v_mfma_f32_16x16x32_bf16 v[36:39], v[158:161], v[202:205], v[36:39]
	v_mfma_f32_16x16x32_bf16 v[28:31], v[146:149], v[206:209], v[28:31]
	v_mfma_f32_16x16x32_bf16 v[28:31], v[150:153], v[210:213], v[28:31]
	v_mfma_f32_16x16x32_bf16 v[20:23], v[154:157], v[206:209], v[20:23]
	v_mfma_f32_16x16x32_bf16 v[20:23], v[158:161], v[210:213], v[20:23]
	v_mfma_f32_16x16x32_bf16 v[12:15], v[146:149], v[214:217], v[12:15]
	v_mfma_f32_16x16x32_bf16 v[12:15], v[150:153], v[218:221], v[12:15]
	v_mfma_f32_16x16x32_bf16 v[4:7], v[154:157], v[214:217], v[4:7]
	v_mfma_f32_16x16x32_bf16 v[4:7], v[158:161], v[218:221], v[4:7]
	v_mfma_f32_16x16x32_bf16 v[56:59], v[162:165], v[190:193], v[56:59]
	v_mfma_f32_16x16x32_bf16 v[56:59], v[178:181], v[194:197], v[56:59]
	v_mfma_f32_16x16x32_bf16 v[48:51], v[182:185], v[190:193], v[48:51]
	v_mfma_f32_16x16x32_bf16 v[48:51], v[186:189], v[194:197], v[48:51]
	v_mfma_f32_16x16x32_bf16 v[40:43], v[162:165], v[198:201], v[40:43]
	v_mfma_f32_16x16x32_bf16 v[40:43], v[178:181], v[202:205], v[40:43]
	v_mfma_f32_16x16x32_bf16 v[32:35], v[182:185], v[198:201], v[32:35]
	v_mfma_f32_16x16x32_bf16 v[32:35], v[186:189], v[202:205], v[32:35]
	v_mfma_f32_16x16x32_bf16 v[24:27], v[162:165], v[206:209], v[24:27]
	v_mfma_f32_16x16x32_bf16 v[24:27], v[178:181], v[210:213], v[24:27]
	v_mfma_f32_16x16x32_bf16 v[16:19], v[182:185], v[206:209], v[16:19]
	v_mfma_f32_16x16x32_bf16 v[16:19], v[186:189], v[210:213], v[16:19]
	v_mfma_f32_16x16x32_bf16 v[8:11], v[162:165], v[214:217], v[8:11]
	v_mfma_f32_16x16x32_bf16 v[8:11], v[178:181], v[218:221], v[8:11]
	s_setprio 3
	s_barrier
	v_mfma_f32_16x16x32_bf16 v[0:3], v[182:185], v[214:217], v[0:3]
	v_mfma_f32_16x16x32_bf16 v[0:3], v[186:189], v[218:221], v[0:3]
	s_setprio 0
	s_add_i32 s69, s69, 2
	s_add_u32 s58, s58, 0x100
	s_addc_u32 s59, s59, 0
	s_add_u32 s67, s67, 0x100
	s_addc_u32 s68, s68, 0
	s_cmp_gt_u32 s69, 13
	s_cbranch_scc0 .LBB0_2192
	s_and_b64 vcc, exec, s[42:43]
	s_cbranch_vccz .LBB0_2195
	s_barrier

.LBB0_2340:
	s_add_u32 s16, s16, 0xb0080
	s_addc_u32 s17, s17, 0
	s_add_u32 s43, s18, 0x100
	v_mov_b32_e32 v0, 0
	s_addc_u32 s44, s19, 0
	s_mov_b32 s45, -2
	ds_read_b128 v[128:131], v197
	ds_read_b128 v[132:135], v197 offset:1024
	ds_read_b128 v[136:139], v197 offset:2048
	ds_read_b128 v[140:143], v197 offset:3072
	ds_read_b128 v[144:147], v198
	ds_read_b128 v[148:151], v198 offset:1024
	ds_read_b128 v[152:155], v198 offset:2048
	ds_read_b128 v[156:159], v198 offset:3072
	s_add_u32 s18, s16, 0xfff50080
	s_addc_u32 s19, s17, -1
	s_cmp_eq_u32 s45, 40
	s_cselect_b32 s21, s5, s19
	s_cselect_b32 s20, s4, s18
	s_cselect_b32 s19, s15, s44
	s_cselect_b32 s18, s14, s43
	v_lshl_add_u64 v[192:193], s[16:17], 0, v[172:173]
	s_add_i32 m0, s25, 0xc000
	ds_read_b128 v[160:163], v199
	ds_read_b128 v[180:183], v199 offset:1024
	ds_read_b128 v[184:187], v199 offset:2048
	ds_read_b128 v[188:191], v199 offset:3072
	ds_read_b128 v[200:203], v199 offset:4096
	ds_read_b128 v[204:207], v199 offset:5120
	ds_read_b128 v[208:211], v199 offset:6144
	ds_read_b128 v[212:215], v199 offset:7168
	global_load_lds_dwordx4 v[192:193], off
	s_add_i32 m0, s25, 0xe000
	v_lshl_add_u64 v[192:193], s[16:17], 0, v[174:175]
	global_load_lds_dwordx4 v[192:193], off
	s_waitcnt vmcnt(8) lgkmcnt(0)
	s_barrier
	s_setprio 1
	v_mfma_f32_16x16x32_bf16 v[124:127], v[128:131], v[160:163], 0
	v_mfma_f32_16x16x32_bf16 v[124:127], v[132:135], v[180:183], v[124:127]
	v_mfma_f32_16x16x32_bf16 v[120:123], v[136:139], v[160:163], 0
	v_mfma_f32_16x16x32_bf16 v[120:123], v[140:143], v[180:183], v[120:123]
	v_mfma_f32_16x16x32_bf16 v[108:111], v[128:131], v[184:187], 0
	v_mfma_f32_16x16x32_bf16 v[108:111], v[132:135], v[188:191], v[108:111]
	v_mfma_f32_16x16x32_bf16 v[104:107], v[136:139], v[184:187], 0
	v_mfma_f32_16x16x32_bf16 v[104:107], v[140:143], v[188:191], v[104:107]
	v_mfma_f32_16x16x32_bf16 v[96:99], v[128:131], v[200:203], 0
	v_mfma_f32_16x16x32_bf16 v[96:99], v[132:135], v[204:207], v[96:99]
	v_mfma_f32_16x16x32_bf16 v[88:91], v[136:139], v[200:203], 0
	v_mfma_f32_16x16x32_bf16 v[88:91], v[140:143], v[204:207], v[88:91]
	v_mfma_f32_16x16x32_bf16 v[80:83], v[128:131], v[208:211], 0
	v_mfma_f32_16x16x32_bf16 v[80:83], v[132:135], v[212:215], v[80:83]
	v_mfma_f32_16x16x32_bf16 v[72:75], v[136:139], v[208:211], 0
	v_mfma_f32_16x16x32_bf16 v[72:75], v[140:143], v[212:215], v[72:75]
	v_mfma_f32_16x16x32_bf16 v[116:119], v[144:147], v[160:163], 0
	v_mfma_f32_16x16x32_bf16 v[116:119], v[148:151], v[180:183], v[116:119]
	v_mfma_f32_16x16x32_bf16 v[112:115], v[152:155], v[160:163], 0
	v_mfma_f32_16x16x32_bf16 v[112:115], v[156:159], v[180:183], v[112:115]
	v_mfma_f32_16x16x32_bf16 v[100:103], v[144:147], v[184:187], 0
	v_mfma_f32_16x16x32_bf16 v[100:103], v[148:151], v[188:191], v[100:103]
	v_mfma_f32_16x16x32_bf16 v[92:95], v[152:155], v[184:187], 0
	v_mfma_f32_16x16x32_bf16 v[92:95], v[156:159], v[188:191], v[92:95]
	v_mfma_f32_16x16x32_bf16 v[84:87], v[144:147], v[200:203], 0
	v_mfma_f32_16x16x32_bf16 v[84:87], v[148:151], v[204:207], v[84:87]
	v_mfma_f32_16x16x32_bf16 v[76:79], v[152:155], v[200:203], 0
	v_mfma_f32_16x16x32_bf16 v[76:79], v[156:159], v[204:207], v[76:79]
	v_mfma_f32_16x16x32_bf16 v[68:71], v[144:147], v[208:211], 0
	v_mfma_f32_16x16x32_bf16 v[68:71], v[148:151], v[212:215], v[68:71]
	s_setprio 3
	s_barrier
	v_mfma_f32_16x16x32_bf16 v[64:67], v[152:155], v[208:211], 0
	v_mfma_f32_16x16x32_bf16 v[64:67], v[156:159], v[212:215], v[64:67]
	s_setprio 0
	s_add_i32 s46, s37, s24
	v_lshl_add_u64 v[192:193], s[18:19], 0, v[166:167]
	s_mov_b32 m0, s46
	ds_read_b128 v[160:163], v199 offset:16384
	ds_read_b128 v[180:183], v199 offset:17408
	ds_read_b128 v[184:187], v199 offset:18432
	ds_read_b128 v[188:191], v199 offset:19456
	ds_read_b128 v[200:203], v199 offset:20480
	ds_read_b128 v[204:207], v199 offset:21504
	ds_read_b128 v[208:211], v199 offset:22528
	ds_read_b128 v[212:215], v199 offset:23552
	global_load_lds_dwordx4 v[192:193], off
	s_add_i32 m0, s46, 0x2000
	s_add_u32 s46, s18, 0xb0000
	v_lshl_add_u64 v[216:217], s[18:19], 0, v[170:171]
	s_addc_u32 s47, s19, 0
	s_add_i32 s48, s38, s24
	global_load_lds_dwordx4 v[216:217], off
	v_lshl_add_u64 v[218:219], s[46:47], 0, v[166:167]
	s_mov_b32 m0, s48
	global_load_lds_dwordx4 v[218:219], off
	s_add_i32 m0, s48, 0x2000
	v_lshl_add_u64 v[218:219], s[46:47], 0, v[170:171]
	global_load_lds_dwordx4 v[218:219], off
	s_mov_b32 m0, s25
	v_lshl_add_u64 v[218:219], s[20:21], 0, v[164:165]
	global_load_lds_dwordx4 v[218:219], off
	s_mov_b32 m0, s26
	v_lshl_add_u64 v[220:221], s[20:21], 0, v[168:169]
	global_load_lds_dwordx4 v[220:221], off
	s_waitcnt vmcnt(8) lgkmcnt(0)
	s_barrier
	s_setprio 1
	v_mfma_f32_16x16x32_bf16 v[60:63], v[128:131], v[160:163], 0
	v_mfma_f32_16x16x32_bf16 v[60:63], v[132:135], v[180:183], v[60:63]
	v_mfma_f32_16x16x32_bf16 v[56:59], v[136:139], v[160:163], 0
	v_mfma_f32_16x16x32_bf16 v[56:59], v[140:143], v[180:183], v[56:59]
	v_mfma_f32_16x16x32_bf16 v[48:51], v[128:131], v[184:187], 0
	v_mfma_f32_16x16x32_bf16 v[48:51], v[132:135], v[188:191], v[48:51]
	v_mfma_f32_16x16x32_bf16 v[40:43], v[136:139], v[184:187], 0
	v_mfma_f32_16x16x32_bf16 v[40:43], v[140:143], v[188:191], v[40:43]
	v_mfma_f32_16x16x32_bf16 v[32:35], v[128:131], v[200:203], 0
	v_mfma_f32_16x16x32_bf16 v[32:35], v[132:135], v[204:207], v[32:35]
	v_mfma_f32_16x16x32_bf16 v[24:27], v[136:139], v[200:203], 0
	v_mfma_f32_16x16x32_bf16 v[24:27], v[140:143], v[204:207], v[24:27]
	v_mfma_f32_16x16x32_bf16 v[16:19], v[128:131], v[208:211], 0
	v_mfma_f32_16x16x32_bf16 v[16:19], v[132:135], v[212:215], v[16:19]
	v_mfma_f32_16x16x32_bf16 v[8:11], v[136:139], v[208:211], 0
	v_mfma_f32_16x16x32_bf16 v[8:11], v[140:143], v[212:215], v[8:11]
	v_mfma_f32_16x16x32_bf16 v[52:55], v[144:147], v[160:163], 0
	v_mfma_f32_16x16x32_bf16 v[52:55], v[148:151], v[180:183], v[52:55]
	v_mfma_f32_16x16x32_bf16 v[44:47], v[152:155], v[160:163], 0
	v_mfma_f32_16x16x32_bf16 v[44:47], v[156:159], v[180:183], v[44:47]
	v_mfma_f32_16x16x32_bf16 v[36:39], v[144:147], v[184:187], 0
	v_mfma_f32_16x16x32_bf16 v[36:39], v[148:151], v[188:191], v[36:39]
	v_mfma_f32_16x16x32_bf16 v[28:31], v[152:155], v[184:187], 0
	v_mfma_f32_16x16x32_bf16 v[28:31], v[156:159], v[188:191], v[28:31]
	v_mfma_f32_16x16x32_bf16 v[20:23], v[144:147], v[200:203], 0
	v_mfma_f32_16x16x32_bf16 v[20:23], v[148:151], v[204:207], v[20:23]
	v_mfma_f32_16x16x32_bf16 v[12:15], v[152:155], v[200:203], 0
	v_mfma_f32_16x16x32_bf16 v[12:15], v[156:159], v[204:207], v[12:15]
	v_mfma_f32_16x16x32_bf16 v[4:7], v[144:147], v[208:211], 0
	v_mfma_f32_16x16x32_bf16 v[4:7], v[148:151], v[212:215], v[4:7]
	s_setprio 3
	s_barrier
	v_mfma_f32_16x16x32_bf16 v[0:3], v[152:155], v[208:211], 0
	v_mfma_f32_16x16x32_bf16 v[0:3], v[156:159], v[212:215], v[0:3]
	s_setprio 0
	s_add_i32 s46, 0, 0x18000
	s_add_i32 s47, 0, 0x1c000
	v_add_u32_e32 v140, s46, v195
	v_add_u32_e32 v156, s47, v195
	ds_read_b128 v[128:131], v140
	ds_read_b128 v[132:135], v140 offset:1024
	ds_read_b128 v[136:139], v140 offset:2048
	ds_read_b128 v[140:143], v140 offset:3072
	ds_read_b128 v[144:147], v156
	ds_read_b128 v[148:151], v156 offset:1024
	ds_read_b128 v[152:155], v156 offset:2048
	ds_read_b128 v[156:159], v156 offset:3072
	s_add_u32 s20, s20, 0xb0000
	s_addc_u32 s21, s21, 0
	s_mov_b32 m0, s27
	v_lshl_add_u64 v[222:223], s[20:21], 0, v[164:165]
	ds_read_b128 v[160:163], v199 offset:32768
	ds_read_b128 v[180:183], v199 offset:33792
	ds_read_b128 v[184:187], v199 offset:34816
	ds_read_b128 v[188:191], v199 offset:35840
	ds_read_b128 v[200:203], v199 offset:36864
	ds_read_b128 v[204:207], v199 offset:37888
	ds_read_b128 v[208:211], v199 offset:38912
	ds_read_b128 v[212:215], v199 offset:39936
	global_load_lds_dwordx4 v[222:223], off
	s_mov_b32 m0, s28
	v_lshl_add_u64 v[222:223], s[20:21], 0, v[168:169]
	global_load_lds_dwordx4 v[222:223], off
	s_waitcnt vmcnt(8) lgkmcnt(0)
	s_barrier
	s_setprio 1
	v_mfma_f32_16x16x32_bf16 v[124:127], v[128:131], v[160:163], v[124:127]
	v_mfma_f32_16x16x32_bf16 v[124:127], v[132:135], v[180:183], v[124:127]
	v_mfma_f32_16x16x32_bf16 v[120:123], v[136:139], v[160:163], v[120:123]
	v_mfma_f32_16x16x32_bf16 v[120:123], v[140:143], v[180:183], v[120:123]
	v_mfma_f32_16x16x32_bf16 v[108:111], v[128:131], v[184:187], v[108:111]
	v_mfma_f32_16x16x32_bf16 v[108:111], v[132:135], v[188:191], v[108:111]
	v_mfma_f32_16x16x32_bf16 v[104:107], v[136:139], v[184:187], v[104:107]
	v_mfma_f32_16x16x32_bf16 v[104:107], v[140:143], v[188:191], v[104:107]
	v_mfma_f32_16x16x32_bf16 v[96:99], v[128:131], v[200:203], v[96:99]
	v_mfma_f32_16x16x32_bf16 v[96:99], v[132:135], v[204:207], v[96:99]
	v_mfma_f32_16x16x32_bf16 v[88:91], v[136:139], v[200:203], v[88:91]
	v_mfma_f32_16x16x32_bf16 v[88:91], v[140:143], v[204:207], v[88:91]
	v_mfma_f32_16x16x32_bf16 v[80:83], v[128:131], v[208:211], v[80:83]
	v_mfma_f32_16x16x32_bf16 v[80:83], v[132:135], v[212:215], v[80:83]
	v_mfma_f32_16x16x32_bf16 v[72:75], v[136:139], v[208:211], v[72:75]
	v_mfma_f32_16x16x32_bf16 v[72:75], v[140:143], v[212:215], v[72:75]
	v_mfma_f32_16x16x32_bf16 v[116:119], v[144:147], v[160:163], v[116:119]
	v_mfma_f32_16x16x32_bf16 v[116:119], v[148:151], v[180:183], v[116:119]
	v_mfma_f32_16x16x32_bf16 v[112:115], v[152:155], v[160:163], v[112:115]
	v_mfma_f32_16x16x32_bf16 v[112:115], v[156:159], v[180:183], v[112:115]
	v_mfma_f32_16x16x32_bf16 v[100:103], v[144:147], v[184:187], v[100:103]
	v_mfma_f32_16x16x32_bf16 v[100:103], v[148:151], v[188:191], v[100:103]
	v_mfma_f32_16x16x32_bf16 v[92:95], v[152:155], v[184:187], v[92:95]
	v_mfma_f32_16x16x32_bf16 v[92:95], v[156:159], v[188:191], v[92:95]
	v_mfma_f32_16x16x32_bf16 v[84:87], v[144:147], v[200:203], v[84:87]
	v_mfma_f32_16x16x32_bf16 v[84:87], v[148:151], v[204:207], v[84:87]
	v_mfma_f32_16x16x32_bf16 v[76:79], v[152:155], v[200:203], v[76:79]
	v_mfma_f32_16x16x32_bf16 v[76:79], v[156:159], v[204:207], v[76:79]
	v_mfma_f32_16x16x32_bf16 v[68:71], v[144:147], v[208:211], v[68:71]
	v_mfma_f32_16x16x32_bf16 v[68:71], v[148:151], v[212:215], v[68:71]
	s_setprio 3
	s_barrier
	v_mfma_f32_16x16x32_bf16 v[64:67], v[152:155], v[208:211], v[64:67]
	v_mfma_f32_16x16x32_bf16 v[64:67], v[156:159], v[212:215], v[64:67]
	s_setprio 0
	s_add_i32 s20, s46, s24
	v_lshl_add_u64 v[192:193], v[192:193], 0, s[8:9]
	s_mov_b32 m0, s20
	ds_read_b128 v[160:163], v199 offset:49152
	ds_read_b128 v[180:183], v199 offset:50176
	ds_read_b128 v[184:187], v199 offset:51200
	ds_read_b128 v[188:191], v199 offset:52224
	ds_read_b128 v[200:203], v199 offset:53248
	ds_read_b128 v[204:207], v199 offset:54272
	ds_read_b128 v[208:211], v199 offset:55296
	ds_read_b128 v[212:215], v199 offset:56320
	global_load_lds_dwordx4 v[192:193], off
	s_add_i32 m0, s20, 0x2000
	s_add_u32 s18, s18, 0xb0080
	v_lshl_add_u64 v[192:193], v[216:217], 0, s[8:9]
	s_addc_u32 s19, s19, 0
	s_add_i32 s20, s47, s24
	global_load_lds_dwordx4 v[192:193], off
	s_mov_b32 m0, s20
	v_lshl_add_u64 v[192:193], s[18:19], 0, v[166:167]
	global_load_lds_dwordx4 v[192:193], off
	s_add_i32 m0, s20, 0x2000
	v_lshl_add_u64 v[192:193], s[18:19], 0, v[170:171]
	global_load_lds_dwordx4 v[192:193], off
	s_mov_b32 m0, s33
	v_lshl_add_u64 v[192:193], v[218:219], 0, s[8:9]
	global_load_lds_dwordx4 v[192:193], off
	s_mov_b32 m0, s35
	v_lshl_add_u64 v[192:193], v[220:221], 0, s[8:9]
	global_load_lds_dwordx4 v[192:193], off
	s_waitcnt vmcnt(8) lgkmcnt(0)
	s_barrier
	s_setprio 1
	v_mfma_f32_16x16x32_bf16 v[60:63], v[128:131], v[160:163], v[60:63]
	v_mfma_f32_16x16x32_bf16 v[60:63], v[132:135], v[180:183], v[60:63]
	v_mfma_f32_16x16x32_bf16 v[56:59], v[136:139], v[160:163], v[56:59]
	v_mfma_f32_16x16x32_bf16 v[56:59], v[140:143], v[180:183], v[56:59]
	v_mfma_f32_16x16x32_bf16 v[48:51], v[128:131], v[184:187], v[48:51]
	v_mfma_f32_16x16x32_bf16 v[48:51], v[132:135], v[188:191], v[48:51]
	v_mfma_f32_16x16x32_bf16 v[40:43], v[136:139], v[184:187], v[40:43]
	v_mfma_f32_16x16x32_bf16 v[40:43], v[140:143], v[188:191], v[40:43]
	v_mfma_f32_16x16x32_bf16 v[32:35], v[128:131], v[200:203], v[32:35]
	v_mfma_f32_16x16x32_bf16 v[32:35], v[132:135], v[204:207], v[32:35]
	v_mfma_f32_16x16x32_bf16 v[24:27], v[136:139], v[200:203], v[24:27]
	v_mfma_f32_16x16x32_bf16 v[24:27], v[140:143], v[204:207], v[24:27]
	v_mfma_f32_16x16x32_bf16 v[16:19], v[128:131], v[208:211], v[16:19]
	v_mfma_f32_16x16x32_bf16 v[16:19], v[132:135], v[212:215], v[16:19]
	v_mfma_f32_16x16x32_bf16 v[8:11], v[136:139], v[208:211], v[8:11]
	v_mfma_f32_16x16x32_bf16 v[8:11], v[140:143], v[212:215], v[8:11]
	v_mfma_f32_16x16x32_bf16 v[52:55], v[144:147], v[160:163], v[52:55]
	v_mfma_f32_16x16x32_bf16 v[52:55], v[148:151], v[180:183], v[52:55]
	v_mfma_f32_16x16x32_bf16 v[44:47], v[152:155], v[160:163], v[44:47]
	v_mfma_f32_16x16x32_bf16 v[44:47], v[156:159], v[180:183], v[44:47]
	v_mfma_f32_16x16x32_bf16 v[36:39], v[144:147], v[184:187], v[36:39]
	v_mfma_f32_16x16x32_bf16 v[36:39], v[148:151], v[188:191], v[36:39]
	v_mfma_f32_16x16x32_bf16 v[28:31], v[152:155], v[184:187], v[28:31]
	v_mfma_f32_16x16x32_bf16 v[28:31], v[156:159], v[188:191], v[28:31]
	v_mfma_f32_16x16x32_bf16 v[20:23], v[144:147], v[200:203], v[20:23]
	v_mfma_f32_16x16x32_bf16 v[20:23], v[148:151], v[204:207], v[20:23]
	v_mfma_f32_16x16x32_bf16 v[12:15], v[152:155], v[200:203], v[12:15]
	v_mfma_f32_16x16x32_bf16 v[12:15], v[156:159], v[204:207], v[12:15]
	v_mfma_f32_16x16x32_bf16 v[4:7], v[144:147], v[208:211], v[4:7]
	v_mfma_f32_16x16x32_bf16 v[4:7], v[148:151], v[212:215], v[4:7]
	s_setprio 3
	s_barrier
	v_mfma_f32_16x16x32_bf16 v[0:3], v[152:155], v[208:211], v[0:3]
	v_mfma_f32_16x16x32_bf16 v[0:3], v[156:159], v[212:215], v[0:3]
	s_setprio 0
	s_add_i32 s45, s45, 2
	s_add_u32 s16, s16, 0x100
	s_addc_u32 s17, s17, 0
	s_add_u32 s43, s43, 0x100
	s_addc_u32 s44, s44, 0
	s_cmp_gt_u32 s45, 41
.LBB0_2341:
	ds_read_b128 v[128:131], v197
	ds_read_b128 v[132:135], v197 offset:1024
	ds_read_b128 v[136:139], v197 offset:2048
	ds_read_b128 v[140:143], v197 offset:3072
	ds_read_b128 v[144:147], v198
	ds_read_b128 v[148:151], v198 offset:1024
	ds_read_b128 v[152:155], v198 offset:2048
	ds_read_b128 v[156:159], v198 offset:3072
	s_add_u32 s18, s16, 0xfff50080
	s_addc_u32 s19, s17, -1
	s_cmp_eq_u32 s45, 40
	s_cselect_b32 s21, s5, s19
	s_cselect_b32 s20, s4, s18
	s_cselect_b32 s19, s15, s44
	s_cselect_b32 s18, s14, s43
	v_lshl_add_u64 v[192:193], s[16:17], 0, v[172:173]
	s_add_i32 m0, s25, 0xc000
	ds_read_b128 v[160:163], v199
	ds_read_b128 v[180:183], v199 offset:1024
	ds_read_b128 v[184:187], v199 offset:2048
	ds_read_b128 v[188:191], v199 offset:3072
	ds_read_b128 v[200:203], v199 offset:4096
	ds_read_b128 v[204:207], v199 offset:5120
	ds_read_b128 v[208:211], v199 offset:6144
	ds_read_b128 v[212:215], v199 offset:7168
	global_load_lds_dwordx4 v[192:193], off
	s_add_i32 m0, s25, 0xe000
	v_lshl_add_u64 v[192:193], s[16:17], 0, v[174:175]
	global_load_lds_dwordx4 v[192:193], off
	s_waitcnt vmcnt(8) lgkmcnt(0)
	s_barrier
	s_setprio 1
	v_mfma_f32_16x16x32_bf16 v[124:127], v[128:131], v[160:163], v[124:127]
	v_mfma_f32_16x16x32_bf16 v[124:127], v[132:135], v[180:183], v[124:127]
	v_mfma_f32_16x16x32_bf16 v[120:123], v[136:139], v[160:163], v[120:123]
	v_mfma_f32_16x16x32_bf16 v[120:123], v[140:143], v[180:183], v[120:123]
	v_mfma_f32_16x16x32_bf16 v[108:111], v[128:131], v[184:187], v[108:111]
	v_mfma_f32_16x16x32_bf16 v[108:111], v[132:135], v[188:191], v[108:111]
	v_mfma_f32_16x16x32_bf16 v[104:107], v[136:139], v[184:187], v[104:107]
	v_mfma_f32_16x16x32_bf16 v[104:107], v[140:143], v[188:191], v[104:107]
	v_mfma_f32_16x16x32_bf16 v[96:99], v[128:131], v[200:203], v[96:99]
	v_mfma_f32_16x16x32_bf16 v[96:99], v[132:135], v[204:207], v[96:99]
	v_mfma_f32_16x16x32_bf16 v[88:91], v[136:139], v[200:203], v[88:91]
	v_mfma_f32_16x16x32_bf16 v[88:91], v[140:143], v[204:207], v[88:91]
	v_mfma_f32_16x16x32_bf16 v[80:83], v[128:131], v[208:211], v[80:83]
	v_mfma_f32_16x16x32_bf16 v[80:83], v[132:135], v[212:215], v[80:83]
	v_mfma_f32_16x16x32_bf16 v[72:75], v[136:139], v[208:211], v[72:75]
	v_mfma_f32_16x16x32_bf16 v[72:75], v[140:143], v[212:215], v[72:75]
	v_mfma_f32_16x16x32_bf16 v[116:119], v[144:147], v[160:163], v[116:119]
	v_mfma_f32_16x16x32_bf16 v[116:119], v[148:151], v[180:183], v[116:119]
	v_mfma_f32_16x16x32_bf16 v[112:115], v[152:155], v[160:163], v[112:115]
	v_mfma_f32_16x16x32_bf16 v[112:115], v[156:159], v[180:183], v[112:115]
	v_mfma_f32_16x16x32_bf16 v[100:103], v[144:147], v[184:187], v[100:103]
	v_mfma_f32_16x16x32_bf16 v[100:103], v[148:151], v[188:191], v[100:103]
	v_mfma_f32_16x16x32_bf16 v[92:95], v[152:155], v[184:187], v[92:95]
	v_mfma_f32_16x16x32_bf16 v[92:95], v[156:159], v[188:191], v[92:95]
	v_mfma_f32_16x16x32_bf16 v[84:87], v[144:147], v[200:203], v[84:87]
	v_mfma_f32_16x16x32_bf16 v[84:87], v[148:151], v[204:207], v[84:87]
	v_mfma_f32_16x16x32_bf16 v[76:79], v[152:155], v[200:203], v[76:79]
	v_mfma_f32_16x16x32_bf16 v[76:79], v[156:159], v[204:207], v[76:79]
	v_mfma_f32_16x16x32_bf16 v[68:71], v[144:147], v[208:211], v[68:71]
	v_mfma_f32_16x16x32_bf16 v[68:71], v[148:151], v[212:215], v[68:71]
	s_setprio 3
	s_barrier
	v_mfma_f32_16x16x32_bf16 v[64:67], v[152:155], v[208:211], v[64:67]
	v_mfma_f32_16x16x32_bf16 v[64:67], v[156:159], v[212:215], v[64:67]
	s_setprio 0
	s_add_i32 s46, s37, s24
	v_lshl_add_u64 v[192:193], s[18:19], 0, v[166:167]
	s_mov_b32 m0, s46
	ds_read_b128 v[160:163], v199 offset:16384
	ds_read_b128 v[180:183], v199 offset:17408
	ds_read_b128 v[184:187], v199 offset:18432
	ds_read_b128 v[188:191], v199 offset:19456
	ds_read_b128 v[200:203], v199 offset:20480
	ds_read_b128 v[204:207], v199 offset:21504
	ds_read_b128 v[208:211], v199 offset:22528
	ds_read_b128 v[212:215], v199 offset:23552
	global_load_lds_dwordx4 v[192:193], off
	s_add_i32 m0, s46, 0x2000
	s_add_u32 s46, s18, 0xb0000
	v_lshl_add_u64 v[216:217], s[18:19], 0, v[170:171]
	s_addc_u32 s47, s19, 0
	s_add_i32 s48, s38, s24
	global_load_lds_dwordx4 v[216:217], off
	v_lshl_add_u64 v[218:219], s[46:47], 0, v[166:167]
	s_mov_b32 m0, s48
	global_load_lds_dwordx4 v[218:219], off
	s_add_i32 m0, s48, 0x2000
	v_lshl_add_u64 v[218:219], s[46:47], 0, v[170:171]
	global_load_lds_dwordx4 v[218:219], off
	s_mov_b32 m0, s25
	v_lshl_add_u64 v[218:219], s[20:21], 0, v[164:165]
	global_load_lds_dwordx4 v[218:219], off
	s_mov_b32 m0, s26
	v_lshl_add_u64 v[220:221], s[20:21], 0, v[168:169]
	global_load_lds_dwordx4 v[220:221], off
	s_waitcnt vmcnt(8) lgkmcnt(0)
	s_barrier
	s_setprio 1
	v_mfma_f32_16x16x32_bf16 v[60:63], v[128:131], v[160:163], v[60:63]
	v_mfma_f32_16x16x32_bf16 v[60:63], v[132:135], v[180:183], v[60:63]
	v_mfma_f32_16x16x32_bf16 v[56:59], v[136:139], v[160:163], v[56:59]
	v_mfma_f32_16x16x32_bf16 v[56:59], v[140:143], v[180:183], v[56:59]
	v_mfma_f32_16x16x32_bf16 v[48:51], v[128:131], v[184:187], v[48:51]
	v_mfma_f32_16x16x32_bf16 v[48:51], v[132:135], v[188:191], v[48:51]
	v_mfma_f32_16x16x32_bf16 v[40:43], v[136:139], v[184:187], v[40:43]
	v_mfma_f32_16x16x32_bf16 v[40:43], v[140:143], v[188:191], v[40:43]
	v_mfma_f32_16x16x32_bf16 v[32:35], v[128:131], v[200:203], v[32:35]
	v_mfma_f32_16x16x32_bf16 v[32:35], v[132:135], v[204:207], v[32:35]
	v_mfma_f32_16x16x32_bf16 v[24:27], v[136:139], v[200:203], v[24:27]
	v_mfma_f32_16x16x32_bf16 v[24:27], v[140:143], v[204:207], v[24:27]
	v_mfma_f32_16x16x32_bf16 v[16:19], v[128:131], v[208:211], v[16:19]
	v_mfma_f32_16x16x32_bf16 v[16:19], v[132:135], v[212:215], v[16:19]
	v_mfma_f32_16x16x32_bf16 v[8:11], v[136:139], v[208:211], v[8:11]
	v_mfma_f32_16x16x32_bf16 v[8:11], v[140:143], v[212:215], v[8:11]
	v_mfma_f32_16x16x32_bf16 v[52:55], v[144:147], v[160:163], v[52:55]
	v_mfma_f32_16x16x32_bf16 v[52:55], v[148:151], v[180:183], v[52:55]
	v_mfma_f32_16x16x32_bf16 v[44:47], v[152:155], v[160:163], v[44:47]
	v_mfma_f32_16x16x32_bf16 v[44:47], v[156:159], v[180:183], v[44:47]
	v_mfma_f32_16x16x32_bf16 v[36:39], v[144:147], v[184:187], v[36:39]
	v_mfma_f32_16x16x32_bf16 v[36:39], v[148:151], v[188:191], v[36:39]
	v_mfma_f32_16x16x32_bf16 v[28:31], v[152:155], v[184:187], v[28:31]
	v_mfma_f32_16x16x32_bf16 v[28:31], v[156:159], v[188:191], v[28:31]
	v_mfma_f32_16x16x32_bf16 v[20:23], v[144:147], v[200:203], v[20:23]
	v_mfma_f32_16x16x32_bf16 v[20:23], v[148:151], v[204:207], v[20:23]
	v_mfma_f32_16x16x32_bf16 v[12:15], v[152:155], v[200:203], v[12:15]
	v_mfma_f32_16x16x32_bf16 v[12:15], v[156:159], v[204:207], v[12:15]
	v_mfma_f32_16x16x32_bf16 v[4:7], v[144:147], v[208:211], v[4:7]
	v_mfma_f32_16x16x32_bf16 v[4:7], v[148:151], v[212:215], v[4:7]
	s_setprio 3
	s_barrier
	v_mfma_f32_16x16x32_bf16 v[0:3], v[152:155], v[208:211], v[0:3]
	v_mfma_f32_16x16x32_bf16 v[0:3], v[156:159], v[212:215], v[0:3]
	s_setprio 0
	s_add_i32 s46, 0, 0x18000
	s_add_i32 s47, 0, 0x1c000
	v_add_u32_e32 v140, s46, v195
	v_add_u32_e32 v156, s47, v195
	ds_read_b128 v[128:131], v140
	ds_read_b128 v[132:135], v140 offset:1024
	ds_read_b128 v[136:139], v140 offset:2048
	ds_read_b128 v[140:143], v140 offset:3072
	ds_read_b128 v[144:147], v156
	ds_read_b128 v[148:151], v156 offset:1024
	ds_read_b128 v[152:155], v156 offset:2048
	ds_read_b128 v[156:159], v156 offset:3072
	s_add_u32 s20, s20, 0xb0000
	s_addc_u32 s21, s21, 0
	s_mov_b32 m0, s27
	v_lshl_add_u64 v[222:223], s[20:21], 0, v[164:165]
	ds_read_b128 v[160:163], v199 offset:32768
	ds_read_b128 v[180:183], v199 offset:33792
	ds_read_b128 v[184:187], v199 offset:34816
	ds_read_b128 v[188:191], v199 offset:35840
	ds_read_b128 v[200:203], v199 offset:36864
	ds_read_b128 v[204:207], v199 offset:37888
	ds_read_b128 v[208:211], v199 offset:38912
	ds_read_b128 v[212:215], v199 offset:39936
	global_load_lds_dwordx4 v[222:223], off
	s_mov_b32 m0, s28
	v_lshl_add_u64 v[222:223], s[20:21], 0, v[168:169]
	global_load_lds_dwordx4 v[222:223], off
	s_waitcnt vmcnt(8) lgkmcnt(0)
	s_barrier
	s_setprio 1
	v_mfma_f32_16x16x32_bf16 v[124:127], v[128:131], v[160:163], v[124:127]
	v_mfma_f32_16x16x32_bf16 v[124:127], v[132:135], v[180:183], v[124:127]
	v_mfma_f32_16x16x32_bf16 v[120:123], v[136:139], v[160:163], v[120:123]
	v_mfma_f32_16x16x32_bf16 v[120:123], v[140:143], v[180:183], v[120:123]
	v_mfma_f32_16x16x32_bf16 v[108:111], v[128:131], v[184:187], v[108:111]
	v_mfma_f32_16x16x32_bf16 v[108:111], v[132:135], v[188:191], v[108:111]
	v_mfma_f32_16x16x32_bf16 v[104:107], v[136:139], v[184:187], v[104:107]
	v_mfma_f32_16x16x32_bf16 v[104:107], v[140:143], v[188:191], v[104:107]
	v_mfma_f32_16x16x32_bf16 v[96:99], v[128:131], v[200:203], v[96:99]
	v_mfma_f32_16x16x32_bf16 v[96:99], v[132:135], v[204:207], v[96:99]
	v_mfma_f32_16x16x32_bf16 v[88:91], v[136:139], v[200:203], v[88:91]
	v_mfma_f32_16x16x32_bf16 v[88:91], v[140:143], v[204:207], v[88:91]
	v_mfma_f32_16x16x32_bf16 v[80:83], v[128:131], v[208:211], v[80:83]
	v_mfma_f32_16x16x32_bf16 v[80:83], v[132:135], v[212:215], v[80:83]
	v_mfma_f32_16x16x32_bf16 v[72:75], v[136:139], v[208:211], v[72:75]
	v_mfma_f32_16x16x32_bf16 v[72:75], v[140:143], v[212:215], v[72:75]
	v_mfma_f32_16x16x32_bf16 v[116:119], v[144:147], v[160:163], v[116:119]
	v_mfma_f32_16x16x32_bf16 v[116:119], v[148:151], v[180:183], v[116:119]
	v_mfma_f32_16x16x32_bf16 v[112:115], v[152:155], v[160:163], v[112:115]
	v_mfma_f32_16x16x32_bf16 v[112:115], v[156:159], v[180:183], v[112:115]
	v_mfma_f32_16x16x32_bf16 v[100:103], v[144:147], v[184:187], v[100:103]
	v_mfma_f32_16x16x32_bf16 v[100:103], v[148:151], v[188:191], v[100:103]
	v_mfma_f32_16x16x32_bf16 v[92:95], v[152:155], v[184:187], v[92:95]
	v_mfma_f32_16x16x32_bf16 v[92:95], v[156:159], v[188:191], v[92:95]
	v_mfma_f32_16x16x32_bf16 v[84:87], v[144:147], v[200:203], v[84:87]
	v_mfma_f32_16x16x32_bf16 v[84:87], v[148:151], v[204:207], v[84:87]
	v_mfma_f32_16x16x32_bf16 v[76:79], v[152:155], v[200:203], v[76:79]
	v_mfma_f32_16x16x32_bf16 v[76:79], v[156:159], v[204:207], v[76:79]
	v_mfma_f32_16x16x32_bf16 v[68:71], v[144:147], v[208:211], v[68:71]
	v_mfma_f32_16x16x32_bf16 v[68:71], v[148:151], v[212:215], v[68:71]
	s_setprio 3
	s_barrier
	v_mfma_f32_16x16x32_bf16 v[64:67], v[152:155], v[208:211], v[64:67]
	v_mfma_f32_16x16x32_bf16 v[64:67], v[156:159], v[212:215], v[64:67]
	s_setprio 0
	s_add_i32 s20, s46, s24
	v_lshl_add_u64 v[192:193], v[192:193], 0, s[8:9]
	s_mov_b32 m0, s20
	ds_read_b128 v[160:163], v199 offset:49152
	ds_read_b128 v[180:183], v199 offset:50176
	ds_read_b128 v[184:187], v199 offset:51200
	ds_read_b128 v[188:191], v199 offset:52224
	ds_read_b128 v[200:203], v199 offset:53248
	ds_read_b128 v[204:207], v199 offset:54272
	ds_read_b128 v[208:211], v199 offset:55296
	ds_read_b128 v[212:215], v199 offset:56320
	global_load_lds_dwordx4 v[192:193], off
	s_add_i32 m0, s20, 0x2000
	s_add_u32 s18, s18, 0xb0080
	v_lshl_add_u64 v[192:193], v[216:217], 0, s[8:9]
	s_addc_u32 s19, s19, 0
	s_add_i32 s20, s47, s24
	global_load_lds_dwordx4 v[192:193], off
	s_mov_b32 m0, s20
	v_lshl_add_u64 v[192:193], s[18:19], 0, v[166:167]
	global_load_lds_dwordx4 v[192:193], off
	s_add_i32 m0, s20, 0x2000
	v_lshl_add_u64 v[192:193], s[18:19], 0, v[170:171]
	global_load_lds_dwordx4 v[192:193], off
	s_mov_b32 m0, s33
	v_lshl_add_u64 v[192:193], v[218:219], 0, s[8:9]
	global_load_lds_dwordx4 v[192:193], off
	s_mov_b32 m0, s35
	v_lshl_add_u64 v[192:193], v[220:221], 0, s[8:9]
	global_load_lds_dwordx4 v[192:193], off
	s_waitcnt vmcnt(8) lgkmcnt(0)
	s_barrier
	s_setprio 1
	v_mfma_f32_16x16x32_bf16 v[60:63], v[128:131], v[160:163], v[60:63]
	v_mfma_f32_16x16x32_bf16 v[60:63], v[132:135], v[180:183], v[60:63]
	v_mfma_f32_16x16x32_bf16 v[56:59], v[136:139], v[160:163], v[56:59]
	v_mfma_f32_16x16x32_bf16 v[56:59], v[140:143], v[180:183], v[56:59]
	v_mfma_f32_16x16x32_bf16 v[48:51], v[128:131], v[184:187], v[48:51]
	v_mfma_f32_16x16x32_bf16 v[48:51], v[132:135], v[188:191], v[48:51]
	v_mfma_f32_16x16x32_bf16 v[40:43], v[136:139], v[184:187], v[40:43]
	v_mfma_f32_16x16x32_bf16 v[40:43], v[140:143], v[188:191], v[40:43]
	v_mfma_f32_16x16x32_bf16 v[32:35], v[128:131], v[200:203], v[32:35]
	v_mfma_f32_16x16x32_bf16 v[32:35], v[132:135], v[204:207], v[32:35]
	v_mfma_f32_16x16x32_bf16 v[24:27], v[136:139], v[200:203], v[24:27]
	v_mfma_f32_16x16x32_bf16 v[24:27], v[140:143], v[204:207], v[24:27]
	v_mfma_f32_16x16x32_bf16 v[16:19], v[128:131], v[208:211], v[16:19]
	v_mfma_f32_16x16x32_bf16 v[16:19], v[132:135], v[212:215], v[16:19]
	v_mfma_f32_16x16x32_bf16 v[8:11], v[136:139], v[208:211], v[8:11]
	v_mfma_f32_16x16x32_bf16 v[8:11], v[140:143], v[212:215], v[8:11]
	v_mfma_f32_16x16x32_bf16 v[52:55], v[144:147], v[160:163], v[52:55]
	v_mfma_f32_16x16x32_bf16 v[52:55], v[148:151], v[180:183], v[52:55]
	v_mfma_f32_16x16x32_bf16 v[44:47], v[152:155], v[160:163], v[44:47]
	v_mfma_f32_16x16x32_bf16 v[44:47], v[156:159], v[180:183], v[44:47]
	v_mfma_f32_16x16x32_bf16 v[36:39], v[144:147], v[184:187], v[36:39]
	v_mfma_f32_16x16x32_bf16 v[36:39], v[148:151], v[188:191], v[36:39]
	v_mfma_f32_16x16x32_bf16 v[28:31], v[152:155], v[184:187], v[28:31]
	v_mfma_f32_16x16x32_bf16 v[28:31], v[156:159], v[188:191], v[28:31]
	v_mfma_f32_16x16x32_bf16 v[20:23], v[144:147], v[200:203], v[20:23]
	v_mfma_f32_16x16x32_bf16 v[20:23], v[148:151], v[204:207], v[20:23]
	v_mfma_f32_16x16x32_bf16 v[12:15], v[152:155], v[200:203], v[12:15]
	v_mfma_f32_16x16x32_bf16 v[12:15], v[156:159], v[204:207], v[12:15]
	v_mfma_f32_16x16x32_bf16 v[4:7], v[144:147], v[208:211], v[4:7]
	v_mfma_f32_16x16x32_bf16 v[4:7], v[148:151], v[212:215], v[4:7]
	s_setprio 3
	s_barrier
	v_mfma_f32_16x16x32_bf16 v[0:3], v[152:155], v[208:211], v[0:3]
	v_mfma_f32_16x16x32_bf16 v[0:3], v[156:159], v[212:215], v[0:3]
	s_setprio 0
	s_add_i32 s45, s45, 2
	s_add_u32 s16, s16, 0x100
	s_addc_u32 s17, s17, 0
	s_add_u32 s43, s43, 0x100
	s_addc_u32 s44, s44, 0
	s_cmp_gt_u32 s45, 41
	s_cbranch_scc0 .LBB0_2341
	s_and_b64 vcc, exec, s[10:11]
	s_cbranch_vccz .LBB0_2344
	s_barrier
